# K-loop LDS-DMA loads use SGPR base + 32-bit VGPR offset (drops 64-bit VALU address adds)
# speedup vs baseline: 1.0025x; 1.0025x over previous
; #define PG8_STAGE(bufoff, gbase, voff) do { _Pragma("unroll") for (int _i = 0; _i < 2; ++_i) \
;         __builtin_amdgcn_global_load_lds((const unsigned*)((const char*)(gbase) + (voff)[_i]), (LAS unsigned*)(lds + (bufoff) + ldsw + _i * 8192), 16, 0, 0); } while (0)
; #define PG8_LDA(dst, b, h) do { _Pragma("unroll") for (int m = 0; m < 4; ++m) _Pragma("unroll") for (int k = 0; k < 2; ++k) dst[m][k] = *(const LAS bf16x8*)(lds + PG8_SA(b, h) + aoff + m * 2048 + k * 1024); } while (0)
; #define PG8_LDB(dst, b, h) do { _Pragma("unroll") for (int n = 0; n < 2; ++n) _Pragma("unroll") for (int k = 0; k < 2; ++k) dst[n][k] = *(const LAS bf16x8*)(lds + PG8_SB(b, h) + boff + n * 2048 + k * 1024); } while (0)
; #define PG8_WAIT_V(n) asm volatile("s_waitcnt vmcnt(" #n ")" ::: "memory")
; #define PG8_WAIT_L(n) asm volatile("s_waitcnt lgkmcnt(" #n ")" ::: "memory")
; #define PG8_BAR __builtin_amdgcn_s_barrier()
; #define PG8_SCHED __builtin_amdgcn_sched_barrier(0)
; template <class Epi>
; __device__ __forceinline__ void gemm_phase(LAS unsigned char* lds, const bf16_t* A, int lda, const bf16_t* Bt, int ldb, int M, int N, int K, int asel, const Epi& E, const int fixed_round = -1) {
;     ...
;         for (int t = 0; t < nt; t += 2) {
;             const bool last = (t == nt - 2);
;             const char* a1 = cA + (size_t)(t + 1) * kstep;
;             const char* a2 = last ? nA : cA + (size_t)(t + 2) * kstep; const char* b2 = last ? nB : cB + (size_t)(t + 2) * kstep;
;             const char* a3 = a2 + kstep; const char* b3 = b2 + kstep;
;             PG8_LDB(B0, 0, 0); PG8_SCHED; PG8_LDA(At, 0, 0); PG8_STAGE(PG8_SA(1, 1), a1 + hstepA, voffA);
;             PG8_WAIT_L(8); PG8_BAR; PG8_WAIT_L(0); PG8_MMA(0, 0, At, B0); PG8_BAR; PG8_SCHED;
;             PG8_LDB(B1, 0, 1); PG8_STAGE(PG8_SB(0, 0), b2, voffB);
;             PG8_BAR; PG8_WAIT_L(0); PG8_MMA(0, 1, At, B1); PG8_BAR;
;             PG8_LDA(At, 0, 1); PG8_STAGE(PG8_SA(0, 0), a2, voffA);
;             PG8_BAR; PG8_WAIT_L(0); PG8_MMA(1, 0, At, B0); PG8_BAR; PG8_SCHED;
;             PG8_STAGE(PG8_SB(0, 1), b2 + hstepB, voffB);
;             PG8_WAIT_V(6); PG8_BAR; PG8_MMA(1, 1, At, B1); PG8_BAR;
.LBB0_199:
	ds_read_b128 v[148:151], v161
	ds_read_b128 v[152:155], v161 offset:1024
	ds_read_b128 v[156:159], v161 offset:2048
	ds_read_b128 v[166:169], v161 offset:3072
	s_add_u32 s30, s28, 0xfff80080
	s_addc_u32 s31, s29, -1
	s_cmp_eq_u32 s58, 28
	s_cselect_b32 s35, s4, s31
	s_cselect_b32 s34, s21, s30
	s_cselect_b32 s31, s19, s57
	s_cselect_b32 s30, s55, s56
	s_add_i32 m0, s39, 0xc000
	ds_read_b128 v[170:173], v162
	ds_read_b128 v[174:177], v162 offset:1024
	ds_read_b128 v[178:181], v162 offset:2048
	ds_read_b128 v[182:185], v162 offset:3072
	ds_read_b128 v[186:189], v162 offset:4096
	ds_read_b128 v[190:193], v162 offset:5120
	ds_read_b128 v[196:199], v162 offset:6144
	ds_read_b128 v[202:205], v162 offset:7168
	global_load_lds_dwordx4 v140, s[28:29]
	s_add_i32 m0, s39, 0xe000
	s_nop 0
	global_load_lds_dwordx4 v142, s[28:29]
	s_waitcnt lgkmcnt(8)
	s_barrier
	s_waitcnt lgkmcnt(0)
	s_setprio 1
	s_waitcnt lgkmcnt(0)
	v_mfma_f32_16x16x32_bf16 v[124:127], v[148:151], v[170:173], v[124:127]
	v_mfma_f32_16x16x32_bf16 v[120:123], v[156:159], v[170:173], v[120:123]
	v_mfma_f32_16x16x32_bf16 v[112:115], v[148:151], v[178:181], v[112:115]
	v_mfma_f32_16x16x32_bf16 v[108:111], v[156:159], v[178:181], v[108:111]
	v_mfma_f32_16x16x32_bf16 v[100:103], v[148:151], v[186:189], v[100:103]
	v_mfma_f32_16x16x32_bf16 v[92:95], v[156:159], v[186:189], v[92:95]
	v_mfma_f32_16x16x32_bf16 v[84:87], v[148:151], v[196:199], v[84:87]
	v_mfma_f32_16x16x32_bf16 v[76:79], v[156:159], v[196:199], v[76:79]
	v_mfma_f32_16x16x32_bf16 v[124:127], v[152:155], v[174:177], v[124:127]
	v_mfma_f32_16x16x32_bf16 v[120:123], v[166:169], v[174:177], v[120:123]
	v_mfma_f32_16x16x32_bf16 v[112:115], v[152:155], v[182:185], v[112:115]
	v_mfma_f32_16x16x32_bf16 v[108:111], v[166:169], v[182:185], v[108:111]
	v_mfma_f32_16x16x32_bf16 v[100:103], v[152:155], v[190:193], v[100:103]
	v_mfma_f32_16x16x32_bf16 v[92:95], v[166:169], v[190:193], v[92:95]
	v_mfma_f32_16x16x32_bf16 v[84:87], v[152:155], v[202:205], v[84:87]
	v_mfma_f32_16x16x32_bf16 v[76:79], v[166:169], v[202:205], v[76:79]
	s_setprio 0
	s_barrier
	s_add_i32 s59, s46, s38
	s_add_u32 s98, s30, s6
	s_addc_u32 s99, s31, s7
	s_mov_b32 m0, s59
	ds_read_b128 v[206:209], v163
	ds_read_b128 v[210:213], v163 offset:1024
	ds_read_b128 v[214:217], v163 offset:2048
	ds_read_b128 v[218:221], v163 offset:3072
	global_load_lds_dwordx4 v130, s[30:31]
	s_add_i32 m0, s59, 0x2000
	s_nop 0
	global_load_lds_dwordx4 v134, s[30:31]
	s_barrier
	s_waitcnt lgkmcnt(0)
	s_setprio 1
	s_waitcnt lgkmcnt(0)
	v_mfma_f32_16x16x32_bf16 v[116:119], v[206:209], v[170:173], v[116:119]
	v_mfma_f32_16x16x32_bf16 v[104:107], v[214:217], v[170:173], v[104:107]
	v_mfma_f32_16x16x32_bf16 v[96:99], v[206:209], v[178:181], v[96:99]
	v_mfma_f32_16x16x32_bf16 v[88:91], v[214:217], v[178:181], v[88:91]
	v_mfma_f32_16x16x32_bf16 v[80:83], v[206:209], v[186:189], v[80:83]
	v_mfma_f32_16x16x32_bf16 v[72:75], v[214:217], v[186:189], v[72:75]
	v_mfma_f32_16x16x32_bf16 v[68:71], v[206:209], v[196:199], v[68:71]
	v_mfma_f32_16x16x32_bf16 v[64:67], v[214:217], v[196:199], v[64:67]
	v_mfma_f32_16x16x32_bf16 v[116:119], v[210:213], v[174:177], v[116:119]
	v_mfma_f32_16x16x32_bf16 v[104:107], v[218:221], v[174:177], v[104:107]
	v_mfma_f32_16x16x32_bf16 v[96:99], v[210:213], v[182:185], v[96:99]
	v_mfma_f32_16x16x32_bf16 v[88:91], v[218:221], v[182:185], v[88:91]
	v_mfma_f32_16x16x32_bf16 v[80:83], v[210:213], v[190:193], v[80:83]
	v_mfma_f32_16x16x32_bf16 v[72:75], v[218:221], v[190:193], v[72:75]
	v_mfma_f32_16x16x32_bf16 v[68:71], v[210:213], v[202:205], v[68:71]
	v_mfma_f32_16x16x32_bf16 v[64:67], v[218:221], v[202:205], v[64:67]
	s_setprio 0
	s_mov_b32 m0, s39
	s_add_u32 s100, s34, s6
	s_addc_u32 s101, s35, s7
	s_barrier
	ds_read_b128 v[170:173], v162 offset:16384
	ds_read_b128 v[174:177], v162 offset:17408
	ds_read_b128 v[178:181], v162 offset:18432
	ds_read_b128 v[182:185], v162 offset:19456
	ds_read_b128 v[186:189], v162 offset:20480
	ds_read_b128 v[190:193], v162 offset:21504
	ds_read_b128 v[196:199], v162 offset:22528
	ds_read_b128 v[202:205], v162 offset:23552
	global_load_lds_dwordx4 v128, s[34:35]
	s_mov_b32 m0, s40
	s_nop 0
	global_load_lds_dwordx4 v132, s[34:35]
	s_barrier
	s_waitcnt lgkmcnt(0)
	s_setprio 1
	s_waitcnt lgkmcnt(0)
	v_mfma_f32_16x16x32_bf16 v[60:63], v[148:151], v[170:173], v[60:63]
	v_mfma_f32_16x16x32_bf16 v[56:59], v[156:159], v[170:173], v[56:59]
	v_mfma_f32_16x16x32_bf16 v[52:55], v[148:151], v[178:181], v[52:55]
	v_mfma_f32_16x16x32_bf16 v[44:47], v[156:159], v[178:181], v[44:47]
	v_mfma_f32_16x16x32_bf16 v[36:39], v[148:151], v[186:189], v[36:39]
	v_mfma_f32_16x16x32_bf16 v[28:31], v[156:159], v[186:189], v[28:31]
	v_mfma_f32_16x16x32_bf16 v[20:23], v[148:151], v[196:199], v[20:23]
	v_mfma_f32_16x16x32_bf16 v[12:15], v[156:159], v[196:199], v[12:15]
	v_mfma_f32_16x16x32_bf16 v[60:63], v[152:155], v[174:177], v[60:63]
	v_mfma_f32_16x16x32_bf16 v[56:59], v[166:169], v[174:177], v[56:59]
	v_mfma_f32_16x16x32_bf16 v[52:55], v[152:155], v[182:185], v[52:55]
	v_mfma_f32_16x16x32_bf16 v[44:47], v[166:169], v[182:185], v[44:47]
	v_mfma_f32_16x16x32_bf16 v[36:39], v[152:155], v[190:193], v[36:39]
	v_mfma_f32_16x16x32_bf16 v[28:31], v[166:169], v[190:193], v[28:31]
	v_mfma_f32_16x16x32_bf16 v[20:23], v[152:155], v[202:205], v[20:23]
	v_mfma_f32_16x16x32_bf16 v[12:15], v[166:169], v[202:205], v[12:15]
	s_setprio 0
	s_barrier
	s_add_u32 s60, s30, 0x80000
	s_addc_u32 s61, s31, 0
	s_add_i32 s59, s47, s38
	s_mov_b32 m0, s59
	s_nop 0
	global_load_lds_dwordx4 v130, s[60:61]
	s_add_i32 m0, s59, 0x2000
	s_nop 0
	global_load_lds_dwordx4 v134, s[60:61]
	s_waitcnt vmcnt(6)
	s_barrier
; #define PG8_STAGE(bufoff, gbase, voff) do { _Pragma("unroll") for (int _i = 0; _i < 2; ++_i) \
;         __builtin_amdgcn_global_load_lds((const unsigned*)((const char*)(gbase) + (voff)[_i]), (LAS unsigned*)(lds + (bufoff) + ldsw + _i * 8192), 16, 0, 0); } while (0)
; #define PG8_LDA(dst, b, h) do { _Pragma("unroll") for (int m = 0; m < 4; ++m) _Pragma("unroll") for (int k = 0; k < 2; ++k) dst[m][k] = *(const LAS bf16x8*)(lds + PG8_SA(b, h) + aoff + m * 2048 + k * 1024); } while (0)
; #define PG8_LDB(dst, b, h) do { _Pragma("unroll") for (int n = 0; n < 2; ++n) _Pragma("unroll") for (int k = 0; k < 2; ++k) dst[n][k] = *(const LAS bf16x8*)(lds + PG8_SB(b, h) + boff + n * 2048 + k * 1024); } while (0)
; #define PG8_WAIT_L(n) asm volatile("s_waitcnt lgkmcnt(" #n ")" ::: "memory")
; #define PG8_BAR __builtin_amdgcn_s_barrier()
; #define PG8_SCHED __builtin_amdgcn_sched_barrier(0)
; template <class Epi>
; __device__ __forceinline__ void gemm_phase(LAS unsigned char* lds, const bf16_t* A, int lda, const bf16_t* Bt, int ldb, int M, int N, int K, int asel, const Epi& E, const int fixed_round = -1) {
;     ...
;             PG8_LDB(B0, 1, 0); PG8_SCHED; PG8_LDA(At, 1, 0); PG8_STAGE(PG8_SA(0, 1), a2 + hstepA, voffA);
;             PG8_WAIT_L(8); PG8_BAR; PG8_WAIT_L(0); PG8_MMA(0, 0, At, B0); PG8_BAR; PG8_SCHED;
;             PG8_LDB(B1, 1, 1); PG8_STAGE(PG8_SB(1, 0), b3, voffB);
;             PG8_BAR; PG8_WAIT_L(0); PG8_MMA(0, 1, At, B1); PG8_BAR;
;             PG8_LDA(At, 1, 1); PG8_STAGE(PG8_SA(1, 0), a3, voffA);
;             PG8_BAR; PG8_WAIT_L(0); PG8_MMA(1, 0, At, B0); PG8_BAR; PG8_SCHED;
	s_setprio 1
	v_mfma_f32_16x16x32_bf16 v[48:51], v[206:209], v[170:173], v[48:51]
	v_mfma_f32_16x16x32_bf16 v[40:43], v[214:217], v[170:173], v[40:43]
	v_mfma_f32_16x16x32_bf16 v[32:35], v[206:209], v[178:181], v[32:35]
	v_mfma_f32_16x16x32_bf16 v[24:27], v[214:217], v[178:181], v[24:27]
	v_mfma_f32_16x16x32_bf16 v[16:19], v[206:209], v[186:189], v[16:19]
	v_mfma_f32_16x16x32_bf16 v[8:11], v[214:217], v[186:189], v[8:11]
	v_mfma_f32_16x16x32_bf16 v[4:7], v[206:209], v[196:199], v[4:7]
	v_mfma_f32_16x16x32_bf16 v[0:3], v[214:217], v[196:199], v[0:3]
	v_mfma_f32_16x16x32_bf16 v[48:51], v[210:213], v[174:177], v[48:51]
	v_mfma_f32_16x16x32_bf16 v[40:43], v[218:221], v[174:177], v[40:43]
	v_mfma_f32_16x16x32_bf16 v[32:35], v[210:213], v[182:185], v[32:35]
	v_mfma_f32_16x16x32_bf16 v[24:27], v[218:221], v[182:185], v[24:27]
	v_mfma_f32_16x16x32_bf16 v[16:19], v[210:213], v[190:193], v[16:19]
	v_mfma_f32_16x16x32_bf16 v[8:11], v[218:221], v[190:193], v[8:11]
	v_mfma_f32_16x16x32_bf16 v[4:7], v[210:213], v[202:205], v[4:7]
	v_mfma_f32_16x16x32_bf16 v[0:3], v[218:221], v[202:205], v[0:3]
	s_setprio 0
	s_add_i32 s59, 0, 0x18000
	v_add_u32_e32 v136, s59, v160
	s_barrier
	ds_read_b128 v[148:151], v136
	ds_read_b128 v[152:155], v136 offset:1024
	ds_read_b128 v[156:159], v136 offset:2048
	ds_read_b128 v[166:169], v136 offset:3072
	s_add_u32 s34, s34, 0x80000
	s_addc_u32 s35, s35, 0
	s_mov_b32 m0, s41
	ds_read_b128 v[170:173], v162 offset:32768
	ds_read_b128 v[174:177], v162 offset:33792
	ds_read_b128 v[178:181], v162 offset:34816
	ds_read_b128 v[182:185], v162 offset:35840
	ds_read_b128 v[186:189], v162 offset:36864
	ds_read_b128 v[190:193], v162 offset:37888
	ds_read_b128 v[196:199], v162 offset:38912
	ds_read_b128 v[202:205], v162 offset:39936
	global_load_lds_dwordx4 v128, s[34:35]
	s_mov_b32 m0, s42
	s_nop 0
	global_load_lds_dwordx4 v132, s[34:35]
	s_waitcnt lgkmcnt(8)
	s_barrier
	s_waitcnt lgkmcnt(0)
	s_setprio 1
	s_waitcnt lgkmcnt(0)
	v_mfma_f32_16x16x32_bf16 v[124:127], v[148:151], v[170:173], v[124:127]
	v_mfma_f32_16x16x32_bf16 v[120:123], v[156:159], v[170:173], v[120:123]
	v_mfma_f32_16x16x32_bf16 v[112:115], v[148:151], v[178:181], v[112:115]
	v_mfma_f32_16x16x32_bf16 v[108:111], v[156:159], v[178:181], v[108:111]
	v_mfma_f32_16x16x32_bf16 v[100:103], v[148:151], v[186:189], v[100:103]
	v_mfma_f32_16x16x32_bf16 v[92:95], v[156:159], v[186:189], v[92:95]
	v_mfma_f32_16x16x32_bf16 v[84:87], v[148:151], v[196:199], v[84:87]
	v_mfma_f32_16x16x32_bf16 v[76:79], v[156:159], v[196:199], v[76:79]
	v_mfma_f32_16x16x32_bf16 v[124:127], v[152:155], v[174:177], v[124:127]
	v_mfma_f32_16x16x32_bf16 v[120:123], v[166:169], v[174:177], v[120:123]
	v_mfma_f32_16x16x32_bf16 v[112:115], v[152:155], v[182:185], v[112:115]
	v_mfma_f32_16x16x32_bf16 v[108:111], v[166:169], v[182:185], v[108:111]
	v_mfma_f32_16x16x32_bf16 v[100:103], v[152:155], v[190:193], v[100:103]
	v_mfma_f32_16x16x32_bf16 v[92:95], v[166:169], v[190:193], v[92:95]
	v_mfma_f32_16x16x32_bf16 v[84:87], v[152:155], v[202:205], v[84:87]
	v_mfma_f32_16x16x32_bf16 v[76:79], v[166:169], v[202:205], v[76:79]
	s_setprio 0
	s_barrier
	s_add_i32 s34, 0, 0x1c000
	s_add_i32 s35, s59, s38
	v_add_u32_e32 v136, s34, v160
	s_mov_b32 m0, s35
	ds_read_b128 v[206:209], v136
	ds_read_b128 v[210:213], v136 offset:1024
	ds_read_b128 v[214:217], v136 offset:2048
	ds_read_b128 v[218:221], v136 offset:3072
	global_load_lds_dwordx4 v130, s[98:99]
	s_add_i32 m0, s35, 0x2000
	s_nop 0
	global_load_lds_dwordx4 v134, s[98:99]
	s_barrier
	s_waitcnt lgkmcnt(0)
	s_setprio 1
	s_waitcnt lgkmcnt(0)
	v_mfma_f32_16x16x32_bf16 v[116:119], v[206:209], v[170:173], v[116:119]
	v_mfma_f32_16x16x32_bf16 v[104:107], v[214:217], v[170:173], v[104:107]
	v_mfma_f32_16x16x32_bf16 v[96:99], v[206:209], v[178:181], v[96:99]
	v_mfma_f32_16x16x32_bf16 v[88:91], v[214:217], v[178:181], v[88:91]
	v_mfma_f32_16x16x32_bf16 v[80:83], v[206:209], v[186:189], v[80:83]
	v_mfma_f32_16x16x32_bf16 v[72:75], v[214:217], v[186:189], v[72:75]
	v_mfma_f32_16x16x32_bf16 v[68:71], v[206:209], v[196:199], v[68:71]
	v_mfma_f32_16x16x32_bf16 v[64:67], v[214:217], v[196:199], v[64:67]
	v_mfma_f32_16x16x32_bf16 v[116:119], v[210:213], v[174:177], v[116:119]
	v_mfma_f32_16x16x32_bf16 v[104:107], v[218:221], v[174:177], v[104:107]
	v_mfma_f32_16x16x32_bf16 v[96:99], v[210:213], v[182:185], v[96:99]
	v_mfma_f32_16x16x32_bf16 v[88:91], v[218:221], v[182:185], v[88:91]
	v_mfma_f32_16x16x32_bf16 v[80:83], v[210:213], v[190:193], v[80:83]
	v_mfma_f32_16x16x32_bf16 v[72:75], v[218:221], v[190:193], v[72:75]
	v_mfma_f32_16x16x32_bf16 v[68:71], v[210:213], v[202:205], v[68:71]
	v_mfma_f32_16x16x32_bf16 v[64:67], v[218:221], v[202:205], v[64:67]
	s_setprio 0
	s_mov_b32 m0, s43
	s_barrier
	ds_read_b128 v[170:173], v162 offset:49152
	ds_read_b128 v[174:177], v162 offset:50176
	ds_read_b128 v[178:181], v162 offset:51200
	ds_read_b128 v[182:185], v162 offset:52224
	ds_read_b128 v[186:189], v162 offset:53248
	ds_read_b128 v[190:193], v162 offset:54272
	ds_read_b128 v[196:199], v162 offset:55296
	ds_read_b128 v[202:205], v162 offset:56320
	global_load_lds_dwordx4 v128, s[100:101]
	s_mov_b32 m0, s44
	s_nop 0
	global_load_lds_dwordx4 v132, s[100:101]
	s_barrier
; #define LAS __attribute__((address_space(3)))
; __device__ __forceinline__ unsigned cvt_pk_bf16(float lo, float hi) { const bf16x2_t r = __builtin_convertvector((f32x2){lo, hi}, bf16x2_t); return __builtin_bit_cast(unsigned, r); }
; #define PG8_WAIT_V(n) asm volatile("s_waitcnt vmcnt(" #n ")" ::: "memory")
; #define PG8_BAR __builtin_amdgcn_s_barrier()
; template <class Epi>
; __device__ __forceinline__ void gemm_phase(LAS unsigned char* lds, const bf16_t* A, int lda, const bf16_t* Bt, int ldb, int M, int N, int K, int asel, const Epi& E, const int fixed_round = -1) {
;     ...
;             PG8_STAGE(PG8_SB(1, 1), b3 + hstepB, voffB);
;             PG8_WAIT_V(6); PG8_BAR; PG8_MMA(1, 1, At, B1); PG8_BAR;
;             if constexpr (Epi::HEADSCALE) {
;                 if (t & 2) {
;                     const LAS float* rt = (const LAS float*)(lds + L_RT) + (t >> 2);
; #pragma unroll
;                     for (int ai = 0; ai < 2; ++ai)
; #pragma unroll
;                         for (int m = 0; m < 4; ++m) { const float f = rt[(ai * HALF + wr * 64 + m * 16 + fr) * 8];
; #pragma unroll
;                             for (int bj = 0; bj < 2; ++bj)
; #pragma unroll
;                                 for (int n = 0; n < 2; ++n) acc[ai][bj][m][n] *= f; }
;                 }
;             }
;         }
;         if constexpr (!Epi::AFTER_DRAIN) E(acc, cur, wr, wc, fr, fq);
;         if (!has_next) break;
;     __device__ __forceinline__ void operator()(const AccT& acc, const Unit& u, int wr, int wc, int fr, int fq) const {
;     ...
;         if (pn < 8) {
;             bf16_t* base = pn < 4 ? Q : Kn; const int colt = (pn & 3) * BM; const float sc = pn < 4 ? 0.08838834764831845f : 1.0f;
; #pragma unroll
;             for (int ai = 0; ai < 2; ++ai)
; #pragma unroll
;                 for (int m = 0; m < 4; ++m) { bf16_t* rowp = base + (size_t)(row0 + ai * HALF + m * 16) * 1024 + colt + cl;
; #pragma unroll
;                     for (int bj = 0; bj < 2; ++bj) { const f32x4 v0 = acc[ai][bj][m][0] * sc, v1 = acc[ai][bj][m][1] * sc;
;                         u32x4 w; w.x = cvt_pk_bf16(v0[0], v0[1]); w.y = cvt_pk_bf16(v0[2], v0[3]); w.z = cvt_pk_bf16(v1[0], v1[1]); w.w = cvt_pk_bf16(v1[2], v1[3]);
;                         *(u32x4*)(rowp + bj * HALF) = w; } }
	s_waitcnt lgkmcnt(0)
	s_setprio 1
	s_waitcnt lgkmcnt(0)
	v_mfma_f32_16x16x32_bf16 v[60:63], v[148:151], v[170:173], v[60:63]
	v_mfma_f32_16x16x32_bf16 v[56:59], v[156:159], v[170:173], v[56:59]
	v_mfma_f32_16x16x32_bf16 v[52:55], v[148:151], v[178:181], v[52:55]
	v_mfma_f32_16x16x32_bf16 v[44:47], v[156:159], v[178:181], v[44:47]
	v_mfma_f32_16x16x32_bf16 v[36:39], v[148:151], v[186:189], v[36:39]
	v_mfma_f32_16x16x32_bf16 v[28:31], v[156:159], v[186:189], v[28:31]
	v_mfma_f32_16x16x32_bf16 v[20:23], v[148:151], v[196:199], v[20:23]
	v_mfma_f32_16x16x32_bf16 v[12:15], v[156:159], v[196:199], v[12:15]
	v_mfma_f32_16x16x32_bf16 v[60:63], v[152:155], v[174:177], v[60:63]
	v_mfma_f32_16x16x32_bf16 v[56:59], v[166:169], v[174:177], v[56:59]
	v_mfma_f32_16x16x32_bf16 v[52:55], v[152:155], v[182:185], v[52:55]
	v_mfma_f32_16x16x32_bf16 v[44:47], v[166:169], v[182:185], v[44:47]
	v_mfma_f32_16x16x32_bf16 v[36:39], v[152:155], v[190:193], v[36:39]
	v_mfma_f32_16x16x32_bf16 v[28:31], v[166:169], v[190:193], v[28:31]
	v_mfma_f32_16x16x32_bf16 v[20:23], v[152:155], v[202:205], v[20:23]
	v_mfma_f32_16x16x32_bf16 v[12:15], v[166:169], v[202:205], v[12:15]
	s_setprio 0
	s_barrier
	s_add_u32 s30, s30, 0x80080
	s_addc_u32 s31, s31, 0
	s_add_i32 s34, s34, s38
	s_mov_b32 m0, s34
	s_nop 0
	global_load_lds_dwordx4 v130, s[30:31]
	s_add_i32 m0, s34, 0x2000
	s_nop 0
	global_load_lds_dwordx4 v134, s[30:31]
	s_waitcnt vmcnt(6)
	s_barrier
	s_setprio 1
	v_mfma_f32_16x16x32_bf16 v[48:51], v[206:209], v[170:173], v[48:51]
	v_mfma_f32_16x16x32_bf16 v[40:43], v[214:217], v[170:173], v[40:43]
	v_mfma_f32_16x16x32_bf16 v[32:35], v[206:209], v[178:181], v[32:35]
	v_mfma_f32_16x16x32_bf16 v[24:27], v[214:217], v[178:181], v[24:27]
	v_mfma_f32_16x16x32_bf16 v[16:19], v[206:209], v[186:189], v[16:19]
	v_mfma_f32_16x16x32_bf16 v[8:11], v[214:217], v[186:189], v[8:11]
	v_mfma_f32_16x16x32_bf16 v[4:7], v[206:209], v[196:199], v[4:7]
	v_mfma_f32_16x16x32_bf16 v[0:3], v[214:217], v[196:199], v[0:3]
	v_mfma_f32_16x16x32_bf16 v[48:51], v[210:213], v[174:177], v[48:51]
	v_mfma_f32_16x16x32_bf16 v[40:43], v[218:221], v[174:177], v[40:43]
	v_mfma_f32_16x16x32_bf16 v[32:35], v[210:213], v[182:185], v[32:35]
	v_mfma_f32_16x16x32_bf16 v[24:27], v[218:221], v[182:185], v[24:27]
	v_mfma_f32_16x16x32_bf16 v[16:19], v[210:213], v[190:193], v[16:19]
	v_mfma_f32_16x16x32_bf16 v[8:11], v[218:221], v[190:193], v[8:11]
	v_mfma_f32_16x16x32_bf16 v[4:7], v[210:213], v[202:205], v[4:7]
	v_mfma_f32_16x16x32_bf16 v[0:3], v[218:221], v[202:205], v[0:3]
	s_setprio 0
	s_add_i32 s58, s58, 2
	s_add_u32 s28, s28, 0x100
	s_addc_u32 s29, s29, 0
	s_add_u32 s56, s56, 0x100
	s_addc_u32 s57, s57, 0
	s_cmp_gt_u32 s58, 29
	s_barrier
	s_cbranch_scc0 .LBB0_199
	s_lshl_b32 s19, s26, 8
	v_add_u32_e32 v154, s19, v139
	s_cmp_lt_i32 s27, 8
	v_or_b32_e32 v152, 16, v154
	v_or_b32_e32 v150, 32, v154
	v_or_b32_e32 v148, 48, v154
	s_cselect_b64 s[28:29], -1, 0
	s_cmp_gt_i32 s27, 7
	v_ashrrev_i32_e32 v155, 31, v154
	v_lshlrev_b32_e32 v136, 1, v138
	v_ashrrev_i32_e32 v153, 31, v152
	v_ashrrev_i32_e32 v151, 31, v150
	v_ashrrev_i32_e32 v149, 31, v148
	s_cbranch_scc1 .LBB0_203
	s_cmp_lt_i32 s27, 4
	s_cselect_b64 vcc, -1, 0
	s_and_b64 s[30:31], vcc, exec
	s_cselect_b32 s4, s89, s81
	s_cselect_b32 s21, s88, s91
	s_lshl_b32 s30, s27, 9
	s_and_b32 s30, s30, 0x600
	s_add_u32 s30, s21, s30
	v_cndmask_b32_e32 v156, 1.0, v164, vcc
	s_addc_u32 s31, s4, 0
	v_lshl_add_u64 v[170:171], s[30:31], 0, v[136:137]
	v_lshlrev_b64 v[158:159], 11, v[154:155]
	v_pk_mul_f32 v[168:169], v[156:157], v[126:127] op_sel_hi:[0,1]
	v_pk_mul_f32 v[166:167], v[156:157], v[124:125] op_sel_hi:[0,1]
	v_pk_mul_f32 v[172:173], v[156:157], v[122:123] op_sel_hi:[0,1]
	v_pk_mul_f32 v[174:175], v[156:157], v[120:121] op_sel_hi:[0,1]
	v_lshl_add_u64 v[158:159], v[170:171], 0, v[158:159]
	v_cvt_pk_bf16_f32 v166, v166, v167
	v_cvt_pk_bf16_f32 v167, v168, v169
	v_cvt_pk_bf16_f32 v168, v174, v175
	v_cvt_pk_bf16_f32 v169, v172, v173
	global_store_dwordx4 v[158:159], v[166:169], off
	v_pk_mul_f32 v[172:173], v[156:157], v[106:107] op_sel_hi:[0,1]
	v_pk_mul_f32 v[174:175], v[156:157], v[104:105] op_sel_hi:[0,1]
	v_pk_mul_f32 v[168:169], v[156:157], v[118:119] op_sel_hi:[0,1]
	v_pk_mul_f32 v[166:167], v[156:157], v[116:117] op_sel_hi:[0,1]
	v_cvt_pk_bf16_f32 v166, v166, v167
	v_cvt_pk_bf16_f32 v167, v168, v169
	v_cvt_pk_bf16_f32 v168, v174, v175
	v_cvt_pk_bf16_f32 v169, v172, v173
	global_store_dwordx4 v[158:159], v[166:169], off offset:256
	v_pk_mul_f32 v[174:175], v[156:157], v[110:111] op_sel_hi:[0,1]
	v_pk_mul_f32 v[176:177], v[156:157], v[108:109] op_sel_hi:[0,1]
	v_lshlrev_b64 v[166:167], 11, v[152:153]
	v_lshl_add_u64 v[172:173], v[170:171], 0, v[166:167]
	v_pk_mul_f32 v[168:169], v[156:157], v[114:115] op_sel_hi:[0,1]
	v_pk_mul_f32 v[166:167], v[156:157], v[112:113] op_sel_hi:[0,1]
	v_cvt_pk_bf16_f32 v166, v166, v167
	v_cvt_pk_bf16_f32 v167, v168, v169
	v_cvt_pk_bf16_f32 v168, v176, v177
	v_cvt_pk_bf16_f32 v169, v174, v175
	global_store_dwordx4 v[172:173], v[166:169], off
	v_pk_mul_f32 v[174:175], v[156:157], v[90:91] op_sel_hi:[0,1]
	v_pk_mul_f32 v[176:177], v[156:157], v[88:89] op_sel_hi:[0,1]
	v_pk_mul_f32 v[168:169], v[156:157], v[98:99] op_sel_hi:[0,1]
	v_pk_mul_f32 v[166:167], v[156:157], v[96:97] op_sel_hi:[0,1]
	v_cvt_pk_bf16_f32 v166, v166, v167
	v_cvt_pk_bf16_f32 v167, v168, v169
	v_cvt_pk_bf16_f32 v168, v176, v177
	v_cvt_pk_bf16_f32 v169, v174, v175
	global_store_dwordx4 v[172:173], v[166:169], off offset:256
	v_pk_mul_f32 v[174:175], v[156:157], v[94:95] op_sel_hi:[0,1]
	v_pk_mul_f32 v[176:177], v[156:157], v[92:93] op_sel_hi:[0,1]
	v_lshlrev_b64 v[166:167], 11, v[150:151]
; __device__ __forceinline__ unsigned cvt_pk_bf16(float lo, float hi) { const bf16x2_t r = __builtin_convertvector((f32x2){lo, hi}, bf16x2_t); return __builtin_bit_cast(unsigned, r); }
;     __device__ __forceinline__ void operator()(const AccT& acc, const Unit& u, int wr, int wc, int fr, int fq) const {
;     ...
;         if (pn < 8) {
;             bf16_t* base = pn < 4 ? Q : Kn; const int colt = (pn & 3) * BM; const float sc = pn < 4 ? 0.08838834764831845f : 1.0f;
; #pragma unroll
;             for (int ai = 0; ai < 2; ++ai)
; #pragma unroll
;                 for (int m = 0; m < 4; ++m) { bf16_t* rowp = base + (size_t)(row0 + ai * HALF + m * 16) * 1024 + colt + cl;
; #pragma unroll
;                     for (int bj = 0; bj < 2; ++bj) { const f32x4 v0 = acc[ai][bj][m][0] * sc, v1 = acc[ai][bj][m][1] * sc;
;                         u32x4 w; w.x = cvt_pk_bf16(v0[0], v0[1]); w.y = cvt_pk_bf16(v0[2], v0[3]); w.z = cvt_pk_bf16(v1[0], v1[1]); w.w = cvt_pk_bf16(v1[2], v1[3]);
;                         *(u32x4*)(rowp + bj * HALF) = w; } }
;         }
;         if (pn >= 16) {
	v_lshl_add_u64 v[172:173], v[170:171], 0, v[166:167]
	v_pk_mul_f32 v[168:169], v[156:157], v[102:103] op_sel_hi:[0,1]
	v_pk_mul_f32 v[166:167], v[156:157], v[100:101] op_sel_hi:[0,1]
	v_cvt_pk_bf16_f32 v166, v166, v167
	v_cvt_pk_bf16_f32 v167, v168, v169
	v_cvt_pk_bf16_f32 v168, v176, v177
	v_cvt_pk_bf16_f32 v169, v174, v175
	global_store_dwordx4 v[172:173], v[166:169], off
	v_pk_mul_f32 v[174:175], v[156:157], v[74:75] op_sel_hi:[0,1]
	v_pk_mul_f32 v[176:177], v[156:157], v[72:73] op_sel_hi:[0,1]
	v_pk_mul_f32 v[168:169], v[156:157], v[82:83] op_sel_hi:[0,1]
	v_pk_mul_f32 v[166:167], v[156:157], v[80:81] op_sel_hi:[0,1]
	v_cvt_pk_bf16_f32 v166, v166, v167
	v_cvt_pk_bf16_f32 v167, v168, v169
	v_cvt_pk_bf16_f32 v168, v176, v177
	v_cvt_pk_bf16_f32 v169, v174, v175
	global_store_dwordx4 v[172:173], v[166:169], off offset:256
	v_pk_mul_f32 v[172:173], v[156:157], v[78:79] op_sel_hi:[0,1]
	v_pk_mul_f32 v[174:175], v[156:157], v[76:77] op_sel_hi:[0,1]
	v_lshlrev_b64 v[166:167], 11, v[148:149]
	v_lshl_add_u64 v[170:171], v[170:171], 0, v[166:167]
	v_pk_mul_f32 v[168:169], v[156:157], v[86:87] op_sel_hi:[0,1]
	v_pk_mul_f32 v[166:167], v[156:157], v[84:85] op_sel_hi:[0,1]
	v_cvt_pk_bf16_f32 v166, v166, v167
	v_cvt_pk_bf16_f32 v167, v168, v169
	v_cvt_pk_bf16_f32 v168, v174, v175
	v_cvt_pk_bf16_f32 v169, v172, v173
	global_store_dwordx4 v[170:171], v[166:169], off
	v_pk_mul_f32 v[172:173], v[156:157], v[66:67] op_sel_hi:[0,1]
	v_pk_mul_f32 v[174:175], v[156:157], v[64:65] op_sel_hi:[0,1]
	v_pk_mul_f32 v[168:169], v[156:157], v[70:71] op_sel_hi:[0,1]
	v_pk_mul_f32 v[166:167], v[156:157], v[68:69] op_sel_hi:[0,1]
	v_cvt_pk_bf16_f32 v166, v166, v167
	v_cvt_pk_bf16_f32 v167, v168, v169
	v_cvt_pk_bf16_f32 v168, v174, v175
	v_cvt_pk_bf16_f32 v169, v172, v173
	global_store_dwordx4 v[170:171], v[166:169], off offset:256
	v_pk_mul_f32 v[172:173], v[156:157], v[58:59] op_sel_hi:[0,1]
	s_mov_b32 s4, 0x40000
	v_pk_mul_f32 v[168:169], v[156:157], v[62:63] op_sel_hi:[0,1]
	v_pk_mul_f32 v[166:167], v[156:157], v[60:61] op_sel_hi:[0,1]
	v_pk_mul_f32 v[174:175], v[156:157], v[56:57] op_sel_hi:[0,1]
	v_cvt_pk_bf16_f32 v166, v166, v167
	v_cvt_pk_bf16_f32 v167, v168, v169
	v_cvt_pk_bf16_f32 v169, v172, v173
	v_add_co_u32_e32 v172, vcc, s4, v158
	v_cvt_pk_bf16_f32 v168, v174, v175
	s_nop 0
	v_addc_co_u32_e32 v173, vcc, 0, v159, vcc
	s_mov_b64 s[30:31], 0x40000
	global_store_dwordx4 v[172:173], v[166:169], off
	v_pk_mul_f32 v[172:173], v[156:157], v[42:43] op_sel_hi:[0,1]
	v_pk_mul_f32 v[174:175], v[156:157], v[40:41] op_sel_hi:[0,1]
	v_pk_mul_f32 v[168:169], v[156:157], v[50:51] op_sel_hi:[0,1]
	v_pk_mul_f32 v[166:167], v[156:157], v[48:49] op_sel_hi:[0,1]
	v_lshl_add_u64 v[170:171], v[158:159], 0, s[30:31]
	v_cvt_pk_bf16_f32 v166, v166, v167
	v_cvt_pk_bf16_f32 v167, v168, v169
	v_cvt_pk_bf16_f32 v168, v174, v175
	v_cvt_pk_bf16_f32 v169, v172, v173
	global_store_dwordx4 v[170:171], v[166:169], off offset:256
	v_pk_mul_f32 v[172:173], v[156:157], v[46:47] op_sel_hi:[0,1]
	s_mov_b32 s4, 0x48000
	v_pk_mul_f32 v[168:169], v[156:157], v[54:55] op_sel_hi:[0,1]
	v_pk_mul_f32 v[166:167], v[156:157], v[52:53] op_sel_hi:[0,1]
	v_pk_mul_f32 v[174:175], v[156:157], v[44:45] op_sel_hi:[0,1]
	v_cvt_pk_bf16_f32 v166, v166, v167
	v_cvt_pk_bf16_f32 v167, v168, v169
	v_cvt_pk_bf16_f32 v169, v172, v173
	v_add_co_u32_e32 v172, vcc, s4, v158
	v_cvt_pk_bf16_f32 v168, v174, v175
	s_nop 0
	v_addc_co_u32_e32 v173, vcc, 0, v159, vcc
	s_mov_b64 s[30:31], 0x48000
	global_store_dwordx4 v[172:173], v[166:169], off
	v_pk_mul_f32 v[172:173], v[156:157], v[26:27] op_sel_hi:[0,1]
	v_pk_mul_f32 v[174:175], v[156:157], v[24:25] op_sel_hi:[0,1]
	v_pk_mul_f32 v[168:169], v[156:157], v[34:35] op_sel_hi:[0,1]
	v_pk_mul_f32 v[166:167], v[156:157], v[32:33] op_sel_hi:[0,1]
	v_lshl_add_u64 v[170:171], v[158:159], 0, s[30:31]
	v_cvt_pk_bf16_f32 v166, v166, v167
	v_cvt_pk_bf16_f32 v167, v168, v169
	v_cvt_pk_bf16_f32 v168, v174, v175
	v_cvt_pk_bf16_f32 v169, v172, v173
	global_store_dwordx4 v[170:171], v[166:169], off offset:256
	v_pk_mul_f32 v[172:173], v[156:157], v[30:31] op_sel_hi:[0,1]
	v_pk_mul_f32 v[174:175], v[156:157], v[28:29] op_sel_hi:[0,1]
	v_pk_mul_f32 v[168:169], v[156:157], v[38:39] op_sel_hi:[0,1]
	v_pk_mul_f32 v[166:167], v[156:157], v[36:37] op_sel_hi:[0,1]
	v_cvt_pk_bf16_f32 v166, v166, v167
	v_cvt_pk_bf16_f32 v167, v168, v169
	v_cvt_pk_bf16_f32 v169, v172, v173
	v_add_co_u32_e32 v172, vcc, s48, v158
	v_cvt_pk_bf16_f32 v168, v174, v175
	s_nop 0
	v_addc_co_u32_e32 v173, vcc, 0, v159, vcc
	global_store_dwordx4 v[172:173], v[166:169], off
	v_pk_mul_f32 v[172:173], v[156:157], v[10:11] op_sel_hi:[0,1]
	v_pk_mul_f32 v[174:175], v[156:157], v[8:9] op_sel_hi:[0,1]
	v_pk_mul_f32 v[168:169], v[156:157], v[18:19] op_sel_hi:[0,1]
	v_pk_mul_f32 v[166:167], v[156:157], v[16:17] op_sel_hi:[0,1]
	v_lshl_add_u64 v[170:171], v[158:159], 0, s[8:9]
	v_cvt_pk_bf16_f32 v166, v166, v167
	v_cvt_pk_bf16_f32 v167, v168, v169
	v_cvt_pk_bf16_f32 v168, v174, v175
	v_cvt_pk_bf16_f32 v169, v172, v173
	global_store_dwordx4 v[170:171], v[166:169], off offset:256
	v_lshl_add_u64 v[170:171], v[158:159], 0, s[10:11]
	v_pk_mul_f32 v[172:173], v[156:157], v[14:15] op_sel_hi:[0,1]
	v_pk_mul_f32 v[168:169], v[156:157], v[22:23] op_sel_hi:[0,1]
	v_pk_mul_f32 v[166:167], v[156:157], v[20:21] op_sel_hi:[0,1]
	v_pk_mul_f32 v[174:175], v[156:157], v[12:13] op_sel_hi:[0,1]
	v_add_co_u32_e32 v158, vcc, s49, v158
	v_cvt_pk_bf16_f32 v166, v166, v167
	v_cvt_pk_bf16_f32 v167, v168, v169
	v_cvt_pk_bf16_f32 v168, v174, v175
	v_cvt_pk_bf16_f32 v169, v172, v173
	v_addc_co_u32_e32 v159, vcc, 0, v159, vcc
	global_store_dwordx4 v[158:159], v[166:169], off
	v_pk_mul_f32 v[158:159], v[156:157], v[6:7] op_sel_hi:[0,1]
	v_pk_mul_f32 v[172:173], v[156:157], v[0:1] op_sel_hi:[0,1]
	v_pk_mul_f32 v[166:167], v[156:157], v[4:5] op_sel_hi:[0,1]
	v_pk_mul_f32 v[168:169], v[156:157], v[2:3] op_sel_hi:[0,1]
	v_cvt_pk_bf16_f32 v156, v166, v167
	v_cvt_pk_bf16_f32 v157, v158, v159
	v_cvt_pk_bf16_f32 v158, v172, v173
	v_cvt_pk_bf16_f32 v159, v168, v169
	global_store_dwordx4 v[170:171], v[156:159], off offset:256
	s_cmp_lt_i32 s27, 16
	s_cbranch_scc0 .LBB0_204

; #define PG8_STAGE(bufoff, gbase, voff) do { _Pragma("unroll") for (int _i = 0; _i < 2; ++_i) \
;         __builtin_amdgcn_global_load_lds((const unsigned*)((const char*)(gbase) + (voff)[_i]), (LAS unsigned*)(lds + (bufoff) + ldsw + _i * 8192), 16, 0, 0); } while (0)
; #define PG8_LDA(dst, b, h) do { _Pragma("unroll") for (int m = 0; m < 4; ++m) _Pragma("unroll") for (int k = 0; k < 2; ++k) dst[m][k] = *(const LAS bf16x8*)(lds + PG8_SA(b, h) + aoff + m * 2048 + k * 1024); } while (0)
; #define PG8_LDB(dst, b, h) do { _Pragma("unroll") for (int n = 0; n < 2; ++n) _Pragma("unroll") for (int k = 0; k < 2; ++k) dst[n][k] = *(const LAS bf16x8*)(lds + PG8_SB(b, h) + boff + n * 2048 + k * 1024); } while (0)
; #define PG8_WAIT_V(n) asm volatile("s_waitcnt vmcnt(" #n ")" ::: "memory")
; #define PG8_WAIT_L(n) asm volatile("s_waitcnt lgkmcnt(" #n ")" ::: "memory")
; #define PG8_BAR __builtin_amdgcn_s_barrier()
; #define PG8_SCHED __builtin_amdgcn_sched_barrier(0)
; template <class Epi>
; __device__ __forceinline__ void gemm_phase(LAS unsigned char* lds, const bf16_t* A, int lda, const bf16_t* Bt, int ldb, int M, int N, int K, int asel, const Epi& E, const int fixed_round = -1) {
;     ...
;         for (int t = 0; t < nt; t += 2) {
;             const bool last = (t == nt - 2);
;             const char* a1 = cA + (size_t)(t + 1) * kstep;
;             const char* a2 = last ? nA : cA + (size_t)(t + 2) * kstep; const char* b2 = last ? nB : cB + (size_t)(t + 2) * kstep;
;             const char* a3 = a2 + kstep; const char* b3 = b2 + kstep;
;             PG8_LDB(B0, 0, 0); PG8_SCHED; PG8_LDA(At, 0, 0); PG8_STAGE(PG8_SA(1, 1), a1 + hstepA, voffA);
;             PG8_WAIT_L(8); PG8_BAR; PG8_WAIT_L(0); PG8_MMA(0, 0, At, B0); PG8_BAR; PG8_SCHED;
;             PG8_LDB(B1, 0, 1); PG8_STAGE(PG8_SB(0, 0), b2, voffB);
;             PG8_BAR; PG8_WAIT_L(0); PG8_MMA(0, 1, At, B1); PG8_BAR;
;             PG8_LDA(At, 0, 1); PG8_STAGE(PG8_SA(0, 0), a2, voffA);
;             PG8_BAR; PG8_WAIT_L(0); PG8_MMA(1, 0, At, B0); PG8_BAR; PG8_SCHED;
;             PG8_STAGE(PG8_SB(0, 1), b2 + hstepB, voffB);
;             PG8_WAIT_V(6); PG8_BAR; PG8_MMA(1, 1, At, B1); PG8_BAR;
.LBB0_224:
	ds_read_b128 v[146:149], v143
	ds_read_b128 v[150:153], v143 offset:1024
	ds_read_b128 v[154:157], v143 offset:2048
	ds_read_b128 v[158:161], v143 offset:3072
	s_add_u32 s18, s16, 0xfff80080
	s_addc_u32 s19, s17, -1
	s_cmp_eq_u32 s41, 28
	s_cselect_b32 s21, s11, s19
	s_cselect_b32 s20, s37, s18
	s_cselect_b32 s19, s9, s40
	s_cselect_b32 s18, s38, s39
	s_add_i32 m0, s7, 0xc000
	ds_read_b128 v[162:165], v144
	ds_read_b128 v[166:169], v144 offset:1024
	ds_read_b128 v[170:173], v144 offset:2048
	ds_read_b128 v[174:177], v144 offset:3072
	ds_read_b128 v[178:181], v144 offset:4096
	ds_read_b128 v[182:185], v144 offset:5120
	ds_read_b128 v[186:189], v144 offset:6144
	ds_read_b128 v[190:193], v144 offset:7168
	global_load_lds_dwordx4 v132, s[16:17]
	s_add_i32 m0, s7, 0xe000
	s_nop 0
	global_load_lds_dwordx4 v134, s[16:17]
	s_waitcnt lgkmcnt(8)
	s_barrier
	s_waitcnt lgkmcnt(0)
	s_setprio 1
	s_waitcnt lgkmcnt(0)
	v_mfma_f32_16x16x32_bf16 v[124:127], v[162:165], v[146:149], v[124:127]
	v_mfma_f32_16x16x32_bf16 v[108:111], v[162:165], v[154:157], v[108:111]
	v_mfma_f32_16x16x32_bf16 v[120:123], v[170:173], v[146:149], v[120:123]
	v_mfma_f32_16x16x32_bf16 v[104:107], v[170:173], v[154:157], v[104:107]
	v_mfma_f32_16x16x32_bf16 v[116:119], v[178:181], v[146:149], v[116:119]
	v_mfma_f32_16x16x32_bf16 v[100:103], v[178:181], v[154:157], v[100:103]
	v_mfma_f32_16x16x32_bf16 v[112:115], v[186:189], v[146:149], v[112:115]
	v_mfma_f32_16x16x32_bf16 v[92:95], v[186:189], v[154:157], v[92:95]
	v_mfma_f32_16x16x32_bf16 v[124:127], v[166:169], v[150:153], v[124:127]
	v_mfma_f32_16x16x32_bf16 v[108:111], v[166:169], v[158:161], v[108:111]
	v_mfma_f32_16x16x32_bf16 v[120:123], v[174:177], v[150:153], v[120:123]
	v_mfma_f32_16x16x32_bf16 v[104:107], v[174:177], v[158:161], v[104:107]
	v_mfma_f32_16x16x32_bf16 v[116:119], v[182:185], v[150:153], v[116:119]
	v_mfma_f32_16x16x32_bf16 v[100:103], v[182:185], v[158:161], v[100:103]
	v_mfma_f32_16x16x32_bf16 v[112:115], v[190:193], v[150:153], v[112:115]
	v_mfma_f32_16x16x32_bf16 v[92:95], v[190:193], v[158:161], v[92:95]
	s_setprio 0
	s_barrier
	s_add_i32 s42, s34, s25
	s_add_u32 s98, s18, s2
	s_addc_u32 s99, s19, s3
	s_mov_b32 m0, s42
	ds_read_b128 v[196:199], v145
	ds_read_b128 v[202:205], v145 offset:1024
	ds_read_b128 v[206:209], v145 offset:2048
	ds_read_b128 v[210:213], v145 offset:3072
	global_load_lds_dwordx4 v128, s[18:19]
	s_add_i32 m0, s42, 0x2000
	s_nop 0
	global_load_lds_dwordx4 v130, s[18:19]
	s_barrier
	s_waitcnt lgkmcnt(0)
	s_setprio 1
	s_waitcnt lgkmcnt(0)
	v_mfma_f32_16x16x32_bf16 v[80:83], v[162:165], v[196:199], v[80:83]
	v_mfma_f32_16x16x32_bf16 v[48:51], v[162:165], v[206:209], v[48:51]
	v_mfma_f32_16x16x32_bf16 v[68:71], v[170:173], v[196:199], v[68:71]
	v_mfma_f32_16x16x32_bf16 v[40:43], v[170:173], v[206:209], v[40:43]
	v_mfma_f32_16x16x32_bf16 v[60:63], v[178:181], v[196:199], v[60:63]
	v_mfma_f32_16x16x32_bf16 v[36:39], v[178:181], v[206:209], v[36:39]
	v_mfma_f32_16x16x32_bf16 v[52:55], v[186:189], v[196:199], v[52:55]
	v_mfma_f32_16x16x32_bf16 v[28:31], v[186:189], v[206:209], v[28:31]
	v_mfma_f32_16x16x32_bf16 v[80:83], v[166:169], v[202:205], v[80:83]
	v_mfma_f32_16x16x32_bf16 v[48:51], v[166:169], v[210:213], v[48:51]
	v_mfma_f32_16x16x32_bf16 v[68:71], v[174:177], v[202:205], v[68:71]
	v_mfma_f32_16x16x32_bf16 v[40:43], v[174:177], v[210:213], v[40:43]
	v_mfma_f32_16x16x32_bf16 v[60:63], v[182:185], v[202:205], v[60:63]
	v_mfma_f32_16x16x32_bf16 v[36:39], v[182:185], v[210:213], v[36:39]
	v_mfma_f32_16x16x32_bf16 v[52:55], v[190:193], v[202:205], v[52:55]
	v_mfma_f32_16x16x32_bf16 v[28:31], v[190:193], v[210:213], v[28:31]
	s_setprio 0
	s_mov_b32 m0, s7
	s_add_u32 s100, s20, s2
	s_addc_u32 s101, s21, s3
	s_barrier
	ds_read_b128 v[162:165], v144 offset:16384
	ds_read_b128 v[166:169], v144 offset:17408
	ds_read_b128 v[170:173], v144 offset:18432
	ds_read_b128 v[174:177], v144 offset:19456
	ds_read_b128 v[178:181], v144 offset:20480
	ds_read_b128 v[182:185], v144 offset:21504
	ds_read_b128 v[186:189], v144 offset:22528
	ds_read_b128 v[190:193], v144 offset:23552
	global_load_lds_dwordx4 v128, s[20:21]
	s_mov_b32 m0, s26
	s_nop 0
	global_load_lds_dwordx4 v130, s[20:21]
	s_barrier
	s_waitcnt lgkmcnt(0)
	s_setprio 1
	s_waitcnt lgkmcnt(0)
	v_mfma_f32_16x16x32_bf16 v[96:99], v[162:165], v[146:149], v[96:99]
	v_mfma_f32_16x16x32_bf16 v[72:75], v[162:165], v[154:157], v[72:75]
	v_mfma_f32_16x16x32_bf16 v[88:91], v[170:173], v[146:149], v[88:91]
	v_mfma_f32_16x16x32_bf16 v[64:67], v[170:173], v[154:157], v[64:67]
	v_mfma_f32_16x16x32_bf16 v[84:87], v[178:181], v[146:149], v[84:87]
	v_mfma_f32_16x16x32_bf16 v[56:59], v[178:181], v[154:157], v[56:59]
	v_mfma_f32_16x16x32_bf16 v[76:79], v[186:189], v[146:149], v[76:79]
	v_mfma_f32_16x16x32_bf16 v[44:47], v[186:189], v[154:157], v[44:47]
	v_mfma_f32_16x16x32_bf16 v[96:99], v[166:169], v[150:153], v[96:99]
	v_mfma_f32_16x16x32_bf16 v[72:75], v[166:169], v[158:161], v[72:75]
	v_mfma_f32_16x16x32_bf16 v[88:91], v[174:177], v[150:153], v[88:91]
	v_mfma_f32_16x16x32_bf16 v[64:67], v[174:177], v[158:161], v[64:67]
	v_mfma_f32_16x16x32_bf16 v[84:87], v[182:185], v[150:153], v[84:87]
	v_mfma_f32_16x16x32_bf16 v[56:59], v[182:185], v[158:161], v[56:59]
	v_mfma_f32_16x16x32_bf16 v[76:79], v[190:193], v[150:153], v[76:79]
	v_mfma_f32_16x16x32_bf16 v[44:47], v[190:193], v[158:161], v[44:47]
	s_setprio 0
	s_barrier
	s_add_u32 s42, s18, 0x80000
	s_addc_u32 s43, s19, 0
	s_add_i32 s44, s35, s25
	s_mov_b32 m0, s44
	s_nop 0
	global_load_lds_dwordx4 v128, s[42:43]
	s_add_i32 m0, s44, 0x2000
	s_nop 0
	global_load_lds_dwordx4 v130, s[42:43]
	s_waitcnt vmcnt(6)
	s_barrier
; #define PG8_STAGE(bufoff, gbase, voff) do { _Pragma("unroll") for (int _i = 0; _i < 2; ++_i) \
;         __builtin_amdgcn_global_load_lds((const unsigned*)((const char*)(gbase) + (voff)[_i]), (LAS unsigned*)(lds + (bufoff) + ldsw + _i * 8192), 16, 0, 0); } while (0)
; #define PG8_LDA(dst, b, h) do { _Pragma("unroll") for (int m = 0; m < 4; ++m) _Pragma("unroll") for (int k = 0; k < 2; ++k) dst[m][k] = *(const LAS bf16x8*)(lds + PG8_SA(b, h) + aoff + m * 2048 + k * 1024); } while (0)
; #define PG8_LDB(dst, b, h) do { _Pragma("unroll") for (int n = 0; n < 2; ++n) _Pragma("unroll") for (int k = 0; k < 2; ++k) dst[n][k] = *(const LAS bf16x8*)(lds + PG8_SB(b, h) + boff + n * 2048 + k * 1024); } while (0)
; #define PG8_WAIT_L(n) asm volatile("s_waitcnt lgkmcnt(" #n ")" ::: "memory")
; #define PG8_BAR __builtin_amdgcn_s_barrier()
; #define PG8_SCHED __builtin_amdgcn_sched_barrier(0)
; template <class Epi>
; __device__ __forceinline__ void gemm_phase(LAS unsigned char* lds, const bf16_t* A, int lda, const bf16_t* Bt, int ldb, int M, int N, int K, int asel, const Epi& E, const int fixed_round = -1) {
;     ...
;             PG8_LDB(B0, 1, 0); PG8_SCHED; PG8_LDA(At, 1, 0); PG8_STAGE(PG8_SA(0, 1), a2 + hstepA, voffA);
;             PG8_WAIT_L(8); PG8_BAR; PG8_WAIT_L(0); PG8_MMA(0, 0, At, B0); PG8_BAR; PG8_SCHED;
;             PG8_LDB(B1, 1, 1); PG8_STAGE(PG8_SB(1, 0), b3, voffB);
;             PG8_BAR; PG8_WAIT_L(0); PG8_MMA(0, 1, At, B1); PG8_BAR;
;             PG8_LDA(At, 1, 1); PG8_STAGE(PG8_SA(1, 0), a3, voffA);
;             PG8_BAR; PG8_WAIT_L(0); PG8_MMA(1, 0, At, B0); PG8_BAR; PG8_SCHED;
	s_setprio 1
	v_mfma_f32_16x16x32_bf16 v[32:35], v[162:165], v[196:199], v[32:35]
	v_mfma_f32_16x16x32_bf16 v[12:15], v[162:165], v[206:209], v[12:15]
	v_mfma_f32_16x16x32_bf16 v[24:27], v[170:173], v[196:199], v[24:27]
	v_mfma_f32_16x16x32_bf16 v[8:11], v[170:173], v[206:209], v[8:11]
	v_mfma_f32_16x16x32_bf16 v[20:23], v[178:181], v[196:199], v[20:23]
	v_mfma_f32_16x16x32_bf16 v[4:7], v[178:181], v[206:209], v[4:7]
	v_mfma_f32_16x16x32_bf16 v[16:19], v[186:189], v[196:199], v[16:19]
	v_mfma_f32_16x16x32_bf16 v[0:3], v[186:189], v[206:209], v[0:3]
	v_mfma_f32_16x16x32_bf16 v[32:35], v[166:169], v[202:205], v[32:35]
	v_mfma_f32_16x16x32_bf16 v[12:15], v[166:169], v[210:213], v[12:15]
	v_mfma_f32_16x16x32_bf16 v[24:27], v[174:177], v[202:205], v[24:27]
	v_mfma_f32_16x16x32_bf16 v[8:11], v[174:177], v[210:213], v[8:11]
	v_mfma_f32_16x16x32_bf16 v[20:23], v[182:185], v[202:205], v[20:23]
	v_mfma_f32_16x16x32_bf16 v[4:7], v[182:185], v[210:213], v[4:7]
	v_mfma_f32_16x16x32_bf16 v[16:19], v[190:193], v[202:205], v[16:19]
	v_mfma_f32_16x16x32_bf16 v[0:3], v[190:193], v[210:213], v[0:3]
	s_setprio 0
	s_add_i32 s42, 0, 0x18000
	v_add_u32_e32 v158, s42, v140
	s_barrier
	ds_read_b128 v[146:149], v158
	ds_read_b128 v[150:153], v158 offset:1024
	ds_read_b128 v[154:157], v158 offset:2048
	ds_read_b128 v[158:161], v158 offset:3072
	s_add_u32 s20, s20, 0x80000
	s_addc_u32 s21, s21, 0
	s_mov_b32 m0, s27
	ds_read_b128 v[162:165], v144 offset:32768
	ds_read_b128 v[166:169], v144 offset:33792
	ds_read_b128 v[170:173], v144 offset:34816
	ds_read_b128 v[174:177], v144 offset:35840
	ds_read_b128 v[178:181], v144 offset:36864
	ds_read_b128 v[182:185], v144 offset:37888
	ds_read_b128 v[186:189], v144 offset:38912
	ds_read_b128 v[190:193], v144 offset:39936
	global_load_lds_dwordx4 v128, s[20:21]
	s_mov_b32 m0, s28
	s_nop 0
	global_load_lds_dwordx4 v130, s[20:21]
	s_waitcnt lgkmcnt(8)
	s_barrier
	s_waitcnt lgkmcnt(0)
	s_setprio 1
	s_waitcnt lgkmcnt(0)
	v_mfma_f32_16x16x32_bf16 v[124:127], v[162:165], v[146:149], v[124:127]
	v_mfma_f32_16x16x32_bf16 v[108:111], v[162:165], v[154:157], v[108:111]
	v_mfma_f32_16x16x32_bf16 v[120:123], v[170:173], v[146:149], v[120:123]
	v_mfma_f32_16x16x32_bf16 v[104:107], v[170:173], v[154:157], v[104:107]
	v_mfma_f32_16x16x32_bf16 v[116:119], v[178:181], v[146:149], v[116:119]
	v_mfma_f32_16x16x32_bf16 v[100:103], v[178:181], v[154:157], v[100:103]
	v_mfma_f32_16x16x32_bf16 v[112:115], v[186:189], v[146:149], v[112:115]
	v_mfma_f32_16x16x32_bf16 v[92:95], v[186:189], v[154:157], v[92:95]
	v_mfma_f32_16x16x32_bf16 v[124:127], v[166:169], v[150:153], v[124:127]
	v_mfma_f32_16x16x32_bf16 v[108:111], v[166:169], v[158:161], v[108:111]
	v_mfma_f32_16x16x32_bf16 v[120:123], v[174:177], v[150:153], v[120:123]
	v_mfma_f32_16x16x32_bf16 v[104:107], v[174:177], v[158:161], v[104:107]
	v_mfma_f32_16x16x32_bf16 v[116:119], v[182:185], v[150:153], v[116:119]
	v_mfma_f32_16x16x32_bf16 v[100:103], v[182:185], v[158:161], v[100:103]
	v_mfma_f32_16x16x32_bf16 v[112:115], v[190:193], v[150:153], v[112:115]
	v_mfma_f32_16x16x32_bf16 v[92:95], v[190:193], v[158:161], v[92:95]
	s_setprio 0
	s_barrier
	s_add_i32 s20, 0, 0x1c000
	s_add_i32 s21, s42, s25
	v_add_u32_e32 v195, s20, v140
	s_mov_b32 m0, s21
	ds_read_b128 v[196:199], v195
	ds_read_b128 v[202:205], v195 offset:1024
	ds_read_b128 v[206:209], v195 offset:2048
	ds_read_b128 v[210:213], v195 offset:3072
	global_load_lds_dwordx4 v128, s[98:99]
	s_add_i32 m0, s21, 0x2000
	s_nop 0
	global_load_lds_dwordx4 v130, s[98:99]
	s_barrier
	s_waitcnt lgkmcnt(0)
	s_setprio 1
	s_waitcnt lgkmcnt(0)
	v_mfma_f32_16x16x32_bf16 v[80:83], v[162:165], v[196:199], v[80:83]
	v_mfma_f32_16x16x32_bf16 v[48:51], v[162:165], v[206:209], v[48:51]
	v_mfma_f32_16x16x32_bf16 v[68:71], v[170:173], v[196:199], v[68:71]
	v_mfma_f32_16x16x32_bf16 v[40:43], v[170:173], v[206:209], v[40:43]
	v_mfma_f32_16x16x32_bf16 v[60:63], v[178:181], v[196:199], v[60:63]
	v_mfma_f32_16x16x32_bf16 v[36:39], v[178:181], v[206:209], v[36:39]
	v_mfma_f32_16x16x32_bf16 v[52:55], v[186:189], v[196:199], v[52:55]
	v_mfma_f32_16x16x32_bf16 v[28:31], v[186:189], v[206:209], v[28:31]
	v_mfma_f32_16x16x32_bf16 v[80:83], v[166:169], v[202:205], v[80:83]
	v_mfma_f32_16x16x32_bf16 v[48:51], v[166:169], v[210:213], v[48:51]
	v_mfma_f32_16x16x32_bf16 v[68:71], v[174:177], v[202:205], v[68:71]
	v_mfma_f32_16x16x32_bf16 v[40:43], v[174:177], v[210:213], v[40:43]
	v_mfma_f32_16x16x32_bf16 v[60:63], v[182:185], v[202:205], v[60:63]
	v_mfma_f32_16x16x32_bf16 v[36:39], v[182:185], v[210:213], v[36:39]
	v_mfma_f32_16x16x32_bf16 v[52:55], v[190:193], v[202:205], v[52:55]
	v_mfma_f32_16x16x32_bf16 v[28:31], v[190:193], v[210:213], v[28:31]
	s_setprio 0
	s_mov_b32 m0, s30
	s_barrier
	ds_read_b128 v[162:165], v144 offset:49152
	ds_read_b128 v[166:169], v144 offset:50176
	ds_read_b128 v[170:173], v144 offset:51200
	ds_read_b128 v[174:177], v144 offset:52224
	ds_read_b128 v[178:181], v144 offset:53248
	ds_read_b128 v[182:185], v144 offset:54272
	ds_read_b128 v[186:189], v144 offset:55296
	ds_read_b128 v[190:193], v144 offset:56320
	global_load_lds_dwordx4 v128, s[100:101]
	s_mov_b32 m0, s31
	s_nop 0
	global_load_lds_dwordx4 v130, s[100:101]
	s_barrier
; #define LAS __attribute__((address_space(3)))
; #define PG8_STAGE(bufoff, gbase, voff) do { _Pragma("unroll") for (int _i = 0; _i < 2; ++_i) \
;         __builtin_amdgcn_global_load_lds((const unsigned*)((const char*)(gbase) + (voff)[_i]), (LAS unsigned*)(lds + (bufoff) + ldsw + _i * 8192), 16, 0, 0); } while (0)
; #define PG8_WAIT_V(n) asm volatile("s_waitcnt vmcnt(" #n ")" ::: "memory")
; #define PG8_BAR __builtin_amdgcn_s_barrier()
; template <class Epi>
; __device__ __forceinline__ void gemm_phase(LAS unsigned char* lds, const bf16_t* A, int lda, const bf16_t* Bt, int ldb, int M, int N, int K, int asel, const Epi& E, const int fixed_round = -1) {
;     ...
;             PG8_STAGE(PG8_SB(1, 1), b3 + hstepB, voffB);
;             PG8_WAIT_V(6); PG8_BAR; PG8_MMA(1, 1, At, B1); PG8_BAR;
;             if constexpr (Epi::HEADSCALE) {
;                 if (t & 2) {
;                     const LAS float* rt = (const LAS float*)(lds + L_RT) + (t >> 2);
; #pragma unroll
;                     for (int ai = 0; ai < 2; ++ai)
; #pragma unroll
;                         for (int m = 0; m < 4; ++m) { const float f = rt[(ai * HALF + wr * 64 + m * 16 + fr) * 8];
; #pragma unroll
;                             for (int bj = 0; bj < 2; ++bj)
; #pragma unroll
;                                 for (int n = 0; n < 2; ++n) acc[ai][bj][m][n] *= f; }
;                 }
;             }
;         }
;         if constexpr (!Epi::AFTER_DRAIN) E(acc, cur, wr, wc, fr, fq);
;         if (!has_next) break;
	s_waitcnt lgkmcnt(0)
	s_setprio 1
	s_waitcnt lgkmcnt(0)
	v_mfma_f32_16x16x32_bf16 v[96:99], v[162:165], v[146:149], v[96:99]
	v_mfma_f32_16x16x32_bf16 v[72:75], v[162:165], v[154:157], v[72:75]
	v_mfma_f32_16x16x32_bf16 v[88:91], v[170:173], v[146:149], v[88:91]
	v_mfma_f32_16x16x32_bf16 v[64:67], v[170:173], v[154:157], v[64:67]
	v_mfma_f32_16x16x32_bf16 v[84:87], v[178:181], v[146:149], v[84:87]
	v_mfma_f32_16x16x32_bf16 v[56:59], v[178:181], v[154:157], v[56:59]
	v_mfma_f32_16x16x32_bf16 v[76:79], v[186:189], v[146:149], v[76:79]
	v_mfma_f32_16x16x32_bf16 v[44:47], v[186:189], v[154:157], v[44:47]
	v_mfma_f32_16x16x32_bf16 v[96:99], v[166:169], v[150:153], v[96:99]
	v_mfma_f32_16x16x32_bf16 v[72:75], v[166:169], v[158:161], v[72:75]
	v_mfma_f32_16x16x32_bf16 v[88:91], v[174:177], v[150:153], v[88:91]
	v_mfma_f32_16x16x32_bf16 v[64:67], v[174:177], v[158:161], v[64:67]
	v_mfma_f32_16x16x32_bf16 v[84:87], v[182:185], v[150:153], v[84:87]
	v_mfma_f32_16x16x32_bf16 v[56:59], v[182:185], v[158:161], v[56:59]
	v_mfma_f32_16x16x32_bf16 v[76:79], v[190:193], v[150:153], v[76:79]
	v_mfma_f32_16x16x32_bf16 v[44:47], v[190:193], v[158:161], v[44:47]
	s_setprio 0
	s_barrier
	s_add_u32 s18, s18, 0x80080
	s_addc_u32 s19, s19, 0
	s_add_i32 s20, s20, s25
	s_mov_b32 m0, s20
	s_nop 0
	global_load_lds_dwordx4 v128, s[18:19]
	s_add_i32 m0, s20, 0x2000
	s_nop 0
	global_load_lds_dwordx4 v130, s[18:19]
	s_waitcnt vmcnt(6)
	s_barrier
	s_setprio 1
	v_mfma_f32_16x16x32_bf16 v[32:35], v[162:165], v[196:199], v[32:35]
	v_mfma_f32_16x16x32_bf16 v[12:15], v[162:165], v[206:209], v[12:15]
	v_mfma_f32_16x16x32_bf16 v[24:27], v[170:173], v[196:199], v[24:27]
	v_mfma_f32_16x16x32_bf16 v[8:11], v[170:173], v[206:209], v[8:11]
	v_mfma_f32_16x16x32_bf16 v[20:23], v[178:181], v[196:199], v[20:23]
	v_mfma_f32_16x16x32_bf16 v[4:7], v[178:181], v[206:209], v[4:7]
	v_mfma_f32_16x16x32_bf16 v[16:19], v[186:189], v[196:199], v[16:19]
	v_mfma_f32_16x16x32_bf16 v[0:3], v[186:189], v[206:209], v[0:3]
	v_mfma_f32_16x16x32_bf16 v[32:35], v[166:169], v[202:205], v[32:35]
	v_mfma_f32_16x16x32_bf16 v[12:15], v[166:169], v[210:213], v[12:15]
	v_mfma_f32_16x16x32_bf16 v[24:27], v[174:177], v[202:205], v[24:27]
	v_mfma_f32_16x16x32_bf16 v[8:11], v[174:177], v[210:213], v[8:11]
	v_mfma_f32_16x16x32_bf16 v[20:23], v[182:185], v[202:205], v[20:23]
	v_mfma_f32_16x16x32_bf16 v[4:7], v[182:185], v[210:213], v[4:7]
	v_mfma_f32_16x16x32_bf16 v[16:19], v[190:193], v[202:205], v[16:19]
	v_mfma_f32_16x16x32_bf16 v[0:3], v[190:193], v[210:213], v[0:3]
	s_setprio 0
	s_add_i32 s41, s41, 2
	s_add_u32 s16, s16, 0x100
	s_addc_u32 s17, s17, 0
	s_add_u32 s39, s39, 0x100
	s_addc_u32 s40, s40, 0
	s_cmp_gt_u32 s41, 29
	s_barrier
	s_cbranch_scc0 .LBB0_224
; __device__ __forceinline__ unsigned cvt_pk_bf16(float lo, float hi) { const bf16x2_t r = __builtin_convertvector((f32x2){lo, hi}, bf16x2_t); return __builtin_bit_cast(unsigned, r); }
; #define PG8_WAIT_V(n) asm volatile("s_waitcnt vmcnt(" #n ")" ::: "memory")
; #define PG8_BAR __builtin_amdgcn_s_barrier()
; template <class Epi>
; __device__ __forceinline__ void gemm_phase(LAS unsigned char* lds, const bf16_t* A, int lda, const bf16_t* Bt, int ldb, int M, int N, int K, int asel, const Epi& E, const int fixed_round = -1) {
;     ...
;         if (!has_next) break;
; #pragma unroll
;         for (int a = 0; a < 2; ++a)
; #pragma unroll
;             for (int b = 0; b < 2; ++b)
; #pragma unroll
;                 for (int m = 0; m < 4; ++m)
; #pragma unroll
;                     for (int n = 0; n < 2; ++n) acc[a][b][m][n] = (f32x4){0.f, 0.f, 0.f, 0.f};
;         cur = nxt; cA = nA; cB = nB; ++ui;
;     }
;     PG8_WAIT_V(0);
;     if (wr == 0) PG8_BAR;
;     PG8_BAR;
;     __device__ __forceinline__ void operator()(const AccT& acc, const Unit& u, int wr, int wc, int fr, int fq) const {
;         const int bb = u.pm >> 4, s0 = (u.pm & 15) * BM + wr * 64 + 4 * fq, feat0 = u.pn * BM + wc * 32 + fr;
; #pragma unroll
;         for (int bj = 0; bj < 2; ++bj)
; #pragma unroll
;             for (int n = 0; n < 2; ++n) { bf16_t* fp = VT + ((size_t)bb * 2048 + feat0 + bj * HALF + n * 16) * SEQ + s0;
; #pragma unroll
;                 for (int ai = 0; ai < 2; ++ai)
; #pragma unroll
;                     for (int m = 0; m < 4; ++m) { const f32x4 v = acc[ai][bj][m][n]; u32x2 w; w.x = cvt_pk_bf16(v[0], v[1]); w.y = cvt_pk_bf16(v[2], v[3]);
;                         *(u32x2*)(fp + ai * HALF + m * 16) = w; } }
;     }
	s_ashr_i32 s16, s6, 4
	v_lshl_or_b32 v148, s36, 8, v142
	s_lshl_b32 s6, s6, 8
	s_ashr_i32 s17, s16, 31
	v_ashrrev_i32_e32 v149, 31, v148
	s_and_b32 s6, s6, 0xf00
	s_lshl_b64 s[16:17], s[16:17], 24
	v_lshlrev_b64 v[148:149], 13, v[148:149]
	v_add_u32_e32 v146, s6, v141
	v_lshl_add_u64 v[148:149], v[148:149], 0, s[16:17]
	v_readlane_b32 s16, v254, 47
	v_ashrrev_i32_e32 v147, 31, v146
	v_readlane_b32 s17, v254, 48
	v_lshlrev_b64 v[146:147], 1, v[146:147]
	v_cvt_pk_bf16_f32 v76, v76, v77
	v_lshl_add_u64 v[150:151], s[16:17], 0, v[148:149]
	v_lshl_add_u64 v[150:151], v[150:151], 0, v[146:147]
	v_cvt_pk_bf16_f32 v77, v78, v79
	global_store_dwordx2 v[150:151], v[76:77], off offset:352
	v_or_b32_e32 v76, 0x20000, v148
	v_mov_b32_e32 v77, v149
	v_lshl_add_u64 v[76:77], s[16:17], 0, v[76:77]
	v_cvt_pk_bf16_f32 v124, v124, v125
	v_cvt_pk_bf16_f32 v125, v126, v127
	v_cvt_pk_bf16_f32 v120, v120, v121
	v_cvt_pk_bf16_f32 v121, v122, v123
	v_cvt_pk_bf16_f32 v116, v116, v117
	v_cvt_pk_bf16_f32 v117, v118, v119
	v_cvt_pk_bf16_f32 v112, v112, v113
	v_cvt_pk_bf16_f32 v113, v114, v115
	v_cvt_pk_bf16_f32 v96, v96, v97
	v_cvt_pk_bf16_f32 v97, v98, v99
	v_cvt_pk_bf16_f32 v88, v88, v89
	v_cvt_pk_bf16_f32 v89, v90, v91
	v_cvt_pk_bf16_f32 v84, v84, v85
	v_cvt_pk_bf16_f32 v85, v86, v87
	v_lshl_add_u64 v[76:77], v[76:77], 0, v[146:147]
	v_cvt_pk_bf16_f32 v78, v108, v109
	v_cvt_pk_bf16_f32 v79, v110, v111
	v_cvt_pk_bf16_f32 v44, v44, v45
	v_cvt_pk_bf16_f32 v45, v46, v47
	global_store_dwordx2 v[150:151], v[124:125], off
	global_store_dwordx2 v[150:151], v[120:121], off offset:32
	global_store_dwordx2 v[150:151], v[116:117], off offset:64
	global_store_dwordx2 v[150:151], v[112:113], off offset:96
	global_store_dwordx2 v[150:151], v[96:97], off offset:256
	global_store_dwordx2 v[150:151], v[88:89], off offset:288
	global_store_dwordx2 v[150:151], v[84:85], off offset:320
	global_store_dwordx2 v[76:77], v[78:79], off
	v_cvt_pk_bf16_f32 v78, v104, v105
	v_cvt_pk_bf16_f32 v79, v106, v107
	global_store_dwordx2 v[76:77], v[44:45], off offset:352
	v_or_b32_e32 v44, 0x100000, v148
	v_mov_b32_e32 v45, v149
	global_store_dwordx2 v[76:77], v[78:79], off offset:32
	v_cvt_pk_bf16_f32 v78, v100, v101
	v_cvt_pk_bf16_f32 v79, v102, v103
	v_lshl_add_u64 v[44:45], s[16:17], 0, v[44:45]
	global_store_dwordx2 v[76:77], v[78:79], off offset:64
	v_cvt_pk_bf16_f32 v78, v92, v93
	v_cvt_pk_bf16_f32 v79, v94, v95
	v_cvt_pk_bf16_f32 v72, v72, v73
	v_cvt_pk_bf16_f32 v73, v74, v75
	v_cvt_pk_bf16_f32 v64, v64, v65
	v_cvt_pk_bf16_f32 v65, v66, v67
	v_cvt_pk_bf16_f32 v56, v56, v57
	v_cvt_pk_bf16_f32 v57, v58, v59
	v_lshl_add_u64 v[44:45], v[44:45], 0, v[146:147]
	v_cvt_pk_bf16_f32 v46, v80, v81
	v_cvt_pk_bf16_f32 v47, v82, v83
	global_store_dwordx2 v[76:77], v[78:79], off offset:96
	global_store_dwordx2 v[76:77], v[72:73], off offset:256
	global_store_dwordx2 v[76:77], v[64:65], off offset:288
	global_store_dwordx2 v[76:77], v[56:57], off offset:320
	global_store_dwordx2 v[44:45], v[46:47], off
	v_cvt_pk_bf16_f32 v46, v68, v69
	v_cvt_pk_bf16_f32 v47, v70, v71
	v_cvt_pk_bf16_f32 v16, v16, v17
	v_cvt_pk_bf16_f32 v17, v18, v19
	v_or_b32_e32 v148, 0x120000, v148
	global_store_dwordx2 v[44:45], v[46:47], off offset:32
	v_cvt_pk_bf16_f32 v46, v60, v61
	v_cvt_pk_bf16_f32 v47, v62, v63
	global_store_dwordx2 v[44:45], v[16:17], off offset:352
	v_lshl_add_u64 v[16:17], s[16:17], 0, v[148:149]
	global_store_dwordx2 v[44:45], v[46:47], off offset:64
	v_cvt_pk_bf16_f32 v46, v52, v53
	v_cvt_pk_bf16_f32 v47, v54, v55
	v_cvt_pk_bf16_f32 v32, v32, v33
	v_cvt_pk_bf16_f32 v33, v34, v35
	v_cvt_pk_bf16_f32 v24, v24, v25
	v_cvt_pk_bf16_f32 v25, v26, v27
	v_cvt_pk_bf16_f32 v20, v20, v21
	v_cvt_pk_bf16_f32 v21, v22, v23
	v_lshl_add_u64 v[16:17], v[16:17], 0, v[146:147]
	v_cvt_pk_bf16_f32 v18, v48, v49
	v_cvt_pk_bf16_f32 v19, v50, v51
	global_store_dwordx2 v[44:45], v[46:47], off offset:96
	global_store_dwordx2 v[44:45], v[32:33], off offset:256
	global_store_dwordx2 v[44:45], v[24:25], off offset:288
	global_store_dwordx2 v[44:45], v[20:21], off offset:320
	global_store_dwordx2 v[16:17], v[18:19], off
	v_cvt_pk_bf16_f32 v18, v40, v41
	v_cvt_pk_bf16_f32 v19, v42, v43
	global_store_dwordx2 v[16:17], v[18:19], off offset:32
	v_cvt_pk_bf16_f32 v18, v36, v37
	v_cvt_pk_bf16_f32 v19, v38, v39
	global_store_dwordx2 v[16:17], v[18:19], off offset:64
	v_cvt_pk_bf16_f32 v18, v28, v29
	v_cvt_pk_bf16_f32 v19, v30, v31
	v_cvt_pk_bf16_f32 v12, v12, v13
	v_cvt_pk_bf16_f32 v13, v14, v15
	v_cvt_pk_bf16_f32 v8, v8, v9
	v_cvt_pk_bf16_f32 v9, v10, v11
	v_cvt_pk_bf16_f32 v4, v4, v5
	v_cvt_pk_bf16_f32 v5, v6, v7
	v_cvt_pk_bf16_f32 v0, v0, v1
	v_cvt_pk_bf16_f32 v1, v2, v3
	s_and_b64 vcc, exec, s[4:5]
	s_mov_b32 s36, s8
	s_mov_b32 s6, s10
	s_mov_b64 s[18:19], s[14:15]
	s_mov_b64 s[16:17], s[12:13]
	global_store_dwordx2 v[16:17], v[18:19], off offset:96
	global_store_dwordx2 v[16:17], v[12:13], off offset:256
	global_store_dwordx2 v[16:17], v[8:9], off offset:288
	global_store_dwordx2 v[16:17], v[4:5], off offset:320
	global_store_dwordx2 v[16:17], v[0:1], off offset:352
	s_cbranch_vccz .LBB0_217
	s_waitcnt vmcnt(0)
	s_cmpk_gt_u32 s22, 0xff
	s_cbranch_scc1 .LBB0_228
	s_barrier

; #define PG8_STAGE(bufoff, gbase, voff) do { _Pragma("unroll") for (int _i = 0; _i < 2; ++_i) \
;         __builtin_amdgcn_global_load_lds((const unsigned*)((const char*)(gbase) + (voff)[_i]), (LAS unsigned*)(lds + (bufoff) + ldsw + _i * 8192), 16, 0, 0); } while (0)
; #define PG8_LDA(dst, b, h) do { _Pragma("unroll") for (int m = 0; m < 4; ++m) _Pragma("unroll") for (int k = 0; k < 2; ++k) dst[m][k] = *(const LAS bf16x8*)(lds + PG8_SA(b, h) + aoff + m * 2048 + k * 1024); } while (0)
; #define PG8_LDB(dst, b, h) do { _Pragma("unroll") for (int n = 0; n < 2; ++n) _Pragma("unroll") for (int k = 0; k < 2; ++k) dst[n][k] = *(const LAS bf16x8*)(lds + PG8_SB(b, h) + boff + n * 2048 + k * 1024); } while (0)
; #define PG8_WAIT_V(n) asm volatile("s_waitcnt vmcnt(" #n ")" ::: "memory")
; #define PG8_WAIT_L(n) asm volatile("s_waitcnt lgkmcnt(" #n ")" ::: "memory")
; #define PG8_BAR __builtin_amdgcn_s_barrier()
; #define PG8_SCHED __builtin_amdgcn_sched_barrier(0)
; template <class Epi>
; __device__ __forceinline__ void gemm_phase(LAS unsigned char* lds, const bf16_t* A, int lda, const bf16_t* Bt, int ldb, int M, int N, int K, int asel, const Epi& E, const int fixed_round = -1) {
;     ...
;         for (int t = 0; t < nt; t += 2) {
;             const bool last = (t == nt - 2);
;             const char* a1 = cA + (size_t)(t + 1) * kstep;
;             const char* a2 = last ? nA : cA + (size_t)(t + 2) * kstep; const char* b2 = last ? nB : cB + (size_t)(t + 2) * kstep;
;             const char* a3 = a2 + kstep; const char* b3 = b2 + kstep;
;             PG8_LDB(B0, 0, 0); PG8_SCHED; PG8_LDA(At, 0, 0); PG8_STAGE(PG8_SA(1, 1), a1 + hstepA, voffA);
;             PG8_WAIT_L(8); PG8_BAR; PG8_WAIT_L(0); PG8_MMA(0, 0, At, B0); PG8_BAR; PG8_SCHED;
;             PG8_LDB(B1, 0, 1); PG8_STAGE(PG8_SB(0, 0), b2, voffB);
;             PG8_BAR; PG8_WAIT_L(0); PG8_MMA(0, 1, At, B1); PG8_BAR;
;             PG8_LDA(At, 0, 1); PG8_STAGE(PG8_SA(0, 0), a2, voffA);
;             PG8_BAR; PG8_WAIT_L(0); PG8_MMA(1, 0, At, B0); PG8_BAR; PG8_SCHED;
;             PG8_STAGE(PG8_SB(0, 1), b2 + hstepB, voffB);
;             PG8_WAIT_V(6); PG8_BAR; PG8_MMA(1, 1, At, B1); PG8_BAR;
.LBB0_245:
	ds_read_b128 v[148:151], v161
	ds_read_b128 v[152:155], v161 offset:1024
	ds_read_b128 v[156:159], v161 offset:2048
	ds_read_b128 v[166:169], v161 offset:3072
	s_add_u32 s28, s26, 0xfff80080
	s_addc_u32 s29, s27, -1
	s_cmp_eq_u32 s57, 28
	s_cselect_b32 s31, s2, s29
	s_cselect_b32 s30, s19, s28
	s_cselect_b32 s29, s17, s56
	s_cselect_b32 s28, s54, s55
	s_add_i32 m0, s37, 0xc000
	ds_read_b128 v[170:173], v162
	ds_read_b128 v[174:177], v162 offset:1024
	ds_read_b128 v[178:181], v162 offset:2048
	ds_read_b128 v[182:185], v162 offset:3072
	ds_read_b128 v[186:189], v162 offset:4096
	ds_read_b128 v[190:193], v162 offset:5120
	ds_read_b128 v[196:199], v162 offset:6144
	ds_read_b128 v[202:205], v162 offset:7168
	global_load_lds_dwordx4 v140, s[26:27]
	s_add_i32 m0, s37, 0xe000
	s_nop 0
	global_load_lds_dwordx4 v142, s[26:27]
	s_waitcnt lgkmcnt(8)
	s_barrier
	s_waitcnt lgkmcnt(0)
	s_setprio 1
	s_waitcnt lgkmcnt(0)
	v_mfma_f32_16x16x32_bf16 v[124:127], v[148:151], v[170:173], v[124:127]
	v_mfma_f32_16x16x32_bf16 v[120:123], v[156:159], v[170:173], v[120:123]
	v_mfma_f32_16x16x32_bf16 v[112:115], v[148:151], v[178:181], v[112:115]
	v_mfma_f32_16x16x32_bf16 v[108:111], v[156:159], v[178:181], v[108:111]
	v_mfma_f32_16x16x32_bf16 v[100:103], v[148:151], v[186:189], v[100:103]
	v_mfma_f32_16x16x32_bf16 v[92:95], v[156:159], v[186:189], v[92:95]
	v_mfma_f32_16x16x32_bf16 v[84:87], v[148:151], v[196:199], v[84:87]
	v_mfma_f32_16x16x32_bf16 v[76:79], v[156:159], v[196:199], v[76:79]
	v_mfma_f32_16x16x32_bf16 v[124:127], v[152:155], v[174:177], v[124:127]
	v_mfma_f32_16x16x32_bf16 v[120:123], v[166:169], v[174:177], v[120:123]
	v_mfma_f32_16x16x32_bf16 v[112:115], v[152:155], v[182:185], v[112:115]
	v_mfma_f32_16x16x32_bf16 v[108:111], v[166:169], v[182:185], v[108:111]
	v_mfma_f32_16x16x32_bf16 v[100:103], v[152:155], v[190:193], v[100:103]
	v_mfma_f32_16x16x32_bf16 v[92:95], v[166:169], v[190:193], v[92:95]
	v_mfma_f32_16x16x32_bf16 v[84:87], v[152:155], v[202:205], v[84:87]
	v_mfma_f32_16x16x32_bf16 v[76:79], v[166:169], v[202:205], v[76:79]
	s_setprio 0
	s_barrier
	s_add_i32 s58, s44, s36
	s_add_u32 s98, s28, s4
	s_addc_u32 s99, s29, s5
	s_mov_b32 m0, s58
	ds_read_b128 v[206:209], v163
	ds_read_b128 v[210:213], v163 offset:1024
	ds_read_b128 v[214:217], v163 offset:2048
	ds_read_b128 v[218:221], v163 offset:3072
	global_load_lds_dwordx4 v130, s[28:29]
	s_add_i32 m0, s58, 0x2000
	s_nop 0
	global_load_lds_dwordx4 v134, s[28:29]
	s_barrier
	s_waitcnt lgkmcnt(0)
	s_setprio 1
	s_waitcnt lgkmcnt(0)
	v_mfma_f32_16x16x32_bf16 v[116:119], v[206:209], v[170:173], v[116:119]
	v_mfma_f32_16x16x32_bf16 v[104:107], v[214:217], v[170:173], v[104:107]
	v_mfma_f32_16x16x32_bf16 v[96:99], v[206:209], v[178:181], v[96:99]
	v_mfma_f32_16x16x32_bf16 v[88:91], v[214:217], v[178:181], v[88:91]
	v_mfma_f32_16x16x32_bf16 v[80:83], v[206:209], v[186:189], v[80:83]
	v_mfma_f32_16x16x32_bf16 v[72:75], v[214:217], v[186:189], v[72:75]
	v_mfma_f32_16x16x32_bf16 v[68:71], v[206:209], v[196:199], v[68:71]
	v_mfma_f32_16x16x32_bf16 v[64:67], v[214:217], v[196:199], v[64:67]
	v_mfma_f32_16x16x32_bf16 v[116:119], v[210:213], v[174:177], v[116:119]
	v_mfma_f32_16x16x32_bf16 v[104:107], v[218:221], v[174:177], v[104:107]
	v_mfma_f32_16x16x32_bf16 v[96:99], v[210:213], v[182:185], v[96:99]
	v_mfma_f32_16x16x32_bf16 v[88:91], v[218:221], v[182:185], v[88:91]
	v_mfma_f32_16x16x32_bf16 v[80:83], v[210:213], v[190:193], v[80:83]
	v_mfma_f32_16x16x32_bf16 v[72:75], v[218:221], v[190:193], v[72:75]
	v_mfma_f32_16x16x32_bf16 v[68:71], v[210:213], v[202:205], v[68:71]
	v_mfma_f32_16x16x32_bf16 v[64:67], v[218:221], v[202:205], v[64:67]
	s_setprio 0
	s_mov_b32 m0, s37
	s_add_u32 s100, s30, s4
	s_addc_u32 s101, s31, s5
	s_barrier
	ds_read_b128 v[170:173], v162 offset:16384
	ds_read_b128 v[174:177], v162 offset:17408
	ds_read_b128 v[178:181], v162 offset:18432
	ds_read_b128 v[182:185], v162 offset:19456
	ds_read_b128 v[186:189], v162 offset:20480
	ds_read_b128 v[190:193], v162 offset:21504
	ds_read_b128 v[196:199], v162 offset:22528
	ds_read_b128 v[202:205], v162 offset:23552
	global_load_lds_dwordx4 v128, s[30:31]
	s_mov_b32 m0, s38
	s_nop 0
	global_load_lds_dwordx4 v132, s[30:31]
	s_barrier
	s_waitcnt lgkmcnt(0)
	s_setprio 1
	s_waitcnt lgkmcnt(0)
	v_mfma_f32_16x16x32_bf16 v[60:63], v[148:151], v[170:173], v[60:63]
	v_mfma_f32_16x16x32_bf16 v[56:59], v[156:159], v[170:173], v[56:59]
	v_mfma_f32_16x16x32_bf16 v[52:55], v[148:151], v[178:181], v[52:55]
	v_mfma_f32_16x16x32_bf16 v[44:47], v[156:159], v[178:181], v[44:47]
	v_mfma_f32_16x16x32_bf16 v[36:39], v[148:151], v[186:189], v[36:39]
	v_mfma_f32_16x16x32_bf16 v[28:31], v[156:159], v[186:189], v[28:31]
	v_mfma_f32_16x16x32_bf16 v[20:23], v[148:151], v[196:199], v[20:23]
	v_mfma_f32_16x16x32_bf16 v[12:15], v[156:159], v[196:199], v[12:15]
	v_mfma_f32_16x16x32_bf16 v[60:63], v[152:155], v[174:177], v[60:63]
	v_mfma_f32_16x16x32_bf16 v[56:59], v[166:169], v[174:177], v[56:59]
	v_mfma_f32_16x16x32_bf16 v[52:55], v[152:155], v[182:185], v[52:55]
	v_mfma_f32_16x16x32_bf16 v[44:47], v[166:169], v[182:185], v[44:47]
	v_mfma_f32_16x16x32_bf16 v[36:39], v[152:155], v[190:193], v[36:39]
	v_mfma_f32_16x16x32_bf16 v[28:31], v[166:169], v[190:193], v[28:31]
	v_mfma_f32_16x16x32_bf16 v[20:23], v[152:155], v[202:205], v[20:23]
	v_mfma_f32_16x16x32_bf16 v[12:15], v[166:169], v[202:205], v[12:15]
	s_setprio 0
	s_barrier
	s_add_u32 s58, s28, 0x80000
	s_addc_u32 s59, s29, 0
	s_add_i32 s60, s45, s36
	s_mov_b32 m0, s60
	s_nop 0
	global_load_lds_dwordx4 v130, s[58:59]
	s_add_i32 m0, s60, 0x2000
	s_nop 0
	global_load_lds_dwordx4 v134, s[58:59]
	s_waitcnt vmcnt(6)
	s_barrier
; #define PG8_STAGE(bufoff, gbase, voff) do { _Pragma("unroll") for (int _i = 0; _i < 2; ++_i) \
;         __builtin_amdgcn_global_load_lds((const unsigned*)((const char*)(gbase) + (voff)[_i]), (LAS unsigned*)(lds + (bufoff) + ldsw + _i * 8192), 16, 0, 0); } while (0)
; #define PG8_LDA(dst, b, h) do { _Pragma("unroll") for (int m = 0; m < 4; ++m) _Pragma("unroll") for (int k = 0; k < 2; ++k) dst[m][k] = *(const LAS bf16x8*)(lds + PG8_SA(b, h) + aoff + m * 2048 + k * 1024); } while (0)
; #define PG8_LDB(dst, b, h) do { _Pragma("unroll") for (int n = 0; n < 2; ++n) _Pragma("unroll") for (int k = 0; k < 2; ++k) dst[n][k] = *(const LAS bf16x8*)(lds + PG8_SB(b, h) + boff + n * 2048 + k * 1024); } while (0)
; #define PG8_WAIT_L(n) asm volatile("s_waitcnt lgkmcnt(" #n ")" ::: "memory")
; #define PG8_BAR __builtin_amdgcn_s_barrier()
; #define PG8_SCHED __builtin_amdgcn_sched_barrier(0)
; template <class Epi>
; __device__ __forceinline__ void gemm_phase(LAS unsigned char* lds, const bf16_t* A, int lda, const bf16_t* Bt, int ldb, int M, int N, int K, int asel, const Epi& E, const int fixed_round = -1) {
;     ...
;             PG8_LDB(B0, 1, 0); PG8_SCHED; PG8_LDA(At, 1, 0); PG8_STAGE(PG8_SA(0, 1), a2 + hstepA, voffA);
;             PG8_WAIT_L(8); PG8_BAR; PG8_WAIT_L(0); PG8_MMA(0, 0, At, B0); PG8_BAR; PG8_SCHED;
;             PG8_LDB(B1, 1, 1); PG8_STAGE(PG8_SB(1, 0), b3, voffB);
;             PG8_BAR; PG8_WAIT_L(0); PG8_MMA(0, 1, At, B1); PG8_BAR;
;             PG8_LDA(At, 1, 1); PG8_STAGE(PG8_SA(1, 0), a3, voffA);
;             PG8_BAR; PG8_WAIT_L(0); PG8_MMA(1, 0, At, B0); PG8_BAR; PG8_SCHED;
	s_setprio 1
	v_mfma_f32_16x16x32_bf16 v[48:51], v[206:209], v[170:173], v[48:51]
	v_mfma_f32_16x16x32_bf16 v[40:43], v[214:217], v[170:173], v[40:43]
	v_mfma_f32_16x16x32_bf16 v[32:35], v[206:209], v[178:181], v[32:35]
	v_mfma_f32_16x16x32_bf16 v[24:27], v[214:217], v[178:181], v[24:27]
	v_mfma_f32_16x16x32_bf16 v[16:19], v[206:209], v[186:189], v[16:19]
	v_mfma_f32_16x16x32_bf16 v[8:11], v[214:217], v[186:189], v[8:11]
	v_mfma_f32_16x16x32_bf16 v[4:7], v[206:209], v[196:199], v[4:7]
	v_mfma_f32_16x16x32_bf16 v[0:3], v[214:217], v[196:199], v[0:3]
	v_mfma_f32_16x16x32_bf16 v[48:51], v[210:213], v[174:177], v[48:51]
	v_mfma_f32_16x16x32_bf16 v[40:43], v[218:221], v[174:177], v[40:43]
	v_mfma_f32_16x16x32_bf16 v[32:35], v[210:213], v[182:185], v[32:35]
	v_mfma_f32_16x16x32_bf16 v[24:27], v[218:221], v[182:185], v[24:27]
	v_mfma_f32_16x16x32_bf16 v[16:19], v[210:213], v[190:193], v[16:19]
	v_mfma_f32_16x16x32_bf16 v[8:11], v[218:221], v[190:193], v[8:11]
	v_mfma_f32_16x16x32_bf16 v[4:7], v[210:213], v[202:205], v[4:7]
	v_mfma_f32_16x16x32_bf16 v[0:3], v[218:221], v[202:205], v[0:3]
	s_setprio 0
	s_add_i32 s58, 0, 0x18000
	v_add_u32_e32 v136, s58, v160
	s_barrier
	ds_read_b128 v[148:151], v136
	ds_read_b128 v[152:155], v136 offset:1024
	ds_read_b128 v[156:159], v136 offset:2048
	ds_read_b128 v[166:169], v136 offset:3072
	s_add_u32 s30, s30, 0x80000
	s_addc_u32 s31, s31, 0
	s_mov_b32 m0, s39
	ds_read_b128 v[170:173], v162 offset:32768
	ds_read_b128 v[174:177], v162 offset:33792
	ds_read_b128 v[178:181], v162 offset:34816
	ds_read_b128 v[182:185], v162 offset:35840
	ds_read_b128 v[186:189], v162 offset:36864
	ds_read_b128 v[190:193], v162 offset:37888
	ds_read_b128 v[196:199], v162 offset:38912
	ds_read_b128 v[202:205], v162 offset:39936
	global_load_lds_dwordx4 v128, s[30:31]
	s_mov_b32 m0, s40
	s_nop 0
	global_load_lds_dwordx4 v132, s[30:31]
	s_waitcnt lgkmcnt(8)
	s_barrier
	s_waitcnt lgkmcnt(0)
	s_setprio 1
	s_waitcnt lgkmcnt(0)
	v_mfma_f32_16x16x32_bf16 v[124:127], v[148:151], v[170:173], v[124:127]
	v_mfma_f32_16x16x32_bf16 v[120:123], v[156:159], v[170:173], v[120:123]
	v_mfma_f32_16x16x32_bf16 v[112:115], v[148:151], v[178:181], v[112:115]
	v_mfma_f32_16x16x32_bf16 v[108:111], v[156:159], v[178:181], v[108:111]
	v_mfma_f32_16x16x32_bf16 v[100:103], v[148:151], v[186:189], v[100:103]
	v_mfma_f32_16x16x32_bf16 v[92:95], v[156:159], v[186:189], v[92:95]
	v_mfma_f32_16x16x32_bf16 v[84:87], v[148:151], v[196:199], v[84:87]
	v_mfma_f32_16x16x32_bf16 v[76:79], v[156:159], v[196:199], v[76:79]
	v_mfma_f32_16x16x32_bf16 v[124:127], v[152:155], v[174:177], v[124:127]
	v_mfma_f32_16x16x32_bf16 v[120:123], v[166:169], v[174:177], v[120:123]
	v_mfma_f32_16x16x32_bf16 v[112:115], v[152:155], v[182:185], v[112:115]
	v_mfma_f32_16x16x32_bf16 v[108:111], v[166:169], v[182:185], v[108:111]
	v_mfma_f32_16x16x32_bf16 v[100:103], v[152:155], v[190:193], v[100:103]
	v_mfma_f32_16x16x32_bf16 v[92:95], v[166:169], v[190:193], v[92:95]
	v_mfma_f32_16x16x32_bf16 v[84:87], v[152:155], v[202:205], v[84:87]
	v_mfma_f32_16x16x32_bf16 v[76:79], v[166:169], v[202:205], v[76:79]
	s_setprio 0
	s_barrier
	s_add_i32 s30, 0, 0x1c000
	s_add_i32 s31, s58, s36
	v_add_u32_e32 v136, s30, v160
	s_mov_b32 m0, s31
	ds_read_b128 v[206:209], v136
	ds_read_b128 v[210:213], v136 offset:1024
	ds_read_b128 v[214:217], v136 offset:2048
	ds_read_b128 v[218:221], v136 offset:3072
	global_load_lds_dwordx4 v130, s[98:99]
	s_add_i32 m0, s31, 0x2000
	s_nop 0
	global_load_lds_dwordx4 v134, s[98:99]
	s_barrier
	s_waitcnt lgkmcnt(0)
	s_setprio 1
	s_waitcnt lgkmcnt(0)
	v_mfma_f32_16x16x32_bf16 v[116:119], v[206:209], v[170:173], v[116:119]
	v_mfma_f32_16x16x32_bf16 v[104:107], v[214:217], v[170:173], v[104:107]
	v_mfma_f32_16x16x32_bf16 v[96:99], v[206:209], v[178:181], v[96:99]
	v_mfma_f32_16x16x32_bf16 v[88:91], v[214:217], v[178:181], v[88:91]
	v_mfma_f32_16x16x32_bf16 v[80:83], v[206:209], v[186:189], v[80:83]
	v_mfma_f32_16x16x32_bf16 v[72:75], v[214:217], v[186:189], v[72:75]
	v_mfma_f32_16x16x32_bf16 v[68:71], v[206:209], v[196:199], v[68:71]
	v_mfma_f32_16x16x32_bf16 v[64:67], v[214:217], v[196:199], v[64:67]
	v_mfma_f32_16x16x32_bf16 v[116:119], v[210:213], v[174:177], v[116:119]
	v_mfma_f32_16x16x32_bf16 v[104:107], v[218:221], v[174:177], v[104:107]
	v_mfma_f32_16x16x32_bf16 v[96:99], v[210:213], v[182:185], v[96:99]
	v_mfma_f32_16x16x32_bf16 v[88:91], v[218:221], v[182:185], v[88:91]
	v_mfma_f32_16x16x32_bf16 v[80:83], v[210:213], v[190:193], v[80:83]
	v_mfma_f32_16x16x32_bf16 v[72:75], v[218:221], v[190:193], v[72:75]
	v_mfma_f32_16x16x32_bf16 v[68:71], v[210:213], v[202:205], v[68:71]
	v_mfma_f32_16x16x32_bf16 v[64:67], v[218:221], v[202:205], v[64:67]
	s_setprio 0
	s_mov_b32 m0, s41
	s_barrier
	ds_read_b128 v[170:173], v162 offset:49152
	ds_read_b128 v[174:177], v162 offset:50176
	ds_read_b128 v[178:181], v162 offset:51200
	ds_read_b128 v[182:185], v162 offset:52224
	ds_read_b128 v[186:189], v162 offset:53248
	ds_read_b128 v[190:193], v162 offset:54272
	ds_read_b128 v[196:199], v162 offset:55296
	ds_read_b128 v[202:205], v162 offset:56320
	global_load_lds_dwordx4 v128, s[100:101]
	s_mov_b32 m0, s42
	s_nop 0
	global_load_lds_dwordx4 v132, s[100:101]
	s_barrier
; #define LAS __attribute__((address_space(3)))
; __device__ __forceinline__ unsigned cvt_pk_bf16(float lo, float hi) { const bf16x2_t r = __builtin_convertvector((f32x2){lo, hi}, bf16x2_t); return __builtin_bit_cast(unsigned, r); }
; #define PG8_WAIT_V(n) asm volatile("s_waitcnt vmcnt(" #n ")" ::: "memory")
; #define PG8_BAR __builtin_amdgcn_s_barrier()
; template <class Epi>
; __device__ __forceinline__ void gemm_phase(LAS unsigned char* lds, const bf16_t* A, int lda, const bf16_t* Bt, int ldb, int M, int N, int K, int asel, const Epi& E, const int fixed_round = -1) {
;     ...
;             PG8_STAGE(PG8_SB(1, 1), b3 + hstepB, voffB);
;             PG8_WAIT_V(6); PG8_BAR; PG8_MMA(1, 1, At, B1); PG8_BAR;
;             if constexpr (Epi::HEADSCALE) {
;                 if (t & 2) {
;                     const LAS float* rt = (const LAS float*)(lds + L_RT) + (t >> 2);
; #pragma unroll
;                     for (int ai = 0; ai < 2; ++ai)
; #pragma unroll
;                         for (int m = 0; m < 4; ++m) { const float f = rt[(ai * HALF + wr * 64 + m * 16 + fr) * 8];
; #pragma unroll
;                             for (int bj = 0; bj < 2; ++bj)
; #pragma unroll
;                                 for (int n = 0; n < 2; ++n) acc[ai][bj][m][n] *= f; }
;                 }
;             }
;         }
;         if constexpr (!Epi::AFTER_DRAIN) E(acc, cur, wr, wc, fr, fq);
;         if (!has_next) break;
;     __device__ __forceinline__ void operator()(const AccT& acc, const Unit& u, int wr, int wc, int fr, int fq) const {
;     ...
;         if (pn < 8) {
;             bf16_t* base = pn < 4 ? Q : Kn; const int colt = (pn & 3) * BM; const float sc = pn < 4 ? 0.08838834764831845f : 1.0f;
; #pragma unroll
;             for (int ai = 0; ai < 2; ++ai)
; #pragma unroll
;                 for (int m = 0; m < 4; ++m) { bf16_t* rowp = base + (size_t)(row0 + ai * HALF + m * 16) * 1024 + colt + cl;
; #pragma unroll
;                     for (int bj = 0; bj < 2; ++bj) { const f32x4 v0 = acc[ai][bj][m][0] * sc, v1 = acc[ai][bj][m][1] * sc;
;                         u32x4 w; w.x = cvt_pk_bf16(v0[0], v0[1]); w.y = cvt_pk_bf16(v0[2], v0[3]); w.z = cvt_pk_bf16(v1[0], v1[1]); w.w = cvt_pk_bf16(v1[2], v1[3]);
;                         *(u32x4*)(rowp + bj * HALF) = w; } }
	s_waitcnt lgkmcnt(0)
	s_setprio 1
	s_waitcnt lgkmcnt(0)
	v_mfma_f32_16x16x32_bf16 v[60:63], v[148:151], v[170:173], v[60:63]
	v_mfma_f32_16x16x32_bf16 v[56:59], v[156:159], v[170:173], v[56:59]
	v_mfma_f32_16x16x32_bf16 v[52:55], v[148:151], v[178:181], v[52:55]
	v_mfma_f32_16x16x32_bf16 v[44:47], v[156:159], v[178:181], v[44:47]
	v_mfma_f32_16x16x32_bf16 v[36:39], v[148:151], v[186:189], v[36:39]
	v_mfma_f32_16x16x32_bf16 v[28:31], v[156:159], v[186:189], v[28:31]
	v_mfma_f32_16x16x32_bf16 v[20:23], v[148:151], v[196:199], v[20:23]
	v_mfma_f32_16x16x32_bf16 v[12:15], v[156:159], v[196:199], v[12:15]
	v_mfma_f32_16x16x32_bf16 v[60:63], v[152:155], v[174:177], v[60:63]
	v_mfma_f32_16x16x32_bf16 v[56:59], v[166:169], v[174:177], v[56:59]
	v_mfma_f32_16x16x32_bf16 v[52:55], v[152:155], v[182:185], v[52:55]
	v_mfma_f32_16x16x32_bf16 v[44:47], v[166:169], v[182:185], v[44:47]
	v_mfma_f32_16x16x32_bf16 v[36:39], v[152:155], v[190:193], v[36:39]
	v_mfma_f32_16x16x32_bf16 v[28:31], v[166:169], v[190:193], v[28:31]
	v_mfma_f32_16x16x32_bf16 v[20:23], v[152:155], v[202:205], v[20:23]
	v_mfma_f32_16x16x32_bf16 v[12:15], v[166:169], v[202:205], v[12:15]
	s_setprio 0
	s_barrier
	s_add_u32 s28, s28, 0x80080
	s_addc_u32 s29, s29, 0
	s_add_i32 s30, s30, s36
	s_mov_b32 m0, s30
	s_nop 0
	global_load_lds_dwordx4 v130, s[28:29]
	s_add_i32 m0, s30, 0x2000
	s_nop 0
	global_load_lds_dwordx4 v134, s[28:29]
	s_waitcnt vmcnt(6)
	s_barrier
	s_setprio 1
	v_mfma_f32_16x16x32_bf16 v[48:51], v[206:209], v[170:173], v[48:51]
	v_mfma_f32_16x16x32_bf16 v[40:43], v[214:217], v[170:173], v[40:43]
	v_mfma_f32_16x16x32_bf16 v[32:35], v[206:209], v[178:181], v[32:35]
	v_mfma_f32_16x16x32_bf16 v[24:27], v[214:217], v[178:181], v[24:27]
	v_mfma_f32_16x16x32_bf16 v[16:19], v[206:209], v[186:189], v[16:19]
	v_mfma_f32_16x16x32_bf16 v[8:11], v[214:217], v[186:189], v[8:11]
	v_mfma_f32_16x16x32_bf16 v[4:7], v[206:209], v[196:199], v[4:7]
	v_mfma_f32_16x16x32_bf16 v[0:3], v[214:217], v[196:199], v[0:3]
	v_mfma_f32_16x16x32_bf16 v[48:51], v[210:213], v[174:177], v[48:51]
	v_mfma_f32_16x16x32_bf16 v[40:43], v[218:221], v[174:177], v[40:43]
	v_mfma_f32_16x16x32_bf16 v[32:35], v[210:213], v[182:185], v[32:35]
	v_mfma_f32_16x16x32_bf16 v[24:27], v[218:221], v[182:185], v[24:27]
	v_mfma_f32_16x16x32_bf16 v[16:19], v[210:213], v[190:193], v[16:19]
	v_mfma_f32_16x16x32_bf16 v[8:11], v[218:221], v[190:193], v[8:11]
	v_mfma_f32_16x16x32_bf16 v[4:7], v[210:213], v[202:205], v[4:7]
	v_mfma_f32_16x16x32_bf16 v[0:3], v[218:221], v[202:205], v[0:3]
	s_setprio 0
	s_add_i32 s57, s57, 2
	s_add_u32 s26, s26, 0x100
	s_addc_u32 s27, s27, 0
	s_add_u32 s55, s55, 0x100
	s_addc_u32 s56, s56, 0
	s_cmp_gt_u32 s57, 29
	s_barrier
	s_cbranch_scc0 .LBB0_245
	s_lshl_b32 s17, s24, 8
	v_add_u32_e32 v154, s17, v139
	s_cmp_lt_i32 s25, -8
	v_or_b32_e32 v152, 16, v154
	v_or_b32_e32 v150, 32, v154
	v_or_b32_e32 v148, 48, v154
	s_cselect_b64 s[26:27], -1, 0
	s_cmp_gt_i32 s25, -9
	v_ashrrev_i32_e32 v155, 31, v154
	v_lshlrev_b32_e32 v136, 1, v138
	v_ashrrev_i32_e32 v153, 31, v152
	v_ashrrev_i32_e32 v151, 31, v150
	v_ashrrev_i32_e32 v149, 31, v148
	s_cbranch_scc1 .LBB0_248
	s_cmp_lt_u32 s25, -12
	s_cselect_b64 vcc, -1, 0
	s_and_b64 s[28:29], vcc, exec
	s_cselect_b32 s2, s89, s81
	s_cselect_b32 s19, s88, s91
	s_lshl_b32 s28, s25, 9
	s_and_b32 s28, s28, 0x600
	s_add_u32 s28, s19, s28
	v_cndmask_b32_e32 v156, 1.0, v164, vcc
	s_addc_u32 s29, s2, 0
	v_lshl_add_u64 v[170:171], s[28:29], 0, v[136:137]
	v_lshlrev_b64 v[158:159], 11, v[154:155]
	v_pk_mul_f32 v[168:169], v[156:157], v[126:127] op_sel_hi:[0,1]
	v_pk_mul_f32 v[166:167], v[156:157], v[124:125] op_sel_hi:[0,1]
	v_pk_mul_f32 v[172:173], v[156:157], v[122:123] op_sel_hi:[0,1]
	v_pk_mul_f32 v[174:175], v[156:157], v[120:121] op_sel_hi:[0,1]
	v_lshl_add_u64 v[158:159], v[170:171], 0, v[158:159]
	v_cvt_pk_bf16_f32 v166, v166, v167
	v_cvt_pk_bf16_f32 v167, v168, v169
	v_cvt_pk_bf16_f32 v168, v174, v175
	v_cvt_pk_bf16_f32 v169, v172, v173
	global_store_dwordx4 v[158:159], v[166:169], off
	v_pk_mul_f32 v[172:173], v[156:157], v[106:107] op_sel_hi:[0,1]
	v_pk_mul_f32 v[174:175], v[156:157], v[104:105] op_sel_hi:[0,1]
	v_pk_mul_f32 v[168:169], v[156:157], v[118:119] op_sel_hi:[0,1]
	v_pk_mul_f32 v[166:167], v[156:157], v[116:117] op_sel_hi:[0,1]
	v_cvt_pk_bf16_f32 v166, v166, v167
	v_cvt_pk_bf16_f32 v167, v168, v169
	v_cvt_pk_bf16_f32 v168, v174, v175
	v_cvt_pk_bf16_f32 v169, v172, v173
	global_store_dwordx4 v[158:159], v[166:169], off offset:256
	v_pk_mul_f32 v[174:175], v[156:157], v[110:111] op_sel_hi:[0,1]
	v_pk_mul_f32 v[176:177], v[156:157], v[108:109] op_sel_hi:[0,1]
	v_lshlrev_b64 v[166:167], 11, v[152:153]
	v_lshl_add_u64 v[172:173], v[170:171], 0, v[166:167]
	v_pk_mul_f32 v[168:169], v[156:157], v[114:115] op_sel_hi:[0,1]
	v_pk_mul_f32 v[166:167], v[156:157], v[112:113] op_sel_hi:[0,1]
	v_cvt_pk_bf16_f32 v166, v166, v167
	v_cvt_pk_bf16_f32 v167, v168, v169
	v_cvt_pk_bf16_f32 v168, v176, v177
	v_cvt_pk_bf16_f32 v169, v174, v175
	global_store_dwordx4 v[172:173], v[166:169], off
	v_pk_mul_f32 v[174:175], v[156:157], v[90:91] op_sel_hi:[0,1]
	v_pk_mul_f32 v[176:177], v[156:157], v[88:89] op_sel_hi:[0,1]
	v_pk_mul_f32 v[168:169], v[156:157], v[98:99] op_sel_hi:[0,1]
	v_pk_mul_f32 v[166:167], v[156:157], v[96:97] op_sel_hi:[0,1]
	v_cvt_pk_bf16_f32 v166, v166, v167
	v_cvt_pk_bf16_f32 v167, v168, v169
	v_cvt_pk_bf16_f32 v168, v176, v177
	v_cvt_pk_bf16_f32 v169, v174, v175
	global_store_dwordx4 v[172:173], v[166:169], off offset:256
	v_pk_mul_f32 v[174:175], v[156:157], v[94:95] op_sel_hi:[0,1]
	v_pk_mul_f32 v[176:177], v[156:157], v[92:93] op_sel_hi:[0,1]
; __device__ __forceinline__ unsigned cvt_pk_bf16(float lo, float hi) { const bf16x2_t r = __builtin_convertvector((f32x2){lo, hi}, bf16x2_t); return __builtin_bit_cast(unsigned, r); }
;     __device__ __forceinline__ void operator()(const AccT& acc, const Unit& u, int wr, int wc, int fr, int fq) const {
;     ...
;         if (pn < 8) {
;             bf16_t* base = pn < 4 ? Q : Kn; const int colt = (pn & 3) * BM; const float sc = pn < 4 ? 0.08838834764831845f : 1.0f;
; #pragma unroll
;             for (int ai = 0; ai < 2; ++ai)
; #pragma unroll
;                 for (int m = 0; m < 4; ++m) { bf16_t* rowp = base + (size_t)(row0 + ai * HALF + m * 16) * 1024 + colt + cl;
; #pragma unroll
;                     for (int bj = 0; bj < 2; ++bj) { const f32x4 v0 = acc[ai][bj][m][0] * sc, v1 = acc[ai][bj][m][1] * sc;
;                         u32x4 w; w.x = cvt_pk_bf16(v0[0], v0[1]); w.y = cvt_pk_bf16(v0[2], v0[3]); w.z = cvt_pk_bf16(v1[0], v1[1]); w.w = cvt_pk_bf16(v1[2], v1[3]);
;                         *(u32x4*)(rowp + bj * HALF) = w; } }
;         }
	v_lshlrev_b64 v[166:167], 11, v[150:151]
	v_lshl_add_u64 v[172:173], v[170:171], 0, v[166:167]
	v_pk_mul_f32 v[168:169], v[156:157], v[102:103] op_sel_hi:[0,1]
	v_pk_mul_f32 v[166:167], v[156:157], v[100:101] op_sel_hi:[0,1]
	v_cvt_pk_bf16_f32 v166, v166, v167
	v_cvt_pk_bf16_f32 v167, v168, v169
	v_cvt_pk_bf16_f32 v168, v176, v177
	v_cvt_pk_bf16_f32 v169, v174, v175
	global_store_dwordx4 v[172:173], v[166:169], off
	v_pk_mul_f32 v[174:175], v[156:157], v[74:75] op_sel_hi:[0,1]
	v_pk_mul_f32 v[176:177], v[156:157], v[72:73] op_sel_hi:[0,1]
	v_pk_mul_f32 v[168:169], v[156:157], v[82:83] op_sel_hi:[0,1]
	v_pk_mul_f32 v[166:167], v[156:157], v[80:81] op_sel_hi:[0,1]
	v_cvt_pk_bf16_f32 v166, v166, v167
	v_cvt_pk_bf16_f32 v167, v168, v169
	v_cvt_pk_bf16_f32 v168, v176, v177
	v_cvt_pk_bf16_f32 v169, v174, v175
	global_store_dwordx4 v[172:173], v[166:169], off offset:256
	v_pk_mul_f32 v[172:173], v[156:157], v[78:79] op_sel_hi:[0,1]
	v_pk_mul_f32 v[174:175], v[156:157], v[76:77] op_sel_hi:[0,1]
	v_lshlrev_b64 v[166:167], 11, v[148:149]
	v_lshl_add_u64 v[170:171], v[170:171], 0, v[166:167]
	v_pk_mul_f32 v[168:169], v[156:157], v[86:87] op_sel_hi:[0,1]
	v_pk_mul_f32 v[166:167], v[156:157], v[84:85] op_sel_hi:[0,1]
	v_cvt_pk_bf16_f32 v166, v166, v167
	v_cvt_pk_bf16_f32 v167, v168, v169
	v_cvt_pk_bf16_f32 v168, v174, v175
	v_cvt_pk_bf16_f32 v169, v172, v173
	global_store_dwordx4 v[170:171], v[166:169], off
	v_pk_mul_f32 v[172:173], v[156:157], v[66:67] op_sel_hi:[0,1]
	v_pk_mul_f32 v[174:175], v[156:157], v[64:65] op_sel_hi:[0,1]
	v_pk_mul_f32 v[168:169], v[156:157], v[70:71] op_sel_hi:[0,1]
	v_pk_mul_f32 v[166:167], v[156:157], v[68:69] op_sel_hi:[0,1]
	v_cvt_pk_bf16_f32 v166, v166, v167
	v_cvt_pk_bf16_f32 v167, v168, v169
	v_cvt_pk_bf16_f32 v168, v174, v175
	v_cvt_pk_bf16_f32 v169, v172, v173
	global_store_dwordx4 v[170:171], v[166:169], off offset:256
	v_pk_mul_f32 v[172:173], v[156:157], v[58:59] op_sel_hi:[0,1]
	s_mov_b32 s2, 0x40000
	v_pk_mul_f32 v[168:169], v[156:157], v[62:63] op_sel_hi:[0,1]
	v_pk_mul_f32 v[166:167], v[156:157], v[60:61] op_sel_hi:[0,1]
	v_pk_mul_f32 v[174:175], v[156:157], v[56:57] op_sel_hi:[0,1]
	v_cvt_pk_bf16_f32 v166, v166, v167
	v_cvt_pk_bf16_f32 v167, v168, v169
	v_cvt_pk_bf16_f32 v169, v172, v173
	v_add_co_u32_e32 v172, vcc, s2, v158
	v_cvt_pk_bf16_f32 v168, v174, v175
	s_nop 0
	v_addc_co_u32_e32 v173, vcc, 0, v159, vcc
	s_mov_b64 s[28:29], 0x40000
	global_store_dwordx4 v[172:173], v[166:169], off
	v_pk_mul_f32 v[172:173], v[156:157], v[42:43] op_sel_hi:[0,1]
	v_pk_mul_f32 v[174:175], v[156:157], v[40:41] op_sel_hi:[0,1]
	v_pk_mul_f32 v[168:169], v[156:157], v[50:51] op_sel_hi:[0,1]
	v_pk_mul_f32 v[166:167], v[156:157], v[48:49] op_sel_hi:[0,1]
	v_lshl_add_u64 v[170:171], v[158:159], 0, s[28:29]
	v_cvt_pk_bf16_f32 v166, v166, v167
	v_cvt_pk_bf16_f32 v167, v168, v169
	v_cvt_pk_bf16_f32 v168, v174, v175
	v_cvt_pk_bf16_f32 v169, v172, v173
	global_store_dwordx4 v[170:171], v[166:169], off offset:256
	v_pk_mul_f32 v[172:173], v[156:157], v[46:47] op_sel_hi:[0,1]
	v_pk_mul_f32 v[174:175], v[156:157], v[44:45] op_sel_hi:[0,1]
	v_pk_mul_f32 v[168:169], v[156:157], v[54:55] op_sel_hi:[0,1]
	v_pk_mul_f32 v[166:167], v[156:157], v[52:53] op_sel_hi:[0,1]
	v_cvt_pk_bf16_f32 v166, v166, v167
	v_cvt_pk_bf16_f32 v167, v168, v169
	v_cvt_pk_bf16_f32 v169, v172, v173
	v_add_co_u32_e32 v172, vcc, s46, v158
	v_cvt_pk_bf16_f32 v168, v174, v175
	s_nop 0
	v_addc_co_u32_e32 v173, vcc, 0, v159, vcc
	s_mov_b64 s[28:29], 0x48000
	global_store_dwordx4 v[172:173], v[166:169], off
	v_pk_mul_f32 v[172:173], v[156:157], v[26:27] op_sel_hi:[0,1]
	v_pk_mul_f32 v[174:175], v[156:157], v[24:25] op_sel_hi:[0,1]
	v_pk_mul_f32 v[168:169], v[156:157], v[34:35] op_sel_hi:[0,1]
	v_pk_mul_f32 v[166:167], v[156:157], v[32:33] op_sel_hi:[0,1]
	v_lshl_add_u64 v[170:171], v[158:159], 0, s[28:29]
	v_cvt_pk_bf16_f32 v166, v166, v167
	v_cvt_pk_bf16_f32 v167, v168, v169
	v_cvt_pk_bf16_f32 v168, v174, v175
	v_cvt_pk_bf16_f32 v169, v172, v173
	global_store_dwordx4 v[170:171], v[166:169], off offset:256
	v_pk_mul_f32 v[172:173], v[156:157], v[30:31] op_sel_hi:[0,1]
	v_pk_mul_f32 v[174:175], v[156:157], v[28:29] op_sel_hi:[0,1]
	v_pk_mul_f32 v[168:169], v[156:157], v[38:39] op_sel_hi:[0,1]
	v_pk_mul_f32 v[166:167], v[156:157], v[36:37] op_sel_hi:[0,1]
	v_cvt_pk_bf16_f32 v166, v166, v167
	v_cvt_pk_bf16_f32 v167, v168, v169
	v_cvt_pk_bf16_f32 v169, v172, v173
	v_add_co_u32_e32 v172, vcc, s47, v158
	v_cvt_pk_bf16_f32 v168, v174, v175
	s_nop 0
	v_addc_co_u32_e32 v173, vcc, 0, v159, vcc
	global_store_dwordx4 v[172:173], v[166:169], off
	v_pk_mul_f32 v[172:173], v[156:157], v[10:11] op_sel_hi:[0,1]
	v_pk_mul_f32 v[174:175], v[156:157], v[8:9] op_sel_hi:[0,1]
	v_pk_mul_f32 v[168:169], v[156:157], v[18:19] op_sel_hi:[0,1]
	v_pk_mul_f32 v[166:167], v[156:157], v[16:17] op_sel_hi:[0,1]
	v_lshl_add_u64 v[170:171], v[158:159], 0, s[6:7]
	v_cvt_pk_bf16_f32 v166, v166, v167
	v_cvt_pk_bf16_f32 v167, v168, v169
	v_cvt_pk_bf16_f32 v168, v174, v175
	v_cvt_pk_bf16_f32 v169, v172, v173
	global_store_dwordx4 v[170:171], v[166:169], off offset:256
	v_lshl_add_u64 v[170:171], v[158:159], 0, s[8:9]
	v_pk_mul_f32 v[172:173], v[156:157], v[14:15] op_sel_hi:[0,1]
	v_pk_mul_f32 v[168:169], v[156:157], v[22:23] op_sel_hi:[0,1]
	v_pk_mul_f32 v[166:167], v[156:157], v[20:21] op_sel_hi:[0,1]
	v_pk_mul_f32 v[174:175], v[156:157], v[12:13] op_sel_hi:[0,1]
	v_add_co_u32_e32 v158, vcc, s48, v158
	v_cvt_pk_bf16_f32 v166, v166, v167
	v_cvt_pk_bf16_f32 v167, v168, v169
	v_cvt_pk_bf16_f32 v168, v174, v175
	v_cvt_pk_bf16_f32 v169, v172, v173
	v_addc_co_u32_e32 v159, vcc, 0, v159, vcc
	global_store_dwordx4 v[158:159], v[166:169], off
	v_pk_mul_f32 v[158:159], v[156:157], v[6:7] op_sel_hi:[0,1]
	v_pk_mul_f32 v[172:173], v[156:157], v[0:1] op_sel_hi:[0,1]
	v_pk_mul_f32 v[166:167], v[156:157], v[4:5] op_sel_hi:[0,1]
	v_pk_mul_f32 v[168:169], v[156:157], v[2:3] op_sel_hi:[0,1]
	v_cvt_pk_bf16_f32 v156, v166, v167
	v_cvt_pk_bf16_f32 v157, v158, v159
	v_cvt_pk_bf16_f32 v158, v172, v173
	v_cvt_pk_bf16_f32 v159, v168, v169
	global_store_dwordx4 v[170:171], v[156:159], off offset:256

; #define PG8_STAGE(bufoff, gbase, voff) do { _Pragma("unroll") for (int _i = 0; _i < 2; ++_i) \
;         __builtin_amdgcn_global_load_lds((const unsigned*)((const char*)(gbase) + (voff)[_i]), (LAS unsigned*)(lds + (bufoff) + ldsw + _i * 8192), 16, 0, 0); } while (0)
; #define PG8_LDA(dst, b, h) do { _Pragma("unroll") for (int m = 0; m < 4; ++m) _Pragma("unroll") for (int k = 0; k < 2; ++k) dst[m][k] = *(const LAS bf16x8*)(lds + PG8_SA(b, h) + aoff + m * 2048 + k * 1024); } while (0)
; #define PG8_LDB(dst, b, h) do { _Pragma("unroll") for (int n = 0; n < 2; ++n) _Pragma("unroll") for (int k = 0; k < 2; ++k) dst[n][k] = *(const LAS bf16x8*)(lds + PG8_SB(b, h) + boff + n * 2048 + k * 1024); } while (0)
; #define PG8_WAIT_V(n) asm volatile("s_waitcnt vmcnt(" #n ")" ::: "memory")
; #define PG8_WAIT_L(n) asm volatile("s_waitcnt lgkmcnt(" #n ")" ::: "memory")
; #define PG8_BAR __builtin_amdgcn_s_barrier()
; #define PG8_SCHED __builtin_amdgcn_sched_barrier(0)
; template <class Epi>
; __device__ __forceinline__ void gemm_phase(LAS unsigned char* lds, const bf16_t* A, int lda, const bf16_t* Bt, int ldb, int M, int N, int K, int asel, const Epi& E, const int fixed_round = -1) {
;     ...
;         for (int t = 0; t < nt; t += 2) {
;             const bool last = (t == nt - 2);
;             const char* a1 = cA + (size_t)(t + 1) * kstep;
;             const char* a2 = last ? nA : cA + (size_t)(t + 2) * kstep; const char* b2 = last ? nB : cB + (size_t)(t + 2) * kstep;
;             const char* a3 = a2 + kstep; const char* b3 = b2 + kstep;
;             PG8_LDB(B0, 0, 0); PG8_SCHED; PG8_LDA(At, 0, 0); PG8_STAGE(PG8_SA(1, 1), a1 + hstepA, voffA);
;             PG8_WAIT_L(8); PG8_BAR; PG8_WAIT_L(0); PG8_MMA(0, 0, At, B0); PG8_BAR; PG8_SCHED;
;             PG8_LDB(B1, 0, 1); PG8_STAGE(PG8_SB(0, 0), b2, voffB);
;             PG8_BAR; PG8_WAIT_L(0); PG8_MMA(0, 1, At, B1); PG8_BAR;
;             PG8_LDA(At, 0, 1); PG8_STAGE(PG8_SA(0, 0), a2, voffA);
;             PG8_BAR; PG8_WAIT_L(0); PG8_MMA(1, 0, At, B0); PG8_BAR; PG8_SCHED;
;             PG8_STAGE(PG8_SB(0, 1), b2 + hstepB, voffB);
;             PG8_WAIT_V(6); PG8_BAR; PG8_MMA(1, 1, At, B1); PG8_BAR;
.LBB0_440:
	s_add_i32 s34, s34, 2
	s_add_u32 s16, s12, s14
	ds_read_b128 v[150:153], v141
	ds_read_b128 v[154:157], v141 offset:1024
	ds_read_b128 v[160:163], v141 offset:2048
	ds_read_b128 v[168:171], v141 offset:3072
	s_addc_u32 s17, s13, s15
	s_add_u32 s16, s16, 0x14500100
	s_addc_u32 s17, s17, 0
	s_add_u32 s46, s26, s14
	s_addc_u32 s47, s27, s15
	s_cmpk_eq_i32 s14, 0xf00
	s_cselect_b32 s19, s1, s17
	s_cselect_b32 s18, s0, s16
	s_cselect_b32 s17, s3, s47
	s_cselect_b32 s16, s2, s46
	s_mov_b32 m0, s36
	v_lshl_add_u64 v[146:147], v[136:137], 0, s[14:15]
	ds_read_b128 v[172:175], v142
	ds_read_b128 v[176:179], v142 offset:1024
	ds_read_b128 v[180:183], v142 offset:2048
	ds_read_b128 v[184:187], v142 offset:3072
	ds_read_b128 v[188:191], v142 offset:4096
	ds_read_b128 v[196:199], v142 offset:5120
	ds_read_b128 v[202:205], v142 offset:6144
	ds_read_b128 v[206:209], v142 offset:7168
	global_load_lds_dwordx4 v[146:147], off
	v_lshl_add_u64 v[146:147], v[138:139], 0, s[14:15]
	s_mov_b32 m0, s37
	s_nop 0
	global_load_lds_dwordx4 v[146:147], off
	s_waitcnt lgkmcnt(8)
	s_barrier
	s_waitcnt lgkmcnt(0)
	s_setprio 1
	s_waitcnt lgkmcnt(0)
	v_mfma_f32_16x16x32_bf16 v[124:127], v[150:153], v[172:175], v[124:127]
	v_mfma_f32_16x16x32_bf16 v[120:123], v[160:163], v[172:175], v[120:123]
	v_mfma_f32_16x16x32_bf16 v[116:119], v[150:153], v[180:183], v[116:119]
	v_mfma_f32_16x16x32_bf16 v[112:115], v[160:163], v[180:183], v[112:115]
	v_mfma_f32_16x16x32_bf16 v[100:103], v[150:153], v[188:191], v[100:103]
	v_mfma_f32_16x16x32_bf16 v[92:95], v[160:163], v[188:191], v[92:95]
	v_mfma_f32_16x16x32_bf16 v[84:87], v[150:153], v[202:205], v[84:87]
	v_mfma_f32_16x16x32_bf16 v[76:79], v[160:163], v[202:205], v[76:79]
	v_mfma_f32_16x16x32_bf16 v[124:127], v[154:157], v[176:179], v[124:127]
	v_mfma_f32_16x16x32_bf16 v[120:123], v[168:171], v[176:179], v[120:123]
	v_mfma_f32_16x16x32_bf16 v[116:119], v[154:157], v[184:187], v[116:119]
	v_mfma_f32_16x16x32_bf16 v[112:115], v[168:171], v[184:187], v[112:115]
	v_mfma_f32_16x16x32_bf16 v[100:103], v[154:157], v[196:199], v[100:103]
	v_mfma_f32_16x16x32_bf16 v[92:95], v[168:171], v[196:199], v[92:95]
	v_mfma_f32_16x16x32_bf16 v[84:87], v[154:157], v[206:209], v[84:87]
	v_mfma_f32_16x16x32_bf16 v[76:79], v[168:171], v[206:209], v[76:79]
	s_setprio 0
	s_barrier
	s_mov_b32 m0, s38
	s_add_u32 s98, s16, s10
	s_addc_u32 s99, s17, s11
	ds_read_b128 v[210:213], v143
	ds_read_b128 v[214:217], v143 offset:1024
	ds_read_b128 v[218:221], v143 offset:2048
	ds_read_b128 v[222:225], v143 offset:3072
	global_load_lds_dwordx4 v130, s[16:17]
	s_mov_b32 m0, s39
	s_nop 0
	global_load_lds_dwordx4 v134, s[16:17]
	s_barrier
	s_waitcnt lgkmcnt(0)
	s_setprio 1
	s_waitcnt lgkmcnt(0)
	v_mfma_f32_16x16x32_bf16 v[108:111], v[210:213], v[172:175], v[108:111]
	v_mfma_f32_16x16x32_bf16 v[104:107], v[218:221], v[172:175], v[104:107]
	v_mfma_f32_16x16x32_bf16 v[96:99], v[210:213], v[180:183], v[96:99]
	v_mfma_f32_16x16x32_bf16 v[88:91], v[218:221], v[180:183], v[88:91]
	v_mfma_f32_16x16x32_bf16 v[80:83], v[210:213], v[188:191], v[80:83]
	v_mfma_f32_16x16x32_bf16 v[72:75], v[218:221], v[188:191], v[72:75]
	v_mfma_f32_16x16x32_bf16 v[68:71], v[210:213], v[202:205], v[68:71]
	v_mfma_f32_16x16x32_bf16 v[64:67], v[218:221], v[202:205], v[64:67]
	v_mfma_f32_16x16x32_bf16 v[108:111], v[214:217], v[176:179], v[108:111]
	v_mfma_f32_16x16x32_bf16 v[104:107], v[222:225], v[176:179], v[104:107]
	v_mfma_f32_16x16x32_bf16 v[96:99], v[214:217], v[184:187], v[96:99]
	v_mfma_f32_16x16x32_bf16 v[88:91], v[222:225], v[184:187], v[88:91]
	v_mfma_f32_16x16x32_bf16 v[80:83], v[214:217], v[196:199], v[80:83]
	v_mfma_f32_16x16x32_bf16 v[72:75], v[222:225], v[196:199], v[72:75]
	v_mfma_f32_16x16x32_bf16 v[68:71], v[214:217], v[206:209], v[68:71]
	v_mfma_f32_16x16x32_bf16 v[64:67], v[222:225], v[206:209], v[64:67]
	s_setprio 0
	s_mov_b32 m0, s25
	s_add_u32 s100, s18, s10
	s_addc_u32 s101, s19, s11
	s_barrier
	ds_read_b128 v[172:175], v142 offset:16384
	ds_read_b128 v[176:179], v142 offset:17408
	ds_read_b128 v[180:183], v142 offset:18432
	ds_read_b128 v[184:187], v142 offset:19456
	ds_read_b128 v[188:191], v142 offset:20480
	ds_read_b128 v[196:199], v142 offset:21504
	ds_read_b128 v[202:205], v142 offset:22528
	ds_read_b128 v[206:209], v142 offset:23552
	global_load_lds_dwordx4 v128, s[18:19]
	s_mov_b32 m0, s28
	s_nop 0
	global_load_lds_dwordx4 v132, s[18:19]
	s_barrier
	s_waitcnt lgkmcnt(0)
	s_setprio 1
	s_waitcnt lgkmcnt(0)
	v_mfma_f32_16x16x32_bf16 v[60:63], v[150:153], v[172:175], v[60:63]
	v_mfma_f32_16x16x32_bf16 v[56:59], v[160:163], v[172:175], v[56:59]
	v_mfma_f32_16x16x32_bf16 v[52:55], v[150:153], v[180:183], v[52:55]
	v_mfma_f32_16x16x32_bf16 v[44:47], v[160:163], v[180:183], v[44:47]
	v_mfma_f32_16x16x32_bf16 v[36:39], v[150:153], v[188:191], v[36:39]
	v_mfma_f32_16x16x32_bf16 v[28:31], v[160:163], v[188:191], v[28:31]
	v_mfma_f32_16x16x32_bf16 v[20:23], v[150:153], v[202:205], v[20:23]
	v_mfma_f32_16x16x32_bf16 v[12:15], v[160:163], v[202:205], v[12:15]
	v_mfma_f32_16x16x32_bf16 v[60:63], v[154:157], v[176:179], v[60:63]
	v_mfma_f32_16x16x32_bf16 v[56:59], v[168:171], v[176:179], v[56:59]
	v_mfma_f32_16x16x32_bf16 v[52:55], v[154:157], v[184:187], v[52:55]
	v_mfma_f32_16x16x32_bf16 v[44:47], v[168:171], v[184:187], v[44:47]
	v_mfma_f32_16x16x32_bf16 v[36:39], v[154:157], v[196:199], v[36:39]
	v_mfma_f32_16x16x32_bf16 v[28:31], v[168:171], v[196:199], v[28:31]
	v_mfma_f32_16x16x32_bf16 v[20:23], v[154:157], v[206:209], v[20:23]
	v_mfma_f32_16x16x32_bf16 v[12:15], v[168:171], v[206:209], v[12:15]
	s_setprio 0
	s_barrier
; #define PG8_STAGE(bufoff, gbase, voff) do { _Pragma("unroll") for (int _i = 0; _i < 2; ++_i) \
;         __builtin_amdgcn_global_load_lds((const unsigned*)((const char*)(gbase) + (voff)[_i]), (LAS unsigned*)(lds + (bufoff) + ldsw + _i * 8192), 16, 0, 0); } while (0)
; #define PG8_LDA(dst, b, h) do { _Pragma("unroll") for (int m = 0; m < 4; ++m) _Pragma("unroll") for (int k = 0; k < 2; ++k) dst[m][k] = *(const LAS bf16x8*)(lds + PG8_SA(b, h) + aoff + m * 2048 + k * 1024); } while (0)
; #define PG8_LDB(dst, b, h) do { _Pragma("unroll") for (int n = 0; n < 2; ++n) _Pragma("unroll") for (int k = 0; k < 2; ++k) dst[n][k] = *(const LAS bf16x8*)(lds + PG8_SB(b, h) + boff + n * 2048 + k * 1024); } while (0)
; #define PG8_WAIT_V(n) asm volatile("s_waitcnt vmcnt(" #n ")" ::: "memory")
; #define PG8_WAIT_L(n) asm volatile("s_waitcnt lgkmcnt(" #n ")" ::: "memory")
; #define PG8_BAR __builtin_amdgcn_s_barrier()
; #define PG8_SCHED __builtin_amdgcn_sched_barrier(0)
; template <class Epi>
; __device__ __forceinline__ void gemm_phase(LAS unsigned char* lds, const bf16_t* A, int lda, const bf16_t* Bt, int ldb, int M, int N, int K, int asel, const Epi& E, const int fixed_round = -1) {
;     ...
;             PG8_WAIT_V(6); PG8_BAR; PG8_MMA(1, 1, At, B1); PG8_BAR;
;             PG8_LDB(B0, 1, 0); PG8_SCHED; PG8_LDA(At, 1, 0); PG8_STAGE(PG8_SA(0, 1), a2 + hstepA, voffA);
;             PG8_WAIT_L(8); PG8_BAR; PG8_WAIT_L(0); PG8_MMA(0, 0, At, B0); PG8_BAR; PG8_SCHED;
;             PG8_LDB(B1, 1, 1); PG8_STAGE(PG8_SB(1, 0), b3, voffB);
;             PG8_BAR; PG8_WAIT_L(0); PG8_MMA(0, 1, At, B1); PG8_BAR;
;             PG8_LDA(At, 1, 1); PG8_STAGE(PG8_SA(1, 0), a3, voffA);
;             PG8_BAR; PG8_WAIT_L(0); PG8_MMA(1, 0, At, B0); PG8_BAR; PG8_SCHED;
	s_add_u32 s46, s16, 0x80000
	s_addc_u32 s47, s17, 0
	s_mov_b32 m0, s40
	s_nop 0
	global_load_lds_dwordx4 v130, s[46:47]
	s_mov_b32 m0, s41
	s_nop 0
	global_load_lds_dwordx4 v134, s[46:47]
	s_waitcnt vmcnt(6)
	s_barrier
	s_setprio 1
	v_mfma_f32_16x16x32_bf16 v[48:51], v[210:213], v[172:175], v[48:51]
	v_mfma_f32_16x16x32_bf16 v[40:43], v[218:221], v[172:175], v[40:43]
	v_mfma_f32_16x16x32_bf16 v[32:35], v[210:213], v[180:183], v[32:35]
	v_mfma_f32_16x16x32_bf16 v[24:27], v[218:221], v[180:183], v[24:27]
	v_mfma_f32_16x16x32_bf16 v[16:19], v[210:213], v[188:191], v[16:19]
	v_mfma_f32_16x16x32_bf16 v[8:11], v[218:221], v[188:191], v[8:11]
	v_mfma_f32_16x16x32_bf16 v[4:7], v[210:213], v[202:205], v[4:7]
	v_mfma_f32_16x16x32_bf16 v[0:3], v[218:221], v[202:205], v[0:3]
	v_mfma_f32_16x16x32_bf16 v[48:51], v[214:217], v[176:179], v[48:51]
	v_mfma_f32_16x16x32_bf16 v[40:43], v[222:225], v[176:179], v[40:43]
	v_mfma_f32_16x16x32_bf16 v[32:35], v[214:217], v[184:187], v[32:35]
	v_mfma_f32_16x16x32_bf16 v[24:27], v[222:225], v[184:187], v[24:27]
	v_mfma_f32_16x16x32_bf16 v[16:19], v[214:217], v[196:199], v[16:19]
	v_mfma_f32_16x16x32_bf16 v[8:11], v[222:225], v[196:199], v[8:11]
	v_mfma_f32_16x16x32_bf16 v[4:7], v[214:217], v[206:209], v[4:7]
	v_mfma_f32_16x16x32_bf16 v[0:3], v[222:225], v[206:209], v[0:3]
	s_setprio 0
	s_barrier
	ds_read_b128 v[150:153], v144
	ds_read_b128 v[154:157], v144 offset:1024
	ds_read_b128 v[160:163], v144 offset:2048
	ds_read_b128 v[168:171], v144 offset:3072
	s_add_u32 s18, s18, 0x80000
	s_addc_u32 s19, s19, 0
	s_mov_b32 m0, s29
	ds_read_b128 v[172:175], v142 offset:32768
	ds_read_b128 v[176:179], v142 offset:33792
	ds_read_b128 v[180:183], v142 offset:34816
	ds_read_b128 v[184:187], v142 offset:35840
	ds_read_b128 v[188:191], v142 offset:36864
	ds_read_b128 v[196:199], v142 offset:37888
	ds_read_b128 v[202:205], v142 offset:38912
	ds_read_b128 v[206:209], v142 offset:39936
	global_load_lds_dwordx4 v128, s[18:19]
	s_mov_b32 m0, s30
	s_nop 0
	global_load_lds_dwordx4 v132, s[18:19]
	s_waitcnt lgkmcnt(8)
	s_barrier
	s_waitcnt lgkmcnt(0)
	s_setprio 1
	s_waitcnt lgkmcnt(0)
	v_mfma_f32_16x16x32_bf16 v[124:127], v[150:153], v[172:175], v[124:127]
	v_mfma_f32_16x16x32_bf16 v[120:123], v[160:163], v[172:175], v[120:123]
	v_mfma_f32_16x16x32_bf16 v[116:119], v[150:153], v[180:183], v[116:119]
	v_mfma_f32_16x16x32_bf16 v[112:115], v[160:163], v[180:183], v[112:115]
	v_mfma_f32_16x16x32_bf16 v[100:103], v[150:153], v[188:191], v[100:103]
	v_mfma_f32_16x16x32_bf16 v[92:95], v[160:163], v[188:191], v[92:95]
	v_mfma_f32_16x16x32_bf16 v[84:87], v[150:153], v[202:205], v[84:87]
	v_mfma_f32_16x16x32_bf16 v[76:79], v[160:163], v[202:205], v[76:79]
	v_mfma_f32_16x16x32_bf16 v[124:127], v[154:157], v[176:179], v[124:127]
	v_mfma_f32_16x16x32_bf16 v[120:123], v[168:171], v[176:179], v[120:123]
	v_mfma_f32_16x16x32_bf16 v[116:119], v[154:157], v[184:187], v[116:119]
	v_mfma_f32_16x16x32_bf16 v[112:115], v[168:171], v[184:187], v[112:115]
	v_mfma_f32_16x16x32_bf16 v[100:103], v[154:157], v[196:199], v[100:103]
	v_mfma_f32_16x16x32_bf16 v[92:95], v[168:171], v[196:199], v[92:95]
	v_mfma_f32_16x16x32_bf16 v[84:87], v[154:157], v[206:209], v[84:87]
	v_mfma_f32_16x16x32_bf16 v[76:79], v[168:171], v[206:209], v[76:79]
	s_setprio 0
	s_barrier
	s_mov_b32 m0, s42
	ds_read_b128 v[210:213], v145
	ds_read_b128 v[214:217], v145 offset:1024
	ds_read_b128 v[218:221], v145 offset:2048
	ds_read_b128 v[222:225], v145 offset:3072
	global_load_lds_dwordx4 v130, s[98:99]
	s_mov_b32 m0, s43
	s_nop 0
	global_load_lds_dwordx4 v134, s[98:99]
	s_barrier
	s_waitcnt lgkmcnt(0)
	s_setprio 1
	s_waitcnt lgkmcnt(0)
	v_mfma_f32_16x16x32_bf16 v[108:111], v[210:213], v[172:175], v[108:111]
	v_mfma_f32_16x16x32_bf16 v[104:107], v[218:221], v[172:175], v[104:107]
	v_mfma_f32_16x16x32_bf16 v[96:99], v[210:213], v[180:183], v[96:99]
	v_mfma_f32_16x16x32_bf16 v[88:91], v[218:221], v[180:183], v[88:91]
	v_mfma_f32_16x16x32_bf16 v[80:83], v[210:213], v[188:191], v[80:83]
	v_mfma_f32_16x16x32_bf16 v[72:75], v[218:221], v[188:191], v[72:75]
	v_mfma_f32_16x16x32_bf16 v[68:71], v[210:213], v[202:205], v[68:71]
	v_mfma_f32_16x16x32_bf16 v[64:67], v[218:221], v[202:205], v[64:67]
	v_mfma_f32_16x16x32_bf16 v[108:111], v[214:217], v[176:179], v[108:111]
	v_mfma_f32_16x16x32_bf16 v[104:107], v[222:225], v[176:179], v[104:107]
	v_mfma_f32_16x16x32_bf16 v[96:99], v[214:217], v[184:187], v[96:99]
	v_mfma_f32_16x16x32_bf16 v[88:91], v[222:225], v[184:187], v[88:91]
	v_mfma_f32_16x16x32_bf16 v[80:83], v[214:217], v[196:199], v[80:83]
	v_mfma_f32_16x16x32_bf16 v[72:75], v[222:225], v[196:199], v[72:75]
	v_mfma_f32_16x16x32_bf16 v[68:71], v[214:217], v[206:209], v[68:71]
	v_mfma_f32_16x16x32_bf16 v[64:67], v[222:225], v[206:209], v[64:67]
	s_setprio 0
	s_mov_b32 m0, s31
	s_barrier
	ds_read_b128 v[172:175], v142 offset:49152
	ds_read_b128 v[176:179], v142 offset:50176
	ds_read_b128 v[180:183], v142 offset:51200
	ds_read_b128 v[184:187], v142 offset:52224
	ds_read_b128 v[188:191], v142 offset:53248
	ds_read_b128 v[196:199], v142 offset:54272
	ds_read_b128 v[202:205], v142 offset:55296
	ds_read_b128 v[206:209], v142 offset:56320
	global_load_lds_dwordx4 v128, s[100:101]
	s_mov_b32 m0, s33
	s_nop 0
	global_load_lds_dwordx4 v132, s[100:101]
	s_barrier
; #define LAS __attribute__((address_space(3)))
; #define PG8_STAGE(bufoff, gbase, voff) do { _Pragma("unroll") for (int _i = 0; _i < 2; ++_i) \
;         __builtin_amdgcn_global_load_lds((const unsigned*)((const char*)(gbase) + (voff)[_i]), (LAS unsigned*)(lds + (bufoff) + ldsw + _i * 8192), 16, 0, 0); } while (0)
; #define PG8_WAIT_V(n) asm volatile("s_waitcnt vmcnt(" #n ")" ::: "memory")
; #define PG8_BAR __builtin_amdgcn_s_barrier()
; template <class Epi>
; __device__ __forceinline__ void gemm_phase(LAS unsigned char* lds, const bf16_t* A, int lda, const bf16_t* Bt, int ldb, int M, int N, int K, int asel, const Epi& E, const int fixed_round = -1) {
;     ...
;             PG8_STAGE(PG8_SB(1, 1), b3 + hstepB, voffB);
;             PG8_WAIT_V(6); PG8_BAR; PG8_MMA(1, 1, At, B1); PG8_BAR;
;             if constexpr (Epi::HEADSCALE) {
;                 if (t & 2) {
;                     const LAS float* rt = (const LAS float*)(lds + L_RT) + (t >> 2);
; #pragma unroll
;                     for (int ai = 0; ai < 2; ++ai)
; #pragma unroll
;                         for (int m = 0; m < 4; ++m) { const float f = rt[(ai * HALF + wr * 64 + m * 16 + fr) * 8];
; #pragma unroll
;                             for (int bj = 0; bj < 2; ++bj)
; #pragma unroll
;                                 for (int n = 0; n < 2; ++n) acc[ai][bj][m][n] *= f; }
;                 }
	s_waitcnt lgkmcnt(0)
	s_setprio 1
	s_waitcnt lgkmcnt(0)
	v_mfma_f32_16x16x32_bf16 v[60:63], v[150:153], v[172:175], v[60:63]
	v_mfma_f32_16x16x32_bf16 v[56:59], v[160:163], v[172:175], v[56:59]
	v_mfma_f32_16x16x32_bf16 v[52:55], v[150:153], v[180:183], v[52:55]
	v_mfma_f32_16x16x32_bf16 v[44:47], v[160:163], v[180:183], v[44:47]
	v_mfma_f32_16x16x32_bf16 v[36:39], v[150:153], v[188:191], v[36:39]
	v_mfma_f32_16x16x32_bf16 v[28:31], v[160:163], v[188:191], v[28:31]
	v_mfma_f32_16x16x32_bf16 v[20:23], v[150:153], v[202:205], v[20:23]
	v_mfma_f32_16x16x32_bf16 v[12:15], v[160:163], v[202:205], v[12:15]
	v_mfma_f32_16x16x32_bf16 v[60:63], v[154:157], v[176:179], v[60:63]
	v_mfma_f32_16x16x32_bf16 v[56:59], v[168:171], v[176:179], v[56:59]
	v_mfma_f32_16x16x32_bf16 v[52:55], v[154:157], v[184:187], v[52:55]
	v_mfma_f32_16x16x32_bf16 v[44:47], v[168:171], v[184:187], v[44:47]
	v_mfma_f32_16x16x32_bf16 v[36:39], v[154:157], v[196:199], v[36:39]
	v_mfma_f32_16x16x32_bf16 v[28:31], v[168:171], v[196:199], v[28:31]
	v_mfma_f32_16x16x32_bf16 v[20:23], v[154:157], v[206:209], v[20:23]
	v_mfma_f32_16x16x32_bf16 v[12:15], v[168:171], v[206:209], v[12:15]
	s_setprio 0
	s_barrier
	s_add_u32 s16, s16, 0x80080
	s_addc_u32 s17, s17, 0
	s_mov_b32 m0, s44
	s_nop 0
	global_load_lds_dwordx4 v130, s[16:17]
	s_mov_b32 m0, s45
	s_nop 0
	global_load_lds_dwordx4 v134, s[16:17]
	s_waitcnt vmcnt(6)
	s_barrier
	s_setprio 1
	v_mfma_f32_16x16x32_bf16 v[48:51], v[210:213], v[172:175], v[48:51]
	v_mfma_f32_16x16x32_bf16 v[40:43], v[218:221], v[172:175], v[40:43]
	v_mfma_f32_16x16x32_bf16 v[32:35], v[210:213], v[180:183], v[32:35]
	v_mfma_f32_16x16x32_bf16 v[24:27], v[218:221], v[180:183], v[24:27]
	v_mfma_f32_16x16x32_bf16 v[16:19], v[210:213], v[188:191], v[16:19]
	v_mfma_f32_16x16x32_bf16 v[8:11], v[218:221], v[188:191], v[8:11]
	v_mfma_f32_16x16x32_bf16 v[4:7], v[210:213], v[202:205], v[4:7]
	v_mfma_f32_16x16x32_bf16 v[0:3], v[218:221], v[202:205], v[0:3]
	v_mfma_f32_16x16x32_bf16 v[48:51], v[214:217], v[176:179], v[48:51]
	v_mfma_f32_16x16x32_bf16 v[40:43], v[222:225], v[176:179], v[40:43]
	v_mfma_f32_16x16x32_bf16 v[32:35], v[214:217], v[184:187], v[32:35]
	v_mfma_f32_16x16x32_bf16 v[24:27], v[222:225], v[184:187], v[24:27]
	v_mfma_f32_16x16x32_bf16 v[16:19], v[214:217], v[196:199], v[16:19]
	v_mfma_f32_16x16x32_bf16 v[8:11], v[222:225], v[196:199], v[8:11]
	v_mfma_f32_16x16x32_bf16 v[4:7], v[214:217], v[206:209], v[4:7]
	v_mfma_f32_16x16x32_bf16 v[0:3], v[222:225], v[206:209], v[0:3]
	s_setprio 0
	s_bitcmp0_b32 s34, 1
	s_barrier
	s_cbranch_scc1 .LBB0_439
	s_and_b32 s16, s34, -4
	v_add_u32_e32 v148, s16, v140
	ds_read2st64_b32 v[146:147], v148 offset1:2
	ds_read2st64_b32 v[150:151], v148 offset0:4 offset1:6
	s_waitcnt lgkmcnt(0)
	v_pk_mul_f32 v[126:127], v[126:127], v[146:147] op_sel_hi:[1,0]
	v_pk_mul_f32 v[124:125], v[124:125], v[146:147] op_sel_hi:[1,0]
	v_pk_mul_f32 v[122:123], v[122:123], v[146:147] op_sel_hi:[1,0]
	v_pk_mul_f32 v[120:121], v[120:121], v[146:147] op_sel_hi:[1,0]
	v_pk_mul_f32 v[110:111], v[110:111], v[146:147] op_sel_hi:[1,0]
	v_pk_mul_f32 v[108:109], v[108:109], v[146:147] op_sel_hi:[1,0]
	v_pk_mul_f32 v[106:107], v[106:107], v[146:147] op_sel_hi:[1,0]
	v_pk_mul_f32 v[104:105], v[104:105], v[146:147] op_sel_hi:[1,0]
	v_mov_b32_e32 v146, v147
	v_pk_mul_f32 v[118:119], v[118:119], v[146:147] op_sel_hi:[1,0]
	v_pk_mul_f32 v[116:117], v[116:117], v[146:147] op_sel_hi:[1,0]
	v_pk_mul_f32 v[114:115], v[114:115], v[146:147] op_sel_hi:[1,0]
	v_pk_mul_f32 v[112:113], v[112:113], v[146:147] op_sel_hi:[1,0]
	v_pk_mul_f32 v[98:99], v[98:99], v[146:147] op_sel_hi:[1,0]
	v_pk_mul_f32 v[96:97], v[96:97], v[146:147] op_sel_hi:[1,0]
	v_pk_mul_f32 v[90:91], v[90:91], v[146:147] op_sel_hi:[1,0]
	v_pk_mul_f32 v[88:89], v[88:89], v[146:147] op_sel_hi:[1,0]
	v_pk_mul_f32 v[102:103], v[102:103], v[150:151] op_sel_hi:[1,0]
	v_pk_mul_f32 v[100:101], v[100:101], v[150:151] op_sel_hi:[1,0]
	v_pk_mul_f32 v[94:95], v[94:95], v[150:151] op_sel_hi:[1,0]
	v_pk_mul_f32 v[92:93], v[92:93], v[150:151] op_sel_hi:[1,0]
	v_pk_mul_f32 v[82:83], v[82:83], v[150:151] op_sel_hi:[1,0]
	v_pk_mul_f32 v[80:81], v[80:81], v[150:151] op_sel_hi:[1,0]
	v_pk_mul_f32 v[74:75], v[74:75], v[150:151] op_sel_hi:[1,0]
	v_pk_mul_f32 v[72:73], v[72:73], v[150:151] op_sel_hi:[1,0]
	v_mov_b32_e32 v146, v151
	ds_read2st64_b32 v[150:151], v148 offset0:16 offset1:18
	v_pk_mul_f32 v[86:87], v[86:87], v[146:147] op_sel_hi:[1,0]
	v_pk_mul_f32 v[84:85], v[84:85], v[146:147] op_sel_hi:[1,0]
	v_pk_mul_f32 v[78:79], v[78:79], v[146:147] op_sel_hi:[1,0]
	v_pk_mul_f32 v[76:77], v[76:77], v[146:147] op_sel_hi:[1,0]
	v_pk_mul_f32 v[70:71], v[70:71], v[146:147] op_sel_hi:[1,0]
	v_pk_mul_f32 v[68:69], v[68:69], v[146:147] op_sel_hi:[1,0]
	v_pk_mul_f32 v[66:67], v[66:67], v[146:147] op_sel_hi:[1,0]
	v_pk_mul_f32 v[64:65], v[64:65], v[146:147] op_sel_hi:[1,0]
	s_waitcnt lgkmcnt(0)
	v_pk_mul_f32 v[62:63], v[62:63], v[150:151] op_sel_hi:[1,0]
	v_pk_mul_f32 v[60:61], v[60:61], v[150:151] op_sel_hi:[1,0]
	v_pk_mul_f32 v[58:59], v[58:59], v[150:151] op_sel_hi:[1,0]
	v_pk_mul_f32 v[56:57], v[56:57], v[150:151] op_sel_hi:[1,0]
	v_pk_mul_f32 v[50:51], v[50:51], v[150:151] op_sel_hi:[1,0]
	v_pk_mul_f32 v[48:49], v[48:49], v[150:151] op_sel_hi:[1,0]
	v_pk_mul_f32 v[42:43], v[42:43], v[150:151] op_sel_hi:[1,0]
	v_pk_mul_f32 v[40:41], v[40:41], v[150:151] op_sel_hi:[1,0]
	v_mov_b32_e32 v146, v151
	ds_read2st64_b32 v[150:151], v148 offset0:20 offset1:22
	v_pk_mul_f32 v[54:55], v[54:55], v[146:147] op_sel_hi:[1,0]
	v_pk_mul_f32 v[52:53], v[52:53], v[146:147] op_sel_hi:[1,0]
	v_pk_mul_f32 v[46:47], v[46:47], v[146:147] op_sel_hi:[1,0]
	v_pk_mul_f32 v[44:45], v[44:45], v[146:147] op_sel_hi:[1,0]
	v_pk_mul_f32 v[34:35], v[34:35], v[146:147] op_sel_hi:[1,0]
	v_pk_mul_f32 v[32:33], v[32:33], v[146:147] op_sel_hi:[1,0]
	v_pk_mul_f32 v[26:27], v[26:27], v[146:147] op_sel_hi:[1,0]
	v_pk_mul_f32 v[24:25], v[24:25], v[146:147] op_sel_hi:[1,0]
	s_waitcnt lgkmcnt(0)
	v_mov_b32_e32 v146, v151
	v_pk_mul_f32 v[38:39], v[38:39], v[150:151] op_sel_hi:[1,0]
	v_pk_mul_f32 v[36:37], v[36:37], v[150:151] op_sel_hi:[1,0]
	v_pk_mul_f32 v[30:31], v[30:31], v[150:151] op_sel_hi:[1,0]
	v_pk_mul_f32 v[28:29], v[28:29], v[150:151] op_sel_hi:[1,0]
	v_pk_mul_f32 v[18:19], v[18:19], v[150:151] op_sel_hi:[1,0]
	v_pk_mul_f32 v[16:17], v[16:17], v[150:151] op_sel_hi:[1,0]
	v_pk_mul_f32 v[10:11], v[10:11], v[150:151] op_sel_hi:[1,0]
	v_pk_mul_f32 v[8:9], v[8:9], v[150:151] op_sel_hi:[1,0]
	v_pk_mul_f32 v[22:23], v[22:23], v[146:147] op_sel_hi:[1,0]
	v_pk_mul_f32 v[20:21], v[20:21], v[146:147] op_sel_hi:[1,0]
	v_pk_mul_f32 v[14:15], v[14:15], v[146:147] op_sel_hi:[1,0]
	v_pk_mul_f32 v[12:13], v[12:13], v[146:147] op_sel_hi:[1,0]
	v_pk_mul_f32 v[6:7], v[6:7], v[146:147] op_sel_hi:[1,0]
	v_pk_mul_f32 v[4:5], v[4:5], v[146:147] op_sel_hi:[1,0]
	v_pk_mul_f32 v[2:3], v[2:3], v[146:147] op_sel_hi:[1,0]
	v_pk_mul_f32 v[0:1], v[0:1], v[146:147] op_sel_hi:[1,0]
	s_branch .LBB0_439

; #define PG8_STAGE(bufoff, gbase, voff) do { _Pragma("unroll") for (int _i = 0; _i < 2; ++_i) \
;         __builtin_amdgcn_global_load_lds((const unsigned*)((const char*)(gbase) + (voff)[_i]), (LAS unsigned*)(lds + (bufoff) + ldsw + _i * 8192), 16, 0, 0); } while (0)
; #define PG8_LDA(dst, b, h) do { _Pragma("unroll") for (int m = 0; m < 4; ++m) _Pragma("unroll") for (int k = 0; k < 2; ++k) dst[m][k] = *(const LAS bf16x8*)(lds + PG8_SA(b, h) + aoff + m * 2048 + k * 1024); } while (0)
; #define PG8_LDB(dst, b, h) do { _Pragma("unroll") for (int n = 0; n < 2; ++n) _Pragma("unroll") for (int k = 0; k < 2; ++k) dst[n][k] = *(const LAS bf16x8*)(lds + PG8_SB(b, h) + boff + n * 2048 + k * 1024); } while (0)
; #define PG8_WAIT_V(n) asm volatile("s_waitcnt vmcnt(" #n ")" ::: "memory")
; #define PG8_WAIT_L(n) asm volatile("s_waitcnt lgkmcnt(" #n ")" ::: "memory")
; #define PG8_BAR __builtin_amdgcn_s_barrier()
; #define PG8_SCHED __builtin_amdgcn_sched_barrier(0)
; template <class Epi>
; __device__ __forceinline__ void gemm_phase(LAS unsigned char* lds, const bf16_t* A, int lda, const bf16_t* Bt, int ldb, int M, int N, int K, int asel, const Epi& E, const int fixed_round = -1) {
;     ...
;         for (int t = 0; t < nt; t += 2) {
;             const bool last = (t == nt - 2);
;             const char* a1 = cA + (size_t)(t + 1) * kstep;
;             const char* a2 = last ? nA : cA + (size_t)(t + 2) * kstep; const char* b2 = last ? nB : cB + (size_t)(t + 2) * kstep;
;             const char* a3 = a2 + kstep; const char* b3 = b2 + kstep;
;             PG8_LDB(B0, 0, 0); PG8_SCHED; PG8_LDA(At, 0, 0); PG8_STAGE(PG8_SA(1, 1), a1 + hstepA, voffA);
;             PG8_WAIT_L(8); PG8_BAR; PG8_WAIT_L(0); PG8_MMA(0, 0, At, B0); PG8_BAR; PG8_SCHED;
;             PG8_LDB(B1, 0, 1); PG8_STAGE(PG8_SB(0, 0), b2, voffB);
;             PG8_BAR; PG8_WAIT_L(0); PG8_MMA(0, 1, At, B1); PG8_BAR;
;             PG8_LDA(At, 0, 1); PG8_STAGE(PG8_SA(0, 0), a2, voffA);
;             PG8_BAR; PG8_WAIT_L(0); PG8_MMA(1, 0, At, B0); PG8_BAR; PG8_SCHED;
;             PG8_STAGE(PG8_SB(0, 1), b2 + hstepB, voffB);
;             PG8_WAIT_V(6); PG8_BAR; PG8_MMA(1, 1, At, B1); PG8_BAR;
.LBB0_487:
	s_add_i32 s35, s35, 2
	s_add_u32 s18, s6, s14
	ds_read_b128 v[150:153], v141
	ds_read_b128 v[154:157], v141 offset:1024
	ds_read_b128 v[160:163], v141 offset:2048
	ds_read_b128 v[168:171], v141 offset:3072
	s_addc_u32 s19, s7, s15
	s_add_u32 s18, s18, 0x14500100
	s_addc_u32 s19, s19, 0
	s_add_u32 s59, s26, s14
	s_addc_u32 s60, s27, s15
	s_cmpk_eq_i32 s14, 0xf00
	s_cselect_b32 s21, s1, s19
	s_cselect_b32 s20, s0, s18
	s_cselect_b32 s19, s3, s60
	s_cselect_b32 s18, s2, s59
	s_mov_b32 m0, s49
	v_lshl_add_u64 v[146:147], v[136:137], 0, s[14:15]
	ds_read_b128 v[172:175], v142
	ds_read_b128 v[176:179], v142 offset:1024
	ds_read_b128 v[180:183], v142 offset:2048
	ds_read_b128 v[184:187], v142 offset:3072
	ds_read_b128 v[188:191], v142 offset:4096
	ds_read_b128 v[192:195], v142 offset:5120
	ds_read_b128 v[196:199], v142 offset:6144
	ds_read_b128 v[202:205], v142 offset:7168
	global_load_lds_dwordx4 v[146:147], off
	v_lshl_add_u64 v[146:147], v[138:139], 0, s[14:15]
	s_mov_b32 m0, s50
	s_nop 0
	global_load_lds_dwordx4 v[146:147], off
	s_waitcnt lgkmcnt(8)
	s_barrier
	s_waitcnt lgkmcnt(0)
	s_setprio 1
	s_waitcnt lgkmcnt(0)
	v_mfma_f32_16x16x32_bf16 v[124:127], v[150:153], v[172:175], v[124:127]
	v_mfma_f32_16x16x32_bf16 v[120:123], v[160:163], v[172:175], v[120:123]
	v_mfma_f32_16x16x32_bf16 v[116:119], v[150:153], v[180:183], v[116:119]
	v_mfma_f32_16x16x32_bf16 v[112:115], v[160:163], v[180:183], v[112:115]
	v_mfma_f32_16x16x32_bf16 v[100:103], v[150:153], v[188:191], v[100:103]
	v_mfma_f32_16x16x32_bf16 v[92:95], v[160:163], v[188:191], v[92:95]
	v_mfma_f32_16x16x32_bf16 v[84:87], v[150:153], v[196:199], v[84:87]
	v_mfma_f32_16x16x32_bf16 v[76:79], v[160:163], v[196:199], v[76:79]
	v_mfma_f32_16x16x32_bf16 v[124:127], v[154:157], v[176:179], v[124:127]
	v_mfma_f32_16x16x32_bf16 v[120:123], v[168:171], v[176:179], v[120:123]
	v_mfma_f32_16x16x32_bf16 v[116:119], v[154:157], v[184:187], v[116:119]
	v_mfma_f32_16x16x32_bf16 v[112:115], v[168:171], v[184:187], v[112:115]
	v_mfma_f32_16x16x32_bf16 v[100:103], v[154:157], v[192:195], v[100:103]
	v_mfma_f32_16x16x32_bf16 v[92:95], v[168:171], v[192:195], v[92:95]
	v_mfma_f32_16x16x32_bf16 v[84:87], v[154:157], v[202:205], v[84:87]
	v_mfma_f32_16x16x32_bf16 v[76:79], v[168:171], v[202:205], v[76:79]
	s_setprio 0
	s_barrier
	s_mov_b32 m0, s51
	s_add_u32 s98, s18, s4
	s_addc_u32 s99, s19, s5
	ds_read_b128 v[206:209], v143
	ds_read_b128 v[210:213], v143 offset:1024
	ds_read_b128 v[214:217], v143 offset:2048
	ds_read_b128 v[218:221], v143 offset:3072
	global_load_lds_dwordx4 v130, s[18:19]
	s_mov_b32 m0, s52
	s_nop 0
	global_load_lds_dwordx4 v134, s[18:19]
	s_barrier
	s_waitcnt lgkmcnt(0)
	s_setprio 1
	s_waitcnt lgkmcnt(0)
	v_mfma_f32_16x16x32_bf16 v[108:111], v[206:209], v[172:175], v[108:111]
	v_mfma_f32_16x16x32_bf16 v[104:107], v[214:217], v[172:175], v[104:107]
	v_mfma_f32_16x16x32_bf16 v[96:99], v[206:209], v[180:183], v[96:99]
	v_mfma_f32_16x16x32_bf16 v[88:91], v[214:217], v[180:183], v[88:91]
	v_mfma_f32_16x16x32_bf16 v[80:83], v[206:209], v[188:191], v[80:83]
	v_mfma_f32_16x16x32_bf16 v[72:75], v[214:217], v[188:191], v[72:75]
	v_mfma_f32_16x16x32_bf16 v[68:71], v[206:209], v[196:199], v[68:71]
	v_mfma_f32_16x16x32_bf16 v[64:67], v[214:217], v[196:199], v[64:67]
	v_mfma_f32_16x16x32_bf16 v[108:111], v[210:213], v[176:179], v[108:111]
	v_mfma_f32_16x16x32_bf16 v[104:107], v[218:221], v[176:179], v[104:107]
	v_mfma_f32_16x16x32_bf16 v[96:99], v[210:213], v[184:187], v[96:99]
	v_mfma_f32_16x16x32_bf16 v[88:91], v[218:221], v[184:187], v[88:91]
	v_mfma_f32_16x16x32_bf16 v[80:83], v[210:213], v[192:195], v[80:83]
	v_mfma_f32_16x16x32_bf16 v[72:75], v[218:221], v[192:195], v[72:75]
	v_mfma_f32_16x16x32_bf16 v[68:71], v[210:213], v[202:205], v[68:71]
	v_mfma_f32_16x16x32_bf16 v[64:67], v[218:221], v[202:205], v[64:67]
	s_setprio 0
	s_mov_b32 m0, s43
	s_add_u32 s100, s20, s4
	s_addc_u32 s101, s21, s5
	s_barrier
	ds_read_b128 v[172:175], v142 offset:16384
	ds_read_b128 v[176:179], v142 offset:17408
	ds_read_b128 v[180:183], v142 offset:18432
	ds_read_b128 v[184:187], v142 offset:19456
	ds_read_b128 v[188:191], v142 offset:20480
	ds_read_b128 v[192:195], v142 offset:21504
	ds_read_b128 v[196:199], v142 offset:22528
	ds_read_b128 v[202:205], v142 offset:23552
	global_load_lds_dwordx4 v128, s[20:21]
	s_mov_b32 m0, s44
	s_nop 0
	global_load_lds_dwordx4 v132, s[20:21]
	s_barrier
	s_waitcnt lgkmcnt(0)
	s_setprio 1
	s_waitcnt lgkmcnt(0)
	v_mfma_f32_16x16x32_bf16 v[60:63], v[150:153], v[172:175], v[60:63]
	v_mfma_f32_16x16x32_bf16 v[56:59], v[160:163], v[172:175], v[56:59]
	v_mfma_f32_16x16x32_bf16 v[52:55], v[150:153], v[180:183], v[52:55]
	v_mfma_f32_16x16x32_bf16 v[44:47], v[160:163], v[180:183], v[44:47]
	v_mfma_f32_16x16x32_bf16 v[36:39], v[150:153], v[188:191], v[36:39]
	v_mfma_f32_16x16x32_bf16 v[28:31], v[160:163], v[188:191], v[28:31]
	v_mfma_f32_16x16x32_bf16 v[20:23], v[150:153], v[196:199], v[20:23]
	v_mfma_f32_16x16x32_bf16 v[12:15], v[160:163], v[196:199], v[12:15]
	v_mfma_f32_16x16x32_bf16 v[60:63], v[154:157], v[176:179], v[60:63]
	v_mfma_f32_16x16x32_bf16 v[56:59], v[168:171], v[176:179], v[56:59]
	v_mfma_f32_16x16x32_bf16 v[52:55], v[154:157], v[184:187], v[52:55]
	v_mfma_f32_16x16x32_bf16 v[44:47], v[168:171], v[184:187], v[44:47]
	v_mfma_f32_16x16x32_bf16 v[36:39], v[154:157], v[192:195], v[36:39]
	v_mfma_f32_16x16x32_bf16 v[28:31], v[168:171], v[192:195], v[28:31]
	v_mfma_f32_16x16x32_bf16 v[20:23], v[154:157], v[202:205], v[20:23]
	v_mfma_f32_16x16x32_bf16 v[12:15], v[168:171], v[202:205], v[12:15]
	s_setprio 0
	s_barrier
; #define PG8_STAGE(bufoff, gbase, voff) do { _Pragma("unroll") for (int _i = 0; _i < 2; ++_i) \
;         __builtin_amdgcn_global_load_lds((const unsigned*)((const char*)(gbase) + (voff)[_i]), (LAS unsigned*)(lds + (bufoff) + ldsw + _i * 8192), 16, 0, 0); } while (0)
; #define PG8_LDA(dst, b, h) do { _Pragma("unroll") for (int m = 0; m < 4; ++m) _Pragma("unroll") for (int k = 0; k < 2; ++k) dst[m][k] = *(const LAS bf16x8*)(lds + PG8_SA(b, h) + aoff + m * 2048 + k * 1024); } while (0)
; #define PG8_LDB(dst, b, h) do { _Pragma("unroll") for (int n = 0; n < 2; ++n) _Pragma("unroll") for (int k = 0; k < 2; ++k) dst[n][k] = *(const LAS bf16x8*)(lds + PG8_SB(b, h) + boff + n * 2048 + k * 1024); } while (0)
; #define PG8_WAIT_V(n) asm volatile("s_waitcnt vmcnt(" #n ")" ::: "memory")
; #define PG8_WAIT_L(n) asm volatile("s_waitcnt lgkmcnt(" #n ")" ::: "memory")
; #define PG8_BAR __builtin_amdgcn_s_barrier()
; #define PG8_SCHED __builtin_amdgcn_sched_barrier(0)
; template <class Epi>
; __device__ __forceinline__ void gemm_phase(LAS unsigned char* lds, const bf16_t* A, int lda, const bf16_t* Bt, int ldb, int M, int N, int K, int asel, const Epi& E, const int fixed_round = -1) {
;     ...
;             PG8_WAIT_V(6); PG8_BAR; PG8_MMA(1, 1, At, B1); PG8_BAR;
;             PG8_LDB(B0, 1, 0); PG8_SCHED; PG8_LDA(At, 1, 0); PG8_STAGE(PG8_SA(0, 1), a2 + hstepA, voffA);
;             PG8_WAIT_L(8); PG8_BAR; PG8_WAIT_L(0); PG8_MMA(0, 0, At, B0); PG8_BAR; PG8_SCHED;
;             PG8_LDB(B1, 1, 1); PG8_STAGE(PG8_SB(1, 0), b3, voffB);
;             PG8_BAR; PG8_WAIT_L(0); PG8_MMA(0, 1, At, B1); PG8_BAR;
;             PG8_LDA(At, 1, 1); PG8_STAGE(PG8_SA(1, 0), a3, voffA);
;             PG8_BAR; PG8_WAIT_L(0); PG8_MMA(1, 0, At, B0); PG8_BAR; PG8_SCHED;
	s_add_u32 s60, s18, 0x80000
	s_addc_u32 s61, s19, 0
	s_mov_b32 m0, s53
	s_nop 0
	global_load_lds_dwordx4 v130, s[60:61]
	s_mov_b32 m0, s54
	s_nop 0
	global_load_lds_dwordx4 v134, s[60:61]
	s_waitcnt vmcnt(6)
	s_barrier
	s_setprio 1
	v_mfma_f32_16x16x32_bf16 v[48:51], v[206:209], v[172:175], v[48:51]
	v_mfma_f32_16x16x32_bf16 v[40:43], v[214:217], v[172:175], v[40:43]
	v_mfma_f32_16x16x32_bf16 v[32:35], v[206:209], v[180:183], v[32:35]
	v_mfma_f32_16x16x32_bf16 v[24:27], v[214:217], v[180:183], v[24:27]
	v_mfma_f32_16x16x32_bf16 v[16:19], v[206:209], v[188:191], v[16:19]
	v_mfma_f32_16x16x32_bf16 v[8:11], v[214:217], v[188:191], v[8:11]
	v_mfma_f32_16x16x32_bf16 v[4:7], v[206:209], v[196:199], v[4:7]
	v_mfma_f32_16x16x32_bf16 v[0:3], v[214:217], v[196:199], v[0:3]
	v_mfma_f32_16x16x32_bf16 v[48:51], v[210:213], v[176:179], v[48:51]
	v_mfma_f32_16x16x32_bf16 v[40:43], v[218:221], v[176:179], v[40:43]
	v_mfma_f32_16x16x32_bf16 v[32:35], v[210:213], v[184:187], v[32:35]
	v_mfma_f32_16x16x32_bf16 v[24:27], v[218:221], v[184:187], v[24:27]
	v_mfma_f32_16x16x32_bf16 v[16:19], v[210:213], v[192:195], v[16:19]
	v_mfma_f32_16x16x32_bf16 v[8:11], v[218:221], v[192:195], v[8:11]
	v_mfma_f32_16x16x32_bf16 v[4:7], v[210:213], v[202:205], v[4:7]
	v_mfma_f32_16x16x32_bf16 v[0:3], v[218:221], v[202:205], v[0:3]
	s_setprio 0
	s_barrier
	ds_read_b128 v[150:153], v144
	ds_read_b128 v[154:157], v144 offset:1024
	ds_read_b128 v[160:163], v144 offset:2048
	ds_read_b128 v[168:171], v144 offset:3072
	s_add_u32 s20, s20, 0x80000
	s_addc_u32 s21, s21, 0
	s_mov_b32 m0, s45
	ds_read_b128 v[172:175], v142 offset:32768
	ds_read_b128 v[176:179], v142 offset:33792
	ds_read_b128 v[180:183], v142 offset:34816
	ds_read_b128 v[184:187], v142 offset:35840
	ds_read_b128 v[188:191], v142 offset:36864
	ds_read_b128 v[192:195], v142 offset:37888
	ds_read_b128 v[196:199], v142 offset:38912
	ds_read_b128 v[202:205], v142 offset:39936
	global_load_lds_dwordx4 v128, s[20:21]
	s_mov_b32 m0, s46
	s_nop 0
	global_load_lds_dwordx4 v132, s[20:21]
	s_waitcnt lgkmcnt(8)
	s_barrier
	s_waitcnt lgkmcnt(0)
	s_setprio 1
	s_waitcnt lgkmcnt(0)
	v_mfma_f32_16x16x32_bf16 v[124:127], v[150:153], v[172:175], v[124:127]
	v_mfma_f32_16x16x32_bf16 v[120:123], v[160:163], v[172:175], v[120:123]
	v_mfma_f32_16x16x32_bf16 v[116:119], v[150:153], v[180:183], v[116:119]
	v_mfma_f32_16x16x32_bf16 v[112:115], v[160:163], v[180:183], v[112:115]
	v_mfma_f32_16x16x32_bf16 v[100:103], v[150:153], v[188:191], v[100:103]
	v_mfma_f32_16x16x32_bf16 v[92:95], v[160:163], v[188:191], v[92:95]
	v_mfma_f32_16x16x32_bf16 v[84:87], v[150:153], v[196:199], v[84:87]
	v_mfma_f32_16x16x32_bf16 v[76:79], v[160:163], v[196:199], v[76:79]
	v_mfma_f32_16x16x32_bf16 v[124:127], v[154:157], v[176:179], v[124:127]
	v_mfma_f32_16x16x32_bf16 v[120:123], v[168:171], v[176:179], v[120:123]
	v_mfma_f32_16x16x32_bf16 v[116:119], v[154:157], v[184:187], v[116:119]
	v_mfma_f32_16x16x32_bf16 v[112:115], v[168:171], v[184:187], v[112:115]
	v_mfma_f32_16x16x32_bf16 v[100:103], v[154:157], v[192:195], v[100:103]
	v_mfma_f32_16x16x32_bf16 v[92:95], v[168:171], v[192:195], v[92:95]
	v_mfma_f32_16x16x32_bf16 v[84:87], v[154:157], v[202:205], v[84:87]
	v_mfma_f32_16x16x32_bf16 v[76:79], v[168:171], v[202:205], v[76:79]
	s_setprio 0
	s_barrier
	s_mov_b32 m0, s55
	ds_read_b128 v[206:209], v145
	ds_read_b128 v[210:213], v145 offset:1024
	ds_read_b128 v[214:217], v145 offset:2048
	ds_read_b128 v[218:221], v145 offset:3072
	global_load_lds_dwordx4 v130, s[98:99]
	s_mov_b32 m0, s56
	s_nop 0
	global_load_lds_dwordx4 v134, s[98:99]
	s_barrier
	s_waitcnt lgkmcnt(0)
	s_setprio 1
	s_waitcnt lgkmcnt(0)
	v_mfma_f32_16x16x32_bf16 v[108:111], v[206:209], v[172:175], v[108:111]
	v_mfma_f32_16x16x32_bf16 v[104:107], v[214:217], v[172:175], v[104:107]
	v_mfma_f32_16x16x32_bf16 v[96:99], v[206:209], v[180:183], v[96:99]
	v_mfma_f32_16x16x32_bf16 v[88:91], v[214:217], v[180:183], v[88:91]
	v_mfma_f32_16x16x32_bf16 v[80:83], v[206:209], v[188:191], v[80:83]
	v_mfma_f32_16x16x32_bf16 v[72:75], v[214:217], v[188:191], v[72:75]
	v_mfma_f32_16x16x32_bf16 v[68:71], v[206:209], v[196:199], v[68:71]
	v_mfma_f32_16x16x32_bf16 v[64:67], v[214:217], v[196:199], v[64:67]
	v_mfma_f32_16x16x32_bf16 v[108:111], v[210:213], v[176:179], v[108:111]
	v_mfma_f32_16x16x32_bf16 v[104:107], v[218:221], v[176:179], v[104:107]
	v_mfma_f32_16x16x32_bf16 v[96:99], v[210:213], v[184:187], v[96:99]
	v_mfma_f32_16x16x32_bf16 v[88:91], v[218:221], v[184:187], v[88:91]
	v_mfma_f32_16x16x32_bf16 v[80:83], v[210:213], v[192:195], v[80:83]
	v_mfma_f32_16x16x32_bf16 v[72:75], v[218:221], v[192:195], v[72:75]
	v_mfma_f32_16x16x32_bf16 v[68:71], v[210:213], v[202:205], v[68:71]
	v_mfma_f32_16x16x32_bf16 v[64:67], v[218:221], v[202:205], v[64:67]
	s_setprio 0
	s_mov_b32 m0, s47
	s_barrier
	ds_read_b128 v[172:175], v142 offset:49152
	ds_read_b128 v[176:179], v142 offset:50176
	ds_read_b128 v[180:183], v142 offset:51200
	ds_read_b128 v[184:187], v142 offset:52224
	ds_read_b128 v[188:191], v142 offset:53248
	ds_read_b128 v[192:195], v142 offset:54272
	ds_read_b128 v[196:199], v142 offset:55296
	ds_read_b128 v[202:205], v142 offset:56320
	global_load_lds_dwordx4 v128, s[100:101]
	s_mov_b32 m0, s48
	s_nop 0
	global_load_lds_dwordx4 v132, s[100:101]
	s_barrier
; #define LAS __attribute__((address_space(3)))
; #define PG8_STAGE(bufoff, gbase, voff) do { _Pragma("unroll") for (int _i = 0; _i < 2; ++_i) \
;         __builtin_amdgcn_global_load_lds((const unsigned*)((const char*)(gbase) + (voff)[_i]), (LAS unsigned*)(lds + (bufoff) + ldsw + _i * 8192), 16, 0, 0); } while (0)
; #define PG8_WAIT_V(n) asm volatile("s_waitcnt vmcnt(" #n ")" ::: "memory")
; #define PG8_BAR __builtin_amdgcn_s_barrier()
; template <class Epi>
; __device__ __forceinline__ void gemm_phase(LAS unsigned char* lds, const bf16_t* A, int lda, const bf16_t* Bt, int ldb, int M, int N, int K, int asel, const Epi& E, const int fixed_round = -1) {
;     ...
;             PG8_STAGE(PG8_SB(1, 1), b3 + hstepB, voffB);
;             PG8_WAIT_V(6); PG8_BAR; PG8_MMA(1, 1, At, B1); PG8_BAR;
;             if constexpr (Epi::HEADSCALE) {
;                 if (t & 2) {
;                     const LAS float* rt = (const LAS float*)(lds + L_RT) + (t >> 2);
; #pragma unroll
;                     for (int ai = 0; ai < 2; ++ai)
; #pragma unroll
;                         for (int m = 0; m < 4; ++m) { const float f = rt[(ai * HALF + wr * 64 + m * 16 + fr) * 8];
; #pragma unroll
;                             for (int bj = 0; bj < 2; ++bj)
; #pragma unroll
;                                 for (int n = 0; n < 2; ++n) acc[ai][bj][m][n] *= f; }
;                 }
	s_waitcnt lgkmcnt(0)
	s_setprio 1
	s_waitcnt lgkmcnt(0)
	v_mfma_f32_16x16x32_bf16 v[60:63], v[150:153], v[172:175], v[60:63]
	v_mfma_f32_16x16x32_bf16 v[56:59], v[160:163], v[172:175], v[56:59]
	v_mfma_f32_16x16x32_bf16 v[52:55], v[150:153], v[180:183], v[52:55]
	v_mfma_f32_16x16x32_bf16 v[44:47], v[160:163], v[180:183], v[44:47]
	v_mfma_f32_16x16x32_bf16 v[36:39], v[150:153], v[188:191], v[36:39]
	v_mfma_f32_16x16x32_bf16 v[28:31], v[160:163], v[188:191], v[28:31]
	v_mfma_f32_16x16x32_bf16 v[20:23], v[150:153], v[196:199], v[20:23]
	v_mfma_f32_16x16x32_bf16 v[12:15], v[160:163], v[196:199], v[12:15]
	v_mfma_f32_16x16x32_bf16 v[60:63], v[154:157], v[176:179], v[60:63]
	v_mfma_f32_16x16x32_bf16 v[56:59], v[168:171], v[176:179], v[56:59]
	v_mfma_f32_16x16x32_bf16 v[52:55], v[154:157], v[184:187], v[52:55]
	v_mfma_f32_16x16x32_bf16 v[44:47], v[168:171], v[184:187], v[44:47]
	v_mfma_f32_16x16x32_bf16 v[36:39], v[154:157], v[192:195], v[36:39]
	v_mfma_f32_16x16x32_bf16 v[28:31], v[168:171], v[192:195], v[28:31]
	v_mfma_f32_16x16x32_bf16 v[20:23], v[154:157], v[202:205], v[20:23]
	v_mfma_f32_16x16x32_bf16 v[12:15], v[168:171], v[202:205], v[12:15]
	s_setprio 0
	s_barrier
	s_add_u32 s18, s18, 0x80080
	s_addc_u32 s19, s19, 0
	s_mov_b32 m0, s57
	s_nop 0
	global_load_lds_dwordx4 v130, s[18:19]
	s_mov_b32 m0, s58
	s_nop 0
	global_load_lds_dwordx4 v134, s[18:19]
	s_waitcnt vmcnt(6)
	s_barrier
	s_setprio 1
	v_mfma_f32_16x16x32_bf16 v[48:51], v[206:209], v[172:175], v[48:51]
	v_mfma_f32_16x16x32_bf16 v[40:43], v[214:217], v[172:175], v[40:43]
	v_mfma_f32_16x16x32_bf16 v[32:35], v[206:209], v[180:183], v[32:35]
	v_mfma_f32_16x16x32_bf16 v[24:27], v[214:217], v[180:183], v[24:27]
	v_mfma_f32_16x16x32_bf16 v[16:19], v[206:209], v[188:191], v[16:19]
	v_mfma_f32_16x16x32_bf16 v[8:11], v[214:217], v[188:191], v[8:11]
	v_mfma_f32_16x16x32_bf16 v[4:7], v[206:209], v[196:199], v[4:7]
	v_mfma_f32_16x16x32_bf16 v[0:3], v[214:217], v[196:199], v[0:3]
	v_mfma_f32_16x16x32_bf16 v[48:51], v[210:213], v[176:179], v[48:51]
	v_mfma_f32_16x16x32_bf16 v[40:43], v[218:221], v[176:179], v[40:43]
	v_mfma_f32_16x16x32_bf16 v[32:35], v[210:213], v[184:187], v[32:35]
	v_mfma_f32_16x16x32_bf16 v[24:27], v[218:221], v[184:187], v[24:27]
	v_mfma_f32_16x16x32_bf16 v[16:19], v[210:213], v[192:195], v[16:19]
	v_mfma_f32_16x16x32_bf16 v[8:11], v[218:221], v[192:195], v[8:11]
	v_mfma_f32_16x16x32_bf16 v[4:7], v[210:213], v[202:205], v[4:7]
	v_mfma_f32_16x16x32_bf16 v[0:3], v[218:221], v[202:205], v[0:3]
	s_setprio 0
	s_bitcmp0_b32 s35, 1
	s_barrier
	s_cbranch_scc1 .LBB0_486
	s_and_b32 s18, s35, -4
	v_add_u32_e32 v148, s18, v140
	ds_read2st64_b32 v[146:147], v148 offset1:2
	ds_read2st64_b32 v[150:151], v148 offset0:4 offset1:6
	s_waitcnt lgkmcnt(0)
	v_pk_mul_f32 v[126:127], v[126:127], v[146:147] op_sel_hi:[1,0]
	v_pk_mul_f32 v[124:125], v[124:125], v[146:147] op_sel_hi:[1,0]
	v_pk_mul_f32 v[122:123], v[122:123], v[146:147] op_sel_hi:[1,0]
	v_pk_mul_f32 v[120:121], v[120:121], v[146:147] op_sel_hi:[1,0]
	v_pk_mul_f32 v[110:111], v[110:111], v[146:147] op_sel_hi:[1,0]
	v_pk_mul_f32 v[108:109], v[108:109], v[146:147] op_sel_hi:[1,0]
	v_pk_mul_f32 v[106:107], v[106:107], v[146:147] op_sel_hi:[1,0]
	v_pk_mul_f32 v[104:105], v[104:105], v[146:147] op_sel_hi:[1,0]
	v_mov_b32_e32 v146, v147
	v_pk_mul_f32 v[118:119], v[118:119], v[146:147] op_sel_hi:[1,0]
	v_pk_mul_f32 v[116:117], v[116:117], v[146:147] op_sel_hi:[1,0]
	v_pk_mul_f32 v[114:115], v[114:115], v[146:147] op_sel_hi:[1,0]
	v_pk_mul_f32 v[112:113], v[112:113], v[146:147] op_sel_hi:[1,0]
	v_pk_mul_f32 v[98:99], v[98:99], v[146:147] op_sel_hi:[1,0]
	v_pk_mul_f32 v[96:97], v[96:97], v[146:147] op_sel_hi:[1,0]
	v_pk_mul_f32 v[90:91], v[90:91], v[146:147] op_sel_hi:[1,0]
	v_pk_mul_f32 v[88:89], v[88:89], v[146:147] op_sel_hi:[1,0]
	v_pk_mul_f32 v[102:103], v[102:103], v[150:151] op_sel_hi:[1,0]
	v_pk_mul_f32 v[100:101], v[100:101], v[150:151] op_sel_hi:[1,0]
	v_pk_mul_f32 v[94:95], v[94:95], v[150:151] op_sel_hi:[1,0]
	v_pk_mul_f32 v[92:93], v[92:93], v[150:151] op_sel_hi:[1,0]
	v_pk_mul_f32 v[82:83], v[82:83], v[150:151] op_sel_hi:[1,0]
	v_pk_mul_f32 v[80:81], v[80:81], v[150:151] op_sel_hi:[1,0]
	v_pk_mul_f32 v[74:75], v[74:75], v[150:151] op_sel_hi:[1,0]
	v_pk_mul_f32 v[72:73], v[72:73], v[150:151] op_sel_hi:[1,0]
	v_mov_b32_e32 v146, v151
	ds_read2st64_b32 v[150:151], v148 offset0:16 offset1:18
	v_pk_mul_f32 v[86:87], v[86:87], v[146:147] op_sel_hi:[1,0]
	v_pk_mul_f32 v[84:85], v[84:85], v[146:147] op_sel_hi:[1,0]
	v_pk_mul_f32 v[78:79], v[78:79], v[146:147] op_sel_hi:[1,0]
	v_pk_mul_f32 v[76:77], v[76:77], v[146:147] op_sel_hi:[1,0]
	v_pk_mul_f32 v[70:71], v[70:71], v[146:147] op_sel_hi:[1,0]
	v_pk_mul_f32 v[68:69], v[68:69], v[146:147] op_sel_hi:[1,0]
	v_pk_mul_f32 v[66:67], v[66:67], v[146:147] op_sel_hi:[1,0]
	v_pk_mul_f32 v[64:65], v[64:65], v[146:147] op_sel_hi:[1,0]
	s_waitcnt lgkmcnt(0)
	v_pk_mul_f32 v[62:63], v[62:63], v[150:151] op_sel_hi:[1,0]
	v_pk_mul_f32 v[60:61], v[60:61], v[150:151] op_sel_hi:[1,0]
	v_pk_mul_f32 v[58:59], v[58:59], v[150:151] op_sel_hi:[1,0]
	v_pk_mul_f32 v[56:57], v[56:57], v[150:151] op_sel_hi:[1,0]
	v_pk_mul_f32 v[50:51], v[50:51], v[150:151] op_sel_hi:[1,0]
	v_pk_mul_f32 v[48:49], v[48:49], v[150:151] op_sel_hi:[1,0]
	v_pk_mul_f32 v[42:43], v[42:43], v[150:151] op_sel_hi:[1,0]
	v_pk_mul_f32 v[40:41], v[40:41], v[150:151] op_sel_hi:[1,0]
	v_mov_b32_e32 v146, v151
	ds_read2st64_b32 v[150:151], v148 offset0:20 offset1:22
	v_pk_mul_f32 v[54:55], v[54:55], v[146:147] op_sel_hi:[1,0]
	v_pk_mul_f32 v[52:53], v[52:53], v[146:147] op_sel_hi:[1,0]
	v_pk_mul_f32 v[46:47], v[46:47], v[146:147] op_sel_hi:[1,0]
	v_pk_mul_f32 v[44:45], v[44:45], v[146:147] op_sel_hi:[1,0]
	v_pk_mul_f32 v[34:35], v[34:35], v[146:147] op_sel_hi:[1,0]
	v_pk_mul_f32 v[32:33], v[32:33], v[146:147] op_sel_hi:[1,0]
	v_pk_mul_f32 v[26:27], v[26:27], v[146:147] op_sel_hi:[1,0]
	v_pk_mul_f32 v[24:25], v[24:25], v[146:147] op_sel_hi:[1,0]
	s_waitcnt lgkmcnt(0)
	v_mov_b32_e32 v146, v151
	v_pk_mul_f32 v[38:39], v[38:39], v[150:151] op_sel_hi:[1,0]
	v_pk_mul_f32 v[36:37], v[36:37], v[150:151] op_sel_hi:[1,0]
	v_pk_mul_f32 v[30:31], v[30:31], v[150:151] op_sel_hi:[1,0]
	v_pk_mul_f32 v[28:29], v[28:29], v[150:151] op_sel_hi:[1,0]
	v_pk_mul_f32 v[18:19], v[18:19], v[150:151] op_sel_hi:[1,0]
	v_pk_mul_f32 v[16:17], v[16:17], v[150:151] op_sel_hi:[1,0]
	v_pk_mul_f32 v[10:11], v[10:11], v[150:151] op_sel_hi:[1,0]
	v_pk_mul_f32 v[8:9], v[8:9], v[150:151] op_sel_hi:[1,0]
	v_pk_mul_f32 v[22:23], v[22:23], v[146:147] op_sel_hi:[1,0]
	v_pk_mul_f32 v[20:21], v[20:21], v[146:147] op_sel_hi:[1,0]
	v_pk_mul_f32 v[14:15], v[14:15], v[146:147] op_sel_hi:[1,0]
	v_pk_mul_f32 v[12:13], v[12:13], v[146:147] op_sel_hi:[1,0]
	v_pk_mul_f32 v[6:7], v[6:7], v[146:147] op_sel_hi:[1,0]
	v_pk_mul_f32 v[4:5], v[4:5], v[146:147] op_sel_hi:[1,0]
	v_pk_mul_f32 v[2:3], v[2:3], v[146:147] op_sel_hi:[1,0]
	v_pk_mul_f32 v[0:1], v[0:1], v[146:147] op_sel_hi:[1,0]
	s_branch .LBB0_486

; #define PG8_STAGE(bufoff, gbase, voff) do { _Pragma("unroll") for (int _i = 0; _i < 2; ++_i) \
;         __builtin_amdgcn_global_load_lds((const unsigned*)((const char*)(gbase) + (voff)[_i]), (LAS unsigned*)(lds + (bufoff) + ldsw + _i * 8192), 16, 0, 0); } while (0)
; #define PG8_LDA(dst, b, h) do { _Pragma("unroll") for (int m = 0; m < 4; ++m) _Pragma("unroll") for (int k = 0; k < 2; ++k) dst[m][k] = *(const LAS bf16x8*)(lds + PG8_SA(b, h) + aoff + m * 2048 + k * 1024); } while (0)
; #define PG8_LDB(dst, b, h) do { _Pragma("unroll") for (int n = 0; n < 2; ++n) _Pragma("unroll") for (int k = 0; k < 2; ++k) dst[n][k] = *(const LAS bf16x8*)(lds + PG8_SB(b, h) + boff + n * 2048 + k * 1024); } while (0)
; #define PG8_WAIT_V(n) asm volatile("s_waitcnt vmcnt(" #n ")" ::: "memory")
; #define PG8_WAIT_L(n) asm volatile("s_waitcnt lgkmcnt(" #n ")" ::: "memory")
; #define PG8_BAR __builtin_amdgcn_s_barrier()
; #define PG8_SCHED __builtin_amdgcn_sched_barrier(0)
; template <class Epi>
; __device__ __forceinline__ void gemm_phase(LAS unsigned char* lds, const bf16_t* A, int lda, const bf16_t* Bt, int ldb, int M, int N, int K, int asel, const Epi& E, const int fixed_round = -1) {
;     ...
;         for (int t = 0; t < nt; t += 2) {
;             const bool last = (t == nt - 2);
;             const char* a1 = cA + (size_t)(t + 1) * kstep;
;             const char* a2 = last ? nA : cA + (size_t)(t + 2) * kstep; const char* b2 = last ? nB : cB + (size_t)(t + 2) * kstep;
;             const char* a3 = a2 + kstep; const char* b3 = b2 + kstep;
;             PG8_LDB(B0, 0, 0); PG8_SCHED; PG8_LDA(At, 0, 0); PG8_STAGE(PG8_SA(1, 1), a1 + hstepA, voffA);
;             PG8_WAIT_L(8); PG8_BAR; PG8_WAIT_L(0); PG8_MMA(0, 0, At, B0); PG8_BAR; PG8_SCHED;
;             PG8_LDB(B1, 0, 1); PG8_STAGE(PG8_SB(0, 0), b2, voffB);
;             PG8_BAR; PG8_WAIT_L(0); PG8_MMA(0, 1, At, B1); PG8_BAR;
;             PG8_LDA(At, 0, 1); PG8_STAGE(PG8_SA(0, 0), a2, voffA);
;             PG8_BAR; PG8_WAIT_L(0); PG8_MMA(1, 0, At, B0); PG8_BAR; PG8_SCHED;
;             PG8_STAGE(PG8_SB(0, 1), b2 + hstepB, voffB);
;             PG8_WAIT_V(6); PG8_BAR; PG8_MMA(1, 1, At, B1); PG8_BAR;
.LBB0_591:
	ds_read_b128 v[152:155], v149
	ds_read_b128 v[156:159], v149 offset:1024
	ds_read_b128 v[160:163], v149 offset:2048
	ds_read_b128 v[164:167], v149 offset:3072
	s_add_u32 s28, s30, 0xfff80080
	s_addc_u32 s29, s31, -1
	s_cmp_eq_u32 s56, 28
	s_cselect_b32 s37, s7, s29
	s_cselect_b32 s36, s52, s28
	s_cselect_b32 s35, s5, s55
	s_cselect_b32 s34, s53, s54
	s_add_i32 m0, s27, 0xc000
	ds_read_b128 v[168:171], v150
	ds_read_b128 v[172:175], v150 offset:1024
	ds_read_b128 v[176:179], v150 offset:2048
	ds_read_b128 v[180:183], v150 offset:3072
	ds_read_b128 v[184:187], v150 offset:4096
	ds_read_b128 v[188:191], v150 offset:5120
	ds_read_b128 v[192:195], v150 offset:6144
	ds_read_b128 v[196:199], v150 offset:7168
	global_load_lds_dwordx4 v136, s[30:31]
	s_add_i32 m0, s27, 0xe000
	s_nop 0
	global_load_lds_dwordx4 v138, s[30:31]
	s_waitcnt lgkmcnt(8)
	s_barrier
	s_waitcnt lgkmcnt(0)
	s_setprio 1
	s_waitcnt lgkmcnt(0)
	v_mfma_f32_16x16x32_bf16 v[124:127], v[152:155], v[168:171], v[124:127]
	v_mfma_f32_16x16x32_bf16 v[120:123], v[160:163], v[168:171], v[120:123]
	v_mfma_f32_16x16x32_bf16 v[108:111], v[152:155], v[176:179], v[108:111]
	v_mfma_f32_16x16x32_bf16 v[104:107], v[160:163], v[176:179], v[104:107]
	v_mfma_f32_16x16x32_bf16 v[92:95], v[152:155], v[184:187], v[92:95]
	v_mfma_f32_16x16x32_bf16 v[88:91], v[160:163], v[184:187], v[88:91]
	v_mfma_f32_16x16x32_bf16 v[76:79], v[152:155], v[192:195], v[76:79]
	v_mfma_f32_16x16x32_bf16 v[72:75], v[160:163], v[192:195], v[72:75]
	v_mfma_f32_16x16x32_bf16 v[124:127], v[156:159], v[172:175], v[124:127]
	v_mfma_f32_16x16x32_bf16 v[120:123], v[164:167], v[172:175], v[120:123]
	v_mfma_f32_16x16x32_bf16 v[108:111], v[156:159], v[180:183], v[108:111]
	v_mfma_f32_16x16x32_bf16 v[104:107], v[164:167], v[180:183], v[104:107]
	v_mfma_f32_16x16x32_bf16 v[92:95], v[156:159], v[188:191], v[92:95]
	v_mfma_f32_16x16x32_bf16 v[88:91], v[164:167], v[188:191], v[88:91]
	v_mfma_f32_16x16x32_bf16 v[76:79], v[156:159], v[196:199], v[76:79]
	v_mfma_f32_16x16x32_bf16 v[72:75], v[164:167], v[196:199], v[72:75]
	s_setprio 0
	s_barrier
	s_add_i32 s28, s81, s42
	s_add_u32 s98, s34, s2
	s_addc_u32 s99, s35, s3
	s_mov_b32 m0, s28
	ds_read_b128 v[202:205], v151
	ds_read_b128 v[206:209], v151 offset:1024
	ds_read_b128 v[210:213], v151 offset:2048
	ds_read_b128 v[214:217], v151 offset:3072
	global_load_lds_dwordx4 v130, s[34:35]
	s_add_i32 m0, s28, 0x2000
	s_nop 0
	global_load_lds_dwordx4 v134, s[34:35]
	s_barrier
	s_waitcnt lgkmcnt(0)
	s_setprio 1
	s_waitcnt lgkmcnt(0)
	v_mfma_f32_16x16x32_bf16 v[116:119], v[202:205], v[168:171], v[116:119]
	v_mfma_f32_16x16x32_bf16 v[112:115], v[210:213], v[168:171], v[112:115]
	v_mfma_f32_16x16x32_bf16 v[100:103], v[202:205], v[176:179], v[100:103]
	v_mfma_f32_16x16x32_bf16 v[96:99], v[210:213], v[176:179], v[96:99]
	v_mfma_f32_16x16x32_bf16 v[84:87], v[202:205], v[184:187], v[84:87]
	v_mfma_f32_16x16x32_bf16 v[80:83], v[210:213], v[184:187], v[80:83]
	v_mfma_f32_16x16x32_bf16 v[68:71], v[202:205], v[192:195], v[68:71]
	v_mfma_f32_16x16x32_bf16 v[64:67], v[210:213], v[192:195], v[64:67]
	v_mfma_f32_16x16x32_bf16 v[116:119], v[206:209], v[172:175], v[116:119]
	v_mfma_f32_16x16x32_bf16 v[112:115], v[214:217], v[172:175], v[112:115]
	v_mfma_f32_16x16x32_bf16 v[100:103], v[206:209], v[180:183], v[100:103]
	v_mfma_f32_16x16x32_bf16 v[96:99], v[214:217], v[180:183], v[96:99]
	v_mfma_f32_16x16x32_bf16 v[84:87], v[206:209], v[188:191], v[84:87]
	v_mfma_f32_16x16x32_bf16 v[80:83], v[214:217], v[188:191], v[80:83]
	v_mfma_f32_16x16x32_bf16 v[68:71], v[206:209], v[196:199], v[68:71]
	v_mfma_f32_16x16x32_bf16 v[64:67], v[214:217], v[196:199], v[64:67]
	s_setprio 0
	s_mov_b32 m0, s27
	s_add_u32 s100, s36, s2
	s_addc_u32 s101, s37, s3
	s_barrier
	ds_read_b128 v[168:171], v150 offset:16384
	ds_read_b128 v[172:175], v150 offset:17408
	ds_read_b128 v[176:179], v150 offset:18432
	ds_read_b128 v[180:183], v150 offset:19456
	ds_read_b128 v[184:187], v150 offset:20480
	ds_read_b128 v[188:191], v150 offset:21504
	ds_read_b128 v[192:195], v150 offset:22528
	ds_read_b128 v[196:199], v150 offset:23552
	global_load_lds_dwordx4 v128, s[36:37]
	s_mov_b32 m0, s43
	s_nop 0
	global_load_lds_dwordx4 v132, s[36:37]
	s_barrier
	s_waitcnt lgkmcnt(0)
	s_setprio 1
	s_waitcnt lgkmcnt(0)
	v_mfma_f32_16x16x32_bf16 v[60:63], v[152:155], v[168:171], v[60:63]
	v_mfma_f32_16x16x32_bf16 v[56:59], v[160:163], v[168:171], v[56:59]
	v_mfma_f32_16x16x32_bf16 v[44:47], v[152:155], v[176:179], v[44:47]
	v_mfma_f32_16x16x32_bf16 v[40:43], v[160:163], v[176:179], v[40:43]
	v_mfma_f32_16x16x32_bf16 v[28:31], v[152:155], v[184:187], v[28:31]
	v_mfma_f32_16x16x32_bf16 v[24:27], v[160:163], v[184:187], v[24:27]
	v_mfma_f32_16x16x32_bf16 v[12:15], v[152:155], v[192:195], v[12:15]
	v_mfma_f32_16x16x32_bf16 v[8:11], v[160:163], v[192:195], v[8:11]
	v_mfma_f32_16x16x32_bf16 v[60:63], v[156:159], v[172:175], v[60:63]
	v_mfma_f32_16x16x32_bf16 v[56:59], v[164:167], v[172:175], v[56:59]
	v_mfma_f32_16x16x32_bf16 v[44:47], v[156:159], v[180:183], v[44:47]
	v_mfma_f32_16x16x32_bf16 v[40:43], v[164:167], v[180:183], v[40:43]
	v_mfma_f32_16x16x32_bf16 v[28:31], v[156:159], v[188:191], v[28:31]
	v_mfma_f32_16x16x32_bf16 v[24:27], v[164:167], v[188:191], v[24:27]
	v_mfma_f32_16x16x32_bf16 v[12:15], v[156:159], v[196:199], v[12:15]
	v_mfma_f32_16x16x32_bf16 v[8:11], v[164:167], v[196:199], v[8:11]
	s_setprio 0
	s_barrier
	s_add_u32 s28, s34, 0x80000
	s_addc_u32 s29, s35, 0
	s_add_i32 s57, s82, s42
	s_mov_b32 m0, s57
	s_nop 0
	global_load_lds_dwordx4 v130, s[28:29]
	s_add_i32 m0, s57, 0x2000
	s_nop 0
	global_load_lds_dwordx4 v134, s[28:29]
	s_waitcnt vmcnt(6)
	s_barrier
; #define PG8_STAGE(bufoff, gbase, voff) do { _Pragma("unroll") for (int _i = 0; _i < 2; ++_i) \
;         __builtin_amdgcn_global_load_lds((const unsigned*)((const char*)(gbase) + (voff)[_i]), (LAS unsigned*)(lds + (bufoff) + ldsw + _i * 8192), 16, 0, 0); } while (0)
; #define PG8_LDA(dst, b, h) do { _Pragma("unroll") for (int m = 0; m < 4; ++m) _Pragma("unroll") for (int k = 0; k < 2; ++k) dst[m][k] = *(const LAS bf16x8*)(lds + PG8_SA(b, h) + aoff + m * 2048 + k * 1024); } while (0)
; #define PG8_LDB(dst, b, h) do { _Pragma("unroll") for (int n = 0; n < 2; ++n) _Pragma("unroll") for (int k = 0; k < 2; ++k) dst[n][k] = *(const LAS bf16x8*)(lds + PG8_SB(b, h) + boff + n * 2048 + k * 1024); } while (0)
; #define PG8_WAIT_L(n) asm volatile("s_waitcnt lgkmcnt(" #n ")" ::: "memory")
; #define PG8_BAR __builtin_amdgcn_s_barrier()
; #define PG8_SCHED __builtin_amdgcn_sched_barrier(0)
; template <class Epi>
; __device__ __forceinline__ void gemm_phase(LAS unsigned char* lds, const bf16_t* A, int lda, const bf16_t* Bt, int ldb, int M, int N, int K, int asel, const Epi& E, const int fixed_round = -1) {
;     ...
;             PG8_LDB(B0, 1, 0); PG8_SCHED; PG8_LDA(At, 1, 0); PG8_STAGE(PG8_SA(0, 1), a2 + hstepA, voffA);
;             PG8_WAIT_L(8); PG8_BAR; PG8_WAIT_L(0); PG8_MMA(0, 0, At, B0); PG8_BAR; PG8_SCHED;
;             PG8_LDB(B1, 1, 1); PG8_STAGE(PG8_SB(1, 0), b3, voffB);
;             PG8_BAR; PG8_WAIT_L(0); PG8_MMA(0, 1, At, B1); PG8_BAR;
;             PG8_LDA(At, 1, 1); PG8_STAGE(PG8_SA(1, 0), a3, voffA);
;             PG8_BAR; PG8_WAIT_L(0); PG8_MMA(1, 0, At, B0); PG8_BAR; PG8_SCHED;
	s_setprio 1
	v_mfma_f32_16x16x32_bf16 v[52:55], v[202:205], v[168:171], v[52:55]
	v_mfma_f32_16x16x32_bf16 v[48:51], v[210:213], v[168:171], v[48:51]
	v_mfma_f32_16x16x32_bf16 v[36:39], v[202:205], v[176:179], v[36:39]
	v_mfma_f32_16x16x32_bf16 v[32:35], v[210:213], v[176:179], v[32:35]
	v_mfma_f32_16x16x32_bf16 v[20:23], v[202:205], v[184:187], v[20:23]
	v_mfma_f32_16x16x32_bf16 v[16:19], v[210:213], v[184:187], v[16:19]
	v_mfma_f32_16x16x32_bf16 v[4:7], v[202:205], v[192:195], v[4:7]
	v_mfma_f32_16x16x32_bf16 v[0:3], v[210:213], v[192:195], v[0:3]
	v_mfma_f32_16x16x32_bf16 v[52:55], v[206:209], v[172:175], v[52:55]
	v_mfma_f32_16x16x32_bf16 v[48:51], v[214:217], v[172:175], v[48:51]
	v_mfma_f32_16x16x32_bf16 v[36:39], v[206:209], v[180:183], v[36:39]
	v_mfma_f32_16x16x32_bf16 v[32:35], v[214:217], v[180:183], v[32:35]
	v_mfma_f32_16x16x32_bf16 v[20:23], v[206:209], v[188:191], v[20:23]
	v_mfma_f32_16x16x32_bf16 v[16:19], v[214:217], v[188:191], v[16:19]
	v_mfma_f32_16x16x32_bf16 v[4:7], v[206:209], v[196:199], v[4:7]
	v_mfma_f32_16x16x32_bf16 v[0:3], v[214:217], v[196:199], v[0:3]
	s_setprio 0
	v_add_u32_e32 v164, s83, v147
	s_barrier
	ds_read_b128 v[152:155], v164
	ds_read_b128 v[156:159], v164 offset:1024
	ds_read_b128 v[160:163], v164 offset:2048
	ds_read_b128 v[164:167], v164 offset:3072
	s_add_u32 s28, s36, 0x80000
	s_addc_u32 s29, s37, 0
	s_mov_b32 m0, s44
	ds_read_b128 v[168:171], v150 offset:32768
	ds_read_b128 v[172:175], v150 offset:33792
	ds_read_b128 v[176:179], v150 offset:34816
	ds_read_b128 v[180:183], v150 offset:35840
	ds_read_b128 v[184:187], v150 offset:36864
	ds_read_b128 v[188:191], v150 offset:37888
	ds_read_b128 v[192:195], v150 offset:38912
	ds_read_b128 v[196:199], v150 offset:39936
	global_load_lds_dwordx4 v128, s[28:29]
	s_mov_b32 m0, s45
	s_nop 0
	global_load_lds_dwordx4 v132, s[28:29]
	s_waitcnt lgkmcnt(8)
	s_barrier
	s_waitcnt lgkmcnt(0)
	s_setprio 1
	s_waitcnt lgkmcnt(0)
	v_mfma_f32_16x16x32_bf16 v[124:127], v[152:155], v[168:171], v[124:127]
	v_mfma_f32_16x16x32_bf16 v[120:123], v[160:163], v[168:171], v[120:123]
	v_mfma_f32_16x16x32_bf16 v[108:111], v[152:155], v[176:179], v[108:111]
	v_mfma_f32_16x16x32_bf16 v[104:107], v[160:163], v[176:179], v[104:107]
	v_mfma_f32_16x16x32_bf16 v[92:95], v[152:155], v[184:187], v[92:95]
	v_mfma_f32_16x16x32_bf16 v[88:91], v[160:163], v[184:187], v[88:91]
	v_mfma_f32_16x16x32_bf16 v[76:79], v[152:155], v[192:195], v[76:79]
	v_mfma_f32_16x16x32_bf16 v[72:75], v[160:163], v[192:195], v[72:75]
	v_mfma_f32_16x16x32_bf16 v[124:127], v[156:159], v[172:175], v[124:127]
	v_mfma_f32_16x16x32_bf16 v[120:123], v[164:167], v[172:175], v[120:123]
	v_mfma_f32_16x16x32_bf16 v[108:111], v[156:159], v[180:183], v[108:111]
	v_mfma_f32_16x16x32_bf16 v[104:107], v[164:167], v[180:183], v[104:107]
	v_mfma_f32_16x16x32_bf16 v[92:95], v[156:159], v[188:191], v[92:95]
	v_mfma_f32_16x16x32_bf16 v[88:91], v[164:167], v[188:191], v[88:91]
	v_mfma_f32_16x16x32_bf16 v[76:79], v[156:159], v[196:199], v[76:79]
	v_mfma_f32_16x16x32_bf16 v[72:75], v[164:167], v[196:199], v[72:75]
	s_setprio 0
	s_barrier
	s_add_i32 s28, s83, s42
	v_add_u32_e32 v214, s84, v147
	s_mov_b32 m0, s28
	ds_read_b128 v[202:205], v214
	ds_read_b128 v[206:209], v214 offset:1024
	ds_read_b128 v[210:213], v214 offset:2048
	ds_read_b128 v[214:217], v214 offset:3072
	global_load_lds_dwordx4 v130, s[98:99]
	s_add_i32 m0, s28, 0x2000
	s_nop 0
	global_load_lds_dwordx4 v134, s[98:99]
	s_barrier
	s_waitcnt lgkmcnt(0)
	s_setprio 1
	s_waitcnt lgkmcnt(0)
	v_mfma_f32_16x16x32_bf16 v[116:119], v[202:205], v[168:171], v[116:119]
	v_mfma_f32_16x16x32_bf16 v[112:115], v[210:213], v[168:171], v[112:115]
	v_mfma_f32_16x16x32_bf16 v[100:103], v[202:205], v[176:179], v[100:103]
	v_mfma_f32_16x16x32_bf16 v[96:99], v[210:213], v[176:179], v[96:99]
	v_mfma_f32_16x16x32_bf16 v[84:87], v[202:205], v[184:187], v[84:87]
	v_mfma_f32_16x16x32_bf16 v[80:83], v[210:213], v[184:187], v[80:83]
	v_mfma_f32_16x16x32_bf16 v[68:71], v[202:205], v[192:195], v[68:71]
	v_mfma_f32_16x16x32_bf16 v[64:67], v[210:213], v[192:195], v[64:67]
	v_mfma_f32_16x16x32_bf16 v[116:119], v[206:209], v[172:175], v[116:119]
	v_mfma_f32_16x16x32_bf16 v[112:115], v[214:217], v[172:175], v[112:115]
	v_mfma_f32_16x16x32_bf16 v[100:103], v[206:209], v[180:183], v[100:103]
	v_mfma_f32_16x16x32_bf16 v[96:99], v[214:217], v[180:183], v[96:99]
	v_mfma_f32_16x16x32_bf16 v[84:87], v[206:209], v[188:191], v[84:87]
	v_mfma_f32_16x16x32_bf16 v[80:83], v[214:217], v[188:191], v[80:83]
	v_mfma_f32_16x16x32_bf16 v[68:71], v[206:209], v[196:199], v[68:71]
	v_mfma_f32_16x16x32_bf16 v[64:67], v[214:217], v[196:199], v[64:67]
	s_setprio 0
	s_mov_b32 m0, s47
	s_barrier
	ds_read_b128 v[168:171], v150 offset:49152
	ds_read_b128 v[172:175], v150 offset:50176
	ds_read_b128 v[176:179], v150 offset:51200
	ds_read_b128 v[180:183], v150 offset:52224
	ds_read_b128 v[184:187], v150 offset:53248
	ds_read_b128 v[188:191], v150 offset:54272
	ds_read_b128 v[192:195], v150 offset:55296
	ds_read_b128 v[196:199], v150 offset:56320
	global_load_lds_dwordx4 v128, s[100:101]
	s_mov_b32 m0, s48
	s_nop 0
	global_load_lds_dwordx4 v132, s[100:101]
	s_barrier
; __device__ __forceinline__ unsigned cvt_pk_bf16(float lo, float hi) { const bf16x2_t r = __builtin_convertvector((f32x2){lo, hi}, bf16x2_t); return __builtin_bit_cast(unsigned, r); }
; #define PG8_STAGE(bufoff, gbase, voff) do { _Pragma("unroll") for (int _i = 0; _i < 2; ++_i) \
;         __builtin_amdgcn_global_load_lds((const unsigned*)((const char*)(gbase) + (voff)[_i]), (LAS unsigned*)(lds + (bufoff) + ldsw + _i * 8192), 16, 0, 0); } while (0)
; #define PG8_LDA(dst, b, h) do { _Pragma("unroll") for (int m = 0; m < 4; ++m) _Pragma("unroll") for (int k = 0; k < 2; ++k) dst[m][k] = *(const LAS bf16x8*)(lds + PG8_SA(b, h) + aoff + m * 2048 + k * 1024); } while (0)
; #define PG8_WAIT_V(n) asm volatile("s_waitcnt vmcnt(" #n ")" ::: "memory")
; #define PG8_WAIT_L(n) asm volatile("s_waitcnt lgkmcnt(" #n ")" ::: "memory")
; #define PG8_BAR __builtin_amdgcn_s_barrier()
; #define PG8_SCHED __builtin_amdgcn_sched_barrier(0)
; template <class Epi>
; __device__ __forceinline__ void gemm_phase(LAS unsigned char* lds, const bf16_t* A, int lda, const bf16_t* Bt, int ldb, int M, int N, int K, int asel, const Epi& E, const int fixed_round = -1) {
;     ...
;             PG8_BAR; PG8_WAIT_L(0); PG8_MMA(0, 1, At, B1); PG8_BAR;
;             PG8_LDA(At, 1, 1); PG8_STAGE(PG8_SA(1, 0), a3, voffA);
;             PG8_BAR; PG8_WAIT_L(0); PG8_MMA(1, 0, At, B0); PG8_BAR; PG8_SCHED;
;             PG8_STAGE(PG8_SB(1, 1), b3 + hstepB, voffB);
;             PG8_WAIT_V(6); PG8_BAR; PG8_MMA(1, 1, At, B1); PG8_BAR;
;     __device__ __forceinline__ void operator()(const AccT& acc, const Unit& u, int wr, int wc, int fr, int fq) const {
;         const int row0 = u.pm * BM + wr * 64 + fr, col0 = u.pn * BM + wc * 32 + 8 * fq;
; #pragma unroll
;         for (int ai = 0; ai < 2; ++ai)
; #pragma unroll
;             for (int m = 0; m < 4; ++m) { bf16_t* rowp = O + (size_t)(row0 + ai * HALF + m * 16) * DFF + col0;
; #pragma unroll
;                 for (int bj = 0; bj < 2; ++bj) { f32x4 v0 = acc[ai][bj][m][0], v1 = acc[ai][bj][m][1];
; #pragma unroll
;                     for (int j = 0; j < 4; ++j) { float a = fmaxf(v0[j], 0.f), b = fmaxf(v1[j], 0.f); v0[j] = a * a; v1[j] = b * b; }
;                     u32x4 w; w.x = cvt_pk_bf16(v0[0], v0[1]); w.y = cvt_pk_bf16(v0[2], v0[3]); w.z = cvt_pk_bf16(v1[0], v1[1]); w.w = cvt_pk_bf16(v1[2], v1[3]);
;                     *(u32x4*)(rowp + bj * HALF) = w; } }
	s_waitcnt lgkmcnt(0)
	s_setprio 1
	s_waitcnt lgkmcnt(0)
	v_mfma_f32_16x16x32_bf16 v[60:63], v[152:155], v[168:171], v[60:63]
	v_mfma_f32_16x16x32_bf16 v[56:59], v[160:163], v[168:171], v[56:59]
	v_mfma_f32_16x16x32_bf16 v[44:47], v[152:155], v[176:179], v[44:47]
	v_mfma_f32_16x16x32_bf16 v[40:43], v[160:163], v[176:179], v[40:43]
	v_mfma_f32_16x16x32_bf16 v[28:31], v[152:155], v[184:187], v[28:31]
	v_mfma_f32_16x16x32_bf16 v[24:27], v[160:163], v[184:187], v[24:27]
	v_mfma_f32_16x16x32_bf16 v[12:15], v[152:155], v[192:195], v[12:15]
	v_mfma_f32_16x16x32_bf16 v[8:11], v[160:163], v[192:195], v[8:11]
	v_mfma_f32_16x16x32_bf16 v[60:63], v[156:159], v[172:175], v[60:63]
	v_mfma_f32_16x16x32_bf16 v[56:59], v[164:167], v[172:175], v[56:59]
	v_mfma_f32_16x16x32_bf16 v[44:47], v[156:159], v[180:183], v[44:47]
	v_mfma_f32_16x16x32_bf16 v[40:43], v[164:167], v[180:183], v[40:43]
	v_mfma_f32_16x16x32_bf16 v[28:31], v[156:159], v[188:191], v[28:31]
	v_mfma_f32_16x16x32_bf16 v[24:27], v[164:167], v[188:191], v[24:27]
	v_mfma_f32_16x16x32_bf16 v[12:15], v[156:159], v[196:199], v[12:15]
	v_mfma_f32_16x16x32_bf16 v[8:11], v[164:167], v[196:199], v[8:11]
	s_setprio 0
	s_barrier
	s_add_u32 s28, s34, 0x80080
	s_addc_u32 s29, s35, 0
	s_add_i32 s34, s84, s42
	s_mov_b32 m0, s34
	s_nop 0
	global_load_lds_dwordx4 v130, s[28:29]
	s_add_i32 m0, s34, 0x2000
	s_nop 0
	global_load_lds_dwordx4 v134, s[28:29]
	s_waitcnt vmcnt(6)
	s_barrier
	s_setprio 1
	v_mfma_f32_16x16x32_bf16 v[52:55], v[202:205], v[168:171], v[52:55]
	v_mfma_f32_16x16x32_bf16 v[48:51], v[210:213], v[168:171], v[48:51]
	v_mfma_f32_16x16x32_bf16 v[36:39], v[202:205], v[176:179], v[36:39]
	v_mfma_f32_16x16x32_bf16 v[32:35], v[210:213], v[176:179], v[32:35]
	v_mfma_f32_16x16x32_bf16 v[20:23], v[202:205], v[184:187], v[20:23]
	v_mfma_f32_16x16x32_bf16 v[16:19], v[210:213], v[184:187], v[16:19]
	v_mfma_f32_16x16x32_bf16 v[4:7], v[202:205], v[192:195], v[4:7]
	v_mfma_f32_16x16x32_bf16 v[0:3], v[210:213], v[192:195], v[0:3]
	v_mfma_f32_16x16x32_bf16 v[52:55], v[206:209], v[172:175], v[52:55]
	v_mfma_f32_16x16x32_bf16 v[48:51], v[214:217], v[172:175], v[48:51]
	v_mfma_f32_16x16x32_bf16 v[36:39], v[206:209], v[180:183], v[36:39]
	v_mfma_f32_16x16x32_bf16 v[32:35], v[214:217], v[180:183], v[32:35]
	v_mfma_f32_16x16x32_bf16 v[20:23], v[206:209], v[188:191], v[20:23]
	v_mfma_f32_16x16x32_bf16 v[16:19], v[214:217], v[188:191], v[16:19]
	v_mfma_f32_16x16x32_bf16 v[4:7], v[206:209], v[196:199], v[4:7]
	v_mfma_f32_16x16x32_bf16 v[0:3], v[214:217], v[196:199], v[0:3]
	s_setprio 0
	s_add_i32 s56, s56, 2
	s_add_u32 s30, s30, 0x100
	s_addc_u32 s31, s31, 0
	s_add_u32 s54, s54, 0x100
	s_addc_u32 s55, s55, 0
	s_cmp_gt_u32 s56, 29
	s_barrier
	s_cbranch_scc0 .LBB0_591
	v_lshl_add_u32 v152, s26, 8, v146
	v_lshl_or_b32 v144, s51, 8, v148
	v_ashrrev_i32_e32 v153, 31, v152
	v_ashrrev_i32_e32 v145, 31, v144
	v_lshlrev_b64 v[154:155], 14, v[152:153]
	v_max_f32_e32 v120, v120, v120
	v_max_f32_e32 v121, v121, v121
	v_lshl_add_u64 v[154:155], s[88:89], 0, v[154:155]
	v_lshlrev_b64 v[156:157], 1, v[144:145]
	v_max_f32_e32 v120, 0, v120
	v_max_f32_e32 v121, 0, v121
	v_lshl_add_u64 v[144:145], v[154:155], 0, v[156:157]
	v_pk_mul_f32 v[154:155], v[120:121], v[120:121]
	v_max_f32_e32 v121, v122, v122
	v_max_f32_e32 v124, v124, v124
	v_max_f32_e32 v125, v125, v125
	v_max_f32_e32 v120, v126, v126
	v_max_f32_e32 v122, 0, v121
	v_max_f32_e32 v121, v127, v127
	v_max_f32_e32 v123, v123, v123
	v_max_f32_e32 v124, 0, v124
	v_max_f32_e32 v125, 0, v125
	v_max_f32_e32 v120, 0, v120
	v_max_f32_e32 v121, 0, v121
	v_max_f32_e32 v123, 0, v123
	v_pk_mul_f32 v[124:125], v[124:125], v[124:125]
	v_pk_mul_f32 v[126:127], v[120:121], v[120:121]
	v_pk_mul_f32 v[158:159], v[122:123], v[122:123]
	v_max_f32_e32 v112, v112, v112
	v_max_f32_e32 v113, v113, v113
	v_cvt_pk_bf16_f32 v120, v124, v125
	v_cvt_pk_bf16_f32 v121, v126, v127
	v_cvt_pk_bf16_f32 v122, v154, v155
	v_cvt_pk_bf16_f32 v123, v158, v159
	v_max_f32_e32 v112, 0, v112
	v_max_f32_e32 v113, 0, v113
	global_store_dwordx4 v[144:145], v[120:123], off
	v_max_f32_e32 v116, v116, v116
	v_max_f32_e32 v117, v117, v117
	v_pk_mul_f32 v[120:121], v[112:113], v[112:113]
	v_max_f32_e32 v113, v114, v114
	v_max_f32_e32 v112, v118, v118
	v_max_f32_e32 v114, 0, v113
	v_max_f32_e32 v113, v119, v119
	v_max_f32_e32 v115, v115, v115
	v_max_f32_e32 v116, 0, v116
	v_max_f32_e32 v117, 0, v117
	v_max_f32_e32 v112, 0, v112
	v_max_f32_e32 v113, 0, v113
	v_max_f32_e32 v115, 0, v115
	v_pk_mul_f32 v[116:117], v[116:117], v[116:117]
	v_pk_mul_f32 v[118:119], v[112:113], v[112:113]
	v_pk_mul_f32 v[122:123], v[114:115], v[114:115]
	v_max_f32_e32 v104, v104, v104
	v_max_f32_e32 v105, v105, v105
	v_cvt_pk_bf16_f32 v112, v116, v117
	v_cvt_pk_bf16_f32 v113, v118, v119
	v_cvt_pk_bf16_f32 v114, v120, v121
	v_cvt_pk_bf16_f32 v115, v122, v123
	v_max_f32_e32 v104, 0, v104
	v_max_f32_e32 v105, 0, v105
	global_store_dwordx4 v[144:145], v[112:115], off offset:256
	v_max_f32_e32 v108, v108, v108
	v_max_f32_e32 v109, v109, v109
	v_or_b32_e32 v112, 16, v152
	v_pk_mul_f32 v[114:115], v[104:105], v[104:105]
	v_max_f32_e32 v105, v106, v106
	v_ashrrev_i32_e32 v113, 31, v112
	v_max_f32_e32 v104, v110, v110
	v_max_f32_e32 v106, 0, v105
	v_max_f32_e32 v105, v111, v111
	v_max_f32_e32 v107, v107, v107
	v_lshlrev_b64 v[112:113], 14, v[112:113]
	v_max_f32_e32 v108, 0, v108
	v_max_f32_e32 v109, 0, v109
	v_max_f32_e32 v104, 0, v104
	v_max_f32_e32 v105, 0, v105
	v_max_f32_e32 v107, 0, v107
	v_lshl_add_u64 v[112:113], s[88:89], 0, v[112:113]
	v_pk_mul_f32 v[108:109], v[108:109], v[108:109]
	v_pk_mul_f32 v[110:111], v[104:105], v[104:105]
; __device__ __forceinline__ unsigned cvt_pk_bf16(float lo, float hi) { const bf16x2_t r = __builtin_convertvector((f32x2){lo, hi}, bf16x2_t); return __builtin_bit_cast(unsigned, r); }
;     __device__ __forceinline__ void operator()(const AccT& acc, const Unit& u, int wr, int wc, int fr, int fq) const {
;         const int row0 = u.pm * BM + wr * 64 + fr, col0 = u.pn * BM + wc * 32 + 8 * fq;
; #pragma unroll
;         for (int ai = 0; ai < 2; ++ai)
; #pragma unroll
;             for (int m = 0; m < 4; ++m) { bf16_t* rowp = O + (size_t)(row0 + ai * HALF + m * 16) * DFF + col0;
; #pragma unroll
;                 for (int bj = 0; bj < 2; ++bj) { f32x4 v0 = acc[ai][bj][m][0], v1 = acc[ai][bj][m][1];
; #pragma unroll
;                     for (int j = 0; j < 4; ++j) { float a = fmaxf(v0[j], 0.f), b = fmaxf(v1[j], 0.f); v0[j] = a * a; v1[j] = b * b; }
;                     u32x4 w; w.x = cvt_pk_bf16(v0[0], v0[1]); w.y = cvt_pk_bf16(v0[2], v0[3]); w.z = cvt_pk_bf16(v1[0], v1[1]); w.w = cvt_pk_bf16(v1[2], v1[3]);
;                     *(u32x4*)(rowp + bj * HALF) = w; } }
	v_pk_mul_f32 v[116:117], v[106:107], v[106:107]
	v_max_f32_e32 v96, v96, v96
	v_max_f32_e32 v97, v97, v97
	v_lshl_add_u64 v[112:113], v[112:113], 0, v[156:157]
	v_cvt_pk_bf16_f32 v104, v108, v109
	v_cvt_pk_bf16_f32 v105, v110, v111
	v_cvt_pk_bf16_f32 v106, v114, v115
	v_cvt_pk_bf16_f32 v107, v116, v117
	v_max_f32_e32 v96, 0, v96
	v_max_f32_e32 v97, 0, v97
	global_store_dwordx4 v[112:113], v[104:107], off
	v_max_f32_e32 v100, v100, v100
	v_max_f32_e32 v101, v101, v101
	v_pk_mul_f32 v[104:105], v[96:97], v[96:97]
	v_max_f32_e32 v97, v98, v98
	v_max_f32_e32 v96, v102, v102
	v_max_f32_e32 v98, 0, v97
	v_max_f32_e32 v97, v103, v103
	v_max_f32_e32 v99, v99, v99
	v_max_f32_e32 v100, 0, v100
	v_max_f32_e32 v101, 0, v101
	v_max_f32_e32 v96, 0, v96
	v_max_f32_e32 v97, 0, v97
	v_max_f32_e32 v99, 0, v99
	v_pk_mul_f32 v[100:101], v[100:101], v[100:101]
	v_pk_mul_f32 v[102:103], v[96:97], v[96:97]
	v_pk_mul_f32 v[106:107], v[98:99], v[98:99]
	v_max_f32_e32 v88, v88, v88
	v_max_f32_e32 v89, v89, v89
	v_cvt_pk_bf16_f32 v96, v100, v101
	v_cvt_pk_bf16_f32 v97, v102, v103
	v_cvt_pk_bf16_f32 v98, v104, v105
	v_cvt_pk_bf16_f32 v99, v106, v107
	v_max_f32_e32 v88, 0, v88
	v_max_f32_e32 v89, 0, v89
	global_store_dwordx4 v[112:113], v[96:99], off offset:256
	v_max_f32_e32 v92, v92, v92
	v_max_f32_e32 v93, v93, v93
	v_or_b32_e32 v96, 32, v152
	v_pk_mul_f32 v[98:99], v[88:89], v[88:89]
	v_max_f32_e32 v89, v90, v90
	v_ashrrev_i32_e32 v97, 31, v96
	v_max_f32_e32 v88, v94, v94
	v_max_f32_e32 v90, 0, v89
	v_max_f32_e32 v89, v95, v95
	v_max_f32_e32 v91, v91, v91
	v_lshlrev_b64 v[96:97], 14, v[96:97]
	v_max_f32_e32 v92, 0, v92
	v_max_f32_e32 v93, 0, v93
	v_max_f32_e32 v88, 0, v88
	v_max_f32_e32 v89, 0, v89
	v_max_f32_e32 v91, 0, v91
	v_lshl_add_u64 v[96:97], s[88:89], 0, v[96:97]
	v_pk_mul_f32 v[92:93], v[92:93], v[92:93]
	v_pk_mul_f32 v[94:95], v[88:89], v[88:89]
	v_pk_mul_f32 v[100:101], v[90:91], v[90:91]
	v_max_f32_e32 v80, v80, v80
	v_max_f32_e32 v81, v81, v81
	v_lshl_add_u64 v[96:97], v[96:97], 0, v[156:157]
	v_cvt_pk_bf16_f32 v88, v92, v93
	v_cvt_pk_bf16_f32 v89, v94, v95
	v_cvt_pk_bf16_f32 v90, v98, v99
	v_cvt_pk_bf16_f32 v91, v100, v101
	v_max_f32_e32 v80, 0, v80
	v_max_f32_e32 v81, 0, v81
	global_store_dwordx4 v[96:97], v[88:91], off
	v_max_f32_e32 v84, v84, v84
	v_max_f32_e32 v85, v85, v85
	v_pk_mul_f32 v[88:89], v[80:81], v[80:81]
	v_max_f32_e32 v81, v82, v82
	v_max_f32_e32 v80, v86, v86
	v_max_f32_e32 v82, 0, v81
	v_max_f32_e32 v81, v87, v87
	v_max_f32_e32 v83, v83, v83
	v_max_f32_e32 v84, 0, v84
	v_max_f32_e32 v85, 0, v85
	v_max_f32_e32 v80, 0, v80
	v_max_f32_e32 v81, 0, v81
	v_max_f32_e32 v83, 0, v83
	v_pk_mul_f32 v[84:85], v[84:85], v[84:85]
	v_pk_mul_f32 v[86:87], v[80:81], v[80:81]
	v_pk_mul_f32 v[90:91], v[82:83], v[82:83]
	v_max_f32_e32 v72, v72, v72
	v_max_f32_e32 v73, v73, v73
	v_cvt_pk_bf16_f32 v80, v84, v85
	v_cvt_pk_bf16_f32 v81, v86, v87
	v_cvt_pk_bf16_f32 v82, v88, v89
	v_cvt_pk_bf16_f32 v83, v90, v91
	v_max_f32_e32 v72, 0, v72
	v_max_f32_e32 v73, 0, v73
	global_store_dwordx4 v[96:97], v[80:83], off offset:256
	v_max_f32_e32 v76, v76, v76
	v_max_f32_e32 v77, v77, v77
	v_or_b32_e32 v80, 48, v152
	v_pk_mul_f32 v[82:83], v[72:73], v[72:73]
	v_max_f32_e32 v73, v74, v74
	v_ashrrev_i32_e32 v81, 31, v80
	v_max_f32_e32 v72, v78, v78
	v_max_f32_e32 v74, 0, v73
	v_max_f32_e32 v73, v79, v79
	v_max_f32_e32 v75, v75, v75
	v_lshlrev_b64 v[80:81], 14, v[80:81]
	v_max_f32_e32 v76, 0, v76
	v_max_f32_e32 v77, 0, v77
	v_max_f32_e32 v72, 0, v72
	v_max_f32_e32 v73, 0, v73
	v_max_f32_e32 v75, 0, v75
	v_lshl_add_u64 v[80:81], s[88:89], 0, v[80:81]
	v_pk_mul_f32 v[76:77], v[76:77], v[76:77]
	v_pk_mul_f32 v[78:79], v[72:73], v[72:73]
	v_pk_mul_f32 v[84:85], v[74:75], v[74:75]
	v_max_f32_e32 v64, v64, v64
	v_max_f32_e32 v65, v65, v65
	v_lshl_add_u64 v[80:81], v[80:81], 0, v[156:157]
	v_cvt_pk_bf16_f32 v72, v76, v77
	v_cvt_pk_bf16_f32 v73, v78, v79
	v_cvt_pk_bf16_f32 v74, v82, v83
	v_cvt_pk_bf16_f32 v75, v84, v85
	v_max_f32_e32 v64, 0, v64
	v_max_f32_e32 v65, 0, v65
	global_store_dwordx4 v[80:81], v[72:75], off
	v_max_f32_e32 v68, v68, v68
	v_max_f32_e32 v69, v69, v69
	v_pk_mul_f32 v[72:73], v[64:65], v[64:65]
	v_max_f32_e32 v65, v66, v66
	v_max_f32_e32 v64, v70, v70
	v_max_f32_e32 v66, 0, v65
	v_max_f32_e32 v65, v71, v71
	v_max_f32_e32 v67, v67, v67
	v_max_f32_e32 v68, 0, v68
	v_max_f32_e32 v69, 0, v69
	v_max_f32_e32 v64, 0, v64
	v_max_f32_e32 v65, 0, v65
	v_max_f32_e32 v67, 0, v67
	v_pk_mul_f32 v[68:69], v[68:69], v[68:69]
	v_pk_mul_f32 v[70:71], v[64:65], v[64:65]
	v_pk_mul_f32 v[74:75], v[66:67], v[66:67]
	v_max_f32_e32 v56, v56, v56
	v_max_f32_e32 v57, v57, v57
	v_cvt_pk_bf16_f32 v64, v68, v69
	v_cvt_pk_bf16_f32 v65, v70, v71
	v_cvt_pk_bf16_f32 v66, v72, v73
	v_cvt_pk_bf16_f32 v67, v74, v75
	v_max_f32_e32 v56, 0, v56
	v_max_f32_e32 v57, 0, v57
	global_store_dwordx4 v[80:81], v[64:67], off offset:256
	v_max_f32_e32 v60, v60, v60
	v_max_f32_e32 v61, v61, v61
	v_pk_mul_f32 v[66:67], v[56:57], v[56:57]
	v_max_f32_e32 v57, v58, v58
	v_max_f32_e32 v60, 0, v60
	v_max_f32_e32 v61, 0, v61
	v_max_f32_e32 v56, v62, v62
	v_max_f32_e32 v58, 0, v57
	v_max_f32_e32 v57, v63, v63
	v_max_f32_e32 v59, v59, v59
	v_pk_mul_f32 v[60:61], v[60:61], v[60:61]
	v_max_f32_e32 v56, 0, v56
	v_max_f32_e32 v57, 0, v57
	v_max_f32_e32 v59, 0, v59
	s_mov_b32 s5, 0x200000
	v_pk_mul_f32 v[62:63], v[56:57], v[56:57]
	v_pk_mul_f32 v[68:69], v[58:59], v[58:59]
	v_cvt_pk_bf16_f32 v56, v60, v61
	v_add_co_u32_e32 v60, vcc, s5, v144
	v_max_f32_e32 v48, v48, v48
	v_max_f32_e32 v49, v49, v49
	v_cvt_pk_bf16_f32 v57, v62, v63
	v_cvt_pk_bf16_f32 v58, v66, v67
	v_cvt_pk_bf16_f32 v59, v68, v69
; __device__ __forceinline__ unsigned cvt_pk_bf16(float lo, float hi) { const bf16x2_t r = __builtin_convertvector((f32x2){lo, hi}, bf16x2_t); return __builtin_bit_cast(unsigned, r); }
; template <class Epi>
; __device__ __forceinline__ void gemm_phase(LAS unsigned char* lds, const bf16_t* A, int lda, const bf16_t* Bt, int ldb, int M, int N, int K, int asel, const Epi& E, const int fixed_round = -1) {
;     ...
;         if (!has_next) break;
; #pragma unroll
;         for (int a = 0; a < 2; ++a)
; #pragma unroll
;             for (int b = 0; b < 2; ++b)
; #pragma unroll
;                 for (int m = 0; m < 4; ++m)
; #pragma unroll
;                     for (int n = 0; n < 2; ++n) acc[a][b][m][n] = (f32x4){0.f, 0.f, 0.f, 0.f};
;         cur = nxt; cA = nA; cB = nB; ++ui;
;     }
;     __device__ __forceinline__ void operator()(const AccT& acc, const Unit& u, int wr, int wc, int fr, int fq) const {
;         const int row0 = u.pm * BM + wr * 64 + fr, col0 = u.pn * BM + wc * 32 + 8 * fq;
; #pragma unroll
;         for (int ai = 0; ai < 2; ++ai)
; #pragma unroll
;             for (int m = 0; m < 4; ++m) { bf16_t* rowp = O + (size_t)(row0 + ai * HALF + m * 16) * DFF + col0;
; #pragma unroll
;                 for (int bj = 0; bj < 2; ++bj) { f32x4 v0 = acc[ai][bj][m][0], v1 = acc[ai][bj][m][1];
; #pragma unroll
;                     for (int j = 0; j < 4; ++j) { float a = fmaxf(v0[j], 0.f), b = fmaxf(v1[j], 0.f); v0[j] = a * a; v1[j] = b * b; }
;                     u32x4 w; w.x = cvt_pk_bf16(v0[0], v0[1]); w.y = cvt_pk_bf16(v0[2], v0[3]); w.z = cvt_pk_bf16(v1[0], v1[1]); w.w = cvt_pk_bf16(v1[2], v1[3]);
;                     *(u32x4*)(rowp + bj * HALF) = w; } }
	v_addc_co_u32_e32 v61, vcc, 0, v145, vcc
	v_max_f32_e32 v48, 0, v48
	v_max_f32_e32 v49, 0, v49
	global_store_dwordx4 v[60:61], v[56:59], off
	v_max_f32_e32 v52, v52, v52
	v_max_f32_e32 v53, v53, v53
	v_pk_mul_f32 v[56:57], v[48:49], v[48:49]
	v_max_f32_e32 v49, v50, v50
	v_max_f32_e32 v48, v54, v54
	v_max_f32_e32 v50, 0, v49
	v_max_f32_e32 v49, v55, v55
	v_max_f32_e32 v51, v51, v51
	v_max_f32_e32 v52, 0, v52
	v_max_f32_e32 v53, 0, v53
	v_max_f32_e32 v48, 0, v48
	v_max_f32_e32 v49, 0, v49
	v_max_f32_e32 v51, 0, v51
	s_mov_b64 s[28:29], 0x200000
	v_pk_mul_f32 v[52:53], v[52:53], v[52:53]
	v_pk_mul_f32 v[54:55], v[48:49], v[48:49]
	v_pk_mul_f32 v[58:59], v[50:51], v[50:51]
	v_max_f32_e32 v40, v40, v40
	v_max_f32_e32 v41, v41, v41
	v_lshl_add_u64 v[64:65], v[144:145], 0, s[28:29]
	v_cvt_pk_bf16_f32 v48, v52, v53
	v_cvt_pk_bf16_f32 v49, v54, v55
	v_cvt_pk_bf16_f32 v50, v56, v57
	v_cvt_pk_bf16_f32 v51, v58, v59
	v_max_f32_e32 v40, 0, v40
	v_max_f32_e32 v41, 0, v41
	global_store_dwordx4 v[64:65], v[48:51], off offset:256
	v_max_f32_e32 v44, v44, v44
	v_max_f32_e32 v45, v45, v45
	v_pk_mul_f32 v[50:51], v[40:41], v[40:41]
	v_max_f32_e32 v41, v42, v42
	v_max_f32_e32 v44, 0, v44
	v_max_f32_e32 v45, 0, v45
	v_max_f32_e32 v40, v46, v46
	v_max_f32_e32 v42, 0, v41
	v_max_f32_e32 v41, v47, v47
	v_max_f32_e32 v43, v43, v43
	v_pk_mul_f32 v[44:45], v[44:45], v[44:45]
	v_max_f32_e32 v40, 0, v40
	v_max_f32_e32 v41, 0, v41
	v_max_f32_e32 v43, 0, v43
	s_mov_b32 s5, 0x240000
	v_pk_mul_f32 v[46:47], v[40:41], v[40:41]
	v_pk_mul_f32 v[52:53], v[42:43], v[42:43]
	v_cvt_pk_bf16_f32 v40, v44, v45
	v_add_co_u32_e32 v44, vcc, s5, v144
	v_max_f32_e32 v32, v32, v32
	v_max_f32_e32 v33, v33, v33
	v_cvt_pk_bf16_f32 v41, v46, v47
	v_cvt_pk_bf16_f32 v42, v50, v51
	v_cvt_pk_bf16_f32 v43, v52, v53
	v_addc_co_u32_e32 v45, vcc, 0, v145, vcc
	v_max_f32_e32 v32, 0, v32
	v_max_f32_e32 v33, 0, v33
	global_store_dwordx4 v[44:45], v[40:43], off
	v_max_f32_e32 v36, v36, v36
	v_max_f32_e32 v37, v37, v37
	v_pk_mul_f32 v[40:41], v[32:33], v[32:33]
	v_max_f32_e32 v33, v34, v34
	v_max_f32_e32 v32, v38, v38
	v_max_f32_e32 v34, 0, v33
	v_max_f32_e32 v33, v39, v39
	v_max_f32_e32 v35, v35, v35
	v_max_f32_e32 v36, 0, v36
	v_max_f32_e32 v37, 0, v37
	v_max_f32_e32 v32, 0, v32
	v_max_f32_e32 v33, 0, v33
	v_max_f32_e32 v35, 0, v35
	s_mov_b64 s[28:29], 0x240000
	v_pk_mul_f32 v[36:37], v[36:37], v[36:37]
	v_pk_mul_f32 v[38:39], v[32:33], v[32:33]
	v_pk_mul_f32 v[42:43], v[34:35], v[34:35]
	v_max_f32_e32 v24, v24, v24
	v_max_f32_e32 v25, v25, v25
	v_lshl_add_u64 v[48:49], v[144:145], 0, s[28:29]
	v_cvt_pk_bf16_f32 v32, v36, v37
	v_cvt_pk_bf16_f32 v33, v38, v39
	v_cvt_pk_bf16_f32 v34, v40, v41
	v_cvt_pk_bf16_f32 v35, v42, v43
	v_max_f32_e32 v24, 0, v24
	v_max_f32_e32 v25, 0, v25
	global_store_dwordx4 v[48:49], v[32:35], off offset:256
	v_max_f32_e32 v28, v28, v28
	v_max_f32_e32 v29, v29, v29
	v_pk_mul_f32 v[34:35], v[24:25], v[24:25]
	v_max_f32_e32 v25, v26, v26
	v_max_f32_e32 v28, 0, v28
	v_max_f32_e32 v29, 0, v29
	v_max_f32_e32 v24, v30, v30
	v_max_f32_e32 v26, 0, v25
	v_max_f32_e32 v25, v31, v31
	v_max_f32_e32 v27, v27, v27
	v_pk_mul_f32 v[28:29], v[28:29], v[28:29]
	v_max_f32_e32 v24, 0, v24
	v_max_f32_e32 v25, 0, v25
	v_max_f32_e32 v27, 0, v27
	s_mov_b32 s5, 0x280000
	v_pk_mul_f32 v[30:31], v[24:25], v[24:25]
	v_pk_mul_f32 v[36:37], v[26:27], v[26:27]
	v_cvt_pk_bf16_f32 v24, v28, v29
	v_add_co_u32_e32 v28, vcc, s5, v144
	v_max_f32_e32 v16, v16, v16
	v_max_f32_e32 v17, v17, v17
	v_cvt_pk_bf16_f32 v25, v30, v31
	v_cvt_pk_bf16_f32 v26, v34, v35
	v_cvt_pk_bf16_f32 v27, v36, v37
	v_addc_co_u32_e32 v29, vcc, 0, v145, vcc
	v_max_f32_e32 v16, 0, v16
	v_max_f32_e32 v17, 0, v17
	global_store_dwordx4 v[28:29], v[24:27], off
	v_max_f32_e32 v20, v20, v20
	v_max_f32_e32 v21, v21, v21
	v_pk_mul_f32 v[24:25], v[16:17], v[16:17]
	v_max_f32_e32 v17, v18, v18
	v_max_f32_e32 v16, v22, v22
	v_max_f32_e32 v18, 0, v17
	v_max_f32_e32 v17, v23, v23
	v_max_f32_e32 v19, v19, v19
	v_max_f32_e32 v20, 0, v20
	v_max_f32_e32 v21, 0, v21
	v_max_f32_e32 v16, 0, v16
	v_max_f32_e32 v17, 0, v17
	v_max_f32_e32 v19, 0, v19
	s_mov_b64 s[28:29], 0x280000
	v_pk_mul_f32 v[20:21], v[20:21], v[20:21]
	v_pk_mul_f32 v[22:23], v[16:17], v[16:17]
	v_pk_mul_f32 v[26:27], v[18:19], v[18:19]
	v_max_f32_e32 v8, v8, v8
	v_max_f32_e32 v9, v9, v9
	v_lshl_add_u64 v[32:33], v[144:145], 0, s[28:29]
	v_cvt_pk_bf16_f32 v16, v20, v21
	v_cvt_pk_bf16_f32 v17, v22, v23
	v_cvt_pk_bf16_f32 v18, v24, v25
	v_cvt_pk_bf16_f32 v19, v26, v27
	v_max_f32_e32 v8, 0, v8
	v_max_f32_e32 v9, 0, v9
	global_store_dwordx4 v[32:33], v[16:19], off offset:256
	v_max_f32_e32 v12, v12, v12
	v_max_f32_e32 v13, v13, v13
	v_pk_mul_f32 v[18:19], v[8:9], v[8:9]
	v_max_f32_e32 v9, v10, v10
	v_max_f32_e32 v12, 0, v12
	v_max_f32_e32 v13, 0, v13
	v_max_f32_e32 v8, v14, v14
	v_max_f32_e32 v10, 0, v9
	v_max_f32_e32 v9, v15, v15
	v_max_f32_e32 v11, v11, v11
	v_pk_mul_f32 v[12:13], v[12:13], v[12:13]
	v_max_f32_e32 v8, 0, v8
	v_max_f32_e32 v9, 0, v9
	v_max_f32_e32 v11, 0, v11
	v_pk_mul_f32 v[14:15], v[8:9], v[8:9]
	v_pk_mul_f32 v[20:21], v[10:11], v[10:11]
	v_cvt_pk_bf16_f32 v8, v12, v13
	v_add_co_u32_e32 v12, vcc, s50, v144
	v_max_f32_e32 v0, v0, v0
	v_max_f32_e32 v1, v1, v1
	v_cvt_pk_bf16_f32 v9, v14, v15
	v_cvt_pk_bf16_f32 v10, v18, v19
	v_cvt_pk_bf16_f32 v11, v20, v21
	v_addc_co_u32_e32 v13, vcc, 0, v145, vcc
	v_max_f32_e32 v0, 0, v0
	v_max_f32_e32 v1, 0, v1
	global_store_dwordx4 v[12:13], v[8:11], off
	v_max_f32_e32 v4, v4, v4
	v_max_f32_e32 v5, v5, v5
	v_pk_mul_f32 v[8:9], v[0:1], v[0:1]
	v_max_f32_e32 v1, v2, v2
	v_max_f32_e32 v0, v6, v6
	v_max_f32_e32 v2, 0, v1
	v_max_f32_e32 v1, v7, v7
	v_max_f32_e32 v3, v3, v3
	v_max_f32_e32 v4, 0, v4
	v_max_f32_e32 v5, 0, v5
	v_max_f32_e32 v0, 0, v0
	v_max_f32_e32 v1, 0, v1
	v_max_f32_e32 v3, 0, v3
	s_mov_b64 s[28:29], 0x2c0000
	v_pk_mul_f32 v[4:5], v[4:5], v[4:5]
	v_pk_mul_f32 v[6:7], v[0:1], v[0:1]
	v_pk_mul_f32 v[10:11], v[2:3], v[2:3]
	v_lshl_add_u64 v[16:17], v[144:145], 0, s[28:29]
	v_cvt_pk_bf16_f32 v0, v4, v5
	v_cvt_pk_bf16_f32 v1, v6, v7
	v_cvt_pk_bf16_f32 v2, v8, v9
	v_cvt_pk_bf16_f32 v3, v10, v11
	s_and_b64 vcc, exec, s[0:1]
	s_mov_b32 s51, s4
	s_mov_b32 s26, s6
	s_mov_b64 s[34:35], s[20:21]
	s_mov_b64 s[30:31], s[18:19]
	global_store_dwordx4 v[16:17], v[0:3], off offset:256
	s_cbranch_vccz .LBB0_584
	s_waitcnt vmcnt(0)
	s_cmpk_gt_u32 s33, 0xff
	s_cbranch_scc1 .LBB0_595
	s_barrier

; #define PG8_STAGE(bufoff, gbase, voff) do { _Pragma("unroll") for (int _i = 0; _i < 2; ++_i) \
;         __builtin_amdgcn_global_load_lds((const unsigned*)((const char*)(gbase) + (voff)[_i]), (LAS unsigned*)(lds + (bufoff) + ldsw + _i * 8192), 16, 0, 0); } while (0)
; #define PG8_LDA(dst, b, h) do { _Pragma("unroll") for (int m = 0; m < 4; ++m) _Pragma("unroll") for (int k = 0; k < 2; ++k) dst[m][k] = *(const LAS bf16x8*)(lds + PG8_SA(b, h) + aoff + m * 2048 + k * 1024); } while (0)
; #define PG8_LDB(dst, b, h) do { _Pragma("unroll") for (int n = 0; n < 2; ++n) _Pragma("unroll") for (int k = 0; k < 2; ++k) dst[n][k] = *(const LAS bf16x8*)(lds + PG8_SB(b, h) + boff + n * 2048 + k * 1024); } while (0)
; #define PG8_WAIT_V(n) asm volatile("s_waitcnt vmcnt(" #n ")" ::: "memory")
; #define PG8_WAIT_L(n) asm volatile("s_waitcnt lgkmcnt(" #n ")" ::: "memory")
; #define PG8_BAR __builtin_amdgcn_s_barrier()
; #define PG8_SCHED __builtin_amdgcn_sched_barrier(0)
; template <class Epi>
; __device__ __forceinline__ void gemm_phase(LAS unsigned char* lds, const bf16_t* A, int lda, const bf16_t* Bt, int ldb, int M, int N, int K, int asel, const Epi& E, const int fixed_round = -1) {
;     ...
;             PG8_LDB(B0, 0, 0); PG8_SCHED; PG8_LDA(At, 0, 0); PG8_STAGE(PG8_SA(1, 1), a1 + hstepA, voffA);
;             PG8_WAIT_L(8); PG8_BAR; PG8_WAIT_L(0); PG8_MMA(0, 0, At, B0); PG8_BAR; PG8_SCHED;
;             PG8_LDB(B1, 0, 1); PG8_STAGE(PG8_SB(0, 0), b2, voffB);
;             PG8_BAR; PG8_WAIT_L(0); PG8_MMA(0, 1, At, B1); PG8_BAR;
;             PG8_LDA(At, 0, 1); PG8_STAGE(PG8_SA(0, 0), a2, voffA);
;             PG8_BAR; PG8_WAIT_L(0); PG8_MMA(1, 0, At, B0); PG8_BAR; PG8_SCHED;
;             PG8_STAGE(PG8_SB(0, 1), b2 + hstepB, voffB);
;             PG8_WAIT_V(6); PG8_BAR; PG8_MMA(1, 1, At, B1); PG8_BAR;
.LBB0_651:
	s_add_u32 s28, s20, 0xe7900080
	ds_read_b128 v[146:149], v140
	ds_read_b128 v[150:153], v140 offset:1024
	ds_read_b128 v[160:163], v140 offset:2048
	ds_read_b128 v[166:169], v140 offset:3072
	s_addc_u32 s29, s21, -1
	s_cmpk_lg_i32 s48, 0x7c
	s_cselect_b32 s28, s28, 0
	s_cselect_b32 s29, s29, 0
	s_add_u32 s36, s86, s28
	s_addc_u32 s37, s87, s29
	s_add_u32 s34, s2, s28
	s_addc_u32 s35, s3, s29
	s_mov_b32 m0, s49
	v_lshl_add_u64 v[156:157], v[136:137], 0, s[20:21]
	ds_read_b128 v[170:173], v141
	ds_read_b128 v[174:177], v141 offset:1024
	ds_read_b128 v[178:181], v141 offset:2048
	ds_read_b128 v[182:185], v141 offset:3072
	ds_read_b128 v[186:189], v141 offset:4096
	ds_read_b128 v[190:193], v141 offset:5120
	ds_read_b128 v[194:197], v141 offset:6144
	ds_read_b128 v[202:205], v141 offset:7168
	global_load_lds_dwordx4 v[156:157], off
	v_lshl_add_u64 v[156:157], v[138:139], 0, s[20:21]
	s_mov_b32 m0, s50
	s_nop 0
	global_load_lds_dwordx4 v[156:157], off
	s_waitcnt lgkmcnt(8)
	s_barrier
	s_waitcnt lgkmcnt(0)
	s_setprio 1
	s_waitcnt lgkmcnt(0)
	v_mfma_f32_16x16x32_bf16 v[124:127], v[146:149], v[170:173], v[124:127]
	v_mfma_f32_16x16x32_bf16 v[120:123], v[160:163], v[170:173], v[120:123]
	v_mfma_f32_16x16x32_bf16 v[112:115], v[146:149], v[178:181], v[112:115]
	v_mfma_f32_16x16x32_bf16 v[104:107], v[160:163], v[178:181], v[104:107]
	v_mfma_f32_16x16x32_bf16 v[96:99], v[146:149], v[186:189], v[96:99]
	v_mfma_f32_16x16x32_bf16 v[88:91], v[160:163], v[186:189], v[88:91]
	v_mfma_f32_16x16x32_bf16 v[80:83], v[146:149], v[194:197], v[80:83]
	v_mfma_f32_16x16x32_bf16 v[72:75], v[160:163], v[194:197], v[72:75]
	v_mfma_f32_16x16x32_bf16 v[124:127], v[150:153], v[174:177], v[124:127]
	v_mfma_f32_16x16x32_bf16 v[120:123], v[166:169], v[174:177], v[120:123]
	v_mfma_f32_16x16x32_bf16 v[112:115], v[150:153], v[182:185], v[112:115]
	v_mfma_f32_16x16x32_bf16 v[104:107], v[166:169], v[182:185], v[104:107]
	v_mfma_f32_16x16x32_bf16 v[96:99], v[150:153], v[190:193], v[96:99]
	v_mfma_f32_16x16x32_bf16 v[88:91], v[166:169], v[190:193], v[88:91]
	v_mfma_f32_16x16x32_bf16 v[80:83], v[150:153], v[202:205], v[80:83]
	v_mfma_f32_16x16x32_bf16 v[72:75], v[166:169], v[202:205], v[72:75]
	s_setprio 0
	s_barrier
	s_mov_b32 m0, s51
	s_add_u32 s98, s34, s0
	s_addc_u32 s99, s35, s1
	ds_read_b128 v[206:209], v142
	ds_read_b128 v[210:213], v142 offset:1024
	ds_read_b128 v[214:217], v142 offset:2048
	ds_read_b128 v[218:221], v142 offset:3072
	global_load_lds_dwordx4 v130, s[34:35]
	s_mov_b32 m0, s52
	s_nop 0
	global_load_lds_dwordx4 v134, s[34:35]
	s_barrier
	s_waitcnt lgkmcnt(0)
	s_setprio 1
	s_waitcnt lgkmcnt(0)
	v_mfma_f32_16x16x32_bf16 v[116:119], v[206:209], v[170:173], v[116:119]
	v_mfma_f32_16x16x32_bf16 v[108:111], v[214:217], v[170:173], v[108:111]
	v_mfma_f32_16x16x32_bf16 v[100:103], v[206:209], v[178:181], v[100:103]
	v_mfma_f32_16x16x32_bf16 v[92:95], v[214:217], v[178:181], v[92:95]
	v_mfma_f32_16x16x32_bf16 v[84:87], v[206:209], v[186:189], v[84:87]
	v_mfma_f32_16x16x32_bf16 v[76:79], v[214:217], v[186:189], v[76:79]
	v_mfma_f32_16x16x32_bf16 v[68:71], v[206:209], v[194:197], v[68:71]
	v_mfma_f32_16x16x32_bf16 v[64:67], v[214:217], v[194:197], v[64:67]
	v_mfma_f32_16x16x32_bf16 v[116:119], v[210:213], v[174:177], v[116:119]
	v_mfma_f32_16x16x32_bf16 v[108:111], v[218:221], v[174:177], v[108:111]
	v_mfma_f32_16x16x32_bf16 v[100:103], v[210:213], v[182:185], v[100:103]
	v_mfma_f32_16x16x32_bf16 v[92:95], v[218:221], v[182:185], v[92:95]
	v_mfma_f32_16x16x32_bf16 v[84:87], v[210:213], v[190:193], v[84:87]
	v_mfma_f32_16x16x32_bf16 v[76:79], v[218:221], v[190:193], v[76:79]
	v_mfma_f32_16x16x32_bf16 v[68:71], v[210:213], v[202:205], v[68:71]
	v_mfma_f32_16x16x32_bf16 v[64:67], v[218:221], v[202:205], v[64:67]
	s_setprio 0
	s_mov_b32 m0, s42
	s_add_u32 s100, s36, s0
	s_addc_u32 s101, s37, s1
	s_barrier
	ds_read_b128 v[170:173], v141 offset:16384
	ds_read_b128 v[174:177], v141 offset:17408
	ds_read_b128 v[178:181], v141 offset:18432
	ds_read_b128 v[182:185], v141 offset:19456
	ds_read_b128 v[186:189], v141 offset:20480
	ds_read_b128 v[190:193], v141 offset:21504
	ds_read_b128 v[194:197], v141 offset:22528
	ds_read_b128 v[202:205], v141 offset:23552
	global_load_lds_dwordx4 v128, s[36:37]
	s_mov_b32 m0, s43
	s_nop 0
	global_load_lds_dwordx4 v132, s[36:37]
	s_barrier
	s_waitcnt lgkmcnt(0)
	s_setprio 1
	s_waitcnt lgkmcnt(0)
	v_mfma_f32_16x16x32_bf16 v[60:63], v[146:149], v[170:173], v[60:63]
	v_mfma_f32_16x16x32_bf16 v[56:59], v[160:163], v[170:173], v[56:59]
	v_mfma_f32_16x16x32_bf16 v[48:51], v[146:149], v[178:181], v[48:51]
	v_mfma_f32_16x16x32_bf16 v[40:43], v[160:163], v[178:181], v[40:43]
	v_mfma_f32_16x16x32_bf16 v[32:35], v[146:149], v[186:189], v[32:35]
	v_mfma_f32_16x16x32_bf16 v[24:27], v[160:163], v[186:189], v[24:27]
	v_mfma_f32_16x16x32_bf16 v[16:19], v[146:149], v[194:197], v[16:19]
	v_mfma_f32_16x16x32_bf16 v[8:11], v[160:163], v[194:197], v[8:11]
	v_mfma_f32_16x16x32_bf16 v[60:63], v[150:153], v[174:177], v[60:63]
	v_mfma_f32_16x16x32_bf16 v[56:59], v[166:169], v[174:177], v[56:59]
	v_mfma_f32_16x16x32_bf16 v[48:51], v[150:153], v[182:185], v[48:51]
	v_mfma_f32_16x16x32_bf16 v[40:43], v[166:169], v[182:185], v[40:43]
	v_mfma_f32_16x16x32_bf16 v[32:35], v[150:153], v[190:193], v[32:35]
	v_mfma_f32_16x16x32_bf16 v[24:27], v[166:169], v[190:193], v[24:27]
	v_mfma_f32_16x16x32_bf16 v[16:19], v[150:153], v[202:205], v[16:19]
	v_mfma_f32_16x16x32_bf16 v[8:11], v[166:169], v[202:205], v[8:11]
	s_setprio 0
	s_barrier
	s_add_u32 s28, s34, 0x200000
	s_addc_u32 s29, s35, 0
	s_mov_b32 m0, s53
	s_nop 0
	global_load_lds_dwordx4 v130, s[28:29]
	s_mov_b32 m0, s54
	s_nop 0
	global_load_lds_dwordx4 v134, s[28:29]
	s_waitcnt vmcnt(6)
	s_barrier
; #define PG8_STAGE(bufoff, gbase, voff) do { _Pragma("unroll") for (int _i = 0; _i < 2; ++_i) \
;         __builtin_amdgcn_global_load_lds((const unsigned*)((const char*)(gbase) + (voff)[_i]), (LAS unsigned*)(lds + (bufoff) + ldsw + _i * 8192), 16, 0, 0); } while (0)
; #define PG8_LDA(dst, b, h) do { _Pragma("unroll") for (int m = 0; m < 4; ++m) _Pragma("unroll") for (int k = 0; k < 2; ++k) dst[m][k] = *(const LAS bf16x8*)(lds + PG8_SA(b, h) + aoff + m * 2048 + k * 1024); } while (0)
; #define PG8_LDB(dst, b, h) do { _Pragma("unroll") for (int n = 0; n < 2; ++n) _Pragma("unroll") for (int k = 0; k < 2; ++k) dst[n][k] = *(const LAS bf16x8*)(lds + PG8_SB(b, h) + boff + n * 2048 + k * 1024); } while (0)
; #define PG8_WAIT_V(n) asm volatile("s_waitcnt vmcnt(" #n ")" ::: "memory")
; #define PG8_WAIT_L(n) asm volatile("s_waitcnt lgkmcnt(" #n ")" ::: "memory")
; #define PG8_BAR __builtin_amdgcn_s_barrier()
; #define PG8_SCHED __builtin_amdgcn_sched_barrier(0)
; template <class Epi>
; __device__ __forceinline__ void gemm_phase(LAS unsigned char* lds, const bf16_t* A, int lda, const bf16_t* Bt, int ldb, int M, int N, int K, int asel, const Epi& E, const int fixed_round = -1) {
;     ...
;             PG8_WAIT_V(6); PG8_BAR; PG8_MMA(1, 1, At, B1); PG8_BAR;
;             PG8_LDB(B0, 1, 0); PG8_SCHED; PG8_LDA(At, 1, 0); PG8_STAGE(PG8_SA(0, 1), a2 + hstepA, voffA);
;             PG8_WAIT_L(8); PG8_BAR; PG8_WAIT_L(0); PG8_MMA(0, 0, At, B0); PG8_BAR; PG8_SCHED;
;             PG8_LDB(B1, 1, 1); PG8_STAGE(PG8_SB(1, 0), b3, voffB);
;             PG8_BAR; PG8_WAIT_L(0); PG8_MMA(0, 1, At, B1); PG8_BAR;
	s_setprio 1
	v_mfma_f32_16x16x32_bf16 v[52:55], v[206:209], v[170:173], v[52:55]
	v_mfma_f32_16x16x32_bf16 v[44:47], v[214:217], v[170:173], v[44:47]
	v_mfma_f32_16x16x32_bf16 v[36:39], v[206:209], v[178:181], v[36:39]
	v_mfma_f32_16x16x32_bf16 v[28:31], v[214:217], v[178:181], v[28:31]
	v_mfma_f32_16x16x32_bf16 v[20:23], v[206:209], v[186:189], v[20:23]
	v_mfma_f32_16x16x32_bf16 v[12:15], v[214:217], v[186:189], v[12:15]
	v_mfma_f32_16x16x32_bf16 v[4:7], v[206:209], v[194:197], v[4:7]
	v_mfma_f32_16x16x32_bf16 v[0:3], v[214:217], v[194:197], v[0:3]
	v_mfma_f32_16x16x32_bf16 v[52:55], v[210:213], v[174:177], v[52:55]
	v_mfma_f32_16x16x32_bf16 v[44:47], v[218:221], v[174:177], v[44:47]
	v_mfma_f32_16x16x32_bf16 v[36:39], v[210:213], v[182:185], v[36:39]
	v_mfma_f32_16x16x32_bf16 v[28:31], v[218:221], v[182:185], v[28:31]
	v_mfma_f32_16x16x32_bf16 v[20:23], v[210:213], v[190:193], v[20:23]
	v_mfma_f32_16x16x32_bf16 v[12:15], v[218:221], v[190:193], v[12:15]
	v_mfma_f32_16x16x32_bf16 v[4:7], v[210:213], v[202:205], v[4:7]
	v_mfma_f32_16x16x32_bf16 v[0:3], v[218:221], v[202:205], v[0:3]
	s_setprio 0
	s_barrier
	ds_read_b128 v[146:149], v143
	ds_read_b128 v[150:153], v143 offset:1024
	ds_read_b128 v[160:163], v143 offset:2048
	ds_read_b128 v[166:169], v143 offset:3072
	s_add_u32 s28, s36, 0x200000
	s_addc_u32 s29, s37, 0
	s_mov_b32 m0, s44
	ds_read_b128 v[170:173], v141 offset:32768
	ds_read_b128 v[174:177], v141 offset:33792
	ds_read_b128 v[178:181], v141 offset:34816
	ds_read_b128 v[182:185], v141 offset:35840
	ds_read_b128 v[186:189], v141 offset:36864
	ds_read_b128 v[190:193], v141 offset:37888
	ds_read_b128 v[194:197], v141 offset:38912
	ds_read_b128 v[202:205], v141 offset:39936
	global_load_lds_dwordx4 v128, s[28:29]
	s_mov_b32 m0, s45
	s_nop 0
	global_load_lds_dwordx4 v132, s[28:29]
	s_waitcnt lgkmcnt(8)
	s_barrier
	s_waitcnt lgkmcnt(0)
	s_setprio 1
	s_waitcnt lgkmcnt(0)
	v_mfma_f32_16x16x32_bf16 v[124:127], v[146:149], v[170:173], v[124:127]
	v_mfma_f32_16x16x32_bf16 v[120:123], v[160:163], v[170:173], v[120:123]
	v_mfma_f32_16x16x32_bf16 v[112:115], v[146:149], v[178:181], v[112:115]
	v_mfma_f32_16x16x32_bf16 v[104:107], v[160:163], v[178:181], v[104:107]
	v_mfma_f32_16x16x32_bf16 v[96:99], v[146:149], v[186:189], v[96:99]
	v_mfma_f32_16x16x32_bf16 v[88:91], v[160:163], v[186:189], v[88:91]
	v_mfma_f32_16x16x32_bf16 v[80:83], v[146:149], v[194:197], v[80:83]
	v_mfma_f32_16x16x32_bf16 v[72:75], v[160:163], v[194:197], v[72:75]
	v_mfma_f32_16x16x32_bf16 v[124:127], v[150:153], v[174:177], v[124:127]
	v_mfma_f32_16x16x32_bf16 v[120:123], v[166:169], v[174:177], v[120:123]
	v_mfma_f32_16x16x32_bf16 v[112:115], v[150:153], v[182:185], v[112:115]
	v_mfma_f32_16x16x32_bf16 v[104:107], v[166:169], v[182:185], v[104:107]
	v_mfma_f32_16x16x32_bf16 v[96:99], v[150:153], v[190:193], v[96:99]
	v_mfma_f32_16x16x32_bf16 v[88:91], v[166:169], v[190:193], v[88:91]
	v_mfma_f32_16x16x32_bf16 v[80:83], v[150:153], v[202:205], v[80:83]
	v_mfma_f32_16x16x32_bf16 v[72:75], v[166:169], v[202:205], v[72:75]
	s_setprio 0
	s_barrier
	s_mov_b32 m0, s55
	ds_read_b128 v[206:209], v144
	ds_read_b128 v[210:213], v144 offset:1024
	ds_read_b128 v[214:217], v144 offset:2048
	ds_read_b128 v[218:221], v144 offset:3072
	global_load_lds_dwordx4 v130, s[98:99]
	s_mov_b32 m0, s56
	s_nop 0
	global_load_lds_dwordx4 v134, s[98:99]
	s_barrier
; #define PG8_STAGE(bufoff, gbase, voff) do { _Pragma("unroll") for (int _i = 0; _i < 2; ++_i) \
;         __builtin_amdgcn_global_load_lds((const unsigned*)((const char*)(gbase) + (voff)[_i]), (LAS unsigned*)(lds + (bufoff) + ldsw + _i * 8192), 16, 0, 0); } while (0)
; #define PG8_LDA(dst, b, h) do { _Pragma("unroll") for (int m = 0; m < 4; ++m) _Pragma("unroll") for (int k = 0; k < 2; ++k) dst[m][k] = *(const LAS bf16x8*)(lds + PG8_SA(b, h) + aoff + m * 2048 + k * 1024); } while (0)
; #define PG8_WAIT_V(n) asm volatile("s_waitcnt vmcnt(" #n ")" ::: "memory")
; #define PG8_WAIT_L(n) asm volatile("s_waitcnt lgkmcnt(" #n ")" ::: "memory")
; #define PG8_BAR __builtin_amdgcn_s_barrier()
; #define PG8_SCHED __builtin_amdgcn_sched_barrier(0)
; template <class Epi>
; __device__ __forceinline__ void gemm_phase(LAS unsigned char* lds, const bf16_t* A, int lda, const bf16_t* Bt, int ldb, int M, int N, int K, int asel, const Epi& E, const int fixed_round = -1) {
;     ...
;             PG8_BAR; PG8_WAIT_L(0); PG8_MMA(0, 1, At, B1); PG8_BAR;
;             PG8_LDA(At, 1, 1); PG8_STAGE(PG8_SA(1, 0), a3, voffA);
;             PG8_BAR; PG8_WAIT_L(0); PG8_MMA(1, 0, At, B0); PG8_BAR; PG8_SCHED;
;             PG8_STAGE(PG8_SB(1, 1), b3 + hstepB, voffB);
;             PG8_WAIT_V(6); PG8_BAR; PG8_MMA(1, 1, At, B1); PG8_BAR;
;     ...
;     PG8_WAIT_V(0);
;     if (wr == 0) PG8_BAR;
;     PG8_BAR;
	s_waitcnt lgkmcnt(0)
	s_setprio 1
	s_waitcnt lgkmcnt(0)
	v_mfma_f32_16x16x32_bf16 v[116:119], v[206:209], v[170:173], v[116:119]
	v_mfma_f32_16x16x32_bf16 v[108:111], v[214:217], v[170:173], v[108:111]
	v_mfma_f32_16x16x32_bf16 v[100:103], v[206:209], v[178:181], v[100:103]
	v_mfma_f32_16x16x32_bf16 v[92:95], v[214:217], v[178:181], v[92:95]
	v_mfma_f32_16x16x32_bf16 v[84:87], v[206:209], v[186:189], v[84:87]
	v_mfma_f32_16x16x32_bf16 v[76:79], v[214:217], v[186:189], v[76:79]
	v_mfma_f32_16x16x32_bf16 v[68:71], v[206:209], v[194:197], v[68:71]
	v_mfma_f32_16x16x32_bf16 v[64:67], v[214:217], v[194:197], v[64:67]
	v_mfma_f32_16x16x32_bf16 v[116:119], v[210:213], v[174:177], v[116:119]
	v_mfma_f32_16x16x32_bf16 v[108:111], v[218:221], v[174:177], v[108:111]
	v_mfma_f32_16x16x32_bf16 v[100:103], v[210:213], v[182:185], v[100:103]
	v_mfma_f32_16x16x32_bf16 v[92:95], v[218:221], v[182:185], v[92:95]
	v_mfma_f32_16x16x32_bf16 v[84:87], v[210:213], v[190:193], v[84:87]
	v_mfma_f32_16x16x32_bf16 v[76:79], v[218:221], v[190:193], v[76:79]
	v_mfma_f32_16x16x32_bf16 v[68:71], v[210:213], v[202:205], v[68:71]
	v_mfma_f32_16x16x32_bf16 v[64:67], v[218:221], v[202:205], v[64:67]
	s_setprio 0
	s_mov_b32 m0, s46
	s_barrier
	ds_read_b128 v[170:173], v141 offset:49152
	ds_read_b128 v[174:177], v141 offset:50176
	ds_read_b128 v[178:181], v141 offset:51200
	ds_read_b128 v[182:185], v141 offset:52224
	ds_read_b128 v[186:189], v141 offset:53248
	ds_read_b128 v[190:193], v141 offset:54272
	ds_read_b128 v[194:197], v141 offset:55296
	ds_read_b128 v[202:205], v141 offset:56320
	global_load_lds_dwordx4 v128, s[100:101]
	s_mov_b32 m0, s47
	s_nop 0
	global_load_lds_dwordx4 v132, s[100:101]
	s_barrier
	s_waitcnt lgkmcnt(0)
	s_setprio 1
	s_waitcnt lgkmcnt(0)
	v_mfma_f32_16x16x32_bf16 v[60:63], v[146:149], v[170:173], v[60:63]
	v_mfma_f32_16x16x32_bf16 v[56:59], v[160:163], v[170:173], v[56:59]
	v_mfma_f32_16x16x32_bf16 v[48:51], v[146:149], v[178:181], v[48:51]
	v_mfma_f32_16x16x32_bf16 v[40:43], v[160:163], v[178:181], v[40:43]
	v_mfma_f32_16x16x32_bf16 v[32:35], v[146:149], v[186:189], v[32:35]
	v_mfma_f32_16x16x32_bf16 v[24:27], v[160:163], v[186:189], v[24:27]
	v_mfma_f32_16x16x32_bf16 v[16:19], v[146:149], v[194:197], v[16:19]
	v_mfma_f32_16x16x32_bf16 v[8:11], v[160:163], v[194:197], v[8:11]
	v_mfma_f32_16x16x32_bf16 v[60:63], v[150:153], v[174:177], v[60:63]
	v_mfma_f32_16x16x32_bf16 v[56:59], v[166:169], v[174:177], v[56:59]
	v_mfma_f32_16x16x32_bf16 v[48:51], v[150:153], v[182:185], v[48:51]
	v_mfma_f32_16x16x32_bf16 v[40:43], v[166:169], v[182:185], v[40:43]
	v_mfma_f32_16x16x32_bf16 v[32:35], v[150:153], v[190:193], v[32:35]
	v_mfma_f32_16x16x32_bf16 v[24:27], v[166:169], v[190:193], v[24:27]
	v_mfma_f32_16x16x32_bf16 v[16:19], v[150:153], v[202:205], v[16:19]
	v_mfma_f32_16x16x32_bf16 v[8:11], v[166:169], v[202:205], v[8:11]
	s_setprio 0
	s_barrier
	s_add_u32 s28, s34, 0x200080
	s_addc_u32 s29, s35, 0
	s_mov_b32 m0, s57
	s_nop 0
	global_load_lds_dwordx4 v130, s[28:29]
	s_mov_b32 m0, s58
	s_nop 0
	global_load_lds_dwordx4 v134, s[28:29]
	s_waitcnt vmcnt(6)
	s_barrier
	s_setprio 1
	v_mfma_f32_16x16x32_bf16 v[52:55], v[206:209], v[170:173], v[52:55]
	v_mfma_f32_16x16x32_bf16 v[44:47], v[214:217], v[170:173], v[44:47]
	v_mfma_f32_16x16x32_bf16 v[36:39], v[206:209], v[178:181], v[36:39]
	v_mfma_f32_16x16x32_bf16 v[28:31], v[214:217], v[178:181], v[28:31]
	v_mfma_f32_16x16x32_bf16 v[20:23], v[206:209], v[186:189], v[20:23]
	v_mfma_f32_16x16x32_bf16 v[12:15], v[214:217], v[186:189], v[12:15]
	v_mfma_f32_16x16x32_bf16 v[4:7], v[206:209], v[194:197], v[4:7]
	v_mfma_f32_16x16x32_bf16 v[0:3], v[214:217], v[194:197], v[0:3]
	v_mfma_f32_16x16x32_bf16 v[52:55], v[210:213], v[174:177], v[52:55]
	v_mfma_f32_16x16x32_bf16 v[44:47], v[218:221], v[174:177], v[44:47]
	v_mfma_f32_16x16x32_bf16 v[36:39], v[210:213], v[182:185], v[36:39]
	v_mfma_f32_16x16x32_bf16 v[28:31], v[218:221], v[182:185], v[28:31]
	v_mfma_f32_16x16x32_bf16 v[20:23], v[210:213], v[190:193], v[20:23]
	v_mfma_f32_16x16x32_bf16 v[12:15], v[218:221], v[190:193], v[12:15]
	v_mfma_f32_16x16x32_bf16 v[4:7], v[210:213], v[202:205], v[4:7]
	v_mfma_f32_16x16x32_bf16 v[0:3], v[218:221], v[202:205], v[0:3]
	s_setprio 0
	s_add_i32 s48, s48, 2
	s_add_u32 s20, s20, 0x100
	s_addc_u32 s21, s21, 0
	s_cmpk_lt_u32 s48, 0x7e
	s_barrier
	s_cbranch_scc1 .LBB0_651
	s_waitcnt vmcnt(0)
	v_writelane_b32 v255, s8, 26
	s_cmpk_gt_u32 s41, 0xff
	s_nop 0
	v_writelane_b32 v255, s9, 27
	s_cbranch_scc1 .LBB0_654
	s_barrier

; #define PG8_STAGE(bufoff, gbase, voff) do { _Pragma("unroll") for (int _i = 0; _i < 2; ++_i) \
;         __builtin_amdgcn_global_load_lds((const unsigned*)((const char*)(gbase) + (voff)[_i]), (LAS unsigned*)(lds + (bufoff) + ldsw + _i * 8192), 16, 0, 0); } while (0)
; #define PG8_LDA(dst, b, h) do { _Pragma("unroll") for (int m = 0; m < 4; ++m) _Pragma("unroll") for (int k = 0; k < 2; ++k) dst[m][k] = *(const LAS bf16x8*)(lds + PG8_SA(b, h) + aoff + m * 2048 + k * 1024); } while (0)
; #define PG8_LDB(dst, b, h) do { _Pragma("unroll") for (int n = 0; n < 2; ++n) _Pragma("unroll") for (int k = 0; k < 2; ++k) dst[n][k] = *(const LAS bf16x8*)(lds + PG8_SB(b, h) + boff + n * 2048 + k * 1024); } while (0)
; #define PG8_WAIT_V(n) asm volatile("s_waitcnt vmcnt(" #n ")" ::: "memory")
; #define PG8_WAIT_L(n) asm volatile("s_waitcnt lgkmcnt(" #n ")" ::: "memory")
; #define PG8_BAR __builtin_amdgcn_s_barrier()
; #define PG8_SCHED __builtin_amdgcn_sched_barrier(0)
; template <class Epi>
; __device__ __forceinline__ void gemm_phase(LAS unsigned char* lds, const bf16_t* A, int lda, const bf16_t* Bt, int ldb, int M, int N, int K, int asel, const Epi& E, const int fixed_round = -1) {
;     ...
;             PG8_LDB(B0, 0, 0); PG8_SCHED; PG8_LDA(At, 0, 0); PG8_STAGE(PG8_SA(1, 1), a1 + hstepA, voffA);
;             PG8_WAIT_L(8); PG8_BAR; PG8_WAIT_L(0); PG8_MMA(0, 0, At, B0); PG8_BAR; PG8_SCHED;
;             PG8_LDB(B1, 0, 1); PG8_STAGE(PG8_SB(0, 0), b2, voffB);
;             PG8_BAR; PG8_WAIT_L(0); PG8_MMA(0, 1, At, B1); PG8_BAR;
;             PG8_LDA(At, 0, 1); PG8_STAGE(PG8_SA(0, 0), a2, voffA);
;             PG8_BAR; PG8_WAIT_L(0); PG8_MMA(1, 0, At, B0); PG8_BAR; PG8_SCHED;
;             PG8_STAGE(PG8_SB(0, 1), b2 + hstepB, voffB);
;             PG8_WAIT_V(6); PG8_BAR; PG8_MMA(1, 1, At, B1); PG8_BAR;
.LBB0_690:
	s_add_u32 s6, s4, 0xe7900080
	ds_read_b128 v[146:149], v138
	ds_read_b128 v[150:153], v138 offset:1024
	ds_read_b128 v[160:163], v138 offset:2048
	ds_read_b128 v[166:169], v138 offset:3072
	s_addc_u32 s7, s5, -1
	s_cmpk_lg_i32 s58, 0x7c
	s_cselect_b32 s6, s6, 0
	s_cselect_b32 s7, s7, 0
	s_add_u32 s40, s8, s6
	s_addc_u32 s41, s9, s7
	s_add_u32 s6, s2, s6
	s_addc_u32 s7, s3, s7
	s_mov_b32 m0, s59
	v_lshl_add_u64 v[156:157], v[134:135], 0, s[4:5]
	ds_read_b128 v[170:173], v139
	ds_read_b128 v[174:177], v139 offset:1024
	ds_read_b128 v[178:181], v139 offset:2048
	ds_read_b128 v[182:185], v139 offset:3072
	ds_read_b128 v[186:189], v139 offset:4096
	ds_read_b128 v[190:193], v139 offset:5120
	ds_read_b128 v[194:197], v139 offset:6144
	ds_read_b128 v[202:205], v139 offset:7168
	global_load_lds_dwordx4 v[156:157], off
	v_lshl_add_u64 v[156:157], v[136:137], 0, s[4:5]
	s_mov_b32 m0, s60
	s_nop 0
	global_load_lds_dwordx4 v[156:157], off
	s_waitcnt lgkmcnt(8)
	s_barrier
	s_waitcnt lgkmcnt(0)
	s_setprio 1
	s_waitcnt lgkmcnt(0)
	v_mfma_f32_16x16x32_bf16 v[124:127], v[146:149], v[170:173], v[124:127]
	v_mfma_f32_16x16x32_bf16 v[120:123], v[160:163], v[170:173], v[120:123]
	v_mfma_f32_16x16x32_bf16 v[112:115], v[146:149], v[178:181], v[112:115]
	v_mfma_f32_16x16x32_bf16 v[104:107], v[160:163], v[178:181], v[104:107]
	v_mfma_f32_16x16x32_bf16 v[96:99], v[146:149], v[186:189], v[96:99]
	v_mfma_f32_16x16x32_bf16 v[88:91], v[160:163], v[186:189], v[88:91]
	v_mfma_f32_16x16x32_bf16 v[80:83], v[146:149], v[194:197], v[80:83]
	v_mfma_f32_16x16x32_bf16 v[72:75], v[160:163], v[194:197], v[72:75]
	v_mfma_f32_16x16x32_bf16 v[124:127], v[150:153], v[174:177], v[124:127]
	v_mfma_f32_16x16x32_bf16 v[120:123], v[166:169], v[174:177], v[120:123]
	v_mfma_f32_16x16x32_bf16 v[112:115], v[150:153], v[182:185], v[112:115]
	v_mfma_f32_16x16x32_bf16 v[104:107], v[166:169], v[182:185], v[104:107]
	v_mfma_f32_16x16x32_bf16 v[96:99], v[150:153], v[190:193], v[96:99]
	v_mfma_f32_16x16x32_bf16 v[88:91], v[166:169], v[190:193], v[88:91]
	v_mfma_f32_16x16x32_bf16 v[80:83], v[150:153], v[202:205], v[80:83]
	v_mfma_f32_16x16x32_bf16 v[72:75], v[166:169], v[202:205], v[72:75]
	s_setprio 0
	s_barrier
	s_mov_b32 m0, s61
	s_add_u32 s98, s6, s0
	s_addc_u32 s99, s7, s1
	ds_read_b128 v[206:209], v140
	ds_read_b128 v[210:213], v140 offset:1024
	ds_read_b128 v[214:217], v140 offset:2048
	ds_read_b128 v[218:221], v140 offset:3072
	global_load_lds_dwordx4 v144, s[6:7]
	s_mov_b32 m0, s62
	s_nop 0
	global_load_lds_dwordx4 v132, s[6:7]
	s_barrier
	s_waitcnt lgkmcnt(0)
	s_setprio 1
	s_waitcnt lgkmcnt(0)
	v_mfma_f32_16x16x32_bf16 v[116:119], v[206:209], v[170:173], v[116:119]
	v_mfma_f32_16x16x32_bf16 v[108:111], v[214:217], v[170:173], v[108:111]
	v_mfma_f32_16x16x32_bf16 v[100:103], v[206:209], v[178:181], v[100:103]
	v_mfma_f32_16x16x32_bf16 v[92:95], v[214:217], v[178:181], v[92:95]
	v_mfma_f32_16x16x32_bf16 v[84:87], v[206:209], v[186:189], v[84:87]
	v_mfma_f32_16x16x32_bf16 v[76:79], v[214:217], v[186:189], v[76:79]
	v_mfma_f32_16x16x32_bf16 v[68:71], v[206:209], v[194:197], v[68:71]
	v_mfma_f32_16x16x32_bf16 v[64:67], v[214:217], v[194:197], v[64:67]
	v_mfma_f32_16x16x32_bf16 v[116:119], v[210:213], v[174:177], v[116:119]
	v_mfma_f32_16x16x32_bf16 v[108:111], v[218:221], v[174:177], v[108:111]
	v_mfma_f32_16x16x32_bf16 v[100:103], v[210:213], v[182:185], v[100:103]
	v_mfma_f32_16x16x32_bf16 v[92:95], v[218:221], v[182:185], v[92:95]
	v_mfma_f32_16x16x32_bf16 v[84:87], v[210:213], v[190:193], v[84:87]
	v_mfma_f32_16x16x32_bf16 v[76:79], v[218:221], v[190:193], v[76:79]
	v_mfma_f32_16x16x32_bf16 v[68:71], v[210:213], v[202:205], v[68:71]
	v_mfma_f32_16x16x32_bf16 v[64:67], v[218:221], v[202:205], v[64:67]
	s_setprio 0
	s_mov_b32 m0, s52
	s_add_u32 s100, s40, s0
	s_addc_u32 s101, s41, s1
	s_barrier
	ds_read_b128 v[170:173], v139 offset:16384
	ds_read_b128 v[174:177], v139 offset:17408
	ds_read_b128 v[178:181], v139 offset:18432
	ds_read_b128 v[182:185], v139 offset:19456
	ds_read_b128 v[186:189], v139 offset:20480
	ds_read_b128 v[190:193], v139 offset:21504
	ds_read_b128 v[194:197], v139 offset:22528
	ds_read_b128 v[202:205], v139 offset:23552
	global_load_lds_dwordx4 v128, s[40:41]
	s_mov_b32 m0, s53
	s_nop 0
	global_load_lds_dwordx4 v130, s[40:41]
	s_barrier
	s_waitcnt lgkmcnt(0)
	s_setprio 1
	s_waitcnt lgkmcnt(0)
	v_mfma_f32_16x16x32_bf16 v[60:63], v[146:149], v[170:173], v[60:63]
	v_mfma_f32_16x16x32_bf16 v[56:59], v[160:163], v[170:173], v[56:59]
	v_mfma_f32_16x16x32_bf16 v[48:51], v[146:149], v[178:181], v[48:51]
	v_mfma_f32_16x16x32_bf16 v[40:43], v[160:163], v[178:181], v[40:43]
	v_mfma_f32_16x16x32_bf16 v[32:35], v[146:149], v[186:189], v[32:35]
	v_mfma_f32_16x16x32_bf16 v[24:27], v[160:163], v[186:189], v[24:27]
	v_mfma_f32_16x16x32_bf16 v[16:19], v[146:149], v[194:197], v[16:19]
	v_mfma_f32_16x16x32_bf16 v[8:11], v[160:163], v[194:197], v[8:11]
	v_mfma_f32_16x16x32_bf16 v[60:63], v[150:153], v[174:177], v[60:63]
	v_mfma_f32_16x16x32_bf16 v[56:59], v[166:169], v[174:177], v[56:59]
	v_mfma_f32_16x16x32_bf16 v[48:51], v[150:153], v[182:185], v[48:51]
	v_mfma_f32_16x16x32_bf16 v[40:43], v[166:169], v[182:185], v[40:43]
	v_mfma_f32_16x16x32_bf16 v[32:35], v[150:153], v[190:193], v[32:35]
	v_mfma_f32_16x16x32_bf16 v[24:27], v[166:169], v[190:193], v[24:27]
	v_mfma_f32_16x16x32_bf16 v[16:19], v[150:153], v[202:205], v[16:19]
	v_mfma_f32_16x16x32_bf16 v[8:11], v[166:169], v[202:205], v[8:11]
	s_setprio 0
	s_barrier
	s_add_u32 s28, s6, 0x200000
	s_addc_u32 s29, s7, 0
	s_mov_b32 m0, s63
	s_nop 0
	global_load_lds_dwordx4 v144, s[28:29]
	s_mov_b32 m0, s64
	s_nop 0
	global_load_lds_dwordx4 v132, s[28:29]
	s_waitcnt vmcnt(6)
	s_barrier
; #define PG8_STAGE(bufoff, gbase, voff) do { _Pragma("unroll") for (int _i = 0; _i < 2; ++_i) \
;         __builtin_amdgcn_global_load_lds((const unsigned*)((const char*)(gbase) + (voff)[_i]), (LAS unsigned*)(lds + (bufoff) + ldsw + _i * 8192), 16, 0, 0); } while (0)
; #define PG8_LDA(dst, b, h) do { _Pragma("unroll") for (int m = 0; m < 4; ++m) _Pragma("unroll") for (int k = 0; k < 2; ++k) dst[m][k] = *(const LAS bf16x8*)(lds + PG8_SA(b, h) + aoff + m * 2048 + k * 1024); } while (0)
; #define PG8_LDB(dst, b, h) do { _Pragma("unroll") for (int n = 0; n < 2; ++n) _Pragma("unroll") for (int k = 0; k < 2; ++k) dst[n][k] = *(const LAS bf16x8*)(lds + PG8_SB(b, h) + boff + n * 2048 + k * 1024); } while (0)
; #define PG8_WAIT_V(n) asm volatile("s_waitcnt vmcnt(" #n ")" ::: "memory")
; #define PG8_WAIT_L(n) asm volatile("s_waitcnt lgkmcnt(" #n ")" ::: "memory")
; #define PG8_BAR __builtin_amdgcn_s_barrier()
; #define PG8_SCHED __builtin_amdgcn_sched_barrier(0)
; template <class Epi>
; __device__ __forceinline__ void gemm_phase(LAS unsigned char* lds, const bf16_t* A, int lda, const bf16_t* Bt, int ldb, int M, int N, int K, int asel, const Epi& E, const int fixed_round = -1) {
;     ...
;             PG8_WAIT_V(6); PG8_BAR; PG8_MMA(1, 1, At, B1); PG8_BAR;
;             PG8_LDB(B0, 1, 0); PG8_SCHED; PG8_LDA(At, 1, 0); PG8_STAGE(PG8_SA(0, 1), a2 + hstepA, voffA);
;             PG8_WAIT_L(8); PG8_BAR; PG8_WAIT_L(0); PG8_MMA(0, 0, At, B0); PG8_BAR; PG8_SCHED;
;             PG8_LDB(B1, 1, 1); PG8_STAGE(PG8_SB(1, 0), b3, voffB);
;             PG8_BAR; PG8_WAIT_L(0); PG8_MMA(0, 1, At, B1); PG8_BAR;
	s_setprio 1
	v_mfma_f32_16x16x32_bf16 v[52:55], v[206:209], v[170:173], v[52:55]
	v_mfma_f32_16x16x32_bf16 v[44:47], v[214:217], v[170:173], v[44:47]
	v_mfma_f32_16x16x32_bf16 v[36:39], v[206:209], v[178:181], v[36:39]
	v_mfma_f32_16x16x32_bf16 v[28:31], v[214:217], v[178:181], v[28:31]
	v_mfma_f32_16x16x32_bf16 v[20:23], v[206:209], v[186:189], v[20:23]
	v_mfma_f32_16x16x32_bf16 v[12:15], v[214:217], v[186:189], v[12:15]
	v_mfma_f32_16x16x32_bf16 v[4:7], v[206:209], v[194:197], v[4:7]
	v_mfma_f32_16x16x32_bf16 v[0:3], v[214:217], v[194:197], v[0:3]
	v_mfma_f32_16x16x32_bf16 v[52:55], v[210:213], v[174:177], v[52:55]
	v_mfma_f32_16x16x32_bf16 v[44:47], v[218:221], v[174:177], v[44:47]
	v_mfma_f32_16x16x32_bf16 v[36:39], v[210:213], v[182:185], v[36:39]
	v_mfma_f32_16x16x32_bf16 v[28:31], v[218:221], v[182:185], v[28:31]
	v_mfma_f32_16x16x32_bf16 v[20:23], v[210:213], v[190:193], v[20:23]
	v_mfma_f32_16x16x32_bf16 v[12:15], v[218:221], v[190:193], v[12:15]
	v_mfma_f32_16x16x32_bf16 v[4:7], v[210:213], v[202:205], v[4:7]
	v_mfma_f32_16x16x32_bf16 v[0:3], v[218:221], v[202:205], v[0:3]
	s_setprio 0
	s_barrier
	ds_read_b128 v[146:149], v141
	ds_read_b128 v[150:153], v141 offset:1024
	ds_read_b128 v[160:163], v141 offset:2048
	ds_read_b128 v[166:169], v141 offset:3072
	s_add_u32 s28, s40, 0x200000
	s_addc_u32 s29, s41, 0
	s_mov_b32 m0, s54
	ds_read_b128 v[170:173], v139 offset:32768
	ds_read_b128 v[174:177], v139 offset:33792
	ds_read_b128 v[178:181], v139 offset:34816
	ds_read_b128 v[182:185], v139 offset:35840
	ds_read_b128 v[186:189], v139 offset:36864
	ds_read_b128 v[190:193], v139 offset:37888
	ds_read_b128 v[194:197], v139 offset:38912
	ds_read_b128 v[202:205], v139 offset:39936
	global_load_lds_dwordx4 v128, s[28:29]
	s_mov_b32 m0, s55
	s_nop 0
	global_load_lds_dwordx4 v130, s[28:29]
	s_waitcnt lgkmcnt(8)
	s_barrier
	s_waitcnt lgkmcnt(0)
	s_setprio 1
	s_waitcnt lgkmcnt(0)
	v_mfma_f32_16x16x32_bf16 v[124:127], v[146:149], v[170:173], v[124:127]
	v_mfma_f32_16x16x32_bf16 v[120:123], v[160:163], v[170:173], v[120:123]
	v_mfma_f32_16x16x32_bf16 v[112:115], v[146:149], v[178:181], v[112:115]
	v_mfma_f32_16x16x32_bf16 v[104:107], v[160:163], v[178:181], v[104:107]
	v_mfma_f32_16x16x32_bf16 v[96:99], v[146:149], v[186:189], v[96:99]
	v_mfma_f32_16x16x32_bf16 v[88:91], v[160:163], v[186:189], v[88:91]
	v_mfma_f32_16x16x32_bf16 v[80:83], v[146:149], v[194:197], v[80:83]
	v_mfma_f32_16x16x32_bf16 v[72:75], v[160:163], v[194:197], v[72:75]
	v_mfma_f32_16x16x32_bf16 v[124:127], v[150:153], v[174:177], v[124:127]
	v_mfma_f32_16x16x32_bf16 v[120:123], v[166:169], v[174:177], v[120:123]
	v_mfma_f32_16x16x32_bf16 v[112:115], v[150:153], v[182:185], v[112:115]
	v_mfma_f32_16x16x32_bf16 v[104:107], v[166:169], v[182:185], v[104:107]
	v_mfma_f32_16x16x32_bf16 v[96:99], v[150:153], v[190:193], v[96:99]
	v_mfma_f32_16x16x32_bf16 v[88:91], v[166:169], v[190:193], v[88:91]
	v_mfma_f32_16x16x32_bf16 v[80:83], v[150:153], v[202:205], v[80:83]
	v_mfma_f32_16x16x32_bf16 v[72:75], v[166:169], v[202:205], v[72:75]
	s_setprio 0
	s_barrier
	s_mov_b32 m0, s65
	ds_read_b128 v[206:209], v142
	ds_read_b128 v[210:213], v142 offset:1024
	ds_read_b128 v[214:217], v142 offset:2048
	ds_read_b128 v[218:221], v142 offset:3072
	global_load_lds_dwordx4 v144, s[98:99]
	s_mov_b32 m0, s66
	s_nop 0
	global_load_lds_dwordx4 v132, s[98:99]
	s_barrier
; #define PG8_STAGE(bufoff, gbase, voff) do { _Pragma("unroll") for (int _i = 0; _i < 2; ++_i) \
;         __builtin_amdgcn_global_load_lds((const unsigned*)((const char*)(gbase) + (voff)[_i]), (LAS unsigned*)(lds + (bufoff) + ldsw + _i * 8192), 16, 0, 0); } while (0)
; #define PG8_LDA(dst, b, h) do { _Pragma("unroll") for (int m = 0; m < 4; ++m) _Pragma("unroll") for (int k = 0; k < 2; ++k) dst[m][k] = *(const LAS bf16x8*)(lds + PG8_SA(b, h) + aoff + m * 2048 + k * 1024); } while (0)
; #define PG8_WAIT_V(n) asm volatile("s_waitcnt vmcnt(" #n ")" ::: "memory")
; #define PG8_WAIT_L(n) asm volatile("s_waitcnt lgkmcnt(" #n ")" ::: "memory")
; #define PG8_BAR __builtin_amdgcn_s_barrier()
; #define PG8_SCHED __builtin_amdgcn_sched_barrier(0)
; template <class Epi>
; __device__ __forceinline__ void gemm_phase(LAS unsigned char* lds, const bf16_t* A, int lda, const bf16_t* Bt, int ldb, int M, int N, int K, int asel, const Epi& E, const int fixed_round = -1) {
;     ...
;             PG8_BAR; PG8_WAIT_L(0); PG8_MMA(0, 1, At, B1); PG8_BAR;
;             PG8_LDA(At, 1, 1); PG8_STAGE(PG8_SA(1, 0), a3, voffA);
;             PG8_BAR; PG8_WAIT_L(0); PG8_MMA(1, 0, At, B0); PG8_BAR; PG8_SCHED;
;             PG8_STAGE(PG8_SB(1, 1), b3 + hstepB, voffB);
;             PG8_WAIT_V(6); PG8_BAR; PG8_MMA(1, 1, At, B1); PG8_BAR;
;     ...
;     PG8_WAIT_V(0);
;     if (wr == 0) PG8_BAR;
;     PG8_BAR;
	s_waitcnt lgkmcnt(0)
	s_setprio 1
	s_waitcnt lgkmcnt(0)
	v_mfma_f32_16x16x32_bf16 v[116:119], v[206:209], v[170:173], v[116:119]
	v_mfma_f32_16x16x32_bf16 v[108:111], v[214:217], v[170:173], v[108:111]
	v_mfma_f32_16x16x32_bf16 v[100:103], v[206:209], v[178:181], v[100:103]
	v_mfma_f32_16x16x32_bf16 v[92:95], v[214:217], v[178:181], v[92:95]
	v_mfma_f32_16x16x32_bf16 v[84:87], v[206:209], v[186:189], v[84:87]
	v_mfma_f32_16x16x32_bf16 v[76:79], v[214:217], v[186:189], v[76:79]
	v_mfma_f32_16x16x32_bf16 v[68:71], v[206:209], v[194:197], v[68:71]
	v_mfma_f32_16x16x32_bf16 v[64:67], v[214:217], v[194:197], v[64:67]
	v_mfma_f32_16x16x32_bf16 v[116:119], v[210:213], v[174:177], v[116:119]
	v_mfma_f32_16x16x32_bf16 v[108:111], v[218:221], v[174:177], v[108:111]
	v_mfma_f32_16x16x32_bf16 v[100:103], v[210:213], v[182:185], v[100:103]
	v_mfma_f32_16x16x32_bf16 v[92:95], v[218:221], v[182:185], v[92:95]
	v_mfma_f32_16x16x32_bf16 v[84:87], v[210:213], v[190:193], v[84:87]
	v_mfma_f32_16x16x32_bf16 v[76:79], v[218:221], v[190:193], v[76:79]
	v_mfma_f32_16x16x32_bf16 v[68:71], v[210:213], v[202:205], v[68:71]
	v_mfma_f32_16x16x32_bf16 v[64:67], v[218:221], v[202:205], v[64:67]
	s_setprio 0
	s_mov_b32 m0, s56
	s_barrier
	ds_read_b128 v[170:173], v139 offset:49152
	ds_read_b128 v[174:177], v139 offset:50176
	ds_read_b128 v[178:181], v139 offset:51200
	ds_read_b128 v[182:185], v139 offset:52224
	ds_read_b128 v[186:189], v139 offset:53248
	ds_read_b128 v[190:193], v139 offset:54272
	ds_read_b128 v[194:197], v139 offset:55296
	ds_read_b128 v[202:205], v139 offset:56320
	global_load_lds_dwordx4 v128, s[100:101]
	s_mov_b32 m0, s57
	s_nop 0
	global_load_lds_dwordx4 v130, s[100:101]
	s_barrier
	s_waitcnt lgkmcnt(0)
	s_setprio 1
	s_waitcnt lgkmcnt(0)
	v_mfma_f32_16x16x32_bf16 v[60:63], v[146:149], v[170:173], v[60:63]
	v_mfma_f32_16x16x32_bf16 v[56:59], v[160:163], v[170:173], v[56:59]
	v_mfma_f32_16x16x32_bf16 v[48:51], v[146:149], v[178:181], v[48:51]
	v_mfma_f32_16x16x32_bf16 v[40:43], v[160:163], v[178:181], v[40:43]
	v_mfma_f32_16x16x32_bf16 v[32:35], v[146:149], v[186:189], v[32:35]
	v_mfma_f32_16x16x32_bf16 v[24:27], v[160:163], v[186:189], v[24:27]
	v_mfma_f32_16x16x32_bf16 v[16:19], v[146:149], v[194:197], v[16:19]
	v_mfma_f32_16x16x32_bf16 v[8:11], v[160:163], v[194:197], v[8:11]
	v_mfma_f32_16x16x32_bf16 v[60:63], v[150:153], v[174:177], v[60:63]
	v_mfma_f32_16x16x32_bf16 v[56:59], v[166:169], v[174:177], v[56:59]
	v_mfma_f32_16x16x32_bf16 v[48:51], v[150:153], v[182:185], v[48:51]
	v_mfma_f32_16x16x32_bf16 v[40:43], v[166:169], v[182:185], v[40:43]
	v_mfma_f32_16x16x32_bf16 v[32:35], v[150:153], v[190:193], v[32:35]
	v_mfma_f32_16x16x32_bf16 v[24:27], v[166:169], v[190:193], v[24:27]
	v_mfma_f32_16x16x32_bf16 v[16:19], v[150:153], v[202:205], v[16:19]
	v_mfma_f32_16x16x32_bf16 v[8:11], v[166:169], v[202:205], v[8:11]
	s_setprio 0
	s_barrier
	s_add_u32 s6, s6, 0x200080
	s_addc_u32 s7, s7, 0
	s_mov_b32 m0, s67
	s_nop 0
	global_load_lds_dwordx4 v144, s[6:7]
	s_mov_b32 m0, s68
	s_nop 0
	global_load_lds_dwordx4 v132, s[6:7]
	s_waitcnt vmcnt(6)
	s_barrier
	s_setprio 1
	v_mfma_f32_16x16x32_bf16 v[52:55], v[206:209], v[170:173], v[52:55]
	v_mfma_f32_16x16x32_bf16 v[44:47], v[214:217], v[170:173], v[44:47]
	v_mfma_f32_16x16x32_bf16 v[36:39], v[206:209], v[178:181], v[36:39]
	v_mfma_f32_16x16x32_bf16 v[28:31], v[214:217], v[178:181], v[28:31]
	v_mfma_f32_16x16x32_bf16 v[20:23], v[206:209], v[186:189], v[20:23]
	v_mfma_f32_16x16x32_bf16 v[12:15], v[214:217], v[186:189], v[12:15]
	v_mfma_f32_16x16x32_bf16 v[4:7], v[206:209], v[194:197], v[4:7]
	v_mfma_f32_16x16x32_bf16 v[0:3], v[214:217], v[194:197], v[0:3]
	v_mfma_f32_16x16x32_bf16 v[52:55], v[210:213], v[174:177], v[52:55]
	v_mfma_f32_16x16x32_bf16 v[44:47], v[218:221], v[174:177], v[44:47]
	v_mfma_f32_16x16x32_bf16 v[36:39], v[210:213], v[182:185], v[36:39]
	v_mfma_f32_16x16x32_bf16 v[28:31], v[218:221], v[182:185], v[28:31]
	v_mfma_f32_16x16x32_bf16 v[20:23], v[210:213], v[190:193], v[20:23]
	v_mfma_f32_16x16x32_bf16 v[12:15], v[218:221], v[190:193], v[12:15]
	v_mfma_f32_16x16x32_bf16 v[4:7], v[210:213], v[202:205], v[4:7]
	v_mfma_f32_16x16x32_bf16 v[0:3], v[218:221], v[202:205], v[0:3]
	s_setprio 0
	s_add_i32 s58, s58, 2
	s_add_u32 s4, s4, 0x100
	s_addc_u32 s5, s5, 0
	s_cmpk_lt_u32 s58, 0x7e
	s_barrier
	s_cbranch_scc1 .LBB0_690
	s_waitcnt vmcnt(0)
	s_cmpk_gt_u32 s51, 0xff
	s_cbranch_scc1 .LBB0_693
	s_barrier

; #define PG8_STAGE(bufoff, gbase, voff) do { _Pragma("unroll") for (int _i = 0; _i < 2; ++_i) \
;         __builtin_amdgcn_global_load_lds((const unsigned*)((const char*)(gbase) + (voff)[_i]), (LAS unsigned*)(lds + (bufoff) + ldsw + _i * 8192), 16, 0, 0); } while (0)
; #define PG8_LDA(dst, b, h) do { _Pragma("unroll") for (int m = 0; m < 4; ++m) _Pragma("unroll") for (int k = 0; k < 2; ++k) dst[m][k] = *(const LAS bf16x8*)(lds + PG8_SA(b, h) + aoff + m * 2048 + k * 1024); } while (0)
; #define PG8_LDB(dst, b, h) do { _Pragma("unroll") for (int n = 0; n < 2; ++n) _Pragma("unroll") for (int k = 0; k < 2; ++k) dst[n][k] = *(const LAS bf16x8*)(lds + PG8_SB(b, h) + boff + n * 2048 + k * 1024); } while (0)
; #define PG8_WAIT_V(n) asm volatile("s_waitcnt vmcnt(" #n ")" ::: "memory")
; #define PG8_WAIT_L(n) asm volatile("s_waitcnt lgkmcnt(" #n ")" ::: "memory")
; #define PG8_BAR __builtin_amdgcn_s_barrier()
; #define PG8_SCHED __builtin_amdgcn_sched_barrier(0)
; template <class Epi>
; __device__ __forceinline__ void gemm_phase(LAS unsigned char* lds, const bf16_t* A, int lda, const bf16_t* Bt, int ldb, int M, int N, int K, int asel, const Epi& E, const int fixed_round = -1) {
;     ...
;             PG8_LDB(B0, 0, 0); PG8_SCHED; PG8_LDA(At, 0, 0); PG8_STAGE(PG8_SA(1, 1), a1 + hstepA, voffA);
;             PG8_WAIT_L(8); PG8_BAR; PG8_WAIT_L(0); PG8_MMA(0, 0, At, B0); PG8_BAR; PG8_SCHED;
;             PG8_LDB(B1, 0, 1); PG8_STAGE(PG8_SB(0, 0), b2, voffB);
;             PG8_BAR; PG8_WAIT_L(0); PG8_MMA(0, 1, At, B1); PG8_BAR;
;             PG8_LDA(At, 0, 1); PG8_STAGE(PG8_SA(0, 0), a2, voffA);
;             PG8_BAR; PG8_WAIT_L(0); PG8_MMA(1, 0, At, B0); PG8_BAR; PG8_SCHED;
;             PG8_STAGE(PG8_SB(0, 1), b2 + hstepB, voffB);
;             PG8_WAIT_V(6); PG8_BAR; PG8_MMA(1, 1, At, B1); PG8_BAR;
.LBB0_799:
	ds_read_b128 v[146:149], v155
	ds_read_b128 v[158:161], v155 offset:1024
	ds_read_b128 v[162:165], v155 offset:2048
	ds_read_b128 v[166:169], v155 offset:3072
	s_add_u32 s28, s50, 0xfff80080
	s_addc_u32 s29, s51, -1
	s_cmp_eq_u32 s68, 28
	s_cselect_b32 s55, s5, s29
	s_cselect_b32 s54, s41, s28
	s_cselect_b32 s53, s7, s67
	s_cselect_b32 s52, s65, s66
	s_add_i32 m0, s49, 0xc000
	ds_read_b128 v[170:173], v156
	ds_read_b128 v[174:177], v156 offset:1024
	ds_read_b128 v[178:181], v156 offset:2048
	ds_read_b128 v[182:185], v156 offset:3072
	ds_read_b128 v[186:189], v156 offset:4096
	ds_read_b128 v[190:193], v156 offset:5120
	ds_read_b128 v[194:197], v156 offset:6144
	ds_read_b128 v[202:205], v156 offset:7168
	global_load_lds_dwordx4 v138, s[50:51]
	s_add_i32 m0, s49, 0xe000
	s_nop 0
	global_load_lds_dwordx4 v140, s[50:51]
	s_waitcnt lgkmcnt(8)
	s_barrier
	s_waitcnt lgkmcnt(0)
	s_setprio 1
	s_waitcnt lgkmcnt(0)
	v_mfma_f32_16x16x32_bf16 v[124:127], v[146:149], v[170:173], v[124:127]
	v_mfma_f32_16x16x32_bf16 v[120:123], v[162:165], v[170:173], v[120:123]
	v_mfma_f32_16x16x32_bf16 v[108:111], v[146:149], v[178:181], v[108:111]
	v_mfma_f32_16x16x32_bf16 v[104:107], v[162:165], v[178:181], v[104:107]
	v_mfma_f32_16x16x32_bf16 v[92:95], v[146:149], v[186:189], v[92:95]
	v_mfma_f32_16x16x32_bf16 v[88:91], v[162:165], v[186:189], v[88:91]
	v_mfma_f32_16x16x32_bf16 v[76:79], v[146:149], v[194:197], v[76:79]
	v_mfma_f32_16x16x32_bf16 v[72:75], v[162:165], v[194:197], v[72:75]
	v_mfma_f32_16x16x32_bf16 v[124:127], v[158:161], v[174:177], v[124:127]
	v_mfma_f32_16x16x32_bf16 v[120:123], v[166:169], v[174:177], v[120:123]
	v_mfma_f32_16x16x32_bf16 v[108:111], v[158:161], v[182:185], v[108:111]
	v_mfma_f32_16x16x32_bf16 v[104:107], v[166:169], v[182:185], v[104:107]
	v_mfma_f32_16x16x32_bf16 v[92:95], v[158:161], v[190:193], v[92:95]
	v_mfma_f32_16x16x32_bf16 v[88:91], v[166:169], v[190:193], v[88:91]
	v_mfma_f32_16x16x32_bf16 v[76:79], v[158:161], v[202:205], v[76:79]
	v_mfma_f32_16x16x32_bf16 v[72:75], v[166:169], v[202:205], v[72:75]
	s_setprio 0
	s_barrier
	s_add_i32 s28, s81, s58
	s_add_u32 s98, s52, s2
	s_addc_u32 s99, s53, s3
	s_mov_b32 m0, s28
	ds_read_b128 v[206:209], v157
	ds_read_b128 v[210:213], v157 offset:1024
	ds_read_b128 v[214:217], v157 offset:2048
	ds_read_b128 v[218:221], v157 offset:3072
	global_load_lds_dwordx4 v130, s[52:53]
	s_add_i32 m0, s28, 0x2000
	s_nop 0
	global_load_lds_dwordx4 v134, s[52:53]
	s_barrier
	s_waitcnt lgkmcnt(0)
	s_setprio 1
	s_waitcnt lgkmcnt(0)
	v_mfma_f32_16x16x32_bf16 v[116:119], v[206:209], v[170:173], v[116:119]
	v_mfma_f32_16x16x32_bf16 v[112:115], v[214:217], v[170:173], v[112:115]
	v_mfma_f32_16x16x32_bf16 v[100:103], v[206:209], v[178:181], v[100:103]
	v_mfma_f32_16x16x32_bf16 v[96:99], v[214:217], v[178:181], v[96:99]
	v_mfma_f32_16x16x32_bf16 v[84:87], v[206:209], v[186:189], v[84:87]
	v_mfma_f32_16x16x32_bf16 v[80:83], v[214:217], v[186:189], v[80:83]
	v_mfma_f32_16x16x32_bf16 v[68:71], v[206:209], v[194:197], v[68:71]
	v_mfma_f32_16x16x32_bf16 v[64:67], v[214:217], v[194:197], v[64:67]
	v_mfma_f32_16x16x32_bf16 v[116:119], v[210:213], v[174:177], v[116:119]
	v_mfma_f32_16x16x32_bf16 v[112:115], v[218:221], v[174:177], v[112:115]
	v_mfma_f32_16x16x32_bf16 v[100:103], v[210:213], v[182:185], v[100:103]
	v_mfma_f32_16x16x32_bf16 v[96:99], v[218:221], v[182:185], v[96:99]
	v_mfma_f32_16x16x32_bf16 v[84:87], v[210:213], v[190:193], v[84:87]
	v_mfma_f32_16x16x32_bf16 v[80:83], v[218:221], v[190:193], v[80:83]
	v_mfma_f32_16x16x32_bf16 v[68:71], v[210:213], v[202:205], v[68:71]
	v_mfma_f32_16x16x32_bf16 v[64:67], v[218:221], v[202:205], v[64:67]
	s_setprio 0
	s_mov_b32 m0, s49
	s_add_u32 s100, s54, s2
	s_addc_u32 s101, s55, s3
	s_barrier
	ds_read_b128 v[170:173], v156 offset:16384
	ds_read_b128 v[174:177], v156 offset:17408
	ds_read_b128 v[178:181], v156 offset:18432
	ds_read_b128 v[182:185], v156 offset:19456
	ds_read_b128 v[186:189], v156 offset:20480
	ds_read_b128 v[190:193], v156 offset:21504
	ds_read_b128 v[194:197], v156 offset:22528
	ds_read_b128 v[202:205], v156 offset:23552
	global_load_lds_dwordx4 v128, s[54:55]
	s_mov_b32 m0, s59
	s_nop 0
	global_load_lds_dwordx4 v132, s[54:55]
	s_barrier
	s_waitcnt lgkmcnt(0)
	s_setprio 1
	s_waitcnt lgkmcnt(0)
	v_mfma_f32_16x16x32_bf16 v[60:63], v[146:149], v[170:173], v[60:63]
	v_mfma_f32_16x16x32_bf16 v[56:59], v[162:165], v[170:173], v[56:59]
	v_mfma_f32_16x16x32_bf16 v[44:47], v[146:149], v[178:181], v[44:47]
	v_mfma_f32_16x16x32_bf16 v[40:43], v[162:165], v[178:181], v[40:43]
	v_mfma_f32_16x16x32_bf16 v[28:31], v[146:149], v[186:189], v[28:31]
	v_mfma_f32_16x16x32_bf16 v[24:27], v[162:165], v[186:189], v[24:27]
	v_mfma_f32_16x16x32_bf16 v[12:15], v[146:149], v[194:197], v[12:15]
	v_mfma_f32_16x16x32_bf16 v[8:11], v[162:165], v[194:197], v[8:11]
	v_mfma_f32_16x16x32_bf16 v[60:63], v[158:161], v[174:177], v[60:63]
	v_mfma_f32_16x16x32_bf16 v[56:59], v[166:169], v[174:177], v[56:59]
	v_mfma_f32_16x16x32_bf16 v[44:47], v[158:161], v[182:185], v[44:47]
	v_mfma_f32_16x16x32_bf16 v[40:43], v[166:169], v[182:185], v[40:43]
	v_mfma_f32_16x16x32_bf16 v[28:31], v[158:161], v[190:193], v[28:31]
	v_mfma_f32_16x16x32_bf16 v[24:27], v[166:169], v[190:193], v[24:27]
	v_mfma_f32_16x16x32_bf16 v[12:15], v[158:161], v[202:205], v[12:15]
	v_mfma_f32_16x16x32_bf16 v[8:11], v[166:169], v[202:205], v[8:11]
	s_setprio 0
	s_barrier
	s_add_u32 s28, s52, 0x80000
	s_addc_u32 s29, s53, 0
	s_add_i32 s69, s82, s58
	s_mov_b32 m0, s69
	s_nop 0
	global_load_lds_dwordx4 v130, s[28:29]
	s_add_i32 m0, s69, 0x2000
	s_nop 0
	global_load_lds_dwordx4 v134, s[28:29]
	s_waitcnt vmcnt(6)
	s_barrier
; #define PG8_STAGE(bufoff, gbase, voff) do { _Pragma("unroll") for (int _i = 0; _i < 2; ++_i) \
;         __builtin_amdgcn_global_load_lds((const unsigned*)((const char*)(gbase) + (voff)[_i]), (LAS unsigned*)(lds + (bufoff) + ldsw + _i * 8192), 16, 0, 0); } while (0)
; #define PG8_LDA(dst, b, h) do { _Pragma("unroll") for (int m = 0; m < 4; ++m) _Pragma("unroll") for (int k = 0; k < 2; ++k) dst[m][k] = *(const LAS bf16x8*)(lds + PG8_SA(b, h) + aoff + m * 2048 + k * 1024); } while (0)
; #define PG8_LDB(dst, b, h) do { _Pragma("unroll") for (int n = 0; n < 2; ++n) _Pragma("unroll") for (int k = 0; k < 2; ++k) dst[n][k] = *(const LAS bf16x8*)(lds + PG8_SB(b, h) + boff + n * 2048 + k * 1024); } while (0)
; #define PG8_WAIT_V(n) asm volatile("s_waitcnt vmcnt(" #n ")" ::: "memory")
; #define PG8_WAIT_L(n) asm volatile("s_waitcnt lgkmcnt(" #n ")" ::: "memory")
; #define PG8_BAR __builtin_amdgcn_s_barrier()
; #define PG8_SCHED __builtin_amdgcn_sched_barrier(0)
; template <class Epi>
; __device__ __forceinline__ void gemm_phase(LAS unsigned char* lds, const bf16_t* A, int lda, const bf16_t* Bt, int ldb, int M, int N, int K, int asel, const Epi& E, const int fixed_round = -1) {
;     ...
;             PG8_WAIT_V(6); PG8_BAR; PG8_MMA(1, 1, At, B1); PG8_BAR;
;             PG8_LDB(B0, 1, 0); PG8_SCHED; PG8_LDA(At, 1, 0); PG8_STAGE(PG8_SA(0, 1), a2 + hstepA, voffA);
;             PG8_WAIT_L(8); PG8_BAR; PG8_WAIT_L(0); PG8_MMA(0, 0, At, B0); PG8_BAR; PG8_SCHED;
;             PG8_LDB(B1, 1, 1); PG8_STAGE(PG8_SB(1, 0), b3, voffB);
;             PG8_BAR; PG8_WAIT_L(0); PG8_MMA(0, 1, At, B1); PG8_BAR;
;             PG8_LDA(At, 1, 1); PG8_STAGE(PG8_SA(1, 0), a3, voffA);
	s_setprio 1
	v_mfma_f32_16x16x32_bf16 v[52:55], v[206:209], v[170:173], v[52:55]
	v_mfma_f32_16x16x32_bf16 v[48:51], v[214:217], v[170:173], v[48:51]
	v_mfma_f32_16x16x32_bf16 v[36:39], v[206:209], v[178:181], v[36:39]
	v_mfma_f32_16x16x32_bf16 v[32:35], v[214:217], v[178:181], v[32:35]
	v_mfma_f32_16x16x32_bf16 v[20:23], v[206:209], v[186:189], v[20:23]
	v_mfma_f32_16x16x32_bf16 v[16:19], v[214:217], v[186:189], v[16:19]
	v_mfma_f32_16x16x32_bf16 v[4:7], v[206:209], v[194:197], v[4:7]
	v_mfma_f32_16x16x32_bf16 v[0:3], v[214:217], v[194:197], v[0:3]
	v_mfma_f32_16x16x32_bf16 v[52:55], v[210:213], v[174:177], v[52:55]
	v_mfma_f32_16x16x32_bf16 v[48:51], v[218:221], v[174:177], v[48:51]
	v_mfma_f32_16x16x32_bf16 v[36:39], v[210:213], v[182:185], v[36:39]
	v_mfma_f32_16x16x32_bf16 v[32:35], v[218:221], v[182:185], v[32:35]
	v_mfma_f32_16x16x32_bf16 v[20:23], v[210:213], v[190:193], v[20:23]
	v_mfma_f32_16x16x32_bf16 v[16:19], v[218:221], v[190:193], v[16:19]
	v_mfma_f32_16x16x32_bf16 v[4:7], v[210:213], v[202:205], v[4:7]
	v_mfma_f32_16x16x32_bf16 v[0:3], v[218:221], v[202:205], v[0:3]
	s_setprio 0
	v_add_u32_e32 v136, s83, v153
	s_barrier
	ds_read_b128 v[146:149], v136
	ds_read_b128 v[158:161], v136 offset:1024
	ds_read_b128 v[162:165], v136 offset:2048
	ds_read_b128 v[166:169], v136 offset:3072
	s_add_u32 s28, s54, 0x80000
	s_addc_u32 s29, s55, 0
	s_mov_b32 m0, s60
	ds_read_b128 v[170:173], v156 offset:32768
	ds_read_b128 v[174:177], v156 offset:33792
	ds_read_b128 v[178:181], v156 offset:34816
	ds_read_b128 v[182:185], v156 offset:35840
	ds_read_b128 v[186:189], v156 offset:36864
	ds_read_b128 v[190:193], v156 offset:37888
	ds_read_b128 v[194:197], v156 offset:38912
	ds_read_b128 v[202:205], v156 offset:39936
	global_load_lds_dwordx4 v128, s[28:29]
	s_mov_b32 m0, s61
	s_nop 0
	global_load_lds_dwordx4 v132, s[28:29]
	s_waitcnt lgkmcnt(8)
	s_barrier
	s_waitcnt lgkmcnt(0)
	s_setprio 1
	s_waitcnt lgkmcnt(0)
	v_mfma_f32_16x16x32_bf16 v[124:127], v[146:149], v[170:173], v[124:127]
	v_mfma_f32_16x16x32_bf16 v[120:123], v[162:165], v[170:173], v[120:123]
	v_mfma_f32_16x16x32_bf16 v[108:111], v[146:149], v[178:181], v[108:111]
	v_mfma_f32_16x16x32_bf16 v[104:107], v[162:165], v[178:181], v[104:107]
	v_mfma_f32_16x16x32_bf16 v[92:95], v[146:149], v[186:189], v[92:95]
	v_mfma_f32_16x16x32_bf16 v[88:91], v[162:165], v[186:189], v[88:91]
	v_mfma_f32_16x16x32_bf16 v[76:79], v[146:149], v[194:197], v[76:79]
	v_mfma_f32_16x16x32_bf16 v[72:75], v[162:165], v[194:197], v[72:75]
	v_mfma_f32_16x16x32_bf16 v[124:127], v[158:161], v[174:177], v[124:127]
	v_mfma_f32_16x16x32_bf16 v[120:123], v[166:169], v[174:177], v[120:123]
	v_mfma_f32_16x16x32_bf16 v[108:111], v[158:161], v[182:185], v[108:111]
	v_mfma_f32_16x16x32_bf16 v[104:107], v[166:169], v[182:185], v[104:107]
	v_mfma_f32_16x16x32_bf16 v[92:95], v[158:161], v[190:193], v[92:95]
	v_mfma_f32_16x16x32_bf16 v[88:91], v[166:169], v[190:193], v[88:91]
	v_mfma_f32_16x16x32_bf16 v[76:79], v[158:161], v[202:205], v[76:79]
	v_mfma_f32_16x16x32_bf16 v[72:75], v[166:169], v[202:205], v[72:75]
	s_setprio 0
	s_barrier
	s_add_i32 s28, s83, s58
	v_add_u32_e32 v136, s84, v153
	s_mov_b32 m0, s28
	ds_read_b128 v[206:209], v136
	ds_read_b128 v[210:213], v136 offset:1024
	ds_read_b128 v[214:217], v136 offset:2048
	ds_read_b128 v[218:221], v136 offset:3072
	global_load_lds_dwordx4 v130, s[98:99]
	s_add_i32 m0, s28, 0x2000
	s_nop 0
	global_load_lds_dwordx4 v134, s[98:99]
	s_barrier
	s_waitcnt lgkmcnt(0)
	s_setprio 1
	s_waitcnt lgkmcnt(0)
	v_mfma_f32_16x16x32_bf16 v[116:119], v[206:209], v[170:173], v[116:119]
	v_mfma_f32_16x16x32_bf16 v[112:115], v[214:217], v[170:173], v[112:115]
	v_mfma_f32_16x16x32_bf16 v[100:103], v[206:209], v[178:181], v[100:103]
	v_mfma_f32_16x16x32_bf16 v[96:99], v[214:217], v[178:181], v[96:99]
	v_mfma_f32_16x16x32_bf16 v[84:87], v[206:209], v[186:189], v[84:87]
	v_mfma_f32_16x16x32_bf16 v[80:83], v[214:217], v[186:189], v[80:83]
	v_mfma_f32_16x16x32_bf16 v[68:71], v[206:209], v[194:197], v[68:71]
	v_mfma_f32_16x16x32_bf16 v[64:67], v[214:217], v[194:197], v[64:67]
	v_mfma_f32_16x16x32_bf16 v[116:119], v[210:213], v[174:177], v[116:119]
	v_mfma_f32_16x16x32_bf16 v[112:115], v[218:221], v[174:177], v[112:115]
	v_mfma_f32_16x16x32_bf16 v[100:103], v[210:213], v[182:185], v[100:103]
	v_mfma_f32_16x16x32_bf16 v[96:99], v[218:221], v[182:185], v[96:99]
	v_mfma_f32_16x16x32_bf16 v[84:87], v[210:213], v[190:193], v[84:87]
	v_mfma_f32_16x16x32_bf16 v[80:83], v[218:221], v[190:193], v[80:83]
	v_mfma_f32_16x16x32_bf16 v[68:71], v[210:213], v[202:205], v[68:71]
	v_mfma_f32_16x16x32_bf16 v[64:67], v[218:221], v[202:205], v[64:67]
	s_setprio 0
	s_mov_b32 m0, s63
	s_barrier
	ds_read_b128 v[170:173], v156 offset:49152
	ds_read_b128 v[174:177], v156 offset:50176
	ds_read_b128 v[178:181], v156 offset:51200
	ds_read_b128 v[182:185], v156 offset:52224
	ds_read_b128 v[186:189], v156 offset:53248
	ds_read_b128 v[190:193], v156 offset:54272
	ds_read_b128 v[194:197], v156 offset:55296
	ds_read_b128 v[202:205], v156 offset:56320
	global_load_lds_dwordx4 v128, s[100:101]
	s_mov_b32 m0, s64
	s_nop 0
	global_load_lds_dwordx4 v132, s[100:101]
	s_barrier
; __device__ __forceinline__ unsigned cvt_pk_bf16(float lo, float hi) { const bf16x2_t r = __builtin_convertvector((f32x2){lo, hi}, bf16x2_t); return __builtin_bit_cast(unsigned, r); }
; #define PG8_STAGE(bufoff, gbase, voff) do { _Pragma("unroll") for (int _i = 0; _i < 2; ++_i) \
;         __builtin_amdgcn_global_load_lds((const unsigned*)((const char*)(gbase) + (voff)[_i]), (LAS unsigned*)(lds + (bufoff) + ldsw + _i * 8192), 16, 0, 0); } while (0)
; #define PG8_WAIT_V(n) asm volatile("s_waitcnt vmcnt(" #n ")" ::: "memory")
; #define PG8_WAIT_L(n) asm volatile("s_waitcnt lgkmcnt(" #n ")" ::: "memory")
; #define PG8_BAR __builtin_amdgcn_s_barrier()
; #define PG8_SCHED __builtin_amdgcn_sched_barrier(0)
; template <class Epi>
; __device__ __forceinline__ void gemm_phase(LAS unsigned char* lds, const bf16_t* A, int lda, const bf16_t* Bt, int ldb, int M, int N, int K, int asel, const Epi& E, const int fixed_round = -1) {
;     ...
;             PG8_BAR; PG8_WAIT_L(0); PG8_MMA(1, 0, At, B0); PG8_BAR; PG8_SCHED;
;             PG8_STAGE(PG8_SB(1, 1), b3 + hstepB, voffB);
;             PG8_WAIT_V(6); PG8_BAR; PG8_MMA(1, 1, At, B1); PG8_BAR;
;     __device__ __forceinline__ void operator()(const AccT& acc, const Unit& u, int wr, int wc, int fr, int fq) const {
;     ...
;                 for (int bj = 0; bj < 2; ++bj) { f32x4 v0 = acc[ai][bj][m][0], v1 = acc[ai][bj][m][1];
;                     if (isg) {
; #pragma unroll
;                         for (int j = 0; j < 4; ++j) { float a = v0[j], b = v1[j];
;                             const float ta = 1.5957691216057308f * (a + 0.044715f * a * a * a), tb = 1.5957691216057308f * (b + 0.044715f * b * b * b);
;                             v0[j] = a * __builtin_amdgcn_rcpf(1.0f + __expf(-ta)); v1[j] = b * __builtin_amdgcn_rcpf(1.0f + __expf(-tb)); } }
;                     u32x4 w; w.x = cvt_pk_bf16(v0[0], v0[1]); w.y = cvt_pk_bf16(v0[2], v0[3]); w.z = cvt_pk_bf16(v1[0], v1[1]); w.w = cvt_pk_bf16(v1[2], v1[3]);
;                     *(u32x4*)(rowp + bj * HALF) = w; } }
	s_waitcnt lgkmcnt(0)
	s_setprio 1
	s_waitcnt lgkmcnt(0)
	v_mfma_f32_16x16x32_bf16 v[60:63], v[146:149], v[170:173], v[60:63]
	v_mfma_f32_16x16x32_bf16 v[56:59], v[162:165], v[170:173], v[56:59]
	v_mfma_f32_16x16x32_bf16 v[44:47], v[146:149], v[178:181], v[44:47]
	v_mfma_f32_16x16x32_bf16 v[40:43], v[162:165], v[178:181], v[40:43]
	v_mfma_f32_16x16x32_bf16 v[28:31], v[146:149], v[186:189], v[28:31]
	v_mfma_f32_16x16x32_bf16 v[24:27], v[162:165], v[186:189], v[24:27]
	v_mfma_f32_16x16x32_bf16 v[12:15], v[146:149], v[194:197], v[12:15]
	v_mfma_f32_16x16x32_bf16 v[8:11], v[162:165], v[194:197], v[8:11]
	v_mfma_f32_16x16x32_bf16 v[60:63], v[158:161], v[174:177], v[60:63]
	v_mfma_f32_16x16x32_bf16 v[56:59], v[166:169], v[174:177], v[56:59]
	v_mfma_f32_16x16x32_bf16 v[44:47], v[158:161], v[182:185], v[44:47]
	v_mfma_f32_16x16x32_bf16 v[40:43], v[166:169], v[182:185], v[40:43]
	v_mfma_f32_16x16x32_bf16 v[28:31], v[158:161], v[190:193], v[28:31]
	v_mfma_f32_16x16x32_bf16 v[24:27], v[166:169], v[190:193], v[24:27]
	v_mfma_f32_16x16x32_bf16 v[12:15], v[158:161], v[202:205], v[12:15]
	v_mfma_f32_16x16x32_bf16 v[8:11], v[166:169], v[202:205], v[8:11]
	s_setprio 0
	s_barrier
	s_add_u32 s28, s52, 0x80080
	s_addc_u32 s29, s53, 0
	s_add_i32 s52, s84, s58
	s_mov_b32 m0, s52
	s_nop 0
	global_load_lds_dwordx4 v130, s[28:29]
	s_add_i32 m0, s52, 0x2000
	s_nop 0
	global_load_lds_dwordx4 v134, s[28:29]
	s_waitcnt vmcnt(6)
	s_barrier
	s_setprio 1
	v_mfma_f32_16x16x32_bf16 v[52:55], v[206:209], v[170:173], v[52:55]
	v_mfma_f32_16x16x32_bf16 v[48:51], v[214:217], v[170:173], v[48:51]
	v_mfma_f32_16x16x32_bf16 v[36:39], v[206:209], v[178:181], v[36:39]
	v_mfma_f32_16x16x32_bf16 v[32:35], v[214:217], v[178:181], v[32:35]
	v_mfma_f32_16x16x32_bf16 v[20:23], v[206:209], v[186:189], v[20:23]
	v_mfma_f32_16x16x32_bf16 v[16:19], v[214:217], v[186:189], v[16:19]
	v_mfma_f32_16x16x32_bf16 v[4:7], v[206:209], v[194:197], v[4:7]
	v_mfma_f32_16x16x32_bf16 v[0:3], v[214:217], v[194:197], v[0:3]
	v_mfma_f32_16x16x32_bf16 v[52:55], v[210:213], v[174:177], v[52:55]
	v_mfma_f32_16x16x32_bf16 v[48:51], v[218:221], v[174:177], v[48:51]
	v_mfma_f32_16x16x32_bf16 v[36:39], v[210:213], v[182:185], v[36:39]
	v_mfma_f32_16x16x32_bf16 v[32:35], v[218:221], v[182:185], v[32:35]
	v_mfma_f32_16x16x32_bf16 v[20:23], v[210:213], v[190:193], v[20:23]
	v_mfma_f32_16x16x32_bf16 v[16:19], v[218:221], v[190:193], v[16:19]
	v_mfma_f32_16x16x32_bf16 v[4:7], v[210:213], v[202:205], v[4:7]
	v_mfma_f32_16x16x32_bf16 v[0:3], v[218:221], v[202:205], v[0:3]
	s_setprio 0
	s_add_i32 s68, s68, 2
	s_add_u32 s50, s50, 0x100
	s_addc_u32 s51, s51, 0
	s_add_u32 s66, s66, 0x100
	s_addc_u32 s67, s67, 0
	s_cmp_gt_u32 s68, 29
	s_barrier
	s_cbranch_scc0 .LBB0_799
	s_cmp_gt_i32 s4, 7
	s_cselect_b64 s[50:51], -1, 0
	s_cmp_lt_i32 s4, 8
	s_cbranch_scc1 .LBB0_802
	v_mul_f32_e32 v136, 0x3d372713, v124
	v_mul_f32_e32 v136, v124, v136
	v_mul_f32_e32 v146, 0x3d372713, v120
	v_fma_f32 v136, v124, v136, v124
	v_mul_f32_e32 v146, v120, v146
	v_fma_f32 v146, v120, v146, v120
	v_mul_f32_e32 v136, 0xbfcc422a, v136
	v_mul_f32_e32 v136, 0x3fb8aa3b, v136
	v_mul_f32_e32 v146, 0xbfcc422a, v146
	v_exp_f32_e32 v136, v136
	v_mul_f32_e32 v146, 0x3fb8aa3b, v146
	v_exp_f32_e32 v147, v146
	v_mul_f32_e32 v150, 0x3d372713, v122
	v_add_f32_e32 v136, 1.0, v136
	v_rcp_f32_e32 v146, v136
	v_add_f32_e32 v136, 1.0, v147
	v_rcp_f32_e32 v148, v136
	v_mul_f32_e32 v136, 0x3d372713, v125
	v_mul_f32_e32 v136, v125, v136
	v_fma_f32 v136, v125, v136, v125
	v_mul_f32_e32 v136, 0xbfcc422a, v136
	v_mul_f32_e32 v136, 0x3fb8aa3b, v136
	v_exp_f32_e32 v136, v136
	v_mul_f32_e32 v147, 0x3d372713, v121
	v_mul_f32_e32 v147, v121, v147
	v_fma_f32 v149, v121, v147, v121
	v_add_f32_e32 v136, 1.0, v136
	v_rcp_f32_e32 v147, v136
	v_mul_f32_e32 v136, 0xbfcc422a, v149
	v_mul_f32_e32 v149, 0x3d372713, v126
	v_mul_f32_e32 v149, v126, v149
	v_fma_f32 v149, v126, v149, v126
	v_mul_f32_e32 v150, v122, v150
	v_fma_f32 v150, v122, v150, v122
	v_mul_f32_e32 v149, 0xbfcc422a, v149
	v_mul_f32_e32 v149, 0x3fb8aa3b, v149
	v_mul_f32_e32 v150, 0xbfcc422a, v150
	v_exp_f32_e32 v149, v149
	v_mul_f32_e32 v150, 0x3fb8aa3b, v150
	v_exp_f32_e32 v151, v150
	v_mul_f32_e32 v158, 0x3d372713, v123
	v_add_f32_e32 v149, 1.0, v149
	v_rcp_f32_e32 v150, v149
	v_add_f32_e32 v149, 1.0, v151
	v_mul_f32_e32 v151, 0x3d372713, v127
	v_mul_f32_e32 v151, v127, v151
	v_fma_f32 v151, v127, v151, v127
	v_mul_f32_e32 v158, v123, v158
	v_fma_f32 v158, v123, v158, v123
	v_mul_f32_e32 v151, 0xbfcc422a, v151
	v_mul_f32_e32 v151, 0x3fb8aa3b, v151
	v_mul_f32_e32 v158, 0xbfcc422a, v158
	v_mul_f32_e32 v136, 0x3fb8aa3b, v136
	v_exp_f32_e32 v151, v151
	v_mul_f32_e32 v158, 0x3fb8aa3b, v158
	v_exp_f32_e32 v136, v136
	v_exp_f32_e32 v159, v158
	v_rcp_f32_e32 v158, v149
	v_add_f32_e32 v149, 1.0, v151
	v_add_f32_e32 v136, 1.0, v136
	v_rcp_f32_e32 v151, v149
	v_add_f32_e32 v149, 1.0, v159
	v_rcp_f32_e32 v159, v149
	v_rcp_f32_e32 v149, v136
	v_pk_mul_f32 v[126:127], v[126:127], v[150:151]
	v_pk_mul_f32 v[124:125], v[124:125], v[146:147]
	v_pk_mul_f32 v[122:123], v[122:123], v[158:159]
	v_pk_mul_f32 v[120:121], v[120:121], v[148:149]

; #define PG8_STAGE(bufoff, gbase, voff) do { _Pragma("unroll") for (int _i = 0; _i < 2; ++_i) \
;         __builtin_amdgcn_global_load_lds((const unsigned*)((const char*)(gbase) + (voff)[_i]), (LAS unsigned*)(lds + (bufoff) + ldsw + _i * 8192), 16, 0, 0); } while (0)
; #define PG8_LDA(dst, b, h) do { _Pragma("unroll") for (int m = 0; m < 4; ++m) _Pragma("unroll") for (int k = 0; k < 2; ++k) dst[m][k] = *(const LAS bf16x8*)(lds + PG8_SA(b, h) + aoff + m * 2048 + k * 1024); } while (0)
; #define PG8_LDB(dst, b, h) do { _Pragma("unroll") for (int n = 0; n < 2; ++n) _Pragma("unroll") for (int k = 0; k < 2; ++k) dst[n][k] = *(const LAS bf16x8*)(lds + PG8_SB(b, h) + boff + n * 2048 + k * 1024); } while (0)
; #define PG8_WAIT_V(n) asm volatile("s_waitcnt vmcnt(" #n ")" ::: "memory")
; #define PG8_WAIT_L(n) asm volatile("s_waitcnt lgkmcnt(" #n ")" ::: "memory")
; #define PG8_BAR __builtin_amdgcn_s_barrier()
; #define PG8_SCHED __builtin_amdgcn_sched_barrier(0)
; template <class Epi>
; __device__ __forceinline__ void gemm_phase(LAS unsigned char* lds, const bf16_t* A, int lda, const bf16_t* Bt, int ldb, int M, int N, int K, int asel, const Epi& E, const int fixed_round = -1) {
;     ...
;             PG8_LDB(B0, 0, 0); PG8_SCHED; PG8_LDA(At, 0, 0); PG8_STAGE(PG8_SA(1, 1), a1 + hstepA, voffA);
;             PG8_WAIT_L(8); PG8_BAR; PG8_WAIT_L(0); PG8_MMA(0, 0, At, B0); PG8_BAR; PG8_SCHED;
;             PG8_LDB(B1, 0, 1); PG8_STAGE(PG8_SB(0, 0), b2, voffB);
;             PG8_BAR; PG8_WAIT_L(0); PG8_MMA(0, 1, At, B1); PG8_BAR;
;             PG8_LDA(At, 0, 1); PG8_STAGE(PG8_SA(0, 0), a2, voffA);
;             PG8_BAR; PG8_WAIT_L(0); PG8_MMA(1, 0, At, B0); PG8_BAR; PG8_SCHED;
;             PG8_STAGE(PG8_SB(0, 1), b2 + hstepB, voffB);
;             PG8_WAIT_V(6); PG8_BAR; PG8_MMA(1, 1, At, B1); PG8_BAR;
.LBB0_1081:
	s_add_u32 s28, s22, 0xdfa80080
	ds_read_b128 v[146:149], v140
	ds_read_b128 v[150:153], v140 offset:1024
	ds_read_b128 v[160:163], v140 offset:2048
	ds_read_b128 v[166:169], v140 offset:3072
	s_addc_u32 s29, s23, -1
	s_cmp_lg_u32 s56, 28
	s_cselect_b32 s28, s28, 0
	s_cselect_b32 s29, s29, 0
	s_add_u32 s46, s0, s28
	s_addc_u32 s47, s1, s29
	s_add_u32 s44, s2, s28
	s_addc_u32 s45, s3, s29
	s_mov_b32 m0, s57
	v_lshl_add_u64 v[156:157], v[136:137], 0, s[22:23]
	ds_read_b128 v[170:173], v141
	ds_read_b128 v[174:177], v141 offset:1024
	ds_read_b128 v[178:181], v141 offset:2048
	ds_read_b128 v[182:185], v141 offset:3072
	ds_read_b128 v[186:189], v141 offset:4096
	ds_read_b128 v[190:193], v141 offset:5120
	ds_read_b128 v[194:197], v141 offset:6144
	ds_read_b128 v[202:205], v141 offset:7168
	global_load_lds_dwordx4 v[156:157], off
	v_lshl_add_u64 v[156:157], v[138:139], 0, s[22:23]
	s_mov_b32 m0, s58
	s_nop 0
	global_load_lds_dwordx4 v[156:157], off
	s_waitcnt lgkmcnt(8)
	s_barrier
	s_waitcnt lgkmcnt(0)
	s_setprio 1
	s_waitcnt lgkmcnt(0)
	v_mfma_f32_16x16x32_bf16 v[124:127], v[146:149], v[170:173], v[124:127]
	v_mfma_f32_16x16x32_bf16 v[120:123], v[160:163], v[170:173], v[120:123]
	v_mfma_f32_16x16x32_bf16 v[112:115], v[146:149], v[178:181], v[112:115]
	v_mfma_f32_16x16x32_bf16 v[104:107], v[160:163], v[178:181], v[104:107]
	v_mfma_f32_16x16x32_bf16 v[96:99], v[146:149], v[186:189], v[96:99]
	v_mfma_f32_16x16x32_bf16 v[88:91], v[160:163], v[186:189], v[88:91]
	v_mfma_f32_16x16x32_bf16 v[80:83], v[146:149], v[194:197], v[80:83]
	v_mfma_f32_16x16x32_bf16 v[72:75], v[160:163], v[194:197], v[72:75]
	v_mfma_f32_16x16x32_bf16 v[124:127], v[150:153], v[174:177], v[124:127]
	v_mfma_f32_16x16x32_bf16 v[120:123], v[166:169], v[174:177], v[120:123]
	v_mfma_f32_16x16x32_bf16 v[112:115], v[150:153], v[182:185], v[112:115]
	v_mfma_f32_16x16x32_bf16 v[104:107], v[166:169], v[182:185], v[104:107]
	v_mfma_f32_16x16x32_bf16 v[96:99], v[150:153], v[190:193], v[96:99]
	v_mfma_f32_16x16x32_bf16 v[88:91], v[166:169], v[190:193], v[88:91]
	v_mfma_f32_16x16x32_bf16 v[80:83], v[150:153], v[202:205], v[80:83]
	v_mfma_f32_16x16x32_bf16 v[72:75], v[166:169], v[202:205], v[72:75]
	s_setprio 0
	s_barrier
	s_mov_b32 m0, s59
	s_add_u32 s98, s44, s42
	s_addc_u32 s99, s45, s43
	ds_read_b128 v[206:209], v142
	ds_read_b128 v[210:213], v142 offset:1024
	ds_read_b128 v[214:217], v142 offset:2048
	ds_read_b128 v[218:221], v142 offset:3072
	global_load_lds_dwordx4 v130, s[44:45]
	s_mov_b32 m0, s60
	s_nop 0
	global_load_lds_dwordx4 v134, s[44:45]
	s_barrier
	s_waitcnt lgkmcnt(0)
	s_setprio 1
	s_waitcnt lgkmcnt(0)
	v_mfma_f32_16x16x32_bf16 v[116:119], v[206:209], v[170:173], v[116:119]
	v_mfma_f32_16x16x32_bf16 v[108:111], v[214:217], v[170:173], v[108:111]
	v_mfma_f32_16x16x32_bf16 v[100:103], v[206:209], v[178:181], v[100:103]
	v_mfma_f32_16x16x32_bf16 v[92:95], v[214:217], v[178:181], v[92:95]
	v_mfma_f32_16x16x32_bf16 v[84:87], v[206:209], v[186:189], v[84:87]
	v_mfma_f32_16x16x32_bf16 v[76:79], v[214:217], v[186:189], v[76:79]
	v_mfma_f32_16x16x32_bf16 v[68:71], v[206:209], v[194:197], v[68:71]
	v_mfma_f32_16x16x32_bf16 v[64:67], v[214:217], v[194:197], v[64:67]
	v_mfma_f32_16x16x32_bf16 v[116:119], v[210:213], v[174:177], v[116:119]
	v_mfma_f32_16x16x32_bf16 v[108:111], v[218:221], v[174:177], v[108:111]
	v_mfma_f32_16x16x32_bf16 v[100:103], v[210:213], v[182:185], v[100:103]
	v_mfma_f32_16x16x32_bf16 v[92:95], v[218:221], v[182:185], v[92:95]
	v_mfma_f32_16x16x32_bf16 v[84:87], v[210:213], v[190:193], v[84:87]
	v_mfma_f32_16x16x32_bf16 v[76:79], v[218:221], v[190:193], v[76:79]
	v_mfma_f32_16x16x32_bf16 v[68:71], v[210:213], v[202:205], v[68:71]
	v_mfma_f32_16x16x32_bf16 v[64:67], v[218:221], v[202:205], v[64:67]
	s_setprio 0
	s_mov_b32 m0, s49
	s_add_u32 s100, s46, s42
	s_addc_u32 s101, s47, s43
	s_barrier
	ds_read_b128 v[170:173], v141 offset:16384
	ds_read_b128 v[174:177], v141 offset:17408
	ds_read_b128 v[178:181], v141 offset:18432
	ds_read_b128 v[182:185], v141 offset:19456
	ds_read_b128 v[186:189], v141 offset:20480
	ds_read_b128 v[190:193], v141 offset:21504
	ds_read_b128 v[194:197], v141 offset:22528
	ds_read_b128 v[202:205], v141 offset:23552
	global_load_lds_dwordx4 v128, s[46:47]
	s_mov_b32 m0, s50
	s_nop 0
	global_load_lds_dwordx4 v132, s[46:47]
	s_barrier
	s_waitcnt lgkmcnt(0)
	s_setprio 1
	s_waitcnt lgkmcnt(0)
	v_mfma_f32_16x16x32_bf16 v[60:63], v[146:149], v[170:173], v[60:63]
	v_mfma_f32_16x16x32_bf16 v[56:59], v[160:163], v[170:173], v[56:59]
	v_mfma_f32_16x16x32_bf16 v[48:51], v[146:149], v[178:181], v[48:51]
	v_mfma_f32_16x16x32_bf16 v[40:43], v[160:163], v[178:181], v[40:43]
	v_mfma_f32_16x16x32_bf16 v[32:35], v[146:149], v[186:189], v[32:35]
	v_mfma_f32_16x16x32_bf16 v[24:27], v[160:163], v[186:189], v[24:27]
	v_mfma_f32_16x16x32_bf16 v[16:19], v[146:149], v[194:197], v[16:19]
	v_mfma_f32_16x16x32_bf16 v[8:11], v[160:163], v[194:197], v[8:11]
	v_mfma_f32_16x16x32_bf16 v[60:63], v[150:153], v[174:177], v[60:63]
	v_mfma_f32_16x16x32_bf16 v[56:59], v[166:169], v[174:177], v[56:59]
	v_mfma_f32_16x16x32_bf16 v[48:51], v[150:153], v[182:185], v[48:51]
	v_mfma_f32_16x16x32_bf16 v[40:43], v[166:169], v[182:185], v[40:43]
	v_mfma_f32_16x16x32_bf16 v[32:35], v[150:153], v[190:193], v[32:35]
	v_mfma_f32_16x16x32_bf16 v[24:27], v[166:169], v[190:193], v[24:27]
	v_mfma_f32_16x16x32_bf16 v[16:19], v[150:153], v[202:205], v[16:19]
	v_mfma_f32_16x16x32_bf16 v[8:11], v[166:169], v[202:205], v[8:11]
	s_setprio 0
	s_barrier
	s_add_u32 s28, s44, 0x80000
	s_addc_u32 s29, s45, 0
	s_mov_b32 m0, s61
	s_nop 0
	global_load_lds_dwordx4 v130, s[28:29]
	s_mov_b32 m0, s62
	s_nop 0
	global_load_lds_dwordx4 v134, s[28:29]
	s_waitcnt vmcnt(6)
	s_barrier
; #define PG8_STAGE(bufoff, gbase, voff) do { _Pragma("unroll") for (int _i = 0; _i < 2; ++_i) \
;         __builtin_amdgcn_global_load_lds((const unsigned*)((const char*)(gbase) + (voff)[_i]), (LAS unsigned*)(lds + (bufoff) + ldsw + _i * 8192), 16, 0, 0); } while (0)
; #define PG8_LDA(dst, b, h) do { _Pragma("unroll") for (int m = 0; m < 4; ++m) _Pragma("unroll") for (int k = 0; k < 2; ++k) dst[m][k] = *(const LAS bf16x8*)(lds + PG8_SA(b, h) + aoff + m * 2048 + k * 1024); } while (0)
; #define PG8_LDB(dst, b, h) do { _Pragma("unroll") for (int n = 0; n < 2; ++n) _Pragma("unroll") for (int k = 0; k < 2; ++k) dst[n][k] = *(const LAS bf16x8*)(lds + PG8_SB(b, h) + boff + n * 2048 + k * 1024); } while (0)
; #define PG8_WAIT_V(n) asm volatile("s_waitcnt vmcnt(" #n ")" ::: "memory")
; #define PG8_WAIT_L(n) asm volatile("s_waitcnt lgkmcnt(" #n ")" ::: "memory")
; #define PG8_BAR __builtin_amdgcn_s_barrier()
; #define PG8_SCHED __builtin_amdgcn_sched_barrier(0)
; template <class Epi>
; __device__ __forceinline__ void gemm_phase(LAS unsigned char* lds, const bf16_t* A, int lda, const bf16_t* Bt, int ldb, int M, int N, int K, int asel, const Epi& E, const int fixed_round = -1) {
;     ...
;             PG8_WAIT_V(6); PG8_BAR; PG8_MMA(1, 1, At, B1); PG8_BAR;
;             PG8_LDB(B0, 1, 0); PG8_SCHED; PG8_LDA(At, 1, 0); PG8_STAGE(PG8_SA(0, 1), a2 + hstepA, voffA);
;             PG8_WAIT_L(8); PG8_BAR; PG8_WAIT_L(0); PG8_MMA(0, 0, At, B0); PG8_BAR; PG8_SCHED;
;             PG8_LDB(B1, 1, 1); PG8_STAGE(PG8_SB(1, 0), b3, voffB);
;             PG8_BAR; PG8_WAIT_L(0); PG8_MMA(0, 1, At, B1); PG8_BAR;
	s_setprio 1
	v_mfma_f32_16x16x32_bf16 v[52:55], v[206:209], v[170:173], v[52:55]
	v_mfma_f32_16x16x32_bf16 v[44:47], v[214:217], v[170:173], v[44:47]
	v_mfma_f32_16x16x32_bf16 v[36:39], v[206:209], v[178:181], v[36:39]
	v_mfma_f32_16x16x32_bf16 v[28:31], v[214:217], v[178:181], v[28:31]
	v_mfma_f32_16x16x32_bf16 v[20:23], v[206:209], v[186:189], v[20:23]
	v_mfma_f32_16x16x32_bf16 v[12:15], v[214:217], v[186:189], v[12:15]
	v_mfma_f32_16x16x32_bf16 v[4:7], v[206:209], v[194:197], v[4:7]
	v_mfma_f32_16x16x32_bf16 v[0:3], v[214:217], v[194:197], v[0:3]
	v_mfma_f32_16x16x32_bf16 v[52:55], v[210:213], v[174:177], v[52:55]
	v_mfma_f32_16x16x32_bf16 v[44:47], v[218:221], v[174:177], v[44:47]
	v_mfma_f32_16x16x32_bf16 v[36:39], v[210:213], v[182:185], v[36:39]
	v_mfma_f32_16x16x32_bf16 v[28:31], v[218:221], v[182:185], v[28:31]
	v_mfma_f32_16x16x32_bf16 v[20:23], v[210:213], v[190:193], v[20:23]
	v_mfma_f32_16x16x32_bf16 v[12:15], v[218:221], v[190:193], v[12:15]
	v_mfma_f32_16x16x32_bf16 v[4:7], v[210:213], v[202:205], v[4:7]
	v_mfma_f32_16x16x32_bf16 v[0:3], v[218:221], v[202:205], v[0:3]
	s_setprio 0
	s_barrier
	ds_read_b128 v[146:149], v143
	ds_read_b128 v[150:153], v143 offset:1024
	ds_read_b128 v[160:163], v143 offset:2048
	ds_read_b128 v[166:169], v143 offset:3072
	s_add_u32 s28, s46, 0x80000
	s_addc_u32 s29, s47, 0
	s_mov_b32 m0, s52
	ds_read_b128 v[170:173], v141 offset:32768
	ds_read_b128 v[174:177], v141 offset:33792
	ds_read_b128 v[178:181], v141 offset:34816
	ds_read_b128 v[182:185], v141 offset:35840
	ds_read_b128 v[186:189], v141 offset:36864
	ds_read_b128 v[190:193], v141 offset:37888
	ds_read_b128 v[194:197], v141 offset:38912
	ds_read_b128 v[202:205], v141 offset:39936
	global_load_lds_dwordx4 v128, s[28:29]
	s_mov_b32 m0, s53
	s_nop 0
	global_load_lds_dwordx4 v132, s[28:29]
	s_waitcnt lgkmcnt(8)
	s_barrier
	s_waitcnt lgkmcnt(0)
	s_setprio 1
	s_waitcnt lgkmcnt(0)
	v_mfma_f32_16x16x32_bf16 v[124:127], v[146:149], v[170:173], v[124:127]
	v_mfma_f32_16x16x32_bf16 v[120:123], v[160:163], v[170:173], v[120:123]
	v_mfma_f32_16x16x32_bf16 v[112:115], v[146:149], v[178:181], v[112:115]
	v_mfma_f32_16x16x32_bf16 v[104:107], v[160:163], v[178:181], v[104:107]
	v_mfma_f32_16x16x32_bf16 v[96:99], v[146:149], v[186:189], v[96:99]
	v_mfma_f32_16x16x32_bf16 v[88:91], v[160:163], v[186:189], v[88:91]
	v_mfma_f32_16x16x32_bf16 v[80:83], v[146:149], v[194:197], v[80:83]
	v_mfma_f32_16x16x32_bf16 v[72:75], v[160:163], v[194:197], v[72:75]
	v_mfma_f32_16x16x32_bf16 v[124:127], v[150:153], v[174:177], v[124:127]
	v_mfma_f32_16x16x32_bf16 v[120:123], v[166:169], v[174:177], v[120:123]
	v_mfma_f32_16x16x32_bf16 v[112:115], v[150:153], v[182:185], v[112:115]
	v_mfma_f32_16x16x32_bf16 v[104:107], v[166:169], v[182:185], v[104:107]
	v_mfma_f32_16x16x32_bf16 v[96:99], v[150:153], v[190:193], v[96:99]
	v_mfma_f32_16x16x32_bf16 v[88:91], v[166:169], v[190:193], v[88:91]
	v_mfma_f32_16x16x32_bf16 v[80:83], v[150:153], v[202:205], v[80:83]
	v_mfma_f32_16x16x32_bf16 v[72:75], v[166:169], v[202:205], v[72:75]
	s_setprio 0
	s_barrier
	s_mov_b32 m0, s63
	ds_read_b128 v[206:209], v144
	ds_read_b128 v[210:213], v144 offset:1024
	ds_read_b128 v[214:217], v144 offset:2048
	ds_read_b128 v[218:221], v144 offset:3072
	global_load_lds_dwordx4 v130, s[98:99]
	s_mov_b32 m0, s64
	s_nop 0
	global_load_lds_dwordx4 v134, s[98:99]
	s_barrier
; #define PG8_STAGE(bufoff, gbase, voff) do { _Pragma("unroll") for (int _i = 0; _i < 2; ++_i) \
;         __builtin_amdgcn_global_load_lds((const unsigned*)((const char*)(gbase) + (voff)[_i]), (LAS unsigned*)(lds + (bufoff) + ldsw + _i * 8192), 16, 0, 0); } while (0)
; #define PG8_LDA(dst, b, h) do { _Pragma("unroll") for (int m = 0; m < 4; ++m) _Pragma("unroll") for (int k = 0; k < 2; ++k) dst[m][k] = *(const LAS bf16x8*)(lds + PG8_SA(b, h) + aoff + m * 2048 + k * 1024); } while (0)
; #define PG8_WAIT_V(n) asm volatile("s_waitcnt vmcnt(" #n ")" ::: "memory")
; #define PG8_WAIT_L(n) asm volatile("s_waitcnt lgkmcnt(" #n ")" ::: "memory")
; #define PG8_BAR __builtin_amdgcn_s_barrier()
; #define PG8_SCHED __builtin_amdgcn_sched_barrier(0)
; template <class Epi>
; __device__ __forceinline__ void gemm_phase(LAS unsigned char* lds, const bf16_t* A, int lda, const bf16_t* Bt, int ldb, int M, int N, int K, int asel, const Epi& E, const int fixed_round = -1) {
;     ...
;             PG8_BAR; PG8_WAIT_L(0); PG8_MMA(0, 1, At, B1); PG8_BAR;
;             PG8_LDA(At, 1, 1); PG8_STAGE(PG8_SA(1, 0), a3, voffA);
;             PG8_BAR; PG8_WAIT_L(0); PG8_MMA(1, 0, At, B0); PG8_BAR; PG8_SCHED;
;             PG8_STAGE(PG8_SB(1, 1), b3 + hstepB, voffB);
;             PG8_WAIT_V(6); PG8_BAR; PG8_MMA(1, 1, At, B1); PG8_BAR;
;     ...
;     PG8_WAIT_V(0);
;     if (wr == 0) PG8_BAR;
;     PG8_BAR;
	s_waitcnt lgkmcnt(0)
	s_setprio 1
	s_waitcnt lgkmcnt(0)
	v_mfma_f32_16x16x32_bf16 v[116:119], v[206:209], v[170:173], v[116:119]
	v_mfma_f32_16x16x32_bf16 v[108:111], v[214:217], v[170:173], v[108:111]
	v_mfma_f32_16x16x32_bf16 v[100:103], v[206:209], v[178:181], v[100:103]
	v_mfma_f32_16x16x32_bf16 v[92:95], v[214:217], v[178:181], v[92:95]
	v_mfma_f32_16x16x32_bf16 v[84:87], v[206:209], v[186:189], v[84:87]
	v_mfma_f32_16x16x32_bf16 v[76:79], v[214:217], v[186:189], v[76:79]
	v_mfma_f32_16x16x32_bf16 v[68:71], v[206:209], v[194:197], v[68:71]
	v_mfma_f32_16x16x32_bf16 v[64:67], v[214:217], v[194:197], v[64:67]
	v_mfma_f32_16x16x32_bf16 v[116:119], v[210:213], v[174:177], v[116:119]
	v_mfma_f32_16x16x32_bf16 v[108:111], v[218:221], v[174:177], v[108:111]
	v_mfma_f32_16x16x32_bf16 v[100:103], v[210:213], v[182:185], v[100:103]
	v_mfma_f32_16x16x32_bf16 v[92:95], v[218:221], v[182:185], v[92:95]
	v_mfma_f32_16x16x32_bf16 v[84:87], v[210:213], v[190:193], v[84:87]
	v_mfma_f32_16x16x32_bf16 v[76:79], v[218:221], v[190:193], v[76:79]
	v_mfma_f32_16x16x32_bf16 v[68:71], v[210:213], v[202:205], v[68:71]
	v_mfma_f32_16x16x32_bf16 v[64:67], v[218:221], v[202:205], v[64:67]
	s_setprio 0
	s_mov_b32 m0, s54
	s_barrier
	ds_read_b128 v[170:173], v141 offset:49152
	ds_read_b128 v[174:177], v141 offset:50176
	ds_read_b128 v[178:181], v141 offset:51200
	ds_read_b128 v[182:185], v141 offset:52224
	ds_read_b128 v[186:189], v141 offset:53248
	ds_read_b128 v[190:193], v141 offset:54272
	ds_read_b128 v[194:197], v141 offset:55296
	ds_read_b128 v[202:205], v141 offset:56320
	global_load_lds_dwordx4 v128, s[100:101]
	s_mov_b32 m0, s55
	s_nop 0
	global_load_lds_dwordx4 v132, s[100:101]
	s_barrier
	s_waitcnt lgkmcnt(0)
	s_setprio 1
	s_waitcnt lgkmcnt(0)
	v_mfma_f32_16x16x32_bf16 v[60:63], v[146:149], v[170:173], v[60:63]
	v_mfma_f32_16x16x32_bf16 v[56:59], v[160:163], v[170:173], v[56:59]
	v_mfma_f32_16x16x32_bf16 v[48:51], v[146:149], v[178:181], v[48:51]
	v_mfma_f32_16x16x32_bf16 v[40:43], v[160:163], v[178:181], v[40:43]
	v_mfma_f32_16x16x32_bf16 v[32:35], v[146:149], v[186:189], v[32:35]
	v_mfma_f32_16x16x32_bf16 v[24:27], v[160:163], v[186:189], v[24:27]
	v_mfma_f32_16x16x32_bf16 v[16:19], v[146:149], v[194:197], v[16:19]
	v_mfma_f32_16x16x32_bf16 v[8:11], v[160:163], v[194:197], v[8:11]
	v_mfma_f32_16x16x32_bf16 v[60:63], v[150:153], v[174:177], v[60:63]
	v_mfma_f32_16x16x32_bf16 v[56:59], v[166:169], v[174:177], v[56:59]
	v_mfma_f32_16x16x32_bf16 v[48:51], v[150:153], v[182:185], v[48:51]
	v_mfma_f32_16x16x32_bf16 v[40:43], v[166:169], v[182:185], v[40:43]
	v_mfma_f32_16x16x32_bf16 v[32:35], v[150:153], v[190:193], v[32:35]
	v_mfma_f32_16x16x32_bf16 v[24:27], v[166:169], v[190:193], v[24:27]
	v_mfma_f32_16x16x32_bf16 v[16:19], v[150:153], v[202:205], v[16:19]
	v_mfma_f32_16x16x32_bf16 v[8:11], v[166:169], v[202:205], v[8:11]
	s_setprio 0
	s_barrier
	s_add_u32 s28, s44, 0x80080
	s_addc_u32 s29, s45, 0
	s_mov_b32 m0, s65
	s_nop 0
	global_load_lds_dwordx4 v130, s[28:29]
	s_mov_b32 m0, s66
	s_nop 0
	global_load_lds_dwordx4 v134, s[28:29]
	s_waitcnt vmcnt(6)
	s_barrier
	s_setprio 1
	v_mfma_f32_16x16x32_bf16 v[52:55], v[206:209], v[170:173], v[52:55]
	v_mfma_f32_16x16x32_bf16 v[44:47], v[214:217], v[170:173], v[44:47]
	v_mfma_f32_16x16x32_bf16 v[36:39], v[206:209], v[178:181], v[36:39]
	v_mfma_f32_16x16x32_bf16 v[28:31], v[214:217], v[178:181], v[28:31]
	v_mfma_f32_16x16x32_bf16 v[20:23], v[206:209], v[186:189], v[20:23]
	v_mfma_f32_16x16x32_bf16 v[12:15], v[214:217], v[186:189], v[12:15]
	v_mfma_f32_16x16x32_bf16 v[4:7], v[206:209], v[194:197], v[4:7]
	v_mfma_f32_16x16x32_bf16 v[0:3], v[214:217], v[194:197], v[0:3]
	v_mfma_f32_16x16x32_bf16 v[52:55], v[210:213], v[174:177], v[52:55]
	v_mfma_f32_16x16x32_bf16 v[44:47], v[218:221], v[174:177], v[44:47]
	v_mfma_f32_16x16x32_bf16 v[36:39], v[210:213], v[182:185], v[36:39]
	v_mfma_f32_16x16x32_bf16 v[28:31], v[218:221], v[182:185], v[28:31]
	v_mfma_f32_16x16x32_bf16 v[20:23], v[210:213], v[190:193], v[20:23]
	v_mfma_f32_16x16x32_bf16 v[12:15], v[218:221], v[190:193], v[12:15]
	v_mfma_f32_16x16x32_bf16 v[4:7], v[210:213], v[202:205], v[4:7]
	v_mfma_f32_16x16x32_bf16 v[0:3], v[218:221], v[202:205], v[0:3]
	s_setprio 0
	s_add_i32 s56, s56, 2
	s_add_u32 s22, s22, 0x100
	s_addc_u32 s23, s23, 0
	s_cmp_lt_u32 s56, 30
	s_barrier
	s_cbranch_scc1 .LBB0_1081
	s_waitcnt vmcnt(0)
	s_cmpk_gt_u32 s48, 0xff
	s_cbranch_scc1 .LBB0_1084
	s_barrier

; #define PG8_STAGE(bufoff, gbase, voff) do { _Pragma("unroll") for (int _i = 0; _i < 2; ++_i) \
;         __builtin_amdgcn_global_load_lds((const unsigned*)((const char*)(gbase) + (voff)[_i]), (LAS unsigned*)(lds + (bufoff) + ldsw + _i * 8192), 16, 0, 0); } while (0)
; #define PG8_LDA(dst, b, h) do { _Pragma("unroll") for (int m = 0; m < 4; ++m) _Pragma("unroll") for (int k = 0; k < 2; ++k) dst[m][k] = *(const LAS bf16x8*)(lds + PG8_SA(b, h) + aoff + m * 2048 + k * 1024); } while (0)
; #define PG8_LDB(dst, b, h) do { _Pragma("unroll") for (int n = 0; n < 2; ++n) _Pragma("unroll") for (int k = 0; k < 2; ++k) dst[n][k] = *(const LAS bf16x8*)(lds + PG8_SB(b, h) + boff + n * 2048 + k * 1024); } while (0)
; #define PG8_WAIT_V(n) asm volatile("s_waitcnt vmcnt(" #n ")" ::: "memory")
; #define PG8_WAIT_L(n) asm volatile("s_waitcnt lgkmcnt(" #n ")" ::: "memory")
; #define PG8_BAR __builtin_amdgcn_s_barrier()
; #define PG8_SCHED __builtin_amdgcn_sched_barrier(0)
; template <class Epi>
; __device__ __forceinline__ void gemm_phase(LAS unsigned char* lds, const bf16_t* A, int lda, const bf16_t* Bt, int ldb, int M, int N, int K, int asel, const Epi& E, const int fixed_round = -1) {
;     ...
;             PG8_LDB(B0, 0, 0); PG8_SCHED; PG8_LDA(At, 0, 0); PG8_STAGE(PG8_SA(1, 1), a1 + hstepA, voffA);
;             PG8_WAIT_L(8); PG8_BAR; PG8_WAIT_L(0); PG8_MMA(0, 0, At, B0); PG8_BAR; PG8_SCHED;
;             PG8_LDB(B1, 0, 1); PG8_STAGE(PG8_SB(0, 0), b2, voffB);
;             PG8_BAR; PG8_WAIT_L(0); PG8_MMA(0, 1, At, B1); PG8_BAR;
;             PG8_LDA(At, 0, 1); PG8_STAGE(PG8_SA(0, 0), a2, voffA);
;             PG8_BAR; PG8_WAIT_L(0); PG8_MMA(1, 0, At, B0); PG8_BAR; PG8_SCHED;
;             PG8_STAGE(PG8_SB(0, 1), b2 + hstepB, voffB);
;             PG8_WAIT_V(6); PG8_BAR; PG8_MMA(1, 1, At, B1); PG8_BAR;
.LBB0_1120:
	s_add_u32 s22, s6, 0xdfa80080
	ds_read_b128 v[146:149], v138
	ds_read_b128 v[150:153], v138 offset:1024
	ds_read_b128 v[160:163], v138 offset:2048
	ds_read_b128 v[166:169], v138 offset:3072
	s_addc_u32 s23, s7, -1
	s_cmp_lg_u32 s40, 28
	s_cselect_b32 s22, s22, 0
	s_cselect_b32 s23, s23, 0
	s_add_u32 s24, s0, s22
	s_addc_u32 s25, s1, s23
	s_add_u32 s22, s2, s22
	s_addc_u32 s23, s3, s23
	s_mov_b32 m0, s41
	v_lshl_add_u64 v[156:157], v[134:135], 0, s[6:7]
	ds_read_b128 v[170:173], v139
	ds_read_b128 v[174:177], v139 offset:1024
	ds_read_b128 v[178:181], v139 offset:2048
	ds_read_b128 v[182:185], v139 offset:3072
	ds_read_b128 v[186:189], v139 offset:4096
	ds_read_b128 v[190:193], v139 offset:5120
	ds_read_b128 v[194:197], v139 offset:6144
	ds_read_b128 v[202:205], v139 offset:7168
	global_load_lds_dwordx4 v[156:157], off
	v_lshl_add_u64 v[156:157], v[136:137], 0, s[6:7]
	s_mov_b32 m0, s58
	s_nop 0
	global_load_lds_dwordx4 v[156:157], off
	s_waitcnt lgkmcnt(8)
	s_barrier
	s_waitcnt lgkmcnt(0)
	s_setprio 1
	s_waitcnt lgkmcnt(0)
	v_mfma_f32_16x16x32_bf16 v[124:127], v[146:149], v[170:173], v[124:127]
	v_mfma_f32_16x16x32_bf16 v[120:123], v[160:163], v[170:173], v[120:123]
	v_mfma_f32_16x16x32_bf16 v[112:115], v[146:149], v[178:181], v[112:115]
	v_mfma_f32_16x16x32_bf16 v[104:107], v[160:163], v[178:181], v[104:107]
	v_mfma_f32_16x16x32_bf16 v[96:99], v[146:149], v[186:189], v[96:99]
	v_mfma_f32_16x16x32_bf16 v[88:91], v[160:163], v[186:189], v[88:91]
	v_mfma_f32_16x16x32_bf16 v[80:83], v[146:149], v[194:197], v[80:83]
	v_mfma_f32_16x16x32_bf16 v[72:75], v[160:163], v[194:197], v[72:75]
	v_mfma_f32_16x16x32_bf16 v[124:127], v[150:153], v[174:177], v[124:127]
	v_mfma_f32_16x16x32_bf16 v[120:123], v[166:169], v[174:177], v[120:123]
	v_mfma_f32_16x16x32_bf16 v[112:115], v[150:153], v[182:185], v[112:115]
	v_mfma_f32_16x16x32_bf16 v[104:107], v[166:169], v[182:185], v[104:107]
	v_mfma_f32_16x16x32_bf16 v[96:99], v[150:153], v[190:193], v[96:99]
	v_mfma_f32_16x16x32_bf16 v[88:91], v[166:169], v[190:193], v[88:91]
	v_mfma_f32_16x16x32_bf16 v[80:83], v[150:153], v[202:205], v[80:83]
	v_mfma_f32_16x16x32_bf16 v[72:75], v[166:169], v[202:205], v[72:75]
	s_setprio 0
	s_barrier
	s_mov_b32 m0, s59
	s_add_u32 s98, s22, s4
	s_addc_u32 s99, s23, s5
	ds_read_b128 v[206:209], v140
	ds_read_b128 v[210:213], v140 offset:1024
	ds_read_b128 v[214:217], v140 offset:2048
	ds_read_b128 v[218:221], v140 offset:3072
	global_load_lds_dwordx4 v144, s[22:23]
	s_mov_b32 m0, s60
	s_nop 0
	global_load_lds_dwordx4 v132, s[22:23]
	s_barrier
	s_waitcnt lgkmcnt(0)
	s_setprio 1
	s_waitcnt lgkmcnt(0)
	v_mfma_f32_16x16x32_bf16 v[116:119], v[206:209], v[170:173], v[116:119]
	v_mfma_f32_16x16x32_bf16 v[108:111], v[214:217], v[170:173], v[108:111]
	v_mfma_f32_16x16x32_bf16 v[100:103], v[206:209], v[178:181], v[100:103]
	v_mfma_f32_16x16x32_bf16 v[92:95], v[214:217], v[178:181], v[92:95]
	v_mfma_f32_16x16x32_bf16 v[84:87], v[206:209], v[186:189], v[84:87]
	v_mfma_f32_16x16x32_bf16 v[76:79], v[214:217], v[186:189], v[76:79]
	v_mfma_f32_16x16x32_bf16 v[68:71], v[206:209], v[194:197], v[68:71]
	v_mfma_f32_16x16x32_bf16 v[64:67], v[214:217], v[194:197], v[64:67]
	v_mfma_f32_16x16x32_bf16 v[116:119], v[210:213], v[174:177], v[116:119]
	v_mfma_f32_16x16x32_bf16 v[108:111], v[218:221], v[174:177], v[108:111]
	v_mfma_f32_16x16x32_bf16 v[100:103], v[210:213], v[182:185], v[100:103]
	v_mfma_f32_16x16x32_bf16 v[92:95], v[218:221], v[182:185], v[92:95]
	v_mfma_f32_16x16x32_bf16 v[84:87], v[210:213], v[190:193], v[84:87]
	v_mfma_f32_16x16x32_bf16 v[76:79], v[218:221], v[190:193], v[76:79]
	v_mfma_f32_16x16x32_bf16 v[68:71], v[210:213], v[202:205], v[68:71]
	v_mfma_f32_16x16x32_bf16 v[64:67], v[218:221], v[202:205], v[64:67]
	s_setprio 0
	s_mov_b32 m0, s52
	s_add_u32 s100, s24, s4
	s_addc_u32 s101, s25, s5
	s_barrier
	ds_read_b128 v[170:173], v139 offset:16384
	ds_read_b128 v[174:177], v139 offset:17408
	ds_read_b128 v[178:181], v139 offset:18432
	ds_read_b128 v[182:185], v139 offset:19456
	ds_read_b128 v[186:189], v139 offset:20480
	ds_read_b128 v[190:193], v139 offset:21504
	ds_read_b128 v[194:197], v139 offset:22528
	ds_read_b128 v[202:205], v139 offset:23552
	global_load_lds_dwordx4 v128, s[24:25]
	s_mov_b32 m0, s53
	s_nop 0
	global_load_lds_dwordx4 v130, s[24:25]
	s_barrier
	s_waitcnt lgkmcnt(0)
	s_setprio 1
	s_waitcnt lgkmcnt(0)
	v_mfma_f32_16x16x32_bf16 v[60:63], v[146:149], v[170:173], v[60:63]
	v_mfma_f32_16x16x32_bf16 v[56:59], v[160:163], v[170:173], v[56:59]
	v_mfma_f32_16x16x32_bf16 v[48:51], v[146:149], v[178:181], v[48:51]
	v_mfma_f32_16x16x32_bf16 v[40:43], v[160:163], v[178:181], v[40:43]
	v_mfma_f32_16x16x32_bf16 v[32:35], v[146:149], v[186:189], v[32:35]
	v_mfma_f32_16x16x32_bf16 v[24:27], v[160:163], v[186:189], v[24:27]
	v_mfma_f32_16x16x32_bf16 v[16:19], v[146:149], v[194:197], v[16:19]
	v_mfma_f32_16x16x32_bf16 v[8:11], v[160:163], v[194:197], v[8:11]
	v_mfma_f32_16x16x32_bf16 v[60:63], v[150:153], v[174:177], v[60:63]
	v_mfma_f32_16x16x32_bf16 v[56:59], v[166:169], v[174:177], v[56:59]
	v_mfma_f32_16x16x32_bf16 v[48:51], v[150:153], v[182:185], v[48:51]
	v_mfma_f32_16x16x32_bf16 v[40:43], v[166:169], v[182:185], v[40:43]
	v_mfma_f32_16x16x32_bf16 v[32:35], v[150:153], v[190:193], v[32:35]
	v_mfma_f32_16x16x32_bf16 v[24:27], v[166:169], v[190:193], v[24:27]
	v_mfma_f32_16x16x32_bf16 v[16:19], v[150:153], v[202:205], v[16:19]
	v_mfma_f32_16x16x32_bf16 v[8:11], v[166:169], v[202:205], v[8:11]
	s_setprio 0
	s_barrier
	s_add_u32 s28, s22, 0x80000
	s_addc_u32 s29, s23, 0
	s_mov_b32 m0, s61
	s_nop 0
	global_load_lds_dwordx4 v144, s[28:29]
	s_mov_b32 m0, s62
	s_nop 0
	global_load_lds_dwordx4 v132, s[28:29]
	s_waitcnt vmcnt(6)
	s_barrier
; #define PG8_STAGE(bufoff, gbase, voff) do { _Pragma("unroll") for (int _i = 0; _i < 2; ++_i) \
;         __builtin_amdgcn_global_load_lds((const unsigned*)((const char*)(gbase) + (voff)[_i]), (LAS unsigned*)(lds + (bufoff) + ldsw + _i * 8192), 16, 0, 0); } while (0)
; #define PG8_LDA(dst, b, h) do { _Pragma("unroll") for (int m = 0; m < 4; ++m) _Pragma("unroll") for (int k = 0; k < 2; ++k) dst[m][k] = *(const LAS bf16x8*)(lds + PG8_SA(b, h) + aoff + m * 2048 + k * 1024); } while (0)
; #define PG8_LDB(dst, b, h) do { _Pragma("unroll") for (int n = 0; n < 2; ++n) _Pragma("unroll") for (int k = 0; k < 2; ++k) dst[n][k] = *(const LAS bf16x8*)(lds + PG8_SB(b, h) + boff + n * 2048 + k * 1024); } while (0)
; #define PG8_WAIT_V(n) asm volatile("s_waitcnt vmcnt(" #n ")" ::: "memory")
; #define PG8_WAIT_L(n) asm volatile("s_waitcnt lgkmcnt(" #n ")" ::: "memory")
; #define PG8_BAR __builtin_amdgcn_s_barrier()
; #define PG8_SCHED __builtin_amdgcn_sched_barrier(0)
; template <class Epi>
; __device__ __forceinline__ void gemm_phase(LAS unsigned char* lds, const bf16_t* A, int lda, const bf16_t* Bt, int ldb, int M, int N, int K, int asel, const Epi& E, const int fixed_round = -1) {
;     ...
;             PG8_WAIT_V(6); PG8_BAR; PG8_MMA(1, 1, At, B1); PG8_BAR;
;             PG8_LDB(B0, 1, 0); PG8_SCHED; PG8_LDA(At, 1, 0); PG8_STAGE(PG8_SA(0, 1), a2 + hstepA, voffA);
;             PG8_WAIT_L(8); PG8_BAR; PG8_WAIT_L(0); PG8_MMA(0, 0, At, B0); PG8_BAR; PG8_SCHED;
;             PG8_LDB(B1, 1, 1); PG8_STAGE(PG8_SB(1, 0), b3, voffB);
;             PG8_BAR; PG8_WAIT_L(0); PG8_MMA(0, 1, At, B1); PG8_BAR;
	s_setprio 1
	v_mfma_f32_16x16x32_bf16 v[52:55], v[206:209], v[170:173], v[52:55]
	v_mfma_f32_16x16x32_bf16 v[44:47], v[214:217], v[170:173], v[44:47]
	v_mfma_f32_16x16x32_bf16 v[36:39], v[206:209], v[178:181], v[36:39]
	v_mfma_f32_16x16x32_bf16 v[28:31], v[214:217], v[178:181], v[28:31]
	v_mfma_f32_16x16x32_bf16 v[20:23], v[206:209], v[186:189], v[20:23]
	v_mfma_f32_16x16x32_bf16 v[12:15], v[214:217], v[186:189], v[12:15]
	v_mfma_f32_16x16x32_bf16 v[4:7], v[206:209], v[194:197], v[4:7]
	v_mfma_f32_16x16x32_bf16 v[0:3], v[214:217], v[194:197], v[0:3]
	v_mfma_f32_16x16x32_bf16 v[52:55], v[210:213], v[174:177], v[52:55]
	v_mfma_f32_16x16x32_bf16 v[44:47], v[218:221], v[174:177], v[44:47]
	v_mfma_f32_16x16x32_bf16 v[36:39], v[210:213], v[182:185], v[36:39]
	v_mfma_f32_16x16x32_bf16 v[28:31], v[218:221], v[182:185], v[28:31]
	v_mfma_f32_16x16x32_bf16 v[20:23], v[210:213], v[190:193], v[20:23]
	v_mfma_f32_16x16x32_bf16 v[12:15], v[218:221], v[190:193], v[12:15]
	v_mfma_f32_16x16x32_bf16 v[4:7], v[210:213], v[202:205], v[4:7]
	v_mfma_f32_16x16x32_bf16 v[0:3], v[218:221], v[202:205], v[0:3]
	s_setprio 0
	s_barrier
	ds_read_b128 v[146:149], v141
	ds_read_b128 v[150:153], v141 offset:1024
	ds_read_b128 v[160:163], v141 offset:2048
	ds_read_b128 v[166:169], v141 offset:3072
	s_add_u32 s24, s24, 0x80000
	s_addc_u32 s25, s25, 0
	s_mov_b32 m0, s54
	ds_read_b128 v[170:173], v139 offset:32768
	ds_read_b128 v[174:177], v139 offset:33792
	ds_read_b128 v[178:181], v139 offset:34816
	ds_read_b128 v[182:185], v139 offset:35840
	ds_read_b128 v[186:189], v139 offset:36864
	ds_read_b128 v[190:193], v139 offset:37888
	ds_read_b128 v[194:197], v139 offset:38912
	ds_read_b128 v[202:205], v139 offset:39936
	global_load_lds_dwordx4 v128, s[24:25]
	s_mov_b32 m0, s55
	s_nop 0
	global_load_lds_dwordx4 v130, s[24:25]
	s_waitcnt lgkmcnt(8)
	s_barrier
	s_waitcnt lgkmcnt(0)
	s_setprio 1
	s_waitcnt lgkmcnt(0)
	v_mfma_f32_16x16x32_bf16 v[124:127], v[146:149], v[170:173], v[124:127]
	v_mfma_f32_16x16x32_bf16 v[120:123], v[160:163], v[170:173], v[120:123]
	v_mfma_f32_16x16x32_bf16 v[112:115], v[146:149], v[178:181], v[112:115]
	v_mfma_f32_16x16x32_bf16 v[104:107], v[160:163], v[178:181], v[104:107]
	v_mfma_f32_16x16x32_bf16 v[96:99], v[146:149], v[186:189], v[96:99]
	v_mfma_f32_16x16x32_bf16 v[88:91], v[160:163], v[186:189], v[88:91]
	v_mfma_f32_16x16x32_bf16 v[80:83], v[146:149], v[194:197], v[80:83]
	v_mfma_f32_16x16x32_bf16 v[72:75], v[160:163], v[194:197], v[72:75]
	v_mfma_f32_16x16x32_bf16 v[124:127], v[150:153], v[174:177], v[124:127]
	v_mfma_f32_16x16x32_bf16 v[120:123], v[166:169], v[174:177], v[120:123]
	v_mfma_f32_16x16x32_bf16 v[112:115], v[150:153], v[182:185], v[112:115]
	v_mfma_f32_16x16x32_bf16 v[104:107], v[166:169], v[182:185], v[104:107]
	v_mfma_f32_16x16x32_bf16 v[96:99], v[150:153], v[190:193], v[96:99]
	v_mfma_f32_16x16x32_bf16 v[88:91], v[166:169], v[190:193], v[88:91]
	v_mfma_f32_16x16x32_bf16 v[80:83], v[150:153], v[202:205], v[80:83]
	v_mfma_f32_16x16x32_bf16 v[72:75], v[166:169], v[202:205], v[72:75]
	s_setprio 0
	s_barrier
	s_mov_b32 m0, s63
	ds_read_b128 v[206:209], v142
	ds_read_b128 v[210:213], v142 offset:1024
	ds_read_b128 v[214:217], v142 offset:2048
	ds_read_b128 v[218:221], v142 offset:3072
	global_load_lds_dwordx4 v144, s[98:99]
	s_mov_b32 m0, s64
	s_nop 0
	global_load_lds_dwordx4 v132, s[98:99]
	s_barrier
; #define PG8_STAGE(bufoff, gbase, voff) do { _Pragma("unroll") for (int _i = 0; _i < 2; ++_i) \
;         __builtin_amdgcn_global_load_lds((const unsigned*)((const char*)(gbase) + (voff)[_i]), (LAS unsigned*)(lds + (bufoff) + ldsw + _i * 8192), 16, 0, 0); } while (0)
; #define PG8_LDA(dst, b, h) do { _Pragma("unroll") for (int m = 0; m < 4; ++m) _Pragma("unroll") for (int k = 0; k < 2; ++k) dst[m][k] = *(const LAS bf16x8*)(lds + PG8_SA(b, h) + aoff + m * 2048 + k * 1024); } while (0)
; #define PG8_WAIT_V(n) asm volatile("s_waitcnt vmcnt(" #n ")" ::: "memory")
; #define PG8_WAIT_L(n) asm volatile("s_waitcnt lgkmcnt(" #n ")" ::: "memory")
; #define PG8_BAR __builtin_amdgcn_s_barrier()
; #define PG8_SCHED __builtin_amdgcn_sched_barrier(0)
; template <class Epi>
; __device__ __forceinline__ void gemm_phase(LAS unsigned char* lds, const bf16_t* A, int lda, const bf16_t* Bt, int ldb, int M, int N, int K, int asel, const Epi& E, const int fixed_round = -1) {
;     ...
;             PG8_BAR; PG8_WAIT_L(0); PG8_MMA(0, 1, At, B1); PG8_BAR;
;             PG8_LDA(At, 1, 1); PG8_STAGE(PG8_SA(1, 0), a3, voffA);
;             PG8_BAR; PG8_WAIT_L(0); PG8_MMA(1, 0, At, B0); PG8_BAR; PG8_SCHED;
;             PG8_STAGE(PG8_SB(1, 1), b3 + hstepB, voffB);
;             PG8_WAIT_V(6); PG8_BAR; PG8_MMA(1, 1, At, B1); PG8_BAR;
;     ...
;     PG8_WAIT_V(0);
;     if (wr == 0) PG8_BAR;
;     PG8_BAR;
	s_waitcnt lgkmcnt(0)
	s_setprio 1
	s_waitcnt lgkmcnt(0)
	v_mfma_f32_16x16x32_bf16 v[116:119], v[206:209], v[170:173], v[116:119]
	v_mfma_f32_16x16x32_bf16 v[108:111], v[214:217], v[170:173], v[108:111]
	v_mfma_f32_16x16x32_bf16 v[100:103], v[206:209], v[178:181], v[100:103]
	v_mfma_f32_16x16x32_bf16 v[92:95], v[214:217], v[178:181], v[92:95]
	v_mfma_f32_16x16x32_bf16 v[84:87], v[206:209], v[186:189], v[84:87]
	v_mfma_f32_16x16x32_bf16 v[76:79], v[214:217], v[186:189], v[76:79]
	v_mfma_f32_16x16x32_bf16 v[68:71], v[206:209], v[194:197], v[68:71]
	v_mfma_f32_16x16x32_bf16 v[64:67], v[214:217], v[194:197], v[64:67]
	v_mfma_f32_16x16x32_bf16 v[116:119], v[210:213], v[174:177], v[116:119]
	v_mfma_f32_16x16x32_bf16 v[108:111], v[218:221], v[174:177], v[108:111]
	v_mfma_f32_16x16x32_bf16 v[100:103], v[210:213], v[182:185], v[100:103]
	v_mfma_f32_16x16x32_bf16 v[92:95], v[218:221], v[182:185], v[92:95]
	v_mfma_f32_16x16x32_bf16 v[84:87], v[210:213], v[190:193], v[84:87]
	v_mfma_f32_16x16x32_bf16 v[76:79], v[218:221], v[190:193], v[76:79]
	v_mfma_f32_16x16x32_bf16 v[68:71], v[210:213], v[202:205], v[68:71]
	v_mfma_f32_16x16x32_bf16 v[64:67], v[218:221], v[202:205], v[64:67]
	s_setprio 0
	s_mov_b32 m0, s56
	s_barrier
	ds_read_b128 v[170:173], v139 offset:49152
	ds_read_b128 v[174:177], v139 offset:50176
	ds_read_b128 v[178:181], v139 offset:51200
	ds_read_b128 v[182:185], v139 offset:52224
	ds_read_b128 v[186:189], v139 offset:53248
	ds_read_b128 v[190:193], v139 offset:54272
	ds_read_b128 v[194:197], v139 offset:55296
	ds_read_b128 v[202:205], v139 offset:56320
	global_load_lds_dwordx4 v128, s[100:101]
	s_mov_b32 m0, s57
	s_nop 0
	global_load_lds_dwordx4 v130, s[100:101]
	s_barrier
	s_waitcnt lgkmcnt(0)
	s_setprio 1
	s_waitcnt lgkmcnt(0)
	v_mfma_f32_16x16x32_bf16 v[60:63], v[146:149], v[170:173], v[60:63]
	v_mfma_f32_16x16x32_bf16 v[56:59], v[160:163], v[170:173], v[56:59]
	v_mfma_f32_16x16x32_bf16 v[48:51], v[146:149], v[178:181], v[48:51]
	v_mfma_f32_16x16x32_bf16 v[40:43], v[160:163], v[178:181], v[40:43]
	v_mfma_f32_16x16x32_bf16 v[32:35], v[146:149], v[186:189], v[32:35]
	v_mfma_f32_16x16x32_bf16 v[24:27], v[160:163], v[186:189], v[24:27]
	v_mfma_f32_16x16x32_bf16 v[16:19], v[146:149], v[194:197], v[16:19]
	v_mfma_f32_16x16x32_bf16 v[8:11], v[160:163], v[194:197], v[8:11]
	v_mfma_f32_16x16x32_bf16 v[60:63], v[150:153], v[174:177], v[60:63]
	v_mfma_f32_16x16x32_bf16 v[56:59], v[166:169], v[174:177], v[56:59]
	v_mfma_f32_16x16x32_bf16 v[48:51], v[150:153], v[182:185], v[48:51]
	v_mfma_f32_16x16x32_bf16 v[40:43], v[166:169], v[182:185], v[40:43]
	v_mfma_f32_16x16x32_bf16 v[32:35], v[150:153], v[190:193], v[32:35]
	v_mfma_f32_16x16x32_bf16 v[24:27], v[166:169], v[190:193], v[24:27]
	v_mfma_f32_16x16x32_bf16 v[16:19], v[150:153], v[202:205], v[16:19]
	v_mfma_f32_16x16x32_bf16 v[8:11], v[166:169], v[202:205], v[8:11]
	s_setprio 0
	s_barrier
	s_add_u32 s22, s22, 0x80080
	s_addc_u32 s23, s23, 0
	s_mov_b32 m0, s65
	s_nop 0
	global_load_lds_dwordx4 v144, s[22:23]
	s_mov_b32 m0, s66
	s_nop 0
	global_load_lds_dwordx4 v132, s[22:23]
	s_waitcnt vmcnt(6)
	s_barrier
	s_setprio 1
	v_mfma_f32_16x16x32_bf16 v[52:55], v[206:209], v[170:173], v[52:55]
	v_mfma_f32_16x16x32_bf16 v[44:47], v[214:217], v[170:173], v[44:47]
	v_mfma_f32_16x16x32_bf16 v[36:39], v[206:209], v[178:181], v[36:39]
	v_mfma_f32_16x16x32_bf16 v[28:31], v[214:217], v[178:181], v[28:31]
	v_mfma_f32_16x16x32_bf16 v[20:23], v[206:209], v[186:189], v[20:23]
	v_mfma_f32_16x16x32_bf16 v[12:15], v[214:217], v[186:189], v[12:15]
	v_mfma_f32_16x16x32_bf16 v[4:7], v[206:209], v[194:197], v[4:7]
	v_mfma_f32_16x16x32_bf16 v[0:3], v[214:217], v[194:197], v[0:3]
	v_mfma_f32_16x16x32_bf16 v[52:55], v[210:213], v[174:177], v[52:55]
	v_mfma_f32_16x16x32_bf16 v[44:47], v[218:221], v[174:177], v[44:47]
	v_mfma_f32_16x16x32_bf16 v[36:39], v[210:213], v[182:185], v[36:39]
	v_mfma_f32_16x16x32_bf16 v[28:31], v[218:221], v[182:185], v[28:31]
	v_mfma_f32_16x16x32_bf16 v[20:23], v[210:213], v[190:193], v[20:23]
	v_mfma_f32_16x16x32_bf16 v[12:15], v[218:221], v[190:193], v[12:15]
	v_mfma_f32_16x16x32_bf16 v[4:7], v[210:213], v[202:205], v[4:7]
	v_mfma_f32_16x16x32_bf16 v[0:3], v[218:221], v[202:205], v[0:3]
	s_setprio 0
	s_add_i32 s40, s40, 2
	s_add_u32 s6, s6, 0x100
	s_addc_u32 s7, s7, 0
	s_cmp_lt_u32 s40, 30
	s_barrier
	s_cbranch_scc1 .LBB0_1120
	s_waitcnt vmcnt(0)
	s_cmpk_gt_u32 s51, 0xff
	s_cbranch_scc1 .LBB0_1123
	s_barrier

; #define PG8_STAGE(bufoff, gbase, voff) do { _Pragma("unroll") for (int _i = 0; _i < 2; ++_i) \
;         __builtin_amdgcn_global_load_lds((const unsigned*)((const char*)(gbase) + (voff)[_i]), (LAS unsigned*)(lds + (bufoff) + ldsw + _i * 8192), 16, 0, 0); } while (0)
; #define PG8_LDA(dst, b, h) do { _Pragma("unroll") for (int m = 0; m < 4; ++m) _Pragma("unroll") for (int k = 0; k < 2; ++k) dst[m][k] = *(const LAS bf16x8*)(lds + PG8_SA(b, h) + aoff + m * 2048 + k * 1024); } while (0)
; #define PG8_LDB(dst, b, h) do { _Pragma("unroll") for (int n = 0; n < 2; ++n) _Pragma("unroll") for (int k = 0; k < 2; ++k) dst[n][k] = *(const LAS bf16x8*)(lds + PG8_SB(b, h) + boff + n * 2048 + k * 1024); } while (0)
; #define PG8_WAIT_V(n) asm volatile("s_waitcnt vmcnt(" #n ")" ::: "memory")
; #define PG8_WAIT_L(n) asm volatile("s_waitcnt lgkmcnt(" #n ")" ::: "memory")
; #define PG8_BAR __builtin_amdgcn_s_barrier()
; #define PG8_SCHED __builtin_amdgcn_sched_barrier(0)
; template <class Epi>
; __device__ __forceinline__ void gemm_phase(LAS unsigned char* lds, const bf16_t* A, int lda, const bf16_t* Bt, int ldb, int M, int N, int K, int asel, const Epi& E, const int fixed_round = -1) {
;     ...
;             PG8_LDB(B0, 0, 0); PG8_SCHED; PG8_LDA(At, 0, 0); PG8_STAGE(PG8_SA(1, 1), a1 + hstepA, voffA);
;             PG8_WAIT_L(8); PG8_BAR; PG8_WAIT_L(0); PG8_MMA(0, 0, At, B0); PG8_BAR; PG8_SCHED;
;             PG8_LDB(B1, 0, 1); PG8_STAGE(PG8_SB(0, 0), b2, voffB);
;             PG8_BAR; PG8_WAIT_L(0); PG8_MMA(0, 1, At, B1); PG8_BAR;
;             PG8_LDA(At, 0, 1); PG8_STAGE(PG8_SA(0, 0), a2, voffA);
;             PG8_BAR; PG8_WAIT_L(0); PG8_MMA(1, 0, At, B0); PG8_BAR; PG8_SCHED;
;             PG8_STAGE(PG8_SB(0, 1), b2 + hstepB, voffB);
;             PG8_WAIT_V(6); PG8_BAR; PG8_MMA(1, 1, At, B1); PG8_BAR;
.LBB0_1223:
	ds_read_b128 v[152:155], v149
	ds_read_b128 v[156:159], v149 offset:1024
	ds_read_b128 v[160:163], v149 offset:2048
	ds_read_b128 v[164:167], v149 offset:3072
	s_add_u32 s48, s46, 0xfff80080
	s_addc_u32 s49, s47, -1
	s_cmp_eq_u32 s70, 28
	s_cselect_b32 s51, s29, s49
	s_cselect_b32 s50, s66, s48
	s_cselect_b32 s49, s25, s69
	s_cselect_b32 s48, s67, s68
	s_add_i32 m0, s45, 0xc000
	ds_read_b128 v[168:171], v150
	ds_read_b128 v[172:175], v150 offset:1024
	ds_read_b128 v[176:179], v150 offset:2048
	ds_read_b128 v[180:183], v150 offset:3072
	ds_read_b128 v[184:187], v150 offset:4096
	ds_read_b128 v[188:191], v150 offset:5120
	ds_read_b128 v[192:195], v150 offset:6144
	ds_read_b128 v[196:199], v150 offset:7168
	global_load_lds_dwordx4 v136, s[46:47]
	s_add_i32 m0, s45, 0xe000
	s_nop 0
	global_load_lds_dwordx4 v138, s[46:47]
	s_waitcnt lgkmcnt(8)
	s_barrier
	s_waitcnt lgkmcnt(0)
	s_setprio 1
	s_waitcnt lgkmcnt(0)
	v_mfma_f32_16x16x32_bf16 v[124:127], v[152:155], v[168:171], v[124:127]
	v_mfma_f32_16x16x32_bf16 v[120:123], v[160:163], v[168:171], v[120:123]
	v_mfma_f32_16x16x32_bf16 v[108:111], v[152:155], v[176:179], v[108:111]
	v_mfma_f32_16x16x32_bf16 v[104:107], v[160:163], v[176:179], v[104:107]
	v_mfma_f32_16x16x32_bf16 v[92:95], v[152:155], v[184:187], v[92:95]
	v_mfma_f32_16x16x32_bf16 v[88:91], v[160:163], v[184:187], v[88:91]
	v_mfma_f32_16x16x32_bf16 v[76:79], v[152:155], v[192:195], v[76:79]
	v_mfma_f32_16x16x32_bf16 v[72:75], v[160:163], v[192:195], v[72:75]
	v_mfma_f32_16x16x32_bf16 v[124:127], v[156:159], v[172:175], v[124:127]
	v_mfma_f32_16x16x32_bf16 v[120:123], v[164:167], v[172:175], v[120:123]
	v_mfma_f32_16x16x32_bf16 v[108:111], v[156:159], v[180:183], v[108:111]
	v_mfma_f32_16x16x32_bf16 v[104:107], v[164:167], v[180:183], v[104:107]
	v_mfma_f32_16x16x32_bf16 v[92:95], v[156:159], v[188:191], v[92:95]
	v_mfma_f32_16x16x32_bf16 v[88:91], v[164:167], v[188:191], v[88:91]
	v_mfma_f32_16x16x32_bf16 v[76:79], v[156:159], v[196:199], v[76:79]
	v_mfma_f32_16x16x32_bf16 v[72:75], v[164:167], v[196:199], v[72:75]
	s_setprio 0
	s_barrier
	s_add_i32 s71, s81, s54
	s_add_u32 s98, s48, s2
	s_addc_u32 s99, s49, s3
	s_mov_b32 m0, s71
	ds_read_b128 v[202:205], v151
	ds_read_b128 v[206:209], v151 offset:1024
	ds_read_b128 v[210:213], v151 offset:2048
	ds_read_b128 v[214:217], v151 offset:3072
	global_load_lds_dwordx4 v130, s[48:49]
	s_add_i32 m0, s71, 0x2000
	s_nop 0
	global_load_lds_dwordx4 v134, s[48:49]
	s_barrier
	s_waitcnt lgkmcnt(0)
	s_setprio 1
	s_waitcnt lgkmcnt(0)
	v_mfma_f32_16x16x32_bf16 v[116:119], v[202:205], v[168:171], v[116:119]
	v_mfma_f32_16x16x32_bf16 v[112:115], v[210:213], v[168:171], v[112:115]
	v_mfma_f32_16x16x32_bf16 v[100:103], v[202:205], v[176:179], v[100:103]
	v_mfma_f32_16x16x32_bf16 v[96:99], v[210:213], v[176:179], v[96:99]
	v_mfma_f32_16x16x32_bf16 v[84:87], v[202:205], v[184:187], v[84:87]
	v_mfma_f32_16x16x32_bf16 v[80:83], v[210:213], v[184:187], v[80:83]
	v_mfma_f32_16x16x32_bf16 v[68:71], v[202:205], v[192:195], v[68:71]
	v_mfma_f32_16x16x32_bf16 v[64:67], v[210:213], v[192:195], v[64:67]
	v_mfma_f32_16x16x32_bf16 v[116:119], v[206:209], v[172:175], v[116:119]
	v_mfma_f32_16x16x32_bf16 v[112:115], v[214:217], v[172:175], v[112:115]
	v_mfma_f32_16x16x32_bf16 v[100:103], v[206:209], v[180:183], v[100:103]
	v_mfma_f32_16x16x32_bf16 v[96:99], v[214:217], v[180:183], v[96:99]
	v_mfma_f32_16x16x32_bf16 v[84:87], v[206:209], v[188:191], v[84:87]
	v_mfma_f32_16x16x32_bf16 v[80:83], v[214:217], v[188:191], v[80:83]
	v_mfma_f32_16x16x32_bf16 v[68:71], v[206:209], v[196:199], v[68:71]
	v_mfma_f32_16x16x32_bf16 v[64:67], v[214:217], v[196:199], v[64:67]
	s_setprio 0
	s_mov_b32 m0, s45
	s_add_u32 s100, s50, s2
	s_addc_u32 s101, s51, s3
	s_barrier
	ds_read_b128 v[168:171], v150 offset:16384
	ds_read_b128 v[172:175], v150 offset:17408
	ds_read_b128 v[176:179], v150 offset:18432
	ds_read_b128 v[180:183], v150 offset:19456
	ds_read_b128 v[184:187], v150 offset:20480
	ds_read_b128 v[188:191], v150 offset:21504
	ds_read_b128 v[192:195], v150 offset:22528
	ds_read_b128 v[196:199], v150 offset:23552
	global_load_lds_dwordx4 v128, s[50:51]
	s_mov_b32 m0, s55
	s_nop 0
	global_load_lds_dwordx4 v132, s[50:51]
	s_barrier
	s_waitcnt lgkmcnt(0)
	s_setprio 1
	s_waitcnt lgkmcnt(0)
	v_mfma_f32_16x16x32_bf16 v[60:63], v[152:155], v[168:171], v[60:63]
	v_mfma_f32_16x16x32_bf16 v[56:59], v[160:163], v[168:171], v[56:59]
	v_mfma_f32_16x16x32_bf16 v[44:47], v[152:155], v[176:179], v[44:47]
	v_mfma_f32_16x16x32_bf16 v[40:43], v[160:163], v[176:179], v[40:43]
	v_mfma_f32_16x16x32_bf16 v[28:31], v[152:155], v[184:187], v[28:31]
	v_mfma_f32_16x16x32_bf16 v[24:27], v[160:163], v[184:187], v[24:27]
	v_mfma_f32_16x16x32_bf16 v[12:15], v[152:155], v[192:195], v[12:15]
	v_mfma_f32_16x16x32_bf16 v[8:11], v[160:163], v[192:195], v[8:11]
	v_mfma_f32_16x16x32_bf16 v[60:63], v[156:159], v[172:175], v[60:63]
	v_mfma_f32_16x16x32_bf16 v[56:59], v[164:167], v[172:175], v[56:59]
	v_mfma_f32_16x16x32_bf16 v[44:47], v[156:159], v[180:183], v[44:47]
	v_mfma_f32_16x16x32_bf16 v[40:43], v[164:167], v[180:183], v[40:43]
	v_mfma_f32_16x16x32_bf16 v[28:31], v[156:159], v[188:191], v[28:31]
	v_mfma_f32_16x16x32_bf16 v[24:27], v[164:167], v[188:191], v[24:27]
	v_mfma_f32_16x16x32_bf16 v[12:15], v[156:159], v[196:199], v[12:15]
	v_mfma_f32_16x16x32_bf16 v[8:11], v[164:167], v[196:199], v[8:11]
	s_setprio 0
	s_barrier
	s_add_u32 s72, s48, 0x80000
	s_addc_u32 s73, s49, 0
	s_add_i32 s71, s82, s54
	s_mov_b32 m0, s71
	s_nop 0
	global_load_lds_dwordx4 v130, s[72:73]
	s_add_i32 m0, s71, 0x2000
	s_nop 0
	global_load_lds_dwordx4 v134, s[72:73]
	s_waitcnt vmcnt(6)
	s_barrier
; #define PG8_STAGE(bufoff, gbase, voff) do { _Pragma("unroll") for (int _i = 0; _i < 2; ++_i) \
;         __builtin_amdgcn_global_load_lds((const unsigned*)((const char*)(gbase) + (voff)[_i]), (LAS unsigned*)(lds + (bufoff) + ldsw + _i * 8192), 16, 0, 0); } while (0)
; #define PG8_LDA(dst, b, h) do { _Pragma("unroll") for (int m = 0; m < 4; ++m) _Pragma("unroll") for (int k = 0; k < 2; ++k) dst[m][k] = *(const LAS bf16x8*)(lds + PG8_SA(b, h) + aoff + m * 2048 + k * 1024); } while (0)
; #define PG8_LDB(dst, b, h) do { _Pragma("unroll") for (int n = 0; n < 2; ++n) _Pragma("unroll") for (int k = 0; k < 2; ++k) dst[n][k] = *(const LAS bf16x8*)(lds + PG8_SB(b, h) + boff + n * 2048 + k * 1024); } while (0)
; #define PG8_WAIT_V(n) asm volatile("s_waitcnt vmcnt(" #n ")" ::: "memory")
; #define PG8_WAIT_L(n) asm volatile("s_waitcnt lgkmcnt(" #n ")" ::: "memory")
; #define PG8_BAR __builtin_amdgcn_s_barrier()
; #define PG8_SCHED __builtin_amdgcn_sched_barrier(0)
; template <class Epi>
; __device__ __forceinline__ void gemm_phase(LAS unsigned char* lds, const bf16_t* A, int lda, const bf16_t* Bt, int ldb, int M, int N, int K, int asel, const Epi& E, const int fixed_round = -1) {
;     ...
;             PG8_WAIT_V(6); PG8_BAR; PG8_MMA(1, 1, At, B1); PG8_BAR;
;             PG8_LDB(B0, 1, 0); PG8_SCHED; PG8_LDA(At, 1, 0); PG8_STAGE(PG8_SA(0, 1), a2 + hstepA, voffA);
;             PG8_WAIT_L(8); PG8_BAR; PG8_WAIT_L(0); PG8_MMA(0, 0, At, B0); PG8_BAR; PG8_SCHED;
;             PG8_LDB(B1, 1, 1); PG8_STAGE(PG8_SB(1, 0), b3, voffB);
;             PG8_BAR; PG8_WAIT_L(0); PG8_MMA(0, 1, At, B1); PG8_BAR;
;             PG8_LDA(At, 1, 1); PG8_STAGE(PG8_SA(1, 0), a3, voffA);
	s_setprio 1
	v_mfma_f32_16x16x32_bf16 v[52:55], v[202:205], v[168:171], v[52:55]
	v_mfma_f32_16x16x32_bf16 v[48:51], v[210:213], v[168:171], v[48:51]
	v_mfma_f32_16x16x32_bf16 v[36:39], v[202:205], v[176:179], v[36:39]
	v_mfma_f32_16x16x32_bf16 v[32:35], v[210:213], v[176:179], v[32:35]
	v_mfma_f32_16x16x32_bf16 v[20:23], v[202:205], v[184:187], v[20:23]
	v_mfma_f32_16x16x32_bf16 v[16:19], v[210:213], v[184:187], v[16:19]
	v_mfma_f32_16x16x32_bf16 v[4:7], v[202:205], v[192:195], v[4:7]
	v_mfma_f32_16x16x32_bf16 v[0:3], v[210:213], v[192:195], v[0:3]
	v_mfma_f32_16x16x32_bf16 v[52:55], v[206:209], v[172:175], v[52:55]
	v_mfma_f32_16x16x32_bf16 v[48:51], v[214:217], v[172:175], v[48:51]
	v_mfma_f32_16x16x32_bf16 v[36:39], v[206:209], v[180:183], v[36:39]
	v_mfma_f32_16x16x32_bf16 v[32:35], v[214:217], v[180:183], v[32:35]
	v_mfma_f32_16x16x32_bf16 v[20:23], v[206:209], v[188:191], v[20:23]
	v_mfma_f32_16x16x32_bf16 v[16:19], v[214:217], v[188:191], v[16:19]
	v_mfma_f32_16x16x32_bf16 v[4:7], v[206:209], v[196:199], v[4:7]
	v_mfma_f32_16x16x32_bf16 v[0:3], v[214:217], v[196:199], v[0:3]
	s_setprio 0
	v_add_u32_e32 v164, s83, v147
	s_barrier
	ds_read_b128 v[152:155], v164
	ds_read_b128 v[156:159], v164 offset:1024
	ds_read_b128 v[160:163], v164 offset:2048
	ds_read_b128 v[164:167], v164 offset:3072
	s_add_u32 s50, s50, 0x80000
	s_addc_u32 s51, s51, 0
	s_mov_b32 m0, s56
	ds_read_b128 v[168:171], v150 offset:32768
	ds_read_b128 v[172:175], v150 offset:33792
	ds_read_b128 v[176:179], v150 offset:34816
	ds_read_b128 v[180:183], v150 offset:35840
	ds_read_b128 v[184:187], v150 offset:36864
	ds_read_b128 v[188:191], v150 offset:37888
	ds_read_b128 v[192:195], v150 offset:38912
	ds_read_b128 v[196:199], v150 offset:39936
	global_load_lds_dwordx4 v128, s[50:51]
	s_mov_b32 m0, s57
	s_nop 0
	global_load_lds_dwordx4 v132, s[50:51]
	s_waitcnt lgkmcnt(8)
	s_barrier
	s_waitcnt lgkmcnt(0)
	s_setprio 1
	s_waitcnt lgkmcnt(0)
	v_mfma_f32_16x16x32_bf16 v[124:127], v[152:155], v[168:171], v[124:127]
	v_mfma_f32_16x16x32_bf16 v[120:123], v[160:163], v[168:171], v[120:123]
	v_mfma_f32_16x16x32_bf16 v[108:111], v[152:155], v[176:179], v[108:111]
	v_mfma_f32_16x16x32_bf16 v[104:107], v[160:163], v[176:179], v[104:107]
	v_mfma_f32_16x16x32_bf16 v[92:95], v[152:155], v[184:187], v[92:95]
	v_mfma_f32_16x16x32_bf16 v[88:91], v[160:163], v[184:187], v[88:91]
	v_mfma_f32_16x16x32_bf16 v[76:79], v[152:155], v[192:195], v[76:79]
	v_mfma_f32_16x16x32_bf16 v[72:75], v[160:163], v[192:195], v[72:75]
	v_mfma_f32_16x16x32_bf16 v[124:127], v[156:159], v[172:175], v[124:127]
	v_mfma_f32_16x16x32_bf16 v[120:123], v[164:167], v[172:175], v[120:123]
	v_mfma_f32_16x16x32_bf16 v[108:111], v[156:159], v[180:183], v[108:111]
	v_mfma_f32_16x16x32_bf16 v[104:107], v[164:167], v[180:183], v[104:107]
	v_mfma_f32_16x16x32_bf16 v[92:95], v[156:159], v[188:191], v[92:95]
	v_mfma_f32_16x16x32_bf16 v[88:91], v[164:167], v[188:191], v[88:91]
	v_mfma_f32_16x16x32_bf16 v[76:79], v[156:159], v[196:199], v[76:79]
	v_mfma_f32_16x16x32_bf16 v[72:75], v[164:167], v[196:199], v[72:75]
	s_setprio 0
	s_barrier
	s_add_i32 s50, s83, s54
	v_add_u32_e32 v214, s84, v147
	s_mov_b32 m0, s50
	ds_read_b128 v[202:205], v214
	ds_read_b128 v[206:209], v214 offset:1024
	ds_read_b128 v[210:213], v214 offset:2048
	ds_read_b128 v[214:217], v214 offset:3072
	global_load_lds_dwordx4 v130, s[98:99]
	s_add_i32 m0, s50, 0x2000
	s_nop 0
	global_load_lds_dwordx4 v134, s[98:99]
	s_barrier
	s_waitcnt lgkmcnt(0)
	s_setprio 1
	s_waitcnt lgkmcnt(0)
	v_mfma_f32_16x16x32_bf16 v[116:119], v[202:205], v[168:171], v[116:119]
	v_mfma_f32_16x16x32_bf16 v[112:115], v[210:213], v[168:171], v[112:115]
	v_mfma_f32_16x16x32_bf16 v[100:103], v[202:205], v[176:179], v[100:103]
	v_mfma_f32_16x16x32_bf16 v[96:99], v[210:213], v[176:179], v[96:99]
	v_mfma_f32_16x16x32_bf16 v[84:87], v[202:205], v[184:187], v[84:87]
	v_mfma_f32_16x16x32_bf16 v[80:83], v[210:213], v[184:187], v[80:83]
	v_mfma_f32_16x16x32_bf16 v[68:71], v[202:205], v[192:195], v[68:71]
	v_mfma_f32_16x16x32_bf16 v[64:67], v[210:213], v[192:195], v[64:67]
	v_mfma_f32_16x16x32_bf16 v[116:119], v[206:209], v[172:175], v[116:119]
	v_mfma_f32_16x16x32_bf16 v[112:115], v[214:217], v[172:175], v[112:115]
	v_mfma_f32_16x16x32_bf16 v[100:103], v[206:209], v[180:183], v[100:103]
	v_mfma_f32_16x16x32_bf16 v[96:99], v[214:217], v[180:183], v[96:99]
	v_mfma_f32_16x16x32_bf16 v[84:87], v[206:209], v[188:191], v[84:87]
	v_mfma_f32_16x16x32_bf16 v[80:83], v[214:217], v[188:191], v[80:83]
	v_mfma_f32_16x16x32_bf16 v[68:71], v[206:209], v[196:199], v[68:71]
	v_mfma_f32_16x16x32_bf16 v[64:67], v[214:217], v[196:199], v[64:67]
	s_setprio 0
	s_mov_b32 m0, s59
	s_barrier
	ds_read_b128 v[168:171], v150 offset:49152
	ds_read_b128 v[172:175], v150 offset:50176
	ds_read_b128 v[176:179], v150 offset:51200
	ds_read_b128 v[180:183], v150 offset:52224
	ds_read_b128 v[184:187], v150 offset:53248
	ds_read_b128 v[188:191], v150 offset:54272
	ds_read_b128 v[192:195], v150 offset:55296
	ds_read_b128 v[196:199], v150 offset:56320
	global_load_lds_dwordx4 v128, s[100:101]
	s_mov_b32 m0, s60
	s_nop 0
	global_load_lds_dwordx4 v132, s[100:101]
	s_barrier
; __device__ __forceinline__ unsigned cvt_pk_bf16(float lo, float hi) { const bf16x2_t r = __builtin_convertvector((f32x2){lo, hi}, bf16x2_t); return __builtin_bit_cast(unsigned, r); }
; #define PG8_STAGE(bufoff, gbase, voff) do { _Pragma("unroll") for (int _i = 0; _i < 2; ++_i) \
;         __builtin_amdgcn_global_load_lds((const unsigned*)((const char*)(gbase) + (voff)[_i]), (LAS unsigned*)(lds + (bufoff) + ldsw + _i * 8192), 16, 0, 0); } while (0)
; #define PG8_WAIT_V(n) asm volatile("s_waitcnt vmcnt(" #n ")" ::: "memory")
; #define PG8_WAIT_L(n) asm volatile("s_waitcnt lgkmcnt(" #n ")" ::: "memory")
; #define PG8_BAR __builtin_amdgcn_s_barrier()
; #define PG8_SCHED __builtin_amdgcn_sched_barrier(0)
; template <class Epi>
; __device__ __forceinline__ void gemm_phase(LAS unsigned char* lds, const bf16_t* A, int lda, const bf16_t* Bt, int ldb, int M, int N, int K, int asel, const Epi& E, const int fixed_round = -1) {
;     ...
;             PG8_BAR; PG8_WAIT_L(0); PG8_MMA(1, 0, At, B0); PG8_BAR; PG8_SCHED;
;             PG8_STAGE(PG8_SB(1, 1), b3 + hstepB, voffB);
;             PG8_WAIT_V(6); PG8_BAR; PG8_MMA(1, 1, At, B1); PG8_BAR;
;     __device__ __forceinline__ void operator()(const AccT& acc, const Unit& u, int wr, int wc, int fr, int fq) const {
;         const int row0 = u.pm * BM + wr * 64 + fr, col0 = u.pn * BM + wc * 32 + 8 * fq;
; #pragma unroll
;         for (int ai = 0; ai < 2; ++ai)
; #pragma unroll
;             for (int m = 0; m < 4; ++m) { bf16_t* rowp = O + (size_t)(row0 + ai * HALF + m * 16) * DFF + col0;
; #pragma unroll
;                 for (int bj = 0; bj < 2; ++bj) { f32x4 v0 = acc[ai][bj][m][0], v1 = acc[ai][bj][m][1];
; #pragma unroll
;                     for (int j = 0; j < 4; ++j) { float a = fmaxf(v0[j], 0.f), b = fmaxf(v1[j], 0.f); v0[j] = a * a; v1[j] = b * b; }
;                     u32x4 w; w.x = cvt_pk_bf16(v0[0], v0[1]); w.y = cvt_pk_bf16(v0[2], v0[3]); w.z = cvt_pk_bf16(v1[0], v1[1]); w.w = cvt_pk_bf16(v1[2], v1[3]);
;                     *(u32x4*)(rowp + bj * HALF) = w; } }
	s_waitcnt lgkmcnt(0)
	s_setprio 1
	s_waitcnt lgkmcnt(0)
	v_mfma_f32_16x16x32_bf16 v[60:63], v[152:155], v[168:171], v[60:63]
	v_mfma_f32_16x16x32_bf16 v[56:59], v[160:163], v[168:171], v[56:59]
	v_mfma_f32_16x16x32_bf16 v[44:47], v[152:155], v[176:179], v[44:47]
	v_mfma_f32_16x16x32_bf16 v[40:43], v[160:163], v[176:179], v[40:43]
	v_mfma_f32_16x16x32_bf16 v[28:31], v[152:155], v[184:187], v[28:31]
	v_mfma_f32_16x16x32_bf16 v[24:27], v[160:163], v[184:187], v[24:27]
	v_mfma_f32_16x16x32_bf16 v[12:15], v[152:155], v[192:195], v[12:15]
	v_mfma_f32_16x16x32_bf16 v[8:11], v[160:163], v[192:195], v[8:11]
	v_mfma_f32_16x16x32_bf16 v[60:63], v[156:159], v[172:175], v[60:63]
	v_mfma_f32_16x16x32_bf16 v[56:59], v[164:167], v[172:175], v[56:59]
	v_mfma_f32_16x16x32_bf16 v[44:47], v[156:159], v[180:183], v[44:47]
	v_mfma_f32_16x16x32_bf16 v[40:43], v[164:167], v[180:183], v[40:43]
	v_mfma_f32_16x16x32_bf16 v[28:31], v[156:159], v[188:191], v[28:31]
	v_mfma_f32_16x16x32_bf16 v[24:27], v[164:167], v[188:191], v[24:27]
	v_mfma_f32_16x16x32_bf16 v[12:15], v[156:159], v[196:199], v[12:15]
	v_mfma_f32_16x16x32_bf16 v[8:11], v[164:167], v[196:199], v[8:11]
	s_setprio 0
	s_barrier
	s_add_u32 s48, s48, 0x80080
	s_addc_u32 s49, s49, 0
	s_add_i32 s50, s84, s54
	s_mov_b32 m0, s50
	s_nop 0
	global_load_lds_dwordx4 v130, s[48:49]
	s_add_i32 m0, s50, 0x2000
	s_nop 0
	global_load_lds_dwordx4 v134, s[48:49]
	s_waitcnt vmcnt(6)
	s_barrier
	s_setprio 1
	v_mfma_f32_16x16x32_bf16 v[52:55], v[202:205], v[168:171], v[52:55]
	v_mfma_f32_16x16x32_bf16 v[48:51], v[210:213], v[168:171], v[48:51]
	v_mfma_f32_16x16x32_bf16 v[36:39], v[202:205], v[176:179], v[36:39]
	v_mfma_f32_16x16x32_bf16 v[32:35], v[210:213], v[176:179], v[32:35]
	v_mfma_f32_16x16x32_bf16 v[20:23], v[202:205], v[184:187], v[20:23]
	v_mfma_f32_16x16x32_bf16 v[16:19], v[210:213], v[184:187], v[16:19]
	v_mfma_f32_16x16x32_bf16 v[4:7], v[202:205], v[192:195], v[4:7]
	v_mfma_f32_16x16x32_bf16 v[0:3], v[210:213], v[192:195], v[0:3]
	v_mfma_f32_16x16x32_bf16 v[52:55], v[206:209], v[172:175], v[52:55]
	v_mfma_f32_16x16x32_bf16 v[48:51], v[214:217], v[172:175], v[48:51]
	v_mfma_f32_16x16x32_bf16 v[36:39], v[206:209], v[180:183], v[36:39]
	v_mfma_f32_16x16x32_bf16 v[32:35], v[214:217], v[180:183], v[32:35]
	v_mfma_f32_16x16x32_bf16 v[20:23], v[206:209], v[188:191], v[20:23]
	v_mfma_f32_16x16x32_bf16 v[16:19], v[214:217], v[188:191], v[16:19]
	v_mfma_f32_16x16x32_bf16 v[4:7], v[206:209], v[196:199], v[4:7]
	v_mfma_f32_16x16x32_bf16 v[0:3], v[214:217], v[196:199], v[0:3]
	s_setprio 0
	s_add_i32 s70, s70, 2
	s_add_u32 s46, s46, 0x100
	s_addc_u32 s47, s47, 0
	s_add_u32 s68, s68, 0x100
	s_addc_u32 s69, s69, 0
	s_cmp_gt_u32 s70, 29
	s_barrier
	s_cbranch_scc0 .LBB0_1223
	v_lshl_add_u32 v152, s44, 8, v146
	v_lshl_or_b32 v144, s65, 8, v148
	v_ashrrev_i32_e32 v153, 31, v152
	v_readlane_b32 s46, v254, 60
	v_ashrrev_i32_e32 v145, 31, v144
	v_lshlrev_b64 v[154:155], 14, v[152:153]
	v_readlane_b32 s47, v254, 61
	v_max_f32_e32 v120, v120, v120
	v_max_f32_e32 v121, v121, v121
	v_lshl_add_u64 v[154:155], s[46:47], 0, v[154:155]
	v_lshlrev_b64 v[156:157], 1, v[144:145]
	v_max_f32_e32 v120, 0, v120
	v_max_f32_e32 v121, 0, v121
	v_lshl_add_u64 v[144:145], v[154:155], 0, v[156:157]
	v_pk_mul_f32 v[154:155], v[120:121], v[120:121]
	v_max_f32_e32 v121, v122, v122
	v_max_f32_e32 v124, v124, v124
	v_max_f32_e32 v125, v125, v125
	v_max_f32_e32 v120, v126, v126
	v_max_f32_e32 v122, 0, v121
	v_max_f32_e32 v121, v127, v127
	v_max_f32_e32 v123, v123, v123
	v_max_f32_e32 v124, 0, v124
	v_max_f32_e32 v125, 0, v125
	v_max_f32_e32 v120, 0, v120
	v_max_f32_e32 v121, 0, v121
	v_max_f32_e32 v123, 0, v123
	v_pk_mul_f32 v[124:125], v[124:125], v[124:125]
	v_pk_mul_f32 v[126:127], v[120:121], v[120:121]
	v_pk_mul_f32 v[158:159], v[122:123], v[122:123]
	v_max_f32_e32 v112, v112, v112
	v_max_f32_e32 v113, v113, v113
	v_cvt_pk_bf16_f32 v120, v124, v125
	v_cvt_pk_bf16_f32 v121, v126, v127
	v_cvt_pk_bf16_f32 v122, v154, v155
	v_cvt_pk_bf16_f32 v123, v158, v159
	v_max_f32_e32 v112, 0, v112
	v_max_f32_e32 v113, 0, v113
	global_store_dwordx4 v[144:145], v[120:123], off
	v_max_f32_e32 v116, v116, v116
	v_max_f32_e32 v117, v117, v117
	v_pk_mul_f32 v[120:121], v[112:113], v[112:113]
	v_max_f32_e32 v113, v114, v114
	v_max_f32_e32 v112, v118, v118
	v_max_f32_e32 v114, 0, v113
	v_max_f32_e32 v113, v119, v119
	v_max_f32_e32 v115, v115, v115
	v_max_f32_e32 v116, 0, v116
	v_max_f32_e32 v117, 0, v117
	v_max_f32_e32 v112, 0, v112
	v_max_f32_e32 v113, 0, v113
	v_max_f32_e32 v115, 0, v115
	v_pk_mul_f32 v[116:117], v[116:117], v[116:117]
	v_pk_mul_f32 v[118:119], v[112:113], v[112:113]
	v_pk_mul_f32 v[122:123], v[114:115], v[114:115]
	v_max_f32_e32 v104, v104, v104
	v_max_f32_e32 v105, v105, v105
	v_cvt_pk_bf16_f32 v112, v116, v117
	v_cvt_pk_bf16_f32 v113, v118, v119
	v_cvt_pk_bf16_f32 v114, v120, v121
	v_cvt_pk_bf16_f32 v115, v122, v123
	v_max_f32_e32 v104, 0, v104
	v_max_f32_e32 v105, 0, v105
	global_store_dwordx4 v[144:145], v[112:115], off offset:256
	v_max_f32_e32 v108, v108, v108
	v_max_f32_e32 v109, v109, v109
	v_or_b32_e32 v112, 16, v152
	v_pk_mul_f32 v[114:115], v[104:105], v[104:105]
	v_max_f32_e32 v105, v106, v106
	v_ashrrev_i32_e32 v113, 31, v112
	v_max_f32_e32 v104, v110, v110
	v_max_f32_e32 v106, 0, v105
	v_max_f32_e32 v105, v111, v111
	v_max_f32_e32 v107, v107, v107
	v_lshlrev_b64 v[112:113], 14, v[112:113]
	v_max_f32_e32 v108, 0, v108
	v_max_f32_e32 v109, 0, v109
	v_max_f32_e32 v104, 0, v104
	v_max_f32_e32 v105, 0, v105
	v_max_f32_e32 v107, 0, v107
	v_lshl_add_u64 v[112:113], s[46:47], 0, v[112:113]
	v_pk_mul_f32 v[108:109], v[108:109], v[108:109]
; __device__ __forceinline__ unsigned cvt_pk_bf16(float lo, float hi) { const bf16x2_t r = __builtin_convertvector((f32x2){lo, hi}, bf16x2_t); return __builtin_bit_cast(unsigned, r); }
;     __device__ __forceinline__ void operator()(const AccT& acc, const Unit& u, int wr, int wc, int fr, int fq) const {
;         const int row0 = u.pm * BM + wr * 64 + fr, col0 = u.pn * BM + wc * 32 + 8 * fq;
; #pragma unroll
;         for (int ai = 0; ai < 2; ++ai)
; #pragma unroll
;             for (int m = 0; m < 4; ++m) { bf16_t* rowp = O + (size_t)(row0 + ai * HALF + m * 16) * DFF + col0;
; #pragma unroll
;                 for (int bj = 0; bj < 2; ++bj) { f32x4 v0 = acc[ai][bj][m][0], v1 = acc[ai][bj][m][1];
; #pragma unroll
;                     for (int j = 0; j < 4; ++j) { float a = fmaxf(v0[j], 0.f), b = fmaxf(v1[j], 0.f); v0[j] = a * a; v1[j] = b * b; }
;                     u32x4 w; w.x = cvt_pk_bf16(v0[0], v0[1]); w.y = cvt_pk_bf16(v0[2], v0[3]); w.z = cvt_pk_bf16(v1[0], v1[1]); w.w = cvt_pk_bf16(v1[2], v1[3]);
;                     *(u32x4*)(rowp + bj * HALF) = w; } }
	v_pk_mul_f32 v[110:111], v[104:105], v[104:105]
	v_pk_mul_f32 v[116:117], v[106:107], v[106:107]
	v_max_f32_e32 v96, v96, v96
	v_max_f32_e32 v97, v97, v97
	v_lshl_add_u64 v[112:113], v[112:113], 0, v[156:157]
	v_cvt_pk_bf16_f32 v104, v108, v109
	v_cvt_pk_bf16_f32 v105, v110, v111
	v_cvt_pk_bf16_f32 v106, v114, v115
	v_cvt_pk_bf16_f32 v107, v116, v117
	v_max_f32_e32 v96, 0, v96
	v_max_f32_e32 v97, 0, v97
	global_store_dwordx4 v[112:113], v[104:107], off
	v_max_f32_e32 v100, v100, v100
	v_max_f32_e32 v101, v101, v101
	v_pk_mul_f32 v[104:105], v[96:97], v[96:97]
	v_max_f32_e32 v97, v98, v98
	v_max_f32_e32 v96, v102, v102
	v_max_f32_e32 v98, 0, v97
	v_max_f32_e32 v97, v103, v103
	v_max_f32_e32 v99, v99, v99
	v_max_f32_e32 v100, 0, v100
	v_max_f32_e32 v101, 0, v101
	v_max_f32_e32 v96, 0, v96
	v_max_f32_e32 v97, 0, v97
	v_max_f32_e32 v99, 0, v99
	v_pk_mul_f32 v[100:101], v[100:101], v[100:101]
	v_pk_mul_f32 v[102:103], v[96:97], v[96:97]
	v_pk_mul_f32 v[106:107], v[98:99], v[98:99]
	v_max_f32_e32 v88, v88, v88
	v_max_f32_e32 v89, v89, v89
	v_cvt_pk_bf16_f32 v96, v100, v101
	v_cvt_pk_bf16_f32 v97, v102, v103
	v_cvt_pk_bf16_f32 v98, v104, v105
	v_cvt_pk_bf16_f32 v99, v106, v107
	v_max_f32_e32 v88, 0, v88
	v_max_f32_e32 v89, 0, v89
	global_store_dwordx4 v[112:113], v[96:99], off offset:256
	v_max_f32_e32 v92, v92, v92
	v_max_f32_e32 v93, v93, v93
	v_or_b32_e32 v96, 32, v152
	v_pk_mul_f32 v[98:99], v[88:89], v[88:89]
	v_max_f32_e32 v89, v90, v90
	v_ashrrev_i32_e32 v97, 31, v96
	v_max_f32_e32 v88, v94, v94
	v_max_f32_e32 v90, 0, v89
	v_max_f32_e32 v89, v95, v95
	v_max_f32_e32 v91, v91, v91
	v_lshlrev_b64 v[96:97], 14, v[96:97]
	v_max_f32_e32 v92, 0, v92
	v_max_f32_e32 v93, 0, v93
	v_max_f32_e32 v88, 0, v88
	v_max_f32_e32 v89, 0, v89
	v_max_f32_e32 v91, 0, v91
	v_lshl_add_u64 v[96:97], s[46:47], 0, v[96:97]
	v_pk_mul_f32 v[92:93], v[92:93], v[92:93]
	v_pk_mul_f32 v[94:95], v[88:89], v[88:89]
	v_pk_mul_f32 v[100:101], v[90:91], v[90:91]
	v_max_f32_e32 v80, v80, v80
	v_max_f32_e32 v81, v81, v81
	v_lshl_add_u64 v[96:97], v[96:97], 0, v[156:157]
	v_cvt_pk_bf16_f32 v88, v92, v93
	v_cvt_pk_bf16_f32 v89, v94, v95
	v_cvt_pk_bf16_f32 v90, v98, v99
	v_cvt_pk_bf16_f32 v91, v100, v101
	v_max_f32_e32 v80, 0, v80
	v_max_f32_e32 v81, 0, v81
	global_store_dwordx4 v[96:97], v[88:91], off
	v_max_f32_e32 v84, v84, v84
	v_max_f32_e32 v85, v85, v85
	v_pk_mul_f32 v[88:89], v[80:81], v[80:81]
	v_max_f32_e32 v81, v82, v82
	v_max_f32_e32 v80, v86, v86
	v_max_f32_e32 v82, 0, v81
	v_max_f32_e32 v81, v87, v87
	v_max_f32_e32 v83, v83, v83
	v_max_f32_e32 v84, 0, v84
	v_max_f32_e32 v85, 0, v85
	v_max_f32_e32 v80, 0, v80
	v_max_f32_e32 v81, 0, v81
	v_max_f32_e32 v83, 0, v83
	v_pk_mul_f32 v[84:85], v[84:85], v[84:85]
	v_pk_mul_f32 v[86:87], v[80:81], v[80:81]
	v_pk_mul_f32 v[90:91], v[82:83], v[82:83]
	v_max_f32_e32 v72, v72, v72
	v_max_f32_e32 v73, v73, v73
	v_cvt_pk_bf16_f32 v80, v84, v85
	v_cvt_pk_bf16_f32 v81, v86, v87
	v_cvt_pk_bf16_f32 v82, v88, v89
	v_cvt_pk_bf16_f32 v83, v90, v91
	v_max_f32_e32 v72, 0, v72
	v_max_f32_e32 v73, 0, v73
	global_store_dwordx4 v[96:97], v[80:83], off offset:256
	v_max_f32_e32 v76, v76, v76
	v_max_f32_e32 v77, v77, v77
	v_or_b32_e32 v80, 48, v152
	v_pk_mul_f32 v[82:83], v[72:73], v[72:73]
	v_max_f32_e32 v73, v74, v74
	v_ashrrev_i32_e32 v81, 31, v80
	v_max_f32_e32 v72, v78, v78
	v_max_f32_e32 v74, 0, v73
	v_max_f32_e32 v73, v79, v79
	v_max_f32_e32 v75, v75, v75
	v_lshlrev_b64 v[80:81], 14, v[80:81]
	v_max_f32_e32 v76, 0, v76
	v_max_f32_e32 v77, 0, v77
	v_max_f32_e32 v72, 0, v72
	v_max_f32_e32 v73, 0, v73
	v_max_f32_e32 v75, 0, v75
	v_lshl_add_u64 v[80:81], s[46:47], 0, v[80:81]
	v_pk_mul_f32 v[76:77], v[76:77], v[76:77]
	v_pk_mul_f32 v[78:79], v[72:73], v[72:73]
	v_pk_mul_f32 v[84:85], v[74:75], v[74:75]
	v_max_f32_e32 v64, v64, v64
	v_max_f32_e32 v65, v65, v65
	v_lshl_add_u64 v[80:81], v[80:81], 0, v[156:157]
	v_cvt_pk_bf16_f32 v72, v76, v77
	v_cvt_pk_bf16_f32 v73, v78, v79
	v_cvt_pk_bf16_f32 v74, v82, v83
	v_cvt_pk_bf16_f32 v75, v84, v85
	v_max_f32_e32 v64, 0, v64
	v_max_f32_e32 v65, 0, v65
	global_store_dwordx4 v[80:81], v[72:75], off
	v_max_f32_e32 v68, v68, v68
	v_max_f32_e32 v69, v69, v69
	v_pk_mul_f32 v[72:73], v[64:65], v[64:65]
	v_max_f32_e32 v65, v66, v66
	v_max_f32_e32 v64, v70, v70
	v_max_f32_e32 v66, 0, v65
	v_max_f32_e32 v65, v71, v71
	v_max_f32_e32 v67, v67, v67
	v_max_f32_e32 v68, 0, v68
	v_max_f32_e32 v69, 0, v69
	v_max_f32_e32 v64, 0, v64
	v_max_f32_e32 v65, 0, v65
	v_max_f32_e32 v67, 0, v67
	v_pk_mul_f32 v[68:69], v[68:69], v[68:69]
	v_pk_mul_f32 v[70:71], v[64:65], v[64:65]
	v_pk_mul_f32 v[74:75], v[66:67], v[66:67]
	v_max_f32_e32 v56, v56, v56
	v_max_f32_e32 v57, v57, v57
	v_cvt_pk_bf16_f32 v64, v68, v69
	v_cvt_pk_bf16_f32 v65, v70, v71
	v_cvt_pk_bf16_f32 v66, v72, v73
	v_cvt_pk_bf16_f32 v67, v74, v75
	v_max_f32_e32 v56, 0, v56
	v_max_f32_e32 v57, 0, v57
	global_store_dwordx4 v[80:81], v[64:67], off offset:256
	v_max_f32_e32 v60, v60, v60
	v_max_f32_e32 v61, v61, v61
	v_pk_mul_f32 v[66:67], v[56:57], v[56:57]
	v_max_f32_e32 v57, v58, v58
	v_max_f32_e32 v60, 0, v60
	v_max_f32_e32 v61, 0, v61
	v_max_f32_e32 v56, v62, v62
	v_max_f32_e32 v58, 0, v57
	v_max_f32_e32 v57, v63, v63
	v_max_f32_e32 v59, v59, v59
	v_pk_mul_f32 v[60:61], v[60:61], v[60:61]
	v_max_f32_e32 v56, 0, v56
	v_max_f32_e32 v57, 0, v57
	v_max_f32_e32 v59, 0, v59
	v_pk_mul_f32 v[62:63], v[56:57], v[56:57]
	v_pk_mul_f32 v[68:69], v[58:59], v[58:59]
	v_cvt_pk_bf16_f32 v56, v60, v61
	v_add_co_u32_e32 v60, vcc, s61, v144
	v_max_f32_e32 v48, v48, v48
	v_max_f32_e32 v49, v49, v49
	v_cvt_pk_bf16_f32 v57, v62, v63
	v_cvt_pk_bf16_f32 v58, v66, v67
	v_cvt_pk_bf16_f32 v59, v68, v69
; __device__ __forceinline__ unsigned cvt_pk_bf16(float lo, float hi) { const bf16x2_t r = __builtin_convertvector((f32x2){lo, hi}, bf16x2_t); return __builtin_bit_cast(unsigned, r); }
; #define PG8_WAIT_V(n) asm volatile("s_waitcnt vmcnt(" #n ")" ::: "memory")
; #define PG8_BAR __builtin_amdgcn_s_barrier()
; template <class Epi>
; __device__ __forceinline__ void gemm_phase(LAS unsigned char* lds, const bf16_t* A, int lda, const bf16_t* Bt, int ldb, int M, int N, int K, int asel, const Epi& E, const int fixed_round = -1) {
;     ...
;         if (!has_next) break;
; #pragma unroll
;         for (int a = 0; a < 2; ++a)
; #pragma unroll
;             for (int b = 0; b < 2; ++b)
; #pragma unroll
;                 for (int m = 0; m < 4; ++m)
; #pragma unroll
;                     for (int n = 0; n < 2; ++n) acc[a][b][m][n] = (f32x4){0.f, 0.f, 0.f, 0.f};
;         cur = nxt; cA = nA; cB = nB; ++ui;
;     }
;     PG8_WAIT_V(0);
;     if (wr == 0) PG8_BAR;
;     PG8_BAR;
;     __device__ __forceinline__ void operator()(const AccT& acc, const Unit& u, int wr, int wc, int fr, int fq) const {
;         const int row0 = u.pm * BM + wr * 64 + fr, col0 = u.pn * BM + wc * 32 + 8 * fq;
; #pragma unroll
;         for (int ai = 0; ai < 2; ++ai)
; #pragma unroll
;             for (int m = 0; m < 4; ++m) { bf16_t* rowp = O + (size_t)(row0 + ai * HALF + m * 16) * DFF + col0;
; #pragma unroll
;                 for (int bj = 0; bj < 2; ++bj) { f32x4 v0 = acc[ai][bj][m][0], v1 = acc[ai][bj][m][1];
; #pragma unroll
;                     for (int j = 0; j < 4; ++j) { float a = fmaxf(v0[j], 0.f), b = fmaxf(v1[j], 0.f); v0[j] = a * a; v1[j] = b * b; }
;                     u32x4 w; w.x = cvt_pk_bf16(v0[0], v0[1]); w.y = cvt_pk_bf16(v0[2], v0[3]); w.z = cvt_pk_bf16(v1[0], v1[1]); w.w = cvt_pk_bf16(v1[2], v1[3]);
;                     *(u32x4*)(rowp + bj * HALF) = w; } }
;     }
	v_addc_co_u32_e32 v61, vcc, 0, v145, vcc
	v_max_f32_e32 v48, 0, v48
	v_max_f32_e32 v49, 0, v49
	global_store_dwordx4 v[60:61], v[56:59], off
	v_max_f32_e32 v52, v52, v52
	v_max_f32_e32 v53, v53, v53
	v_pk_mul_f32 v[56:57], v[48:49], v[48:49]
	v_max_f32_e32 v49, v50, v50
	v_max_f32_e32 v48, v54, v54
	v_max_f32_e32 v50, 0, v49
	v_max_f32_e32 v49, v55, v55
	v_max_f32_e32 v51, v51, v51
	v_max_f32_e32 v52, 0, v52
	v_max_f32_e32 v53, 0, v53
	v_max_f32_e32 v48, 0, v48
	v_max_f32_e32 v49, 0, v49
	v_max_f32_e32 v51, 0, v51
	s_mov_b64 s[46:47], 0x200000
	v_pk_mul_f32 v[52:53], v[52:53], v[52:53]
	v_pk_mul_f32 v[54:55], v[48:49], v[48:49]
	v_pk_mul_f32 v[58:59], v[50:51], v[50:51]
	v_max_f32_e32 v40, v40, v40
	v_max_f32_e32 v41, v41, v41
	v_lshl_add_u64 v[64:65], v[144:145], 0, s[46:47]
	v_cvt_pk_bf16_f32 v48, v52, v53
	v_cvt_pk_bf16_f32 v49, v54, v55
	v_cvt_pk_bf16_f32 v50, v56, v57
	v_cvt_pk_bf16_f32 v51, v58, v59
	v_max_f32_e32 v40, 0, v40
	v_max_f32_e32 v41, 0, v41
	global_store_dwordx4 v[64:65], v[48:51], off offset:256
	v_max_f32_e32 v44, v44, v44
	v_max_f32_e32 v45, v45, v45
	v_pk_mul_f32 v[50:51], v[40:41], v[40:41]
	v_max_f32_e32 v41, v42, v42
	v_max_f32_e32 v44, 0, v44
	v_max_f32_e32 v45, 0, v45
	v_max_f32_e32 v40, v46, v46
	v_max_f32_e32 v42, 0, v41
	v_max_f32_e32 v41, v47, v47
	v_max_f32_e32 v43, v43, v43
	v_pk_mul_f32 v[44:45], v[44:45], v[44:45]
	v_max_f32_e32 v40, 0, v40
	v_max_f32_e32 v41, 0, v41
	v_max_f32_e32 v43, 0, v43
	v_pk_mul_f32 v[46:47], v[40:41], v[40:41]
	v_pk_mul_f32 v[52:53], v[42:43], v[42:43]
	v_cvt_pk_bf16_f32 v40, v44, v45
	v_add_co_u32_e32 v44, vcc, s62, v144
	v_max_f32_e32 v32, v32, v32
	v_max_f32_e32 v33, v33, v33
	v_cvt_pk_bf16_f32 v41, v46, v47
	v_cvt_pk_bf16_f32 v42, v50, v51
	v_cvt_pk_bf16_f32 v43, v52, v53
	v_addc_co_u32_e32 v45, vcc, 0, v145, vcc
	v_max_f32_e32 v32, 0, v32
	v_max_f32_e32 v33, 0, v33
	global_store_dwordx4 v[44:45], v[40:43], off
	v_max_f32_e32 v36, v36, v36
	v_max_f32_e32 v37, v37, v37
	v_pk_mul_f32 v[40:41], v[32:33], v[32:33]
	v_max_f32_e32 v33, v34, v34
	v_max_f32_e32 v32, v38, v38
	v_max_f32_e32 v34, 0, v33
	v_max_f32_e32 v33, v39, v39
	v_max_f32_e32 v35, v35, v35
	v_max_f32_e32 v36, 0, v36
	v_max_f32_e32 v37, 0, v37
	v_max_f32_e32 v32, 0, v32
	v_max_f32_e32 v33, 0, v33
	v_max_f32_e32 v35, 0, v35
	v_pk_mul_f32 v[36:37], v[36:37], v[36:37]
	v_pk_mul_f32 v[38:39], v[32:33], v[32:33]
	v_pk_mul_f32 v[42:43], v[34:35], v[34:35]
	v_max_f32_e32 v24, v24, v24
	v_max_f32_e32 v25, v25, v25
	v_lshl_add_u64 v[48:49], v[144:145], 0, s[4:5]
	v_cvt_pk_bf16_f32 v32, v36, v37
	v_cvt_pk_bf16_f32 v33, v38, v39
	v_cvt_pk_bf16_f32 v34, v40, v41
	v_cvt_pk_bf16_f32 v35, v42, v43
	v_max_f32_e32 v24, 0, v24
	v_max_f32_e32 v25, 0, v25
	global_store_dwordx4 v[48:49], v[32:35], off offset:256
	v_max_f32_e32 v28, v28, v28
	v_max_f32_e32 v29, v29, v29
	v_pk_mul_f32 v[34:35], v[24:25], v[24:25]
	v_max_f32_e32 v25, v26, v26
	v_max_f32_e32 v28, 0, v28
	v_max_f32_e32 v29, 0, v29
	v_max_f32_e32 v24, v30, v30
	v_max_f32_e32 v26, 0, v25
	v_max_f32_e32 v25, v31, v31
	v_max_f32_e32 v27, v27, v27
	v_pk_mul_f32 v[28:29], v[28:29], v[28:29]
	v_max_f32_e32 v24, 0, v24
	v_max_f32_e32 v25, 0, v25
	v_max_f32_e32 v27, 0, v27
	v_pk_mul_f32 v[30:31], v[24:25], v[24:25]
	v_pk_mul_f32 v[36:37], v[26:27], v[26:27]
	v_cvt_pk_bf16_f32 v24, v28, v29
	v_add_co_u32_e32 v28, vcc, s63, v144
	v_max_f32_e32 v16, v16, v16
	v_max_f32_e32 v17, v17, v17
	v_cvt_pk_bf16_f32 v25, v30, v31
	v_cvt_pk_bf16_f32 v26, v34, v35
	v_cvt_pk_bf16_f32 v27, v36, v37
	v_addc_co_u32_e32 v29, vcc, 0, v145, vcc
	v_max_f32_e32 v16, 0, v16
	v_max_f32_e32 v17, 0, v17
	global_store_dwordx4 v[28:29], v[24:27], off
	v_max_f32_e32 v20, v20, v20
	v_max_f32_e32 v21, v21, v21
	v_pk_mul_f32 v[24:25], v[16:17], v[16:17]
	v_max_f32_e32 v17, v18, v18
	v_max_f32_e32 v16, v22, v22
	v_max_f32_e32 v18, 0, v17
	v_max_f32_e32 v17, v23, v23
	v_max_f32_e32 v19, v19, v19
	v_max_f32_e32 v20, 0, v20
	v_max_f32_e32 v21, 0, v21
	v_max_f32_e32 v16, 0, v16
	v_max_f32_e32 v17, 0, v17
	v_max_f32_e32 v19, 0, v19
	v_pk_mul_f32 v[20:21], v[20:21], v[20:21]
	v_pk_mul_f32 v[22:23], v[16:17], v[16:17]
	v_pk_mul_f32 v[26:27], v[18:19], v[18:19]
	v_max_f32_e32 v8, v8, v8
	v_max_f32_e32 v9, v9, v9
	v_lshl_add_u64 v[32:33], v[144:145], 0, s[6:7]
	v_cvt_pk_bf16_f32 v16, v20, v21
	v_cvt_pk_bf16_f32 v17, v22, v23
	v_cvt_pk_bf16_f32 v18, v24, v25
	v_cvt_pk_bf16_f32 v19, v26, v27
	v_max_f32_e32 v8, 0, v8
	v_max_f32_e32 v9, 0, v9
	global_store_dwordx4 v[32:33], v[16:19], off offset:256
	v_max_f32_e32 v12, v12, v12
	v_max_f32_e32 v13, v13, v13
	v_pk_mul_f32 v[18:19], v[8:9], v[8:9]
	v_max_f32_e32 v9, v10, v10
	v_max_f32_e32 v12, 0, v12
	v_max_f32_e32 v13, 0, v13
	v_max_f32_e32 v8, v14, v14
	v_max_f32_e32 v10, 0, v9
	v_max_f32_e32 v9, v15, v15
	v_max_f32_e32 v11, v11, v11
	v_pk_mul_f32 v[12:13], v[12:13], v[12:13]
	v_max_f32_e32 v8, 0, v8
	v_max_f32_e32 v9, 0, v9
	v_max_f32_e32 v11, 0, v11
	v_pk_mul_f32 v[14:15], v[8:9], v[8:9]
	v_pk_mul_f32 v[20:21], v[10:11], v[10:11]
	v_cvt_pk_bf16_f32 v8, v12, v13
	v_add_co_u32_e32 v12, vcc, s64, v144
	v_max_f32_e32 v0, v0, v0
	v_max_f32_e32 v1, v1, v1
	v_cvt_pk_bf16_f32 v9, v14, v15
	v_cvt_pk_bf16_f32 v10, v18, v19
	v_cvt_pk_bf16_f32 v11, v20, v21
	v_addc_co_u32_e32 v13, vcc, 0, v145, vcc
	v_max_f32_e32 v0, 0, v0
	v_max_f32_e32 v1, 0, v1
	global_store_dwordx4 v[12:13], v[8:11], off
	v_max_f32_e32 v4, v4, v4
	v_max_f32_e32 v5, v5, v5
	v_pk_mul_f32 v[8:9], v[0:1], v[0:1]
	v_max_f32_e32 v1, v2, v2
	v_max_f32_e32 v0, v6, v6
	v_max_f32_e32 v2, 0, v1
	v_max_f32_e32 v1, v7, v7
	v_max_f32_e32 v3, v3, v3
	v_max_f32_e32 v4, 0, v4
	v_max_f32_e32 v5, 0, v5
	v_max_f32_e32 v0, 0, v0
	v_max_f32_e32 v1, 0, v1
	v_max_f32_e32 v3, 0, v3
	v_pk_mul_f32 v[4:5], v[4:5], v[4:5]
	v_pk_mul_f32 v[6:7], v[0:1], v[0:1]
	v_pk_mul_f32 v[10:11], v[2:3], v[2:3]
	v_lshl_add_u64 v[16:17], v[144:145], 0, s[22:23]
	v_cvt_pk_bf16_f32 v0, v4, v5
	v_cvt_pk_bf16_f32 v1, v6, v7
	v_cvt_pk_bf16_f32 v2, v8, v9
	v_cvt_pk_bf16_f32 v3, v10, v11
	s_and_b64 vcc, exec, s[0:1]
	s_mov_b32 s65, s24
	s_mov_b32 s44, s28
	s_mov_b64 s[48:49], s[42:43]
	s_mov_b64 s[46:47], s[40:41]
	s_mov_b64 s[70:71], s[26:27]
	global_store_dwordx4 v[16:17], v[0:3], off offset:256
	s_cbranch_vccz .LBB0_1216
	s_waitcnt vmcnt(0)
	s_cmpk_gt_u32 s33, 0xff
	s_cbranch_scc1 .LBB0_1227
	s_barrier

; #define PG8_STAGE(bufoff, gbase, voff) do { _Pragma("unroll") for (int _i = 0; _i < 2; ++_i) \
;         __builtin_amdgcn_global_load_lds((const unsigned*)((const char*)(gbase) + (voff)[_i]), (LAS unsigned*)(lds + (bufoff) + ldsw + _i * 8192), 16, 0, 0); } while (0)
; #define PG8_LDA(dst, b, h) do { _Pragma("unroll") for (int m = 0; m < 4; ++m) _Pragma("unroll") for (int k = 0; k < 2; ++k) dst[m][k] = *(const LAS bf16x8*)(lds + PG8_SA(b, h) + aoff + m * 2048 + k * 1024); } while (0)
; #define PG8_LDB(dst, b, h) do { _Pragma("unroll") for (int n = 0; n < 2; ++n) _Pragma("unroll") for (int k = 0; k < 2; ++k) dst[n][k] = *(const LAS bf16x8*)(lds + PG8_SB(b, h) + boff + n * 2048 + k * 1024); } while (0)
; #define PG8_WAIT_V(n) asm volatile("s_waitcnt vmcnt(" #n ")" ::: "memory")
; #define PG8_WAIT_L(n) asm volatile("s_waitcnt lgkmcnt(" #n ")" ::: "memory")
; #define PG8_BAR __builtin_amdgcn_s_barrier()
; #define PG8_SCHED __builtin_amdgcn_sched_barrier(0)
; template <class Epi>
; __device__ __forceinline__ void gemm_phase(LAS unsigned char* lds, const bf16_t* A, int lda, const bf16_t* Bt, int ldb, int M, int N, int K, int asel, const Epi& E, const int fixed_round = -1) {
;     ...
;         for (int t = 0; t < nt; t += 2) {
;             const bool last = (t == nt - 2);
;             const char* a1 = cA + (size_t)(t + 1) * kstep;
;             const char* a2 = last ? nA : cA + (size_t)(t + 2) * kstep; const char* b2 = last ? nB : cB + (size_t)(t + 2) * kstep;
;             const char* a3 = a2 + kstep; const char* b3 = b2 + kstep;
;             PG8_LDB(B0, 0, 0); PG8_SCHED; PG8_LDA(At, 0, 0); PG8_STAGE(PG8_SA(1, 1), a1 + hstepA, voffA);
;             PG8_WAIT_L(8); PG8_BAR; PG8_WAIT_L(0); PG8_MMA(0, 0, At, B0); PG8_BAR; PG8_SCHED;
;             PG8_LDB(B1, 0, 1); PG8_STAGE(PG8_SB(0, 0), b2, voffB);
;             PG8_BAR; PG8_WAIT_L(0); PG8_MMA(0, 1, At, B1); PG8_BAR;
;             PG8_LDA(At, 0, 1); PG8_STAGE(PG8_SA(0, 0), a2, voffA);
;             PG8_BAR; PG8_WAIT_L(0); PG8_MMA(1, 0, At, B0); PG8_BAR; PG8_SCHED;
;             PG8_STAGE(PG8_SB(0, 1), b2 + hstepB, voffB);
;             PG8_WAIT_V(6); PG8_BAR; PG8_MMA(1, 1, At, B1); PG8_BAR;
.LBB0_1283:
	s_add_u32 s24, s16, s22
	ds_read_b128 v[146:149], v124
	ds_read_b128 v[150:153], v124 offset:1024
	ds_read_b128 v[154:157], v124 offset:2048
	ds_read_b128 v[158:161], v124 offset:3072
	s_addc_u32 s25, s17, s23
	s_add_u32 s24, s24, 0x18500100
	s_addc_u32 s25, s25, 0
	s_add_u32 s57, s28, s22
	s_addc_u32 s58, s29, s23
	s_cmpk_eq_i32 s22, 0x3f00
	s_cselect_b32 s27, s87, s25
	s_cselect_b32 s26, s86, s24
	s_cselect_b32 s25, s3, s58
	s_cselect_b32 s24, s2, s57
	s_mov_b32 m0, s47
	v_lshl_add_u64 v[194:195], v[120:121], 0, s[22:23]
	ds_read_b128 v[162:165], v125
	ds_read_b128 v[166:169], v125 offset:1024
	ds_read_b128 v[170:173], v125 offset:2048
	ds_read_b128 v[174:177], v125 offset:3072
	ds_read_b128 v[178:181], v125 offset:4096
	ds_read_b128 v[182:185], v125 offset:5120
	ds_read_b128 v[186:189], v125 offset:6144
	ds_read_b128 v[190:193], v125 offset:7168
	global_load_lds_dwordx4 v[194:195], off
	v_lshl_add_u64 v[194:195], v[122:123], 0, s[22:23]
	s_mov_b32 m0, s48
	s_nop 0
	global_load_lds_dwordx4 v[194:195], off
	s_waitcnt lgkmcnt(8)
	s_barrier
	s_waitcnt lgkmcnt(0)
	s_setprio 1
	s_waitcnt lgkmcnt(0)
	v_mfma_f32_16x16x32_bf16 v[140:143], v[146:149], v[162:165], v[140:143]
	v_mfma_f32_16x16x32_bf16 v[136:139], v[154:157], v[162:165], v[136:139]
	v_mfma_f32_16x16x32_bf16 v[108:111], v[146:149], v[170:173], v[108:111]
	v_mfma_f32_16x16x32_bf16 v[104:107], v[154:157], v[170:173], v[104:107]
	v_mfma_f32_16x16x32_bf16 v[92:95], v[146:149], v[178:181], v[92:95]
	v_mfma_f32_16x16x32_bf16 v[88:91], v[154:157], v[178:181], v[88:91]
	v_mfma_f32_16x16x32_bf16 v[76:79], v[146:149], v[186:189], v[76:79]
	v_mfma_f32_16x16x32_bf16 v[72:75], v[154:157], v[186:189], v[72:75]
	v_mfma_f32_16x16x32_bf16 v[140:143], v[150:153], v[166:169], v[140:143]
	v_mfma_f32_16x16x32_bf16 v[136:139], v[158:161], v[166:169], v[136:139]
	v_mfma_f32_16x16x32_bf16 v[108:111], v[150:153], v[174:177], v[108:111]
	v_mfma_f32_16x16x32_bf16 v[104:107], v[158:161], v[174:177], v[104:107]
	v_mfma_f32_16x16x32_bf16 v[92:95], v[150:153], v[182:185], v[92:95]
	v_mfma_f32_16x16x32_bf16 v[88:91], v[158:161], v[182:185], v[88:91]
	v_mfma_f32_16x16x32_bf16 v[76:79], v[150:153], v[190:193], v[76:79]
	v_mfma_f32_16x16x32_bf16 v[72:75], v[158:161], v[190:193], v[72:75]
	s_setprio 0
	s_barrier
	s_mov_b32 m0, s49
	s_add_u32 s98, s24, s0
	s_addc_u32 s99, s25, s1
	ds_read_b128 v[194:197], v126
	ds_read_b128 v[204:207], v126 offset:1024
	ds_read_b128 v[208:211], v126 offset:2048
	ds_read_b128 v[212:215], v126 offset:3072
	global_load_lds_dwordx4 v114, s[24:25]
	s_mov_b32 m0, s50
	s_nop 0
	global_load_lds_dwordx4 v118, s[24:25]
	s_barrier
	s_waitcnt lgkmcnt(0)
	s_setprio 1
	s_waitcnt lgkmcnt(0)
	v_mfma_f32_16x16x32_bf16 v[132:135], v[194:197], v[162:165], v[132:135]
	v_mfma_f32_16x16x32_bf16 v[128:131], v[208:211], v[162:165], v[128:131]
	v_mfma_f32_16x16x32_bf16 v[100:103], v[194:197], v[170:173], v[100:103]
	v_mfma_f32_16x16x32_bf16 v[96:99], v[208:211], v[170:173], v[96:99]
	v_mfma_f32_16x16x32_bf16 v[84:87], v[194:197], v[178:181], v[84:87]
	v_mfma_f32_16x16x32_bf16 v[80:83], v[208:211], v[178:181], v[80:83]
	v_mfma_f32_16x16x32_bf16 v[68:71], v[194:197], v[186:189], v[68:71]
	v_mfma_f32_16x16x32_bf16 v[64:67], v[208:211], v[186:189], v[64:67]
	v_mfma_f32_16x16x32_bf16 v[132:135], v[204:207], v[166:169], v[132:135]
	v_mfma_f32_16x16x32_bf16 v[128:131], v[212:215], v[166:169], v[128:131]
	v_mfma_f32_16x16x32_bf16 v[100:103], v[204:207], v[174:177], v[100:103]
	v_mfma_f32_16x16x32_bf16 v[96:99], v[212:215], v[174:177], v[96:99]
	v_mfma_f32_16x16x32_bf16 v[84:87], v[204:207], v[182:185], v[84:87]
	v_mfma_f32_16x16x32_bf16 v[80:83], v[212:215], v[182:185], v[80:83]
	v_mfma_f32_16x16x32_bf16 v[68:71], v[204:207], v[190:193], v[68:71]
	v_mfma_f32_16x16x32_bf16 v[64:67], v[212:215], v[190:193], v[64:67]
	s_setprio 0
	s_mov_b32 m0, s40
	s_add_u32 s100, s26, s0
	s_addc_u32 s101, s27, s1
	s_barrier
	ds_read_b128 v[162:165], v125 offset:16384
	ds_read_b128 v[166:169], v125 offset:17408
	ds_read_b128 v[170:173], v125 offset:18432
	ds_read_b128 v[174:177], v125 offset:19456
	ds_read_b128 v[178:181], v125 offset:20480
	ds_read_b128 v[182:185], v125 offset:21504
	ds_read_b128 v[186:189], v125 offset:22528
	ds_read_b128 v[190:193], v125 offset:23552
	global_load_lds_dwordx4 v112, s[26:27]
	s_mov_b32 m0, s41
	s_nop 0
	global_load_lds_dwordx4 v116, s[26:27]
	s_barrier
	s_waitcnt lgkmcnt(0)
	s_setprio 1
	s_waitcnt lgkmcnt(0)
	v_mfma_f32_16x16x32_bf16 v[60:63], v[146:149], v[162:165], v[60:63]
	v_mfma_f32_16x16x32_bf16 v[56:59], v[154:157], v[162:165], v[56:59]
	v_mfma_f32_16x16x32_bf16 v[44:47], v[146:149], v[170:173], v[44:47]
	v_mfma_f32_16x16x32_bf16 v[40:43], v[154:157], v[170:173], v[40:43]
	v_mfma_f32_16x16x32_bf16 v[28:31], v[146:149], v[178:181], v[28:31]
	v_mfma_f32_16x16x32_bf16 v[24:27], v[154:157], v[178:181], v[24:27]
	v_mfma_f32_16x16x32_bf16 v[12:15], v[146:149], v[186:189], v[12:15]
	v_mfma_f32_16x16x32_bf16 v[8:11], v[154:157], v[186:189], v[8:11]
	v_mfma_f32_16x16x32_bf16 v[60:63], v[150:153], v[166:169], v[60:63]
	v_mfma_f32_16x16x32_bf16 v[56:59], v[158:161], v[166:169], v[56:59]
	v_mfma_f32_16x16x32_bf16 v[44:47], v[150:153], v[174:177], v[44:47]
	v_mfma_f32_16x16x32_bf16 v[40:43], v[158:161], v[174:177], v[40:43]
	v_mfma_f32_16x16x32_bf16 v[28:31], v[150:153], v[182:185], v[28:31]
	v_mfma_f32_16x16x32_bf16 v[24:27], v[158:161], v[182:185], v[24:27]
	v_mfma_f32_16x16x32_bf16 v[12:15], v[150:153], v[190:193], v[12:15]
	v_mfma_f32_16x16x32_bf16 v[8:11], v[158:161], v[190:193], v[8:11]
	s_setprio 0
	s_barrier
; #define PG8_STAGE(bufoff, gbase, voff) do { _Pragma("unroll") for (int _i = 0; _i < 2; ++_i) \
;         __builtin_amdgcn_global_load_lds((const unsigned*)((const char*)(gbase) + (voff)[_i]), (LAS unsigned*)(lds + (bufoff) + ldsw + _i * 8192), 16, 0, 0); } while (0)
; #define PG8_LDA(dst, b, h) do { _Pragma("unroll") for (int m = 0; m < 4; ++m) _Pragma("unroll") for (int k = 0; k < 2; ++k) dst[m][k] = *(const LAS bf16x8*)(lds + PG8_SA(b, h) + aoff + m * 2048 + k * 1024); } while (0)
; #define PG8_LDB(dst, b, h) do { _Pragma("unroll") for (int n = 0; n < 2; ++n) _Pragma("unroll") for (int k = 0; k < 2; ++k) dst[n][k] = *(const LAS bf16x8*)(lds + PG8_SB(b, h) + boff + n * 2048 + k * 1024); } while (0)
; #define PG8_WAIT_V(n) asm volatile("s_waitcnt vmcnt(" #n ")" ::: "memory")
; #define PG8_WAIT_L(n) asm volatile("s_waitcnt lgkmcnt(" #n ")" ::: "memory")
; #define PG8_BAR __builtin_amdgcn_s_barrier()
; #define PG8_SCHED __builtin_amdgcn_sched_barrier(0)
; template <class Epi>
; __device__ __forceinline__ void gemm_phase(LAS unsigned char* lds, const bf16_t* A, int lda, const bf16_t* Bt, int ldb, int M, int N, int K, int asel, const Epi& E, const int fixed_round = -1) {
;     ...
;             PG8_STAGE(PG8_SB(0, 1), b2 + hstepB, voffB);
;             PG8_WAIT_V(6); PG8_BAR; PG8_MMA(1, 1, At, B1); PG8_BAR;
;             PG8_LDB(B0, 1, 0); PG8_SCHED; PG8_LDA(At, 1, 0); PG8_STAGE(PG8_SA(0, 1), a2 + hstepA, voffA);
;             PG8_WAIT_L(8); PG8_BAR; PG8_WAIT_L(0); PG8_MMA(0, 0, At, B0); PG8_BAR; PG8_SCHED;
;             PG8_LDB(B1, 1, 1); PG8_STAGE(PG8_SB(1, 0), b3, voffB);
;             PG8_BAR; PG8_WAIT_L(0); PG8_MMA(0, 1, At, B1); PG8_BAR;
;             PG8_LDA(At, 1, 1); PG8_STAGE(PG8_SA(1, 0), a3, voffA);
	s_add_u32 s58, s24, 0x200000
	s_addc_u32 s59, s25, 0
	s_mov_b32 m0, s51
	s_nop 0
	global_load_lds_dwordx4 v114, s[58:59]
	s_mov_b32 m0, s52
	s_nop 0
	global_load_lds_dwordx4 v118, s[58:59]
	s_waitcnt vmcnt(6)
	s_barrier
	s_setprio 1
	v_mfma_f32_16x16x32_bf16 v[52:55], v[194:197], v[162:165], v[52:55]
	v_mfma_f32_16x16x32_bf16 v[48:51], v[208:211], v[162:165], v[48:51]
	v_mfma_f32_16x16x32_bf16 v[36:39], v[194:197], v[170:173], v[36:39]
	v_mfma_f32_16x16x32_bf16 v[32:35], v[208:211], v[170:173], v[32:35]
	v_mfma_f32_16x16x32_bf16 v[20:23], v[194:197], v[178:181], v[20:23]
	v_mfma_f32_16x16x32_bf16 v[16:19], v[208:211], v[178:181], v[16:19]
	v_mfma_f32_16x16x32_bf16 v[4:7], v[194:197], v[186:189], v[4:7]
	v_mfma_f32_16x16x32_bf16 v[0:3], v[208:211], v[186:189], v[0:3]
	v_mfma_f32_16x16x32_bf16 v[52:55], v[204:207], v[166:169], v[52:55]
	v_mfma_f32_16x16x32_bf16 v[48:51], v[212:215], v[166:169], v[48:51]
	v_mfma_f32_16x16x32_bf16 v[36:39], v[204:207], v[174:177], v[36:39]
	v_mfma_f32_16x16x32_bf16 v[32:35], v[212:215], v[174:177], v[32:35]
	v_mfma_f32_16x16x32_bf16 v[20:23], v[204:207], v[182:185], v[20:23]
	v_mfma_f32_16x16x32_bf16 v[16:19], v[212:215], v[182:185], v[16:19]
	v_mfma_f32_16x16x32_bf16 v[4:7], v[204:207], v[190:193], v[4:7]
	v_mfma_f32_16x16x32_bf16 v[0:3], v[212:215], v[190:193], v[0:3]
	s_setprio 0
	s_barrier
	ds_read_b128 v[146:149], v127
	ds_read_b128 v[150:153], v127 offset:1024
	ds_read_b128 v[154:157], v127 offset:2048
	ds_read_b128 v[158:161], v127 offset:3072
	s_add_u32 s26, s26, 0x200000
	s_addc_u32 s27, s27, 0
	s_mov_b32 m0, s42
	ds_read_b128 v[162:165], v125 offset:32768
	ds_read_b128 v[166:169], v125 offset:33792
	ds_read_b128 v[170:173], v125 offset:34816
	ds_read_b128 v[174:177], v125 offset:35840
	ds_read_b128 v[178:181], v125 offset:36864
	ds_read_b128 v[182:185], v125 offset:37888
	ds_read_b128 v[186:189], v125 offset:38912
	ds_read_b128 v[190:193], v125 offset:39936
	global_load_lds_dwordx4 v112, s[26:27]
	s_mov_b32 m0, s43
	s_nop 0
	global_load_lds_dwordx4 v116, s[26:27]
	s_waitcnt lgkmcnt(8)
	s_barrier
	s_waitcnt lgkmcnt(0)
	s_setprio 1
	s_waitcnt lgkmcnt(0)
	v_mfma_f32_16x16x32_bf16 v[140:143], v[146:149], v[162:165], v[140:143]
	v_mfma_f32_16x16x32_bf16 v[136:139], v[154:157], v[162:165], v[136:139]
	v_mfma_f32_16x16x32_bf16 v[108:111], v[146:149], v[170:173], v[108:111]
	v_mfma_f32_16x16x32_bf16 v[104:107], v[154:157], v[170:173], v[104:107]
	v_mfma_f32_16x16x32_bf16 v[92:95], v[146:149], v[178:181], v[92:95]
	v_mfma_f32_16x16x32_bf16 v[88:91], v[154:157], v[178:181], v[88:91]
	v_mfma_f32_16x16x32_bf16 v[76:79], v[146:149], v[186:189], v[76:79]
	v_mfma_f32_16x16x32_bf16 v[72:75], v[154:157], v[186:189], v[72:75]
	v_mfma_f32_16x16x32_bf16 v[140:143], v[150:153], v[166:169], v[140:143]
	v_mfma_f32_16x16x32_bf16 v[136:139], v[158:161], v[166:169], v[136:139]
	v_mfma_f32_16x16x32_bf16 v[108:111], v[150:153], v[174:177], v[108:111]
	v_mfma_f32_16x16x32_bf16 v[104:107], v[158:161], v[174:177], v[104:107]
	v_mfma_f32_16x16x32_bf16 v[92:95], v[150:153], v[182:185], v[92:95]
	v_mfma_f32_16x16x32_bf16 v[88:91], v[158:161], v[182:185], v[88:91]
	v_mfma_f32_16x16x32_bf16 v[76:79], v[150:153], v[190:193], v[76:79]
	v_mfma_f32_16x16x32_bf16 v[72:75], v[158:161], v[190:193], v[72:75]
	s_setprio 0
	s_barrier
	s_mov_b32 m0, s53
	ds_read_b128 v[194:197], v144
	ds_read_b128 v[204:207], v144 offset:1024
	ds_read_b128 v[208:211], v144 offset:2048
	ds_read_b128 v[212:215], v144 offset:3072
	global_load_lds_dwordx4 v114, s[98:99]
	s_mov_b32 m0, s54
	s_nop 0
	global_load_lds_dwordx4 v118, s[98:99]
	s_barrier
; #define PG8_STAGE(bufoff, gbase, voff) do { _Pragma("unroll") for (int _i = 0; _i < 2; ++_i) \
;         __builtin_amdgcn_global_load_lds((const unsigned*)((const char*)(gbase) + (voff)[_i]), (LAS unsigned*)(lds + (bufoff) + ldsw + _i * 8192), 16, 0, 0); } while (0)
; #define PG8_LDA(dst, b, h) do { _Pragma("unroll") for (int m = 0; m < 4; ++m) _Pragma("unroll") for (int k = 0; k < 2; ++k) dst[m][k] = *(const LAS bf16x8*)(lds + PG8_SA(b, h) + aoff + m * 2048 + k * 1024); } while (0)
; #define PG8_WAIT_V(n) asm volatile("s_waitcnt vmcnt(" #n ")" ::: "memory")
; #define PG8_WAIT_L(n) asm volatile("s_waitcnt lgkmcnt(" #n ")" ::: "memory")
; #define PG8_BAR __builtin_amdgcn_s_barrier()
; #define PG8_SCHED __builtin_amdgcn_sched_barrier(0)
; template <class Epi>
; __device__ __forceinline__ void gemm_phase(LAS unsigned char* lds, const bf16_t* A, int lda, const bf16_t* Bt, int ldb, int M, int N, int K, int asel, const Epi& E, const int fixed_round = -1) {
;     ...
;             PG8_BAR; PG8_WAIT_L(0); PG8_MMA(0, 1, At, B1); PG8_BAR;
;             PG8_LDA(At, 1, 1); PG8_STAGE(PG8_SA(1, 0), a3, voffA);
;             PG8_BAR; PG8_WAIT_L(0); PG8_MMA(1, 0, At, B0); PG8_BAR; PG8_SCHED;
;             PG8_STAGE(PG8_SB(1, 1), b3 + hstepB, voffB);
;             PG8_WAIT_V(6); PG8_BAR; PG8_MMA(1, 1, At, B1); PG8_BAR;
;     ...
;     PG8_WAIT_V(0);
;     if (wr == 0) PG8_BAR;
;     PG8_BAR;
	s_waitcnt lgkmcnt(0)
	s_setprio 1
	s_waitcnt lgkmcnt(0)
	v_mfma_f32_16x16x32_bf16 v[132:135], v[194:197], v[162:165], v[132:135]
	v_mfma_f32_16x16x32_bf16 v[128:131], v[208:211], v[162:165], v[128:131]
	v_mfma_f32_16x16x32_bf16 v[100:103], v[194:197], v[170:173], v[100:103]
	v_mfma_f32_16x16x32_bf16 v[96:99], v[208:211], v[170:173], v[96:99]
	v_mfma_f32_16x16x32_bf16 v[84:87], v[194:197], v[178:181], v[84:87]
	v_mfma_f32_16x16x32_bf16 v[80:83], v[208:211], v[178:181], v[80:83]
	v_mfma_f32_16x16x32_bf16 v[68:71], v[194:197], v[186:189], v[68:71]
	v_mfma_f32_16x16x32_bf16 v[64:67], v[208:211], v[186:189], v[64:67]
	v_mfma_f32_16x16x32_bf16 v[132:135], v[204:207], v[166:169], v[132:135]
	v_mfma_f32_16x16x32_bf16 v[128:131], v[212:215], v[166:169], v[128:131]
	v_mfma_f32_16x16x32_bf16 v[100:103], v[204:207], v[174:177], v[100:103]
	v_mfma_f32_16x16x32_bf16 v[96:99], v[212:215], v[174:177], v[96:99]
	v_mfma_f32_16x16x32_bf16 v[84:87], v[204:207], v[182:185], v[84:87]
	v_mfma_f32_16x16x32_bf16 v[80:83], v[212:215], v[182:185], v[80:83]
	v_mfma_f32_16x16x32_bf16 v[68:71], v[204:207], v[190:193], v[68:71]
	v_mfma_f32_16x16x32_bf16 v[64:67], v[212:215], v[190:193], v[64:67]
	s_setprio 0
	s_mov_b32 m0, s44
	s_barrier
	ds_read_b128 v[162:165], v125 offset:49152
	ds_read_b128 v[166:169], v125 offset:50176
	ds_read_b128 v[170:173], v125 offset:51200
	ds_read_b128 v[174:177], v125 offset:52224
	ds_read_b128 v[178:181], v125 offset:53248
	ds_read_b128 v[182:185], v125 offset:54272
	ds_read_b128 v[186:189], v125 offset:55296
	ds_read_b128 v[190:193], v125 offset:56320
	global_load_lds_dwordx4 v112, s[100:101]
	s_mov_b32 m0, s45
	s_nop 0
	global_load_lds_dwordx4 v116, s[100:101]
	s_barrier
	s_waitcnt lgkmcnt(0)
	s_setprio 1
	s_waitcnt lgkmcnt(0)
	v_mfma_f32_16x16x32_bf16 v[60:63], v[146:149], v[162:165], v[60:63]
	v_mfma_f32_16x16x32_bf16 v[56:59], v[154:157], v[162:165], v[56:59]
	v_mfma_f32_16x16x32_bf16 v[44:47], v[146:149], v[170:173], v[44:47]
	v_mfma_f32_16x16x32_bf16 v[40:43], v[154:157], v[170:173], v[40:43]
	v_mfma_f32_16x16x32_bf16 v[28:31], v[146:149], v[178:181], v[28:31]
	v_mfma_f32_16x16x32_bf16 v[24:27], v[154:157], v[178:181], v[24:27]
	v_mfma_f32_16x16x32_bf16 v[12:15], v[146:149], v[186:189], v[12:15]
	v_mfma_f32_16x16x32_bf16 v[8:11], v[154:157], v[186:189], v[8:11]
	v_mfma_f32_16x16x32_bf16 v[60:63], v[150:153], v[166:169], v[60:63]
	v_mfma_f32_16x16x32_bf16 v[56:59], v[158:161], v[166:169], v[56:59]
	v_mfma_f32_16x16x32_bf16 v[44:47], v[150:153], v[174:177], v[44:47]
	v_mfma_f32_16x16x32_bf16 v[40:43], v[158:161], v[174:177], v[40:43]
	v_mfma_f32_16x16x32_bf16 v[28:31], v[150:153], v[182:185], v[28:31]
	v_mfma_f32_16x16x32_bf16 v[24:27], v[158:161], v[182:185], v[24:27]
	v_mfma_f32_16x16x32_bf16 v[12:15], v[150:153], v[190:193], v[12:15]
	v_mfma_f32_16x16x32_bf16 v[8:11], v[158:161], v[190:193], v[8:11]
	s_setprio 0
	s_barrier
	s_add_u32 s24, s24, 0x200080
	s_addc_u32 s25, s25, 0
	s_mov_b32 m0, s55
	s_nop 0
	global_load_lds_dwordx4 v114, s[24:25]
	s_mov_b32 m0, s56
	s_nop 0
	global_load_lds_dwordx4 v118, s[24:25]
	s_waitcnt vmcnt(6)
	s_barrier
	s_setprio 1
	v_mfma_f32_16x16x32_bf16 v[52:55], v[194:197], v[162:165], v[52:55]
	v_mfma_f32_16x16x32_bf16 v[48:51], v[208:211], v[162:165], v[48:51]
	v_mfma_f32_16x16x32_bf16 v[36:39], v[194:197], v[170:173], v[36:39]
	v_mfma_f32_16x16x32_bf16 v[32:35], v[208:211], v[170:173], v[32:35]
	v_mfma_f32_16x16x32_bf16 v[20:23], v[194:197], v[178:181], v[20:23]
	v_mfma_f32_16x16x32_bf16 v[16:19], v[208:211], v[178:181], v[16:19]
	v_mfma_f32_16x16x32_bf16 v[4:7], v[194:197], v[186:189], v[4:7]
	v_mfma_f32_16x16x32_bf16 v[0:3], v[208:211], v[186:189], v[0:3]
	v_mfma_f32_16x16x32_bf16 v[52:55], v[204:207], v[166:169], v[52:55]
	v_mfma_f32_16x16x32_bf16 v[48:51], v[212:215], v[166:169], v[48:51]
	v_mfma_f32_16x16x32_bf16 v[36:39], v[204:207], v[174:177], v[36:39]
	v_mfma_f32_16x16x32_bf16 v[32:35], v[212:215], v[174:177], v[32:35]
	v_mfma_f32_16x16x32_bf16 v[20:23], v[204:207], v[182:185], v[20:23]
	v_mfma_f32_16x16x32_bf16 v[16:19], v[212:215], v[182:185], v[16:19]
	v_mfma_f32_16x16x32_bf16 v[4:7], v[204:207], v[190:193], v[4:7]
	v_mfma_f32_16x16x32_bf16 v[0:3], v[212:215], v[190:193], v[0:3]
	s_setprio 0
	s_add_i32 s46, s46, 2
	s_add_u32 s22, s22, 0x100
	s_addc_u32 s23, s23, 0
	s_cmpk_lt_u32 s46, 0x7e
	s_barrier
	s_cbranch_scc1 .LBB0_1283
	s_waitcnt vmcnt(0)
	v_readlane_b32 s48, v254, 0
	s_cmpk_gt_u32 s33, 0xff
	v_readlane_b32 s54, v254, 6
	v_readlane_b32 s55, v254, 7
	v_readlane_b32 s49, v254, 1
	v_readlane_b32 s50, v254, 2
	v_readlane_b32 s51, v254, 3
	v_readlane_b32 s52, v254, 4
	v_readlane_b32 s53, v254, 5
	s_cbranch_scc1 .LBB0_1286
	s_barrier

; #define PG8_STAGE(bufoff, gbase, voff) do { _Pragma("unroll") for (int _i = 0; _i < 2; ++_i) \
;         __builtin_amdgcn_global_load_lds((const unsigned*)((const char*)(gbase) + (voff)[_i]), (LAS unsigned*)(lds + (bufoff) + ldsw + _i * 8192), 16, 0, 0); } while (0)
; #define PG8_LDA(dst, b, h) do { _Pragma("unroll") for (int m = 0; m < 4; ++m) _Pragma("unroll") for (int k = 0; k < 2; ++k) dst[m][k] = *(const LAS bf16x8*)(lds + PG8_SA(b, h) + aoff + m * 2048 + k * 1024); } while (0)
; #define PG8_LDB(dst, b, h) do { _Pragma("unroll") for (int n = 0; n < 2; ++n) _Pragma("unroll") for (int k = 0; k < 2; ++k) dst[n][k] = *(const LAS bf16x8*)(lds + PG8_SB(b, h) + boff + n * 2048 + k * 1024); } while (0)
; #define PG8_WAIT_V(n) asm volatile("s_waitcnt vmcnt(" #n ")" ::: "memory")
; #define PG8_WAIT_L(n) asm volatile("s_waitcnt lgkmcnt(" #n ")" ::: "memory")
; #define PG8_BAR __builtin_amdgcn_s_barrier()
; #define PG8_SCHED __builtin_amdgcn_sched_barrier(0)
; template <class Epi>
; __device__ __forceinline__ void gemm_phase(LAS unsigned char* lds, const bf16_t* A, int lda, const bf16_t* Bt, int ldb, int M, int N, int K, int asel, const Epi& E, const int fixed_round = -1) {
;     ...
;         for (int t = 0; t < nt; t += 2) {
;             const bool last = (t == nt - 2);
;             const char* a1 = cA + (size_t)(t + 1) * kstep;
;             const char* a2 = last ? nA : cA + (size_t)(t + 2) * kstep; const char* b2 = last ? nB : cB + (size_t)(t + 2) * kstep;
;             const char* a3 = a2 + kstep; const char* b3 = b2 + kstep;
;             PG8_LDB(B0, 0, 0); PG8_SCHED; PG8_LDA(At, 0, 0); PG8_STAGE(PG8_SA(1, 1), a1 + hstepA, voffA);
;             PG8_WAIT_L(8); PG8_BAR; PG8_WAIT_L(0); PG8_MMA(0, 0, At, B0); PG8_BAR; PG8_SCHED;
;             PG8_LDB(B1, 0, 1); PG8_STAGE(PG8_SB(0, 0), b2, voffB);
;             PG8_BAR; PG8_WAIT_L(0); PG8_MMA(0, 1, At, B1); PG8_BAR;
;             PG8_LDA(At, 0, 1); PG8_STAGE(PG8_SA(0, 0), a2, voffA);
;             PG8_BAR; PG8_WAIT_L(0); PG8_MMA(1, 0, At, B0); PG8_BAR; PG8_SCHED;
;             PG8_STAGE(PG8_SB(0, 1), b2 + hstepB, voffB);
;             PG8_WAIT_V(6); PG8_BAR; PG8_MMA(1, 1, At, B1); PG8_BAR;
.LBB0_1322:
	s_add_u32 s8, s4, s6
	ds_read_b128 v[144:147], v122
	ds_read_b128 v[148:151], v122 offset:1024
	ds_read_b128 v[152:155], v122 offset:2048
	ds_read_b128 v[156:159], v122 offset:3072
	s_addc_u32 s9, s5, s7
	s_add_u32 s8, s8, 0x18500100
	s_addc_u32 s9, s9, 0
	s_add_u32 s49, s28, s6
	s_addc_u32 s50, s29, s7
	s_cmpk_eq_i32 s6, 0x3f00
	s_cselect_b32 s13, s11, s9
	s_cselect_b32 s12, s10, s8
	s_cselect_b32 s9, s3, s50
	s_cselect_b32 s8, s2, s49
	s_mov_b32 m0, s35
	v_lshl_add_u64 v[192:193], v[118:119], 0, s[6:7]
	ds_read_b128 v[160:163], v123
	ds_read_b128 v[164:167], v123 offset:1024
	ds_read_b128 v[168:171], v123 offset:2048
	ds_read_b128 v[172:175], v123 offset:3072
	ds_read_b128 v[176:179], v123 offset:4096
	ds_read_b128 v[180:183], v123 offset:5120
	ds_read_b128 v[184:187], v123 offset:6144
	ds_read_b128 v[188:191], v123 offset:7168
	global_load_lds_dwordx4 v[192:193], off
	v_lshl_add_u64 v[192:193], v[120:121], 0, s[6:7]
	s_mov_b32 m0, s40
	s_nop 0
	global_load_lds_dwordx4 v[192:193], off
	s_waitcnt lgkmcnt(8)
	s_barrier
	s_waitcnt lgkmcnt(0)
	s_setprio 1
	s_waitcnt lgkmcnt(0)
	v_mfma_f32_16x16x32_bf16 v[140:143], v[144:147], v[160:163], v[140:143]
	v_mfma_f32_16x16x32_bf16 v[136:139], v[152:155], v[160:163], v[136:139]
	v_mfma_f32_16x16x32_bf16 v[108:111], v[144:147], v[168:171], v[108:111]
	v_mfma_f32_16x16x32_bf16 v[104:107], v[152:155], v[168:171], v[104:107]
	v_mfma_f32_16x16x32_bf16 v[92:95], v[144:147], v[176:179], v[92:95]
	v_mfma_f32_16x16x32_bf16 v[88:91], v[152:155], v[176:179], v[88:91]
	v_mfma_f32_16x16x32_bf16 v[76:79], v[144:147], v[184:187], v[76:79]
	v_mfma_f32_16x16x32_bf16 v[72:75], v[152:155], v[184:187], v[72:75]
	v_mfma_f32_16x16x32_bf16 v[140:143], v[148:151], v[164:167], v[140:143]
	v_mfma_f32_16x16x32_bf16 v[136:139], v[156:159], v[164:167], v[136:139]
	v_mfma_f32_16x16x32_bf16 v[108:111], v[148:151], v[172:175], v[108:111]
	v_mfma_f32_16x16x32_bf16 v[104:107], v[156:159], v[172:175], v[104:107]
	v_mfma_f32_16x16x32_bf16 v[92:95], v[148:151], v[180:183], v[92:95]
	v_mfma_f32_16x16x32_bf16 v[88:91], v[156:159], v[180:183], v[88:91]
	v_mfma_f32_16x16x32_bf16 v[76:79], v[148:151], v[188:191], v[76:79]
	v_mfma_f32_16x16x32_bf16 v[72:75], v[156:159], v[188:191], v[72:75]
	s_setprio 0
	s_barrier
	s_mov_b32 m0, s41
	s_add_u32 s98, s8, s0
	s_addc_u32 s99, s9, s1
	ds_read_b128 v[192:195], v124
	ds_read_b128 v[196:199], v124 offset:1024
	ds_read_b128 v[204:207], v124 offset:2048
	ds_read_b128 v[208:211], v124 offset:3072
	global_load_lds_dwordx4 v202, s[8:9]
	s_mov_b32 m0, s42
	s_nop 0
	global_load_lds_dwordx4 v116, s[8:9]
	s_barrier
	s_waitcnt lgkmcnt(0)
	s_setprio 1
	s_waitcnt lgkmcnt(0)
	v_mfma_f32_16x16x32_bf16 v[132:135], v[192:195], v[160:163], v[132:135]
	v_mfma_f32_16x16x32_bf16 v[128:131], v[204:207], v[160:163], v[128:131]
	v_mfma_f32_16x16x32_bf16 v[100:103], v[192:195], v[168:171], v[100:103]
	v_mfma_f32_16x16x32_bf16 v[96:99], v[204:207], v[168:171], v[96:99]
	v_mfma_f32_16x16x32_bf16 v[84:87], v[192:195], v[176:179], v[84:87]
	v_mfma_f32_16x16x32_bf16 v[80:83], v[204:207], v[176:179], v[80:83]
	v_mfma_f32_16x16x32_bf16 v[68:71], v[192:195], v[184:187], v[68:71]
	v_mfma_f32_16x16x32_bf16 v[64:67], v[204:207], v[184:187], v[64:67]
	v_mfma_f32_16x16x32_bf16 v[132:135], v[196:199], v[164:167], v[132:135]
	v_mfma_f32_16x16x32_bf16 v[128:131], v[208:211], v[164:167], v[128:131]
	v_mfma_f32_16x16x32_bf16 v[100:103], v[196:199], v[172:175], v[100:103]
	v_mfma_f32_16x16x32_bf16 v[96:99], v[208:211], v[172:175], v[96:99]
	v_mfma_f32_16x16x32_bf16 v[84:87], v[196:199], v[180:183], v[84:87]
	v_mfma_f32_16x16x32_bf16 v[80:83], v[208:211], v[180:183], v[80:83]
	v_mfma_f32_16x16x32_bf16 v[68:71], v[196:199], v[188:191], v[68:71]
	v_mfma_f32_16x16x32_bf16 v[64:67], v[208:211], v[188:191], v[64:67]
	s_setprio 0
	s_mov_b32 m0, s19
	s_add_u32 s100, s12, s0
	s_addc_u32 s101, s13, s1
	s_barrier
	ds_read_b128 v[160:163], v123 offset:16384
	ds_read_b128 v[164:167], v123 offset:17408
	ds_read_b128 v[168:171], v123 offset:18432
	ds_read_b128 v[172:175], v123 offset:19456
	ds_read_b128 v[176:179], v123 offset:20480
	ds_read_b128 v[180:183], v123 offset:21504
	ds_read_b128 v[184:187], v123 offset:22528
	ds_read_b128 v[188:191], v123 offset:23552
	global_load_lds_dwordx4 v112, s[12:13]
	s_mov_b32 m0, s30
	s_nop 0
	global_load_lds_dwordx4 v114, s[12:13]
	s_barrier
	s_waitcnt lgkmcnt(0)
	s_setprio 1
	s_waitcnt lgkmcnt(0)
	v_mfma_f32_16x16x32_bf16 v[60:63], v[144:147], v[160:163], v[60:63]
	v_mfma_f32_16x16x32_bf16 v[56:59], v[152:155], v[160:163], v[56:59]
	v_mfma_f32_16x16x32_bf16 v[44:47], v[144:147], v[168:171], v[44:47]
	v_mfma_f32_16x16x32_bf16 v[40:43], v[152:155], v[168:171], v[40:43]
	v_mfma_f32_16x16x32_bf16 v[28:31], v[144:147], v[176:179], v[28:31]
	v_mfma_f32_16x16x32_bf16 v[24:27], v[152:155], v[176:179], v[24:27]
	v_mfma_f32_16x16x32_bf16 v[12:15], v[144:147], v[184:187], v[12:15]
	v_mfma_f32_16x16x32_bf16 v[8:11], v[152:155], v[184:187], v[8:11]
	v_mfma_f32_16x16x32_bf16 v[60:63], v[148:151], v[164:167], v[60:63]
	v_mfma_f32_16x16x32_bf16 v[56:59], v[156:159], v[164:167], v[56:59]
	v_mfma_f32_16x16x32_bf16 v[44:47], v[148:151], v[172:175], v[44:47]
	v_mfma_f32_16x16x32_bf16 v[40:43], v[156:159], v[172:175], v[40:43]
	v_mfma_f32_16x16x32_bf16 v[28:31], v[148:151], v[180:183], v[28:31]
	v_mfma_f32_16x16x32_bf16 v[24:27], v[156:159], v[180:183], v[24:27]
	v_mfma_f32_16x16x32_bf16 v[12:15], v[148:151], v[188:191], v[12:15]
	v_mfma_f32_16x16x32_bf16 v[8:11], v[156:159], v[188:191], v[8:11]
	s_setprio 0
	s_barrier
; #define PG8_STAGE(bufoff, gbase, voff) do { _Pragma("unroll") for (int _i = 0; _i < 2; ++_i) \
;         __builtin_amdgcn_global_load_lds((const unsigned*)((const char*)(gbase) + (voff)[_i]), (LAS unsigned*)(lds + (bufoff) + ldsw + _i * 8192), 16, 0, 0); } while (0)
; #define PG8_LDA(dst, b, h) do { _Pragma("unroll") for (int m = 0; m < 4; ++m) _Pragma("unroll") for (int k = 0; k < 2; ++k) dst[m][k] = *(const LAS bf16x8*)(lds + PG8_SA(b, h) + aoff + m * 2048 + k * 1024); } while (0)
; #define PG8_LDB(dst, b, h) do { _Pragma("unroll") for (int n = 0; n < 2; ++n) _Pragma("unroll") for (int k = 0; k < 2; ++k) dst[n][k] = *(const LAS bf16x8*)(lds + PG8_SB(b, h) + boff + n * 2048 + k * 1024); } while (0)
; #define PG8_WAIT_V(n) asm volatile("s_waitcnt vmcnt(" #n ")" ::: "memory")
; #define PG8_WAIT_L(n) asm volatile("s_waitcnt lgkmcnt(" #n ")" ::: "memory")
; #define PG8_BAR __builtin_amdgcn_s_barrier()
; #define PG8_SCHED __builtin_amdgcn_sched_barrier(0)
; template <class Epi>
; __device__ __forceinline__ void gemm_phase(LAS unsigned char* lds, const bf16_t* A, int lda, const bf16_t* Bt, int ldb, int M, int N, int K, int asel, const Epi& E, const int fixed_round = -1) {
;     ...
;             PG8_STAGE(PG8_SB(0, 1), b2 + hstepB, voffB);
;             PG8_WAIT_V(6); PG8_BAR; PG8_MMA(1, 1, At, B1); PG8_BAR;
;             PG8_LDB(B0, 1, 0); PG8_SCHED; PG8_LDA(At, 1, 0); PG8_STAGE(PG8_SA(0, 1), a2 + hstepA, voffA);
;             PG8_WAIT_L(8); PG8_BAR; PG8_WAIT_L(0); PG8_MMA(0, 0, At, B0); PG8_BAR; PG8_SCHED;
;             PG8_LDB(B1, 1, 1); PG8_STAGE(PG8_SB(1, 0), b3, voffB);
;             PG8_BAR; PG8_WAIT_L(0); PG8_MMA(0, 1, At, B1); PG8_BAR;
;             PG8_LDA(At, 1, 1); PG8_STAGE(PG8_SA(1, 0), a3, voffA);
	s_add_u32 s50, s8, 0x200000
	s_addc_u32 s51, s9, 0
	s_mov_b32 m0, s43
	s_nop 0
	global_load_lds_dwordx4 v202, s[50:51]
	s_mov_b32 m0, s44
	s_nop 0
	global_load_lds_dwordx4 v116, s[50:51]
	s_waitcnt vmcnt(6)
	s_barrier
	s_setprio 1
	v_mfma_f32_16x16x32_bf16 v[52:55], v[192:195], v[160:163], v[52:55]
	v_mfma_f32_16x16x32_bf16 v[48:51], v[204:207], v[160:163], v[48:51]
	v_mfma_f32_16x16x32_bf16 v[36:39], v[192:195], v[168:171], v[36:39]
	v_mfma_f32_16x16x32_bf16 v[32:35], v[204:207], v[168:171], v[32:35]
	v_mfma_f32_16x16x32_bf16 v[20:23], v[192:195], v[176:179], v[20:23]
	v_mfma_f32_16x16x32_bf16 v[16:19], v[204:207], v[176:179], v[16:19]
	v_mfma_f32_16x16x32_bf16 v[4:7], v[192:195], v[184:187], v[4:7]
	v_mfma_f32_16x16x32_bf16 v[0:3], v[204:207], v[184:187], v[0:3]
	v_mfma_f32_16x16x32_bf16 v[52:55], v[196:199], v[164:167], v[52:55]
	v_mfma_f32_16x16x32_bf16 v[48:51], v[208:211], v[164:167], v[48:51]
	v_mfma_f32_16x16x32_bf16 v[36:39], v[196:199], v[172:175], v[36:39]
	v_mfma_f32_16x16x32_bf16 v[32:35], v[208:211], v[172:175], v[32:35]
	v_mfma_f32_16x16x32_bf16 v[20:23], v[196:199], v[180:183], v[20:23]
	v_mfma_f32_16x16x32_bf16 v[16:19], v[208:211], v[180:183], v[16:19]
	v_mfma_f32_16x16x32_bf16 v[4:7], v[196:199], v[188:191], v[4:7]
	v_mfma_f32_16x16x32_bf16 v[0:3], v[208:211], v[188:191], v[0:3]
	s_setprio 0
	s_barrier
	ds_read_b128 v[144:147], v125
	ds_read_b128 v[148:151], v125 offset:1024
	ds_read_b128 v[152:155], v125 offset:2048
	ds_read_b128 v[156:159], v125 offset:3072
	s_add_u32 s12, s12, 0x200000
	s_addc_u32 s13, s13, 0
	s_mov_b32 m0, s31
	ds_read_b128 v[160:163], v123 offset:32768
	ds_read_b128 v[164:167], v123 offset:33792
	ds_read_b128 v[168:171], v123 offset:34816
	ds_read_b128 v[172:175], v123 offset:35840
	ds_read_b128 v[176:179], v123 offset:36864
	ds_read_b128 v[180:183], v123 offset:37888
	ds_read_b128 v[184:187], v123 offset:38912
	ds_read_b128 v[188:191], v123 offset:39936
	global_load_lds_dwordx4 v112, s[12:13]
	s_mov_b32 m0, s33
	s_nop 0
	global_load_lds_dwordx4 v114, s[12:13]
	s_waitcnt lgkmcnt(8)
	s_barrier
	s_waitcnt lgkmcnt(0)
	s_setprio 1
	s_waitcnt lgkmcnt(0)
	v_mfma_f32_16x16x32_bf16 v[140:143], v[144:147], v[160:163], v[140:143]
	v_mfma_f32_16x16x32_bf16 v[136:139], v[152:155], v[160:163], v[136:139]
	v_mfma_f32_16x16x32_bf16 v[108:111], v[144:147], v[168:171], v[108:111]
	v_mfma_f32_16x16x32_bf16 v[104:107], v[152:155], v[168:171], v[104:107]
	v_mfma_f32_16x16x32_bf16 v[92:95], v[144:147], v[176:179], v[92:95]
	v_mfma_f32_16x16x32_bf16 v[88:91], v[152:155], v[176:179], v[88:91]
	v_mfma_f32_16x16x32_bf16 v[76:79], v[144:147], v[184:187], v[76:79]
	v_mfma_f32_16x16x32_bf16 v[72:75], v[152:155], v[184:187], v[72:75]
	v_mfma_f32_16x16x32_bf16 v[140:143], v[148:151], v[164:167], v[140:143]
	v_mfma_f32_16x16x32_bf16 v[136:139], v[156:159], v[164:167], v[136:139]
	v_mfma_f32_16x16x32_bf16 v[108:111], v[148:151], v[172:175], v[108:111]
	v_mfma_f32_16x16x32_bf16 v[104:107], v[156:159], v[172:175], v[104:107]
	v_mfma_f32_16x16x32_bf16 v[92:95], v[148:151], v[180:183], v[92:95]
	v_mfma_f32_16x16x32_bf16 v[88:91], v[156:159], v[180:183], v[88:91]
	v_mfma_f32_16x16x32_bf16 v[76:79], v[148:151], v[188:191], v[76:79]
	v_mfma_f32_16x16x32_bf16 v[72:75], v[156:159], v[188:191], v[72:75]
	s_setprio 0
	s_barrier
	s_mov_b32 m0, s45
	ds_read_b128 v[192:195], v126
	ds_read_b128 v[196:199], v126 offset:1024
	ds_read_b128 v[204:207], v126 offset:2048
	ds_read_b128 v[208:211], v126 offset:3072
	global_load_lds_dwordx4 v202, s[98:99]
	s_mov_b32 m0, s46
	s_nop 0
	global_load_lds_dwordx4 v116, s[98:99]
	s_barrier
; #define PG8_STAGE(bufoff, gbase, voff) do { _Pragma("unroll") for (int _i = 0; _i < 2; ++_i) \
;         __builtin_amdgcn_global_load_lds((const unsigned*)((const char*)(gbase) + (voff)[_i]), (LAS unsigned*)(lds + (bufoff) + ldsw + _i * 8192), 16, 0, 0); } while (0)
; #define PG8_LDA(dst, b, h) do { _Pragma("unroll") for (int m = 0; m < 4; ++m) _Pragma("unroll") for (int k = 0; k < 2; ++k) dst[m][k] = *(const LAS bf16x8*)(lds + PG8_SA(b, h) + aoff + m * 2048 + k * 1024); } while (0)
; #define PG8_WAIT_V(n) asm volatile("s_waitcnt vmcnt(" #n ")" ::: "memory")
; #define PG8_WAIT_L(n) asm volatile("s_waitcnt lgkmcnt(" #n ")" ::: "memory")
; #define PG8_BAR __builtin_amdgcn_s_barrier()
; #define PG8_SCHED __builtin_amdgcn_sched_barrier(0)
; template <class Epi>
; __device__ __forceinline__ void gemm_phase(LAS unsigned char* lds, const bf16_t* A, int lda, const bf16_t* Bt, int ldb, int M, int N, int K, int asel, const Epi& E, const int fixed_round = -1) {
;     ...
;             PG8_BAR; PG8_WAIT_L(0); PG8_MMA(0, 1, At, B1); PG8_BAR;
;             PG8_LDA(At, 1, 1); PG8_STAGE(PG8_SA(1, 0), a3, voffA);
;             PG8_BAR; PG8_WAIT_L(0); PG8_MMA(1, 0, At, B0); PG8_BAR; PG8_SCHED;
;             PG8_STAGE(PG8_SB(1, 1), b3 + hstepB, voffB);
;             PG8_WAIT_V(6); PG8_BAR; PG8_MMA(1, 1, At, B1); PG8_BAR;
;     ...
;     PG8_WAIT_V(0);
;     if (wr == 0) PG8_BAR;
;     PG8_BAR;
	s_waitcnt lgkmcnt(0)
	s_setprio 1
	s_waitcnt lgkmcnt(0)
	v_mfma_f32_16x16x32_bf16 v[132:135], v[192:195], v[160:163], v[132:135]
	v_mfma_f32_16x16x32_bf16 v[128:131], v[204:207], v[160:163], v[128:131]
	v_mfma_f32_16x16x32_bf16 v[100:103], v[192:195], v[168:171], v[100:103]
	v_mfma_f32_16x16x32_bf16 v[96:99], v[204:207], v[168:171], v[96:99]
	v_mfma_f32_16x16x32_bf16 v[84:87], v[192:195], v[176:179], v[84:87]
	v_mfma_f32_16x16x32_bf16 v[80:83], v[204:207], v[176:179], v[80:83]
	v_mfma_f32_16x16x32_bf16 v[68:71], v[192:195], v[184:187], v[68:71]
	v_mfma_f32_16x16x32_bf16 v[64:67], v[204:207], v[184:187], v[64:67]
	v_mfma_f32_16x16x32_bf16 v[132:135], v[196:199], v[164:167], v[132:135]
	v_mfma_f32_16x16x32_bf16 v[128:131], v[208:211], v[164:167], v[128:131]
	v_mfma_f32_16x16x32_bf16 v[100:103], v[196:199], v[172:175], v[100:103]
	v_mfma_f32_16x16x32_bf16 v[96:99], v[208:211], v[172:175], v[96:99]
	v_mfma_f32_16x16x32_bf16 v[84:87], v[196:199], v[180:183], v[84:87]
	v_mfma_f32_16x16x32_bf16 v[80:83], v[208:211], v[180:183], v[80:83]
	v_mfma_f32_16x16x32_bf16 v[68:71], v[196:199], v[188:191], v[68:71]
	v_mfma_f32_16x16x32_bf16 v[64:67], v[208:211], v[188:191], v[64:67]
	s_setprio 0
	s_mov_b32 m0, s36
	s_barrier
	ds_read_b128 v[160:163], v123 offset:49152
	ds_read_b128 v[164:167], v123 offset:50176
	ds_read_b128 v[168:171], v123 offset:51200
	ds_read_b128 v[172:175], v123 offset:52224
	ds_read_b128 v[176:179], v123 offset:53248
	ds_read_b128 v[180:183], v123 offset:54272
	ds_read_b128 v[184:187], v123 offset:55296
	ds_read_b128 v[188:191], v123 offset:56320
	global_load_lds_dwordx4 v112, s[100:101]
	s_mov_b32 m0, s37
	s_nop 0
	global_load_lds_dwordx4 v114, s[100:101]
	s_barrier
	s_waitcnt lgkmcnt(0)
	s_setprio 1
	s_waitcnt lgkmcnt(0)
	v_mfma_f32_16x16x32_bf16 v[60:63], v[144:147], v[160:163], v[60:63]
	v_mfma_f32_16x16x32_bf16 v[56:59], v[152:155], v[160:163], v[56:59]
	v_mfma_f32_16x16x32_bf16 v[44:47], v[144:147], v[168:171], v[44:47]
	v_mfma_f32_16x16x32_bf16 v[40:43], v[152:155], v[168:171], v[40:43]
	v_mfma_f32_16x16x32_bf16 v[28:31], v[144:147], v[176:179], v[28:31]
	v_mfma_f32_16x16x32_bf16 v[24:27], v[152:155], v[176:179], v[24:27]
	v_mfma_f32_16x16x32_bf16 v[12:15], v[144:147], v[184:187], v[12:15]
	v_mfma_f32_16x16x32_bf16 v[8:11], v[152:155], v[184:187], v[8:11]
	v_mfma_f32_16x16x32_bf16 v[60:63], v[148:151], v[164:167], v[60:63]
	v_mfma_f32_16x16x32_bf16 v[56:59], v[156:159], v[164:167], v[56:59]
	v_mfma_f32_16x16x32_bf16 v[44:47], v[148:151], v[172:175], v[44:47]
	v_mfma_f32_16x16x32_bf16 v[40:43], v[156:159], v[172:175], v[40:43]
	v_mfma_f32_16x16x32_bf16 v[28:31], v[148:151], v[180:183], v[28:31]
	v_mfma_f32_16x16x32_bf16 v[24:27], v[156:159], v[180:183], v[24:27]
	v_mfma_f32_16x16x32_bf16 v[12:15], v[148:151], v[188:191], v[12:15]
	v_mfma_f32_16x16x32_bf16 v[8:11], v[156:159], v[188:191], v[8:11]
	s_setprio 0
	s_barrier
	s_add_u32 s8, s8, 0x200080
	s_addc_u32 s9, s9, 0
	s_mov_b32 m0, s47
	s_nop 0
	global_load_lds_dwordx4 v202, s[8:9]
	s_mov_b32 m0, s48
	s_nop 0
	global_load_lds_dwordx4 v116, s[8:9]
	s_waitcnt vmcnt(6)
	s_barrier
	s_setprio 1
	v_mfma_f32_16x16x32_bf16 v[52:55], v[192:195], v[160:163], v[52:55]
	v_mfma_f32_16x16x32_bf16 v[48:51], v[204:207], v[160:163], v[48:51]
	v_mfma_f32_16x16x32_bf16 v[36:39], v[192:195], v[168:171], v[36:39]
	v_mfma_f32_16x16x32_bf16 v[32:35], v[204:207], v[168:171], v[32:35]
	v_mfma_f32_16x16x32_bf16 v[20:23], v[192:195], v[176:179], v[20:23]
	v_mfma_f32_16x16x32_bf16 v[16:19], v[204:207], v[176:179], v[16:19]
	v_mfma_f32_16x16x32_bf16 v[4:7], v[192:195], v[184:187], v[4:7]
	v_mfma_f32_16x16x32_bf16 v[0:3], v[204:207], v[184:187], v[0:3]
	v_mfma_f32_16x16x32_bf16 v[52:55], v[196:199], v[164:167], v[52:55]
	v_mfma_f32_16x16x32_bf16 v[48:51], v[208:211], v[164:167], v[48:51]
	v_mfma_f32_16x16x32_bf16 v[36:39], v[196:199], v[172:175], v[36:39]
	v_mfma_f32_16x16x32_bf16 v[32:35], v[208:211], v[172:175], v[32:35]
	v_mfma_f32_16x16x32_bf16 v[20:23], v[196:199], v[180:183], v[20:23]
	v_mfma_f32_16x16x32_bf16 v[16:19], v[208:211], v[180:183], v[16:19]
	v_mfma_f32_16x16x32_bf16 v[4:7], v[196:199], v[188:191], v[4:7]
	v_mfma_f32_16x16x32_bf16 v[0:3], v[208:211], v[188:191], v[0:3]
	s_setprio 0
	s_add_i32 s34, s34, 2
	s_add_u32 s6, s6, 0x100
	s_addc_u32 s7, s7, 0
	s_cmpk_lt_u32 s34, 0x7e
	s_barrier
	s_cbranch_scc1 .LBB0_1322
	s_waitcnt vmcnt(0)
	s_cmpk_gt_u32 s18, 0xff
	s_cbranch_scc1 .LBB0_1325
	s_barrier

; #define LAS __attribute__((address_space(3)))
; __global__ void __launch_bounds__(512) mega_fwd(Params p) {
;     extern __shared__ __attribute__((aligned(16))) unsigned char smem[];
;     LAS unsigned char* lds = (LAS unsigned char*)smem;
	.amdhsa_kernel _Z8mega_fwd6Params
		.amdhsa_group_segment_fixed_size 0
		.amdhsa_private_segment_fixed_size 0
		.amdhsa_kernarg_size 432
		.amdhsa_user_sgpr_count 2
		.amdhsa_user_sgpr_dispatch_ptr 0
		.amdhsa_user_sgpr_queue_ptr 0
		.amdhsa_user_sgpr_kernarg_segment_ptr 1
		.amdhsa_user_sgpr_dispatch_id 0
		.amdhsa_user_sgpr_kernarg_preload_length 0
		.amdhsa_user_sgpr_kernarg_preload_offset 0
		.amdhsa_user_sgpr_private_segment_size 0
		.amdhsa_uses_dynamic_stack 0
		.amdhsa_enable_private_segment 0
		.amdhsa_system_sgpr_workgroup_id_x 1
		.amdhsa_system_sgpr_workgroup_id_y 0
		.amdhsa_system_sgpr_workgroup_id_z 0
		.amdhsa_system_sgpr_workgroup_info 0
		.amdhsa_system_vgpr_workitem_id 2
		.amdhsa_next_free_vgpr 256
		.amdhsa_next_free_sgpr 102
		.amdhsa_accum_offset 256
		.amdhsa_reserve_vcc 1
		.amdhsa_float_round_mode_32 0
		.amdhsa_float_round_mode_16_64 0
		.amdhsa_float_denorm_mode_32 3
		.amdhsa_float_denorm_mode_16_64 3
		.amdhsa_dx10_clamp 1
		.amdhsa_ieee_mode 1
		.amdhsa_fp16_overflow 0
		.amdhsa_tg_split 0
		.amdhsa_exception_fp_ieee_invalid_op 0
		.amdhsa_exception_fp_denorm_src 0
		.amdhsa_exception_fp_ieee_div_zero 0
		.amdhsa_exception_fp_ieee_overflow 0
		.amdhsa_exception_fp_ieee_underflow 0
		.amdhsa_exception_fp_ieee_inexact 0
		.amdhsa_exception_int_div_zero 0
	.end_amdhsa_kernel

; #define LAS __attribute__((address_space(3)))
; __global__ void __launch_bounds__(512) mega_fwd(Params p) {
;     extern __shared__ __attribute__((aligned(16))) unsigned char smem[];
;     LAS unsigned char* lds = (LAS unsigned char*)smem;
amdhsa.kernels:
  - .agpr_count:     0
    .args:
      - .offset:         0
        .size:           176
        .value_kind:     by_value
      - .offset:         176
        .size:           4
        .value_kind:     hidden_block_count_x
      - .offset:         180
        .size:           4
        .value_kind:     hidden_block_count_y
      - .offset:         184
        .size:           4
        .value_kind:     hidden_block_count_z
      - .offset:         188
        .size:           2
        .value_kind:     hidden_group_size_x
      - .offset:         190
        .size:           2
        .value_kind:     hidden_group_size_y
      - .offset:         192
        .size:           2
        .value_kind:     hidden_group_size_z
      - .offset:         194
        .size:           2
        .value_kind:     hidden_remainder_x
      - .offset:         196
        .size:           2
        .value_kind:     hidden_remainder_y
      - .offset:         198
        .size:           2
        .value_kind:     hidden_remainder_z
      - .offset:         216
        .size:           8
        .value_kind:     hidden_global_offset_x
      - .offset:         224
        .size:           8
        .value_kind:     hidden_global_offset_y
      - .offset:         232
        .size:           8
        .value_kind:     hidden_global_offset_z
      - .offset:         240
        .size:           2
        .value_kind:     hidden_grid_dims
      - .offset:         264
        .size:           8
        .value_kind:     hidden_multigrid_sync_arg
      - .offset:         296
        .size:           4
        .value_kind:     hidden_dynamic_lds_size
    .group_segment_fixed_size: 0
    .kernarg_segment_align: 8
    .kernarg_segment_size: 432
    .language:       OpenCL C
    .language_version:
      - 2
      - 0
    .max_flat_workgroup_size: 512
    .name:           _Z8mega_fwd6Params
    .private_segment_fixed_size: 0
    .sgpr_count:     108
    .sgpr_spill_count: 145
    .symbol:         _Z8mega_fwd6Params.kd
    .uniform_work_group_size: 1
    .uses_dynamic_stack: false
    .vgpr_count:     256
    .vgpr_spill_count: 0
    .wavefront_size: 64
